# GEMM loops: phases 3+4 and 7+8 merged into one load segment + one 32-MFMA segment (12 barriers per K-pair instead of 16), DMA order and counted waits unchanged
# speedup vs baseline: 1.0088x; 1.0088x over previous
; #define PG8_STAGE(bufoff, gbase, voff) do { _Pragma("unroll") for (int _i = 0; _i < 2; ++_i) \
;         __builtin_amdgcn_global_load_lds((const unsigned*)((const char*)(gbase) + (voff)[_i]), (PG8_LAS unsigned*)(lds + (bufoff) + ldsw + _i * 8192), 16, 0, 0); } while (0)
; #define PG8_LDA(dst, b, h) do { _Pragma("unroll") for (int m = 0; m < 4; ++m) _Pragma("unroll") for (int k = 0; k < 2; ++k) dst[m][k] = *(const PG8_LAS bf16x8*)(lds + PG8_SA(b, h) + aoff + m * 2048 + k * 1024); } while (0)
; #define PG8_LDB(dst, b, h) do { _Pragma("unroll") for (int n = 0; n < 2; ++n) _Pragma("unroll") for (int k = 0; k < 2; ++k) dst[n][k] = *(const PG8_LAS bf16x8*)(lds + PG8_SB(b, h) + boff + n * 2048 + k * 1024); } while (0)
; #define PG8_MMA(ai, bj, At, Bt) do { __builtin_amdgcn_s_setprio(1); _Pragma("unroll") for (int m = 0; m < 4; ++m) _Pragma("unroll") for (int n = 0; n < 2; ++n) _Pragma("unroll") for (int k = 0; k < 2; ++k) \
;         acc[ai][bj][m][n] = __builtin_amdgcn_mfma_f32_16x16x32_bf16(Bt[n][k], At[m][k], acc[ai][bj][m][n], 0, 0, 0); __builtin_amdgcn_s_setprio(0); } while (0)
; #define PG8_BAR __builtin_amdgcn_s_barrier()
; template <class Epi, class Sched, bool STAMP = false>
; __device__ __forceinline__ void gemm_phase(PG8_LAS unsigned char* lds, const Gemm g, const Sched& S, const Epi& E, unsigned long long* stamps) {
;     ...
;         for (int t = 0; t < nt; t += 2) {
;             const bool last = (t == nt - 2);
;             const char* a1 = cA + (size_t)(t + 1) * kstep;
;             const char* a2 = last ? nA : cA + (size_t)(t + 2) * kstep; const char* b2 = last ? nB : cB + (size_t)(t + 2) * kstep;
;             const char* a3 = a2 + kstep; const char* b3 = b2 + kstep;
;             if (last && has_next) S.a_ready(nxt);
;             PG8_LDB(B0, 0, 0); PG8_SCHED; PG8_LDA(At, 0, 0); PG8_STAGE(PG8_SA(1, 1), a1 + hstep, voffA);
;             PG8_WAIT_L(8); PG8_BAR; PG8_WAIT_L(0); PG8_MMA(0, 0, At, B0); PG8_BAR; PG8_SCHED;
;             PG8_LDB(B1, 0, 1); PG8_STAGE(PG8_SB(0, 0), b2, voffB);
;             PG8_BAR; PG8_WAIT_L(0); PG8_MMA(0, 1, At, B1); PG8_BAR;
;             PG8_LDA(At, 0, 1); PG8_STAGE(PG8_SA(0, 0), a2, voffA);
;             PG8_BAR; PG8_WAIT_L(0); PG8_MMA(1, 0, At, B0); PG8_BAR; PG8_SCHED;
;             PG8_STAGE(PG8_SB(0, 1), b2 + hstep, voffB);
;             PG8_WAIT_V(6); PG8_BAR; PG8_MMA(1, 1, At, B1); PG8_BAR;
.LBB0_62:
	s_add_u32 s75, s16, 0x100
	s_addc_u32 s76, s17, 0
	s_mov_b32 s77, -2
	s_cmp_eq_u32 s59, s99
	s_cbranch_scc1 .Lgu1_half_loop_z
	ds_read_b128 v[140:143], v148
	ds_read_b128 v[166:169], v149
	ds_read_b128 v[170:173], v150
	ds_read_b128 v[174:177], v151
	s_add_u32 s16, s14, 0x100
	s_addc_u32 s17, s15, 0
	s_cmp_eq_u32 s77, 12
	s_cselect_b32 s29, s5, s17
	s_cselect_b32 s28, s4, s16
	s_cselect_b32 s19, s1, s76
	s_cselect_b32 s18, s0, s75
	s_mov_b32 m0, s68
	ds_read_b128 v[178:181], v146
	ds_read_b128 v[182:185], v146 offset:1024
	ds_read_b128 v[186:189], v146 offset:2048
	ds_read_b128 v[190:193], v146 offset:3072
	ds_read_b128 v[194:197], v146 offset:4096
	ds_read_b128 v[198:201], v146 offset:5120
	ds_read_b128 v[202:205], v146 offset:6144
	ds_read_b128 v[206:209], v146 offset:7168
	global_load_lds_dwordx4 v132, s[14:15]
	s_mov_b32 m0, s69
	s_nop 0
	global_load_lds_dwordx4 v134, s[14:15]
	s_waitcnt lgkmcnt(8)
	s_barrier
	s_waitcnt lgkmcnt(0)
	s_setprio 1
	s_waitcnt lgkmcnt(0)
	v_mfma_f32_16x16x32_bf16 v[124:127], v[140:143], v[178:181], 0
	v_mfma_f32_16x16x32_bf16 v[120:123], v[170:173], v[178:181], 0
	v_mfma_f32_16x16x32_bf16 v[108:111], v[140:143], v[186:189], 0
	v_mfma_f32_16x16x32_bf16 v[104:107], v[170:173], v[186:189], 0
	v_mfma_f32_16x16x32_bf16 v[92:95], v[140:143], v[194:197], 0
	v_mfma_f32_16x16x32_bf16 v[88:91], v[170:173], v[194:197], 0
	v_mfma_f32_16x16x32_bf16 v[76:79], v[140:143], v[202:205], 0
	v_mfma_f32_16x16x32_bf16 v[72:75], v[170:173], v[202:205], 0
	v_mfma_f32_16x16x32_bf16 v[124:127], v[166:169], v[182:185], v[124:127]
	v_mfma_f32_16x16x32_bf16 v[120:123], v[174:177], v[182:185], v[120:123]
	v_mfma_f32_16x16x32_bf16 v[108:111], v[166:169], v[190:193], v[108:111]
	v_mfma_f32_16x16x32_bf16 v[104:107], v[174:177], v[190:193], v[104:107]
	v_mfma_f32_16x16x32_bf16 v[92:95], v[166:169], v[198:201], v[92:95]
	v_mfma_f32_16x16x32_bf16 v[88:91], v[174:177], v[198:201], v[88:91]
	v_mfma_f32_16x16x32_bf16 v[76:79], v[166:169], v[206:209], v[76:79]
	v_mfma_f32_16x16x32_bf16 v[72:75], v[174:177], v[206:209], v[72:75]
	s_setprio 0
	s_barrier
	s_mov_b32 m0, s52
	ds_read_b128 v[210:213], v152
	ds_read_b128 v[214:217], v153
	ds_read_b128 v[218:221], v154
	ds_read_b128 v[222:225], v155
	global_load_lds_dwordx4 v130, s[18:19]
	s_mov_b32 m0, s53
	s_nop 0
	global_load_lds_dwordx4 v128, s[18:19]
	s_waitcnt lgkmcnt(0)
	s_barrier
	s_waitcnt lgkmcnt(0)
	s_setprio 1
	s_waitcnt lgkmcnt(0)
	v_mfma_f32_16x16x32_bf16 v[116:119], v[210:213], v[178:181], 0
	v_mfma_f32_16x16x32_bf16 v[112:115], v[218:221], v[178:181], 0
	v_mfma_f32_16x16x32_bf16 v[100:103], v[210:213], v[186:189], 0
	v_mfma_f32_16x16x32_bf16 v[96:99], v[218:221], v[186:189], 0
	v_mfma_f32_16x16x32_bf16 v[84:87], v[210:213], v[194:197], 0
	v_mfma_f32_16x16x32_bf16 v[80:83], v[218:221], v[194:197], 0
	v_mfma_f32_16x16x32_bf16 v[68:71], v[210:213], v[202:205], 0
	v_mfma_f32_16x16x32_bf16 v[64:67], v[218:221], v[202:205], 0
	v_mfma_f32_16x16x32_bf16 v[116:119], v[214:217], v[182:185], v[116:119]
	v_mfma_f32_16x16x32_bf16 v[112:115], v[222:225], v[182:185], v[112:115]
	v_mfma_f32_16x16x32_bf16 v[100:103], v[214:217], v[190:193], v[100:103]
	v_mfma_f32_16x16x32_bf16 v[96:99], v[222:225], v[190:193], v[96:99]
	v_mfma_f32_16x16x32_bf16 v[84:87], v[214:217], v[198:201], v[84:87]
	v_mfma_f32_16x16x32_bf16 v[80:83], v[222:225], v[198:201], v[80:83]
	v_mfma_f32_16x16x32_bf16 v[68:71], v[214:217], v[206:209], v[68:71]
	v_mfma_f32_16x16x32_bf16 v[64:67], v[222:225], v[206:209], v[64:67]
	s_setprio 0
	s_mov_b32 m0, s33
	s_barrier
	ds_read_b128 v[178:181], v146 offset:16384
	ds_read_b128 v[182:185], v146 offset:17408
	ds_read_b128 v[186:189], v146 offset:18432
	ds_read_b128 v[190:193], v146 offset:19456
	ds_read_b128 v[194:197], v146 offset:20480
	ds_read_b128 v[198:201], v146 offset:21504
	ds_read_b128 v[202:205], v146 offset:22528
	ds_read_b128 v[206:209], v146 offset:23552
	global_load_lds_dwordx4 v130, s[28:29]
	s_mov_b32 m0, s54
	s_nop 0
	global_load_lds_dwordx4 v128, s[28:29]
	s_add_u32 s14, s18, 0x44000
	s_addc_u32 s15, s19, 0
	s_mov_b32 m0, s55
	s_nop 0
	global_load_lds_dwordx4 v130, s[14:15]
	s_mov_b32 m0, s56
	s_nop 0
	global_load_lds_dwordx4 v128, s[14:15]
	s_waitcnt vmcnt(6)
	s_barrier
	s_waitcnt lgkmcnt(0)
	s_setprio 1
	s_waitcnt lgkmcnt(0)
	v_mfma_f32_16x16x32_bf16 v[60:63], v[140:143], v[178:181], 0
	v_mfma_f32_16x16x32_bf16 v[56:59], v[170:173], v[178:181], 0
	v_mfma_f32_16x16x32_bf16 v[44:47], v[140:143], v[186:189], 0
	v_mfma_f32_16x16x32_bf16 v[40:43], v[170:173], v[186:189], 0
	v_mfma_f32_16x16x32_bf16 v[28:31], v[140:143], v[194:197], 0
	v_mfma_f32_16x16x32_bf16 v[24:27], v[170:173], v[194:197], 0
	v_mfma_f32_16x16x32_bf16 v[12:15], v[140:143], v[202:205], 0
	v_mfma_f32_16x16x32_bf16 v[8:11], v[170:173], v[202:205], 0
	v_mfma_f32_16x16x32_bf16 v[60:63], v[166:169], v[182:185], v[60:63]
	v_mfma_f32_16x16x32_bf16 v[56:59], v[174:177], v[182:185], v[56:59]
	v_mfma_f32_16x16x32_bf16 v[44:47], v[166:169], v[190:193], v[44:47]
	v_mfma_f32_16x16x32_bf16 v[40:43], v[174:177], v[190:193], v[40:43]
	v_mfma_f32_16x16x32_bf16 v[28:31], v[166:169], v[198:201], v[28:31]
	v_mfma_f32_16x16x32_bf16 v[24:27], v[174:177], v[198:201], v[24:27]
	v_mfma_f32_16x16x32_bf16 v[12:15], v[166:169], v[206:209], v[12:15]
	v_mfma_f32_16x16x32_bf16 v[8:11], v[174:177], v[206:209], v[8:11]
	v_mfma_f32_16x16x32_bf16 v[52:55], v[210:213], v[178:181], 0
	v_mfma_f32_16x16x32_bf16 v[48:51], v[218:221], v[178:181], 0
	v_mfma_f32_16x16x32_bf16 v[36:39], v[210:213], v[186:189], 0
	v_mfma_f32_16x16x32_bf16 v[32:35], v[218:221], v[186:189], 0
	v_mfma_f32_16x16x32_bf16 v[20:23], v[210:213], v[194:197], 0
	v_mfma_f32_16x16x32_bf16 v[16:19], v[218:221], v[194:197], 0
	v_mfma_f32_16x16x32_bf16 v[4:7], v[210:213], v[202:205], 0
	v_mfma_f32_16x16x32_bf16 v[0:3], v[218:221], v[202:205], 0
	v_mfma_f32_16x16x32_bf16 v[52:55], v[214:217], v[182:185], v[52:55]
	v_mfma_f32_16x16x32_bf16 v[48:51], v[222:225], v[182:185], v[48:51]
	v_mfma_f32_16x16x32_bf16 v[36:39], v[214:217], v[190:193], v[36:39]
	v_mfma_f32_16x16x32_bf16 v[32:35], v[222:225], v[190:193], v[32:35]
	v_mfma_f32_16x16x32_bf16 v[20:23], v[214:217], v[198:201], v[20:23]
	v_mfma_f32_16x16x32_bf16 v[16:19], v[222:225], v[198:201], v[16:19]
	v_mfma_f32_16x16x32_bf16 v[4:7], v[214:217], v[206:209], v[4:7]
	v_mfma_f32_16x16x32_bf16 v[0:3], v[222:225], v[206:209], v[0:3]
	s_setprio 0
	s_barrier
	s_branch .Lzp1_mid
; #define PG8_STAGE(bufoff, gbase, voff) do { _Pragma("unroll") for (int _i = 0; _i < 2; ++_i) \
;         __builtin_amdgcn_global_load_lds((const unsigned*)((const char*)(gbase) + (voff)[_i]), (PG8_LAS unsigned*)(lds + (bufoff) + ldsw + _i * 8192), 16, 0, 0); } while (0)
; #define PG8_LDA(dst, b, h) do { _Pragma("unroll") for (int m = 0; m < 4; ++m) _Pragma("unroll") for (int k = 0; k < 2; ++k) dst[m][k] = *(const PG8_LAS bf16x8*)(lds + PG8_SA(b, h) + aoff + m * 2048 + k * 1024); } while (0)
; #define PG8_LDB(dst, b, h) do { _Pragma("unroll") for (int n = 0; n < 2; ++n) _Pragma("unroll") for (int k = 0; k < 2; ++k) dst[n][k] = *(const PG8_LAS bf16x8*)(lds + PG8_SB(b, h) + boff + n * 2048 + k * 1024); } while (0)
; #define PG8_WAIT_V(n) asm volatile("s_waitcnt vmcnt(" #n ")" ::: "memory")
; #define PG8_WAIT_L(n) asm volatile("s_waitcnt lgkmcnt(" #n ")" ::: "memory")
; #define PG8_BAR __builtin_amdgcn_s_barrier()
; template <class Epi, class Sched, bool STAMP = false>
; __device__ __forceinline__ void gemm_phase(PG8_LAS unsigned char* lds, const Gemm g, const Sched& S, const Epi& E, unsigned long long* stamps) {
;     ...
;             PG8_LDB(B0, 0, 0); PG8_SCHED; PG8_LDA(At, 0, 0); PG8_STAGE(PG8_SA(1, 1), a1 + hstep, voffA);
;             PG8_WAIT_L(8); PG8_BAR; PG8_WAIT_L(0); PG8_MMA(0, 0, At, B0); PG8_BAR; PG8_SCHED;
;             PG8_LDB(B1, 0, 1); PG8_STAGE(PG8_SB(0, 0), b2, voffB);
;             PG8_BAR; PG8_WAIT_L(0); PG8_MMA(0, 1, At, B1); PG8_BAR;
;             PG8_LDA(At, 0, 1); PG8_STAGE(PG8_SA(0, 0), a2, voffA);
;             PG8_BAR; PG8_WAIT_L(0); PG8_MMA(1, 0, At, B0); PG8_BAR; PG8_SCHED;
;             PG8_STAGE(PG8_SB(0, 1), b2 + hstep, voffB);
;             PG8_WAIT_V(6); PG8_BAR; PG8_MMA(1, 1, At, B1); PG8_BAR;
;             PG8_LDB(B0, 1, 0); PG8_SCHED; PG8_LDA(At, 1, 0); PG8_STAGE(PG8_SA(0, 1), a2 + hstep, voffA);
;             PG8_WAIT_L(8); PG8_BAR; PG8_WAIT_L(0); PG8_MMA(0, 0, At, B0); PG8_BAR; PG8_SCHED;
;             PG8_LDB(B1, 1, 1); PG8_STAGE(PG8_SB(1, 0), b3, voffB);
;             PG8_BAR; PG8_WAIT_L(0); PG8_MMA(0, 1, At, B1); PG8_BAR;
;             PG8_LDA(At, 1, 1); PG8_STAGE(PG8_SA(1, 0), a3, voffA);
;             PG8_BAR; PG8_WAIT_L(0); PG8_MMA(1, 0, At, B0); PG8_BAR; PG8_SCHED;
;             PG8_STAGE(PG8_SB(1, 1), b3 + hstep, voffB);
;             PG8_WAIT_V(6); PG8_BAR; PG8_MMA(1, 1, At, B1); PG8_BAR;
.LBB0_63:
	ds_read_b128 v[140:143], v148
	ds_read_b128 v[166:169], v149
	ds_read_b128 v[170:173], v150
	ds_read_b128 v[174:177], v151
	s_add_u32 s16, s14, 0x100
	s_addc_u32 s17, s15, 0
	s_cmp_eq_u32 s77, 12
	s_cselect_b32 s29, s5, s17
	s_cselect_b32 s28, s4, s16
	s_cselect_b32 s19, s1, s76
	s_cselect_b32 s18, s0, s75
	s_mov_b32 m0, s68
	ds_read_b128 v[178:181], v146
	ds_read_b128 v[182:185], v146 offset:1024
	ds_read_b128 v[186:189], v146 offset:2048
	ds_read_b128 v[190:193], v146 offset:3072
	ds_read_b128 v[194:197], v146 offset:4096
	ds_read_b128 v[198:201], v146 offset:5120
	ds_read_b128 v[202:205], v146 offset:6144
	ds_read_b128 v[206:209], v146 offset:7168
	global_load_lds_dwordx4 v132, s[14:15]
	s_mov_b32 m0, s69
	s_nop 0
	global_load_lds_dwordx4 v134, s[14:15]
	s_waitcnt lgkmcnt(8)
	s_barrier
	s_waitcnt lgkmcnt(0)
	s_setprio 1
	s_waitcnt lgkmcnt(0)
	v_mfma_f32_16x16x32_bf16 v[124:127], v[140:143], v[178:181], v[124:127]
	v_mfma_f32_16x16x32_bf16 v[120:123], v[170:173], v[178:181], v[120:123]
	v_mfma_f32_16x16x32_bf16 v[108:111], v[140:143], v[186:189], v[108:111]
	v_mfma_f32_16x16x32_bf16 v[104:107], v[170:173], v[186:189], v[104:107]
	v_mfma_f32_16x16x32_bf16 v[92:95], v[140:143], v[194:197], v[92:95]
	v_mfma_f32_16x16x32_bf16 v[88:91], v[170:173], v[194:197], v[88:91]
	v_mfma_f32_16x16x32_bf16 v[76:79], v[140:143], v[202:205], v[76:79]
	v_mfma_f32_16x16x32_bf16 v[72:75], v[170:173], v[202:205], v[72:75]
	v_mfma_f32_16x16x32_bf16 v[124:127], v[166:169], v[182:185], v[124:127]
	v_mfma_f32_16x16x32_bf16 v[120:123], v[174:177], v[182:185], v[120:123]
	v_mfma_f32_16x16x32_bf16 v[108:111], v[166:169], v[190:193], v[108:111]
	v_mfma_f32_16x16x32_bf16 v[104:107], v[174:177], v[190:193], v[104:107]
	v_mfma_f32_16x16x32_bf16 v[92:95], v[166:169], v[198:201], v[92:95]
	v_mfma_f32_16x16x32_bf16 v[88:91], v[174:177], v[198:201], v[88:91]
	v_mfma_f32_16x16x32_bf16 v[76:79], v[166:169], v[206:209], v[76:79]
	v_mfma_f32_16x16x32_bf16 v[72:75], v[174:177], v[206:209], v[72:75]
	s_setprio 0
	s_barrier
	s_mov_b32 m0, s52
	ds_read_b128 v[210:213], v152
	ds_read_b128 v[214:217], v153
	ds_read_b128 v[218:221], v154
	ds_read_b128 v[222:225], v155
	global_load_lds_dwordx4 v130, s[18:19]
	s_mov_b32 m0, s53
	s_nop 0
	global_load_lds_dwordx4 v128, s[18:19]
	s_waitcnt lgkmcnt(0)
	s_barrier
	s_waitcnt lgkmcnt(0)
	s_setprio 1
	s_waitcnt lgkmcnt(0)
	v_mfma_f32_16x16x32_bf16 v[116:119], v[210:213], v[178:181], v[116:119]
	v_mfma_f32_16x16x32_bf16 v[112:115], v[218:221], v[178:181], v[112:115]
	v_mfma_f32_16x16x32_bf16 v[100:103], v[210:213], v[186:189], v[100:103]
	v_mfma_f32_16x16x32_bf16 v[96:99], v[218:221], v[186:189], v[96:99]
	v_mfma_f32_16x16x32_bf16 v[84:87], v[210:213], v[194:197], v[84:87]
	v_mfma_f32_16x16x32_bf16 v[80:83], v[218:221], v[194:197], v[80:83]
	v_mfma_f32_16x16x32_bf16 v[68:71], v[210:213], v[202:205], v[68:71]
	v_mfma_f32_16x16x32_bf16 v[64:67], v[218:221], v[202:205], v[64:67]
	v_mfma_f32_16x16x32_bf16 v[116:119], v[214:217], v[182:185], v[116:119]
	v_mfma_f32_16x16x32_bf16 v[112:115], v[222:225], v[182:185], v[112:115]
	v_mfma_f32_16x16x32_bf16 v[100:103], v[214:217], v[190:193], v[100:103]
	v_mfma_f32_16x16x32_bf16 v[96:99], v[222:225], v[190:193], v[96:99]
	v_mfma_f32_16x16x32_bf16 v[84:87], v[214:217], v[198:201], v[84:87]
	v_mfma_f32_16x16x32_bf16 v[80:83], v[222:225], v[198:201], v[80:83]
	v_mfma_f32_16x16x32_bf16 v[68:71], v[214:217], v[206:209], v[68:71]
	v_mfma_f32_16x16x32_bf16 v[64:67], v[222:225], v[206:209], v[64:67]
	s_setprio 0
	s_mov_b32 m0, s33
	s_barrier
	ds_read_b128 v[178:181], v146 offset:16384
	ds_read_b128 v[182:185], v146 offset:17408
	ds_read_b128 v[186:189], v146 offset:18432
	ds_read_b128 v[190:193], v146 offset:19456
	ds_read_b128 v[194:197], v146 offset:20480
	ds_read_b128 v[198:201], v146 offset:21504
	ds_read_b128 v[202:205], v146 offset:22528
	ds_read_b128 v[206:209], v146 offset:23552
	global_load_lds_dwordx4 v130, s[28:29]
	s_mov_b32 m0, s54
	s_nop 0
	global_load_lds_dwordx4 v128, s[28:29]
	s_add_u32 s14, s18, 0x44000
	s_addc_u32 s15, s19, 0
	s_mov_b32 m0, s55
	s_nop 0
	global_load_lds_dwordx4 v130, s[14:15]
	s_mov_b32 m0, s56
	s_nop 0
	global_load_lds_dwordx4 v128, s[14:15]
	s_waitcnt vmcnt(6)
	s_barrier
	s_waitcnt lgkmcnt(0)
	s_setprio 1
	s_waitcnt lgkmcnt(0)
	v_mfma_f32_16x16x32_bf16 v[60:63], v[140:143], v[178:181], v[60:63]
	v_mfma_f32_16x16x32_bf16 v[56:59], v[170:173], v[178:181], v[56:59]
	v_mfma_f32_16x16x32_bf16 v[44:47], v[140:143], v[186:189], v[44:47]
	v_mfma_f32_16x16x32_bf16 v[40:43], v[170:173], v[186:189], v[40:43]
	v_mfma_f32_16x16x32_bf16 v[28:31], v[140:143], v[194:197], v[28:31]
	v_mfma_f32_16x16x32_bf16 v[24:27], v[170:173], v[194:197], v[24:27]
	v_mfma_f32_16x16x32_bf16 v[12:15], v[140:143], v[202:205], v[12:15]
	v_mfma_f32_16x16x32_bf16 v[8:11], v[170:173], v[202:205], v[8:11]
	v_mfma_f32_16x16x32_bf16 v[60:63], v[166:169], v[182:185], v[60:63]
	v_mfma_f32_16x16x32_bf16 v[56:59], v[174:177], v[182:185], v[56:59]
	v_mfma_f32_16x16x32_bf16 v[44:47], v[166:169], v[190:193], v[44:47]
	v_mfma_f32_16x16x32_bf16 v[40:43], v[174:177], v[190:193], v[40:43]
	v_mfma_f32_16x16x32_bf16 v[28:31], v[166:169], v[198:201], v[28:31]
	v_mfma_f32_16x16x32_bf16 v[24:27], v[174:177], v[198:201], v[24:27]
	v_mfma_f32_16x16x32_bf16 v[12:15], v[166:169], v[206:209], v[12:15]
	v_mfma_f32_16x16x32_bf16 v[8:11], v[174:177], v[206:209], v[8:11]
	v_mfma_f32_16x16x32_bf16 v[52:55], v[210:213], v[178:181], v[52:55]
	v_mfma_f32_16x16x32_bf16 v[48:51], v[218:221], v[178:181], v[48:51]
	v_mfma_f32_16x16x32_bf16 v[36:39], v[210:213], v[186:189], v[36:39]
	v_mfma_f32_16x16x32_bf16 v[32:35], v[218:221], v[186:189], v[32:35]
	v_mfma_f32_16x16x32_bf16 v[20:23], v[210:213], v[194:197], v[20:23]
	v_mfma_f32_16x16x32_bf16 v[16:19], v[218:221], v[194:197], v[16:19]
	v_mfma_f32_16x16x32_bf16 v[4:7], v[210:213], v[202:205], v[4:7]
	v_mfma_f32_16x16x32_bf16 v[0:3], v[218:221], v[202:205], v[0:3]
	v_mfma_f32_16x16x32_bf16 v[52:55], v[214:217], v[182:185], v[52:55]
	v_mfma_f32_16x16x32_bf16 v[48:51], v[222:225], v[182:185], v[48:51]
	v_mfma_f32_16x16x32_bf16 v[36:39], v[214:217], v[190:193], v[36:39]
	v_mfma_f32_16x16x32_bf16 v[32:35], v[222:225], v[190:193], v[32:35]
	v_mfma_f32_16x16x32_bf16 v[20:23], v[214:217], v[198:201], v[20:23]
	v_mfma_f32_16x16x32_bf16 v[16:19], v[222:225], v[198:201], v[16:19]
	v_mfma_f32_16x16x32_bf16 v[4:7], v[214:217], v[206:209], v[4:7]
	v_mfma_f32_16x16x32_bf16 v[0:3], v[222:225], v[206:209], v[0:3]
	s_setprio 0
	s_barrier
; #define PG8_STAGE(bufoff, gbase, voff) do { _Pragma("unroll") for (int _i = 0; _i < 2; ++_i) \
;         __builtin_amdgcn_global_load_lds((const unsigned*)((const char*)(gbase) + (voff)[_i]), (PG8_LAS unsigned*)(lds + (bufoff) + ldsw + _i * 8192), 16, 0, 0); } while (0)
; #define PG8_LDA(dst, b, h) do { _Pragma("unroll") for (int m = 0; m < 4; ++m) _Pragma("unroll") for (int k = 0; k < 2; ++k) dst[m][k] = *(const PG8_LAS bf16x8*)(lds + PG8_SA(b, h) + aoff + m * 2048 + k * 1024); } while (0)
; #define PG8_LDB(dst, b, h) do { _Pragma("unroll") for (int n = 0; n < 2; ++n) _Pragma("unroll") for (int k = 0; k < 2; ++k) dst[n][k] = *(const PG8_LAS bf16x8*)(lds + PG8_SB(b, h) + boff + n * 2048 + k * 1024); } while (0)
; #define PG8_MMA(ai, bj, At, Bt) do { __builtin_amdgcn_s_setprio(1); _Pragma("unroll") for (int m = 0; m < 4; ++m) _Pragma("unroll") for (int n = 0; n < 2; ++n) _Pragma("unroll") for (int k = 0; k < 2; ++k) \
;         acc[ai][bj][m][n] = __builtin_amdgcn_mfma_f32_16x16x32_bf16(Bt[n][k], At[m][k], acc[ai][bj][m][n], 0, 0, 0); __builtin_amdgcn_s_setprio(0); } while (0)
; #define PG8_WAIT_V(n) asm volatile("s_waitcnt vmcnt(" #n ")" ::: "memory")
; #define PG8_WAIT_L(n) asm volatile("s_waitcnt lgkmcnt(" #n ")" ::: "memory")
; #define PG8_BAR __builtin_amdgcn_s_barrier()
; #define PG8_SCHED __builtin_amdgcn_sched_barrier(0)
; template <class Epi, class Sched, bool STAMP = false>
; __device__ __forceinline__ void gemm_phase(PG8_LAS unsigned char* lds, const Gemm g, const Sched& S, const Epi& E, unsigned long long* stamps) {
;     ...
;             PG8_LDB(B0, 1, 0); PG8_SCHED; PG8_LDA(At, 1, 0); PG8_STAGE(PG8_SA(0, 1), a2 + hstep, voffA);
;             PG8_WAIT_L(8); PG8_BAR; PG8_WAIT_L(0); PG8_MMA(0, 0, At, B0); PG8_BAR; PG8_SCHED;
;             PG8_LDB(B1, 1, 1); PG8_STAGE(PG8_SB(1, 0), b3, voffB);
;             PG8_BAR; PG8_WAIT_L(0); PG8_MMA(0, 1, At, B1); PG8_BAR;
;             PG8_LDA(At, 1, 1); PG8_STAGE(PG8_SA(1, 0), a3, voffA);
;             PG8_BAR; PG8_WAIT_L(0); PG8_MMA(1, 0, At, B0); PG8_BAR; PG8_SCHED;
;             PG8_STAGE(PG8_SB(1, 1), b3 + hstep, voffB);
;             PG8_WAIT_V(6); PG8_BAR; PG8_MMA(1, 1, At, B1); PG8_BAR;
;         }
.Lzp1_mid:
	ds_read_b128 v[140:143], v156
	ds_read_b128 v[166:169], v157
	ds_read_b128 v[170:173], v159
	ds_read_b128 v[174:177], v160
	s_add_u32 s14, s28, 0x44000
	s_addc_u32 s15, s29, 0
	s_mov_b32 m0, s57
	ds_read_b128 v[178:181], v146 offset:32768
	ds_read_b128 v[182:185], v146 offset:33792
	ds_read_b128 v[186:189], v146 offset:34816
	ds_read_b128 v[190:193], v146 offset:35840
	ds_read_b128 v[194:197], v146 offset:36864
	ds_read_b128 v[198:201], v146 offset:37888
	ds_read_b128 v[202:205], v146 offset:38912
	ds_read_b128 v[206:209], v146 offset:39936
	global_load_lds_dwordx4 v130, s[14:15]
	s_mov_b32 m0, s58
	s_nop 0
	global_load_lds_dwordx4 v128, s[14:15]
	s_waitcnt lgkmcnt(8)
	s_barrier
	s_waitcnt lgkmcnt(0)
	s_setprio 1
	s_waitcnt lgkmcnt(0)
	v_mfma_f32_16x16x32_bf16 v[124:127], v[140:143], v[178:181], v[124:127]
	v_mfma_f32_16x16x32_bf16 v[120:123], v[170:173], v[178:181], v[120:123]
	v_mfma_f32_16x16x32_bf16 v[108:111], v[140:143], v[186:189], v[108:111]
	v_mfma_f32_16x16x32_bf16 v[104:107], v[170:173], v[186:189], v[104:107]
	v_mfma_f32_16x16x32_bf16 v[92:95], v[140:143], v[194:197], v[92:95]
	v_mfma_f32_16x16x32_bf16 v[88:91], v[170:173], v[194:197], v[88:91]
	v_mfma_f32_16x16x32_bf16 v[76:79], v[140:143], v[202:205], v[76:79]
	v_mfma_f32_16x16x32_bf16 v[72:75], v[170:173], v[202:205], v[72:75]
	v_mfma_f32_16x16x32_bf16 v[124:127], v[166:169], v[182:185], v[124:127]
	v_mfma_f32_16x16x32_bf16 v[120:123], v[174:177], v[182:185], v[120:123]
	v_mfma_f32_16x16x32_bf16 v[108:111], v[166:169], v[190:193], v[108:111]
	v_mfma_f32_16x16x32_bf16 v[104:107], v[174:177], v[190:193], v[104:107]
	v_mfma_f32_16x16x32_bf16 v[92:95], v[166:169], v[198:201], v[92:95]
	v_mfma_f32_16x16x32_bf16 v[88:91], v[174:177], v[198:201], v[88:91]
	v_mfma_f32_16x16x32_bf16 v[76:79], v[166:169], v[206:209], v[76:79]
	v_mfma_f32_16x16x32_bf16 v[72:75], v[174:177], v[206:209], v[72:75]
	s_setprio 0
	s_barrier
	s_mov_b32 m0, s61
	ds_read_b128 v[210:213], v161
	ds_read_b128 v[214:217], v162
	ds_read_b128 v[218:221], v163
	ds_read_b128 v[222:225], v164
	s_add_u32 s100, s18, 0x80
	s_addc_u32 s101, s19, 0
	global_load_lds_dwordx4 v130, s[100:101]
	s_mov_b32 m0, s62
	s_nop 0
	global_load_lds_dwordx4 v128, s[100:101]
	s_waitcnt lgkmcnt(0)
	s_barrier
	s_waitcnt lgkmcnt(0)
	s_setprio 1
	s_waitcnt lgkmcnt(0)
	v_mfma_f32_16x16x32_bf16 v[116:119], v[210:213], v[178:181], v[116:119]
	v_mfma_f32_16x16x32_bf16 v[112:115], v[218:221], v[178:181], v[112:115]
	v_mfma_f32_16x16x32_bf16 v[100:103], v[210:213], v[186:189], v[100:103]
	v_mfma_f32_16x16x32_bf16 v[96:99], v[218:221], v[186:189], v[96:99]
	v_mfma_f32_16x16x32_bf16 v[84:87], v[210:213], v[194:197], v[84:87]
	v_mfma_f32_16x16x32_bf16 v[80:83], v[218:221], v[194:197], v[80:83]
	v_mfma_f32_16x16x32_bf16 v[68:71], v[210:213], v[202:205], v[68:71]
	v_mfma_f32_16x16x32_bf16 v[64:67], v[218:221], v[202:205], v[64:67]
	v_mfma_f32_16x16x32_bf16 v[116:119], v[214:217], v[182:185], v[116:119]
	v_mfma_f32_16x16x32_bf16 v[112:115], v[222:225], v[182:185], v[112:115]
	v_mfma_f32_16x16x32_bf16 v[100:103], v[214:217], v[190:193], v[100:103]
	v_mfma_f32_16x16x32_bf16 v[96:99], v[222:225], v[190:193], v[96:99]
	v_mfma_f32_16x16x32_bf16 v[84:87], v[214:217], v[198:201], v[84:87]
	v_mfma_f32_16x16x32_bf16 v[80:83], v[222:225], v[198:201], v[80:83]
	v_mfma_f32_16x16x32_bf16 v[68:71], v[214:217], v[206:209], v[68:71]
	v_mfma_f32_16x16x32_bf16 v[64:67], v[222:225], v[206:209], v[64:67]
	s_setprio 0
	s_mov_b32 m0, s63
	s_barrier
	ds_read_b128 v[178:181], v146 offset:49152
	ds_read_b128 v[182:185], v146 offset:50176
	ds_read_b128 v[186:189], v146 offset:51200
	ds_read_b128 v[190:193], v146 offset:52224
	ds_read_b128 v[194:197], v146 offset:53248
	ds_read_b128 v[198:201], v146 offset:54272
	ds_read_b128 v[202:205], v146 offset:55296
	ds_read_b128 v[206:209], v146 offset:56320
	s_add_u32 s100, s28, 0x80
	s_addc_u32 s101, s29, 0
	global_load_lds_dwordx4 v130, s[100:101]
	s_mov_b32 m0, s64
	s_nop 0
	global_load_lds_dwordx4 v128, s[100:101]
	s_add_u32 s14, s18, 0x44080
	s_addc_u32 s15, s19, 0
	s_mov_b32 m0, s65
	s_nop 0
	global_load_lds_dwordx4 v130, s[14:15]
	s_mov_b32 m0, s66
	s_nop 0
	global_load_lds_dwordx4 v128, s[14:15]
	s_waitcnt vmcnt(6)
	s_barrier
	s_waitcnt lgkmcnt(0)
	s_setprio 1
	s_waitcnt lgkmcnt(0)
	v_mfma_f32_16x16x32_bf16 v[60:63], v[140:143], v[178:181], v[60:63]
	v_mfma_f32_16x16x32_bf16 v[56:59], v[170:173], v[178:181], v[56:59]
	v_mfma_f32_16x16x32_bf16 v[44:47], v[140:143], v[186:189], v[44:47]
	v_mfma_f32_16x16x32_bf16 v[40:43], v[170:173], v[186:189], v[40:43]
	v_mfma_f32_16x16x32_bf16 v[28:31], v[140:143], v[194:197], v[28:31]
	v_mfma_f32_16x16x32_bf16 v[24:27], v[170:173], v[194:197], v[24:27]
	v_mfma_f32_16x16x32_bf16 v[12:15], v[140:143], v[202:205], v[12:15]
	v_mfma_f32_16x16x32_bf16 v[8:11], v[170:173], v[202:205], v[8:11]
	v_mfma_f32_16x16x32_bf16 v[60:63], v[166:169], v[182:185], v[60:63]
	v_mfma_f32_16x16x32_bf16 v[56:59], v[174:177], v[182:185], v[56:59]
	v_mfma_f32_16x16x32_bf16 v[44:47], v[166:169], v[190:193], v[44:47]
	v_mfma_f32_16x16x32_bf16 v[40:43], v[174:177], v[190:193], v[40:43]
	v_mfma_f32_16x16x32_bf16 v[28:31], v[166:169], v[198:201], v[28:31]
	v_mfma_f32_16x16x32_bf16 v[24:27], v[174:177], v[198:201], v[24:27]
	v_mfma_f32_16x16x32_bf16 v[12:15], v[166:169], v[206:209], v[12:15]
	v_mfma_f32_16x16x32_bf16 v[8:11], v[174:177], v[206:209], v[8:11]
	v_mfma_f32_16x16x32_bf16 v[52:55], v[210:213], v[178:181], v[52:55]
	v_mfma_f32_16x16x32_bf16 v[48:51], v[218:221], v[178:181], v[48:51]
	v_mfma_f32_16x16x32_bf16 v[36:39], v[210:213], v[186:189], v[36:39]
	v_mfma_f32_16x16x32_bf16 v[32:35], v[218:221], v[186:189], v[32:35]
	v_mfma_f32_16x16x32_bf16 v[20:23], v[210:213], v[194:197], v[20:23]
	v_mfma_f32_16x16x32_bf16 v[16:19], v[218:221], v[194:197], v[16:19]
	v_mfma_f32_16x16x32_bf16 v[4:7], v[210:213], v[202:205], v[4:7]
	v_mfma_f32_16x16x32_bf16 v[0:3], v[218:221], v[202:205], v[0:3]
	v_mfma_f32_16x16x32_bf16 v[52:55], v[214:217], v[182:185], v[52:55]
	v_mfma_f32_16x16x32_bf16 v[48:51], v[222:225], v[182:185], v[48:51]
	v_mfma_f32_16x16x32_bf16 v[36:39], v[214:217], v[190:193], v[36:39]
	v_mfma_f32_16x16x32_bf16 v[32:35], v[222:225], v[190:193], v[32:35]
	v_mfma_f32_16x16x32_bf16 v[20:23], v[214:217], v[198:201], v[20:23]
	v_mfma_f32_16x16x32_bf16 v[16:19], v[222:225], v[198:201], v[16:19]
	v_mfma_f32_16x16x32_bf16 v[4:7], v[214:217], v[206:209], v[4:7]
	v_mfma_f32_16x16x32_bf16 v[0:3], v[222:225], v[206:209], v[0:3]
	s_setprio 0
	s_add_i32 s77, s77, 2
	s_add_u32 s75, s75, 0x100
	s_addc_u32 s76, s76, 0
	s_cmp_gt_u32 s77, 13
	s_mov_b64 s[14:15], s[16:17]
	s_barrier
; DI float ex2(float x) { return __builtin_amdgcn_exp2f(x); }
;     DI void operator()(const f32x4 (&acc)[2][2][4][2], const Unit& u, int wr, int wc, int fr, int fq) const {
;         const int row0 = u.pm * BM + wr * 64 + fr, hcol0 = ((u.pn * BM + wc * 32) >> 1) + 4 * fq;
; #pragma unroll
;         for (int ai = 0; ai < 2; ++ai)
; #pragma unroll
;             for (int m = 0; m < 4; ++m) { u16* rowp = O + (size_t)(row0 + ai * HALF + m * 16) * ldc + hcol0;
; #pragma unroll
;                 for (int bj = 0; bj < 2; ++bj) { const f32x4 g = acc[ai][bj][m][0], up = acc[ai][bj][m][1]; float r[4];
; #pragma unroll
;                     for (int j = 0; j < 4; ++j) r[j] = g[j] * up[j] * __builtin_amdgcn_rcpf(1.f + ex2(-LOG2E * g[j]));
;                     uint2 w = {pack2(r[0], r[1]), pack2(r[2], r[3])}; *(uint2*)(rowp + bj * (HALF / 2)) = w; } }
	s_cbranch_scc0 .LBB0_63
	v_exp_f32_e64 v168, -v124
	v_exp_f32_e64 v169, -v125
	v_exp_f32_e64 v170, -v126
	v_exp_f32_e64 v171, -v127
	v_add_f32_e32 v168, 1.0, v168
	v_add_f32_e32 v169, 1.0, v169
	v_add_f32_e32 v170, 1.0, v170
	v_add_f32_e32 v171, 1.0, v171
	v_rcp_f32_e32 v168, v168
	v_rcp_f32_e32 v169, v169
	v_rcp_f32_e32 v170, v170
	v_rcp_f32_e32 v171, v171
	s_lshl_b32 s10, s74, 8
	v_pk_mul_f32 v[122:123], v[126:127], v[122:123]
	v_pk_mul_f32 v[120:121], v[124:125], v[120:121]
	s_or_b32 s10, s10, s60
	v_pk_mul_f32 v[120:121], v[120:121], v[168:169]
	v_pk_mul_f32 v[122:123], v[122:123], v[170:171]
	s_ashr_i32 s10, s10, 1
	v_cvt_pk_bf16_f32 v120, v120, v121
	v_cvt_pk_bf16_f32 v121, v122, v123
	v_or_b32_e32 v140, s10, v147
	v_exp_f32_e64 v122, -v116
	v_exp_f32_e64 v123, -v117
	v_lshl_add_u32 v165, s73, 8, v145
	v_ashrrev_i32_e32 v141, 31, v140
	v_mov_b64_e32 v[142:143], s[12:13]
	v_mad_i64_i32 v[166:167], s[14:15], v165, s70, v[142:143]
	v_lshlrev_b64 v[140:141], 1, v[140:141]
	v_lshl_add_u64 v[166:167], v[166:167], 0, v[140:141]
	global_store_dwordx2 v[166:167], v[120:121], off
	v_add_f32_e32 v120, 1.0, v122
	v_add_f32_e32 v121, 1.0, v123
	v_exp_f32_e64 v122, -v118
	v_exp_f32_e64 v123, -v119
	v_rcp_f32_e32 v120, v120
	v_rcp_f32_e32 v121, v121
	v_add_f32_e32 v122, 1.0, v122
	v_add_f32_e32 v123, 1.0, v123
	v_rcp_f32_e32 v122, v122
	v_rcp_f32_e32 v123, v123
	v_pk_mul_f32 v[114:115], v[118:119], v[114:115]
	v_pk_mul_f32 v[112:113], v[116:117], v[112:113]
	v_pk_mul_f32 v[112:113], v[112:113], v[120:121]
	v_pk_mul_f32 v[114:115], v[114:115], v[122:123]
	v_cvt_pk_bf16_f32 v112, v112, v113
	v_cvt_pk_bf16_f32 v113, v114, v115
	v_exp_f32_e64 v114, -v108
	v_exp_f32_e64 v115, -v109
	v_exp_f32_e64 v116, -v110
	v_exp_f32_e64 v117, -v111
	v_add_f32_e32 v114, 1.0, v114
	v_add_f32_e32 v115, 1.0, v115
	v_add_f32_e32 v116, 1.0, v116
	v_add_f32_e32 v117, 1.0, v117
	v_rcp_f32_e32 v114, v114
	v_rcp_f32_e32 v115, v115
	v_rcp_f32_e32 v116, v116
	v_rcp_f32_e32 v117, v117
	v_pk_mul_f32 v[106:107], v[110:111], v[106:107]
	v_pk_mul_f32 v[104:105], v[108:109], v[104:105]
	global_store_dwordx2 v[166:167], v[112:113], off offset:128
	v_pk_mul_f32 v[104:105], v[104:105], v[114:115]
	v_pk_mul_f32 v[106:107], v[106:107], v[116:117]
	v_cvt_pk_bf16_f32 v104, v104, v105
	v_cvt_pk_bf16_f32 v105, v106, v107
	v_exp_f32_e64 v106, -v100
	v_exp_f32_e64 v107, -v101
	v_or_b32_e32 v112, 16, v165
	v_mad_i64_i32 v[112:113], s[14:15], v112, s70, v[142:143]
	v_lshl_add_u64 v[112:113], v[112:113], 0, v[140:141]
	global_store_dwordx2 v[112:113], v[104:105], off
	v_add_f32_e32 v104, 1.0, v106
	v_add_f32_e32 v105, 1.0, v107
	v_exp_f32_e64 v106, -v102
	v_exp_f32_e64 v107, -v103
	v_rcp_f32_e32 v104, v104
	v_rcp_f32_e32 v105, v105
	v_add_f32_e32 v106, 1.0, v106
	v_add_f32_e32 v107, 1.0, v107
	v_rcp_f32_e32 v106, v106
	v_rcp_f32_e32 v107, v107
	v_pk_mul_f32 v[98:99], v[102:103], v[98:99]
	v_pk_mul_f32 v[96:97], v[100:101], v[96:97]
	v_pk_mul_f32 v[96:97], v[96:97], v[104:105]
	v_pk_mul_f32 v[98:99], v[98:99], v[106:107]
	v_cvt_pk_bf16_f32 v96, v96, v97
	v_cvt_pk_bf16_f32 v97, v98, v99
	v_exp_f32_e64 v98, -v92
	v_exp_f32_e64 v99, -v93
	v_exp_f32_e64 v100, -v94
	v_exp_f32_e64 v101, -v95
	v_add_f32_e32 v98, 1.0, v98
	v_add_f32_e32 v99, 1.0, v99
	v_add_f32_e32 v100, 1.0, v100
	v_add_f32_e32 v101, 1.0, v101
	v_rcp_f32_e32 v98, v98
	v_rcp_f32_e32 v99, v99
	v_rcp_f32_e32 v100, v100
	v_rcp_f32_e32 v101, v101
	v_pk_mul_f32 v[90:91], v[94:95], v[90:91]
	v_pk_mul_f32 v[88:89], v[92:93], v[88:89]
	global_store_dwordx2 v[112:113], v[96:97], off offset:128
	v_pk_mul_f32 v[88:89], v[88:89], v[98:99]
	v_pk_mul_f32 v[90:91], v[90:91], v[100:101]
	v_cvt_pk_bf16_f32 v88, v88, v89
	v_cvt_pk_bf16_f32 v89, v90, v91
	v_exp_f32_e64 v90, -v84
	v_exp_f32_e64 v91, -v85
	v_or_b32_e32 v96, 32, v165
	v_mad_i64_i32 v[96:97], s[14:15], v96, s70, v[142:143]
	v_lshl_add_u64 v[96:97], v[96:97], 0, v[140:141]
	global_store_dwordx2 v[96:97], v[88:89], off
	v_add_f32_e32 v88, 1.0, v90
	v_add_f32_e32 v89, 1.0, v91
	v_exp_f32_e64 v90, -v86
	v_exp_f32_e64 v91, -v87
	v_rcp_f32_e32 v88, v88
	v_rcp_f32_e32 v89, v89
	v_add_f32_e32 v90, 1.0, v90
	v_add_f32_e32 v91, 1.0, v91
	v_rcp_f32_e32 v90, v90
	v_rcp_f32_e32 v91, v91
	v_pk_mul_f32 v[82:83], v[86:87], v[82:83]
	v_pk_mul_f32 v[80:81], v[84:85], v[80:81]
	v_pk_mul_f32 v[80:81], v[80:81], v[88:89]
	v_pk_mul_f32 v[82:83], v[82:83], v[90:91]
	v_cvt_pk_bf16_f32 v80, v80, v81
	v_cvt_pk_bf16_f32 v81, v82, v83
	v_exp_f32_e64 v82, -v76
	v_exp_f32_e64 v83, -v77
	v_exp_f32_e64 v84, -v78
	v_exp_f32_e64 v85, -v79
	v_add_f32_e32 v82, 1.0, v82
	v_add_f32_e32 v83, 1.0, v83
	v_add_f32_e32 v84, 1.0, v84
	v_add_f32_e32 v85, 1.0, v85
	v_rcp_f32_e32 v82, v82
	v_rcp_f32_e32 v83, v83
	v_rcp_f32_e32 v84, v84
	v_rcp_f32_e32 v85, v85
	v_pk_mul_f32 v[74:75], v[78:79], v[74:75]
	v_pk_mul_f32 v[72:73], v[76:77], v[72:73]
	global_store_dwordx2 v[96:97], v[80:81], off offset:128
	v_pk_mul_f32 v[72:73], v[72:73], v[82:83]
	v_pk_mul_f32 v[74:75], v[74:75], v[84:85]
	v_cvt_pk_bf16_f32 v72, v72, v73
	v_cvt_pk_bf16_f32 v73, v74, v75
	v_exp_f32_e64 v74, -v68
	v_exp_f32_e64 v75, -v69
	v_or_b32_e32 v80, 48, v165
	v_mad_i64_i32 v[80:81], s[14:15], v80, s70, v[142:143]
	v_lshl_add_u64 v[80:81], v[80:81], 0, v[140:141]
	global_store_dwordx2 v[80:81], v[72:73], off
	v_add_f32_e32 v72, 1.0, v74
	v_add_f32_e32 v73, 1.0, v75
	v_exp_f32_e64 v74, -v70
	v_exp_f32_e64 v75, -v71
	v_rcp_f32_e32 v72, v72
	v_rcp_f32_e32 v73, v73
	v_add_f32_e32 v74, 1.0, v74
	v_add_f32_e32 v75, 1.0, v75
	v_rcp_f32_e32 v74, v74
	v_rcp_f32_e32 v75, v75
	v_pk_mul_f32 v[66:67], v[70:71], v[66:67]
	v_pk_mul_f32 v[64:65], v[68:69], v[64:65]
; DI float ex2(float x) { return __builtin_amdgcn_exp2f(x); }
;     DI void operator()(const f32x4 (&acc)[2][2][4][2], const Unit& u, int wr, int wc, int fr, int fq) const {
;         const int row0 = u.pm * BM + wr * 64 + fr, hcol0 = ((u.pn * BM + wc * 32) >> 1) + 4 * fq;
; #pragma unroll
;         for (int ai = 0; ai < 2; ++ai)
; #pragma unroll
;             for (int m = 0; m < 4; ++m) { u16* rowp = O + (size_t)(row0 + ai * HALF + m * 16) * ldc + hcol0;
; #pragma unroll
;                 for (int bj = 0; bj < 2; ++bj) { const f32x4 g = acc[ai][bj][m][0], up = acc[ai][bj][m][1]; float r[4];
; #pragma unroll
;                     for (int j = 0; j < 4; ++j) r[j] = g[j] * up[j] * __builtin_amdgcn_rcpf(1.f + ex2(-LOG2E * g[j]));
;                     uint2 w = {pack2(r[0], r[1]), pack2(r[2], r[3])}; *(uint2*)(rowp + bj * (HALF / 2)) = w; } }
	v_pk_mul_f32 v[64:65], v[64:65], v[72:73]
	v_pk_mul_f32 v[66:67], v[66:67], v[74:75]
	v_cvt_pk_bf16_f32 v64, v64, v65
	v_cvt_pk_bf16_f32 v65, v66, v67
	v_exp_f32_e64 v66, -v60
	v_exp_f32_e64 v67, -v61
	v_exp_f32_e64 v68, -v62
	v_exp_f32_e64 v69, -v63
	v_add_f32_e32 v66, 1.0, v66
	v_add_f32_e32 v67, 1.0, v67
	v_add_f32_e32 v68, 1.0, v68
	v_add_f32_e32 v69, 1.0, v69
	v_rcp_f32_e32 v66, v66
	v_rcp_f32_e32 v67, v67
	v_rcp_f32_e32 v68, v68
	v_rcp_f32_e32 v69, v69
	v_pk_mul_f32 v[58:59], v[62:63], v[58:59]
	v_pk_mul_f32 v[56:57], v[60:61], v[56:57]
	global_store_dwordx2 v[80:81], v[64:65], off offset:128
	v_pk_mul_f32 v[56:57], v[56:57], v[66:67]
	v_pk_mul_f32 v[58:59], v[58:59], v[68:69]
	v_cvt_pk_bf16_f32 v56, v56, v57
	v_cvt_pk_bf16_f32 v57, v58, v59
	v_exp_f32_e64 v58, -v52
	v_exp_f32_e64 v59, -v53
	v_add_u32_e32 v64, 0x80, v165
	v_mad_i64_i32 v[64:65], s[14:15], v64, s70, v[142:143]
	v_lshl_add_u64 v[64:65], v[64:65], 0, v[140:141]
	global_store_dwordx2 v[64:65], v[56:57], off
	v_add_f32_e32 v56, 1.0, v58
	v_add_f32_e32 v57, 1.0, v59
	v_exp_f32_e64 v58, -v54
	v_exp_f32_e64 v59, -v55
	v_rcp_f32_e32 v56, v56
	v_rcp_f32_e32 v57, v57
	v_add_f32_e32 v58, 1.0, v58
	v_add_f32_e32 v59, 1.0, v59
	v_rcp_f32_e32 v58, v58
	v_rcp_f32_e32 v59, v59
	v_pk_mul_f32 v[50:51], v[54:55], v[50:51]
	v_pk_mul_f32 v[48:49], v[52:53], v[48:49]
	v_pk_mul_f32 v[48:49], v[48:49], v[56:57]
	v_pk_mul_f32 v[50:51], v[50:51], v[58:59]
	v_cvt_pk_bf16_f32 v48, v48, v49
	v_cvt_pk_bf16_f32 v49, v50, v51
	v_exp_f32_e64 v50, -v44
	v_exp_f32_e64 v51, -v45
	v_exp_f32_e64 v52, -v46
	v_exp_f32_e64 v53, -v47
	v_add_f32_e32 v50, 1.0, v50
	v_add_f32_e32 v51, 1.0, v51
	v_add_f32_e32 v52, 1.0, v52
	v_add_f32_e32 v53, 1.0, v53
	v_rcp_f32_e32 v50, v50
	v_rcp_f32_e32 v51, v51
	v_rcp_f32_e32 v52, v52
	v_rcp_f32_e32 v53, v53
	v_pk_mul_f32 v[42:43], v[46:47], v[42:43]
	v_pk_mul_f32 v[40:41], v[44:45], v[40:41]
	global_store_dwordx2 v[64:65], v[48:49], off offset:128
	v_pk_mul_f32 v[40:41], v[40:41], v[50:51]
	v_pk_mul_f32 v[42:43], v[42:43], v[52:53]
	v_cvt_pk_bf16_f32 v40, v40, v41
	v_cvt_pk_bf16_f32 v41, v42, v43
	v_exp_f32_e64 v42, -v36
	v_exp_f32_e64 v43, -v37
	v_add_u32_e32 v48, 0x90, v165
	v_mad_i64_i32 v[48:49], s[14:15], v48, s70, v[142:143]
	v_lshl_add_u64 v[48:49], v[48:49], 0, v[140:141]
	global_store_dwordx2 v[48:49], v[40:41], off
	v_add_f32_e32 v40, 1.0, v42
	v_add_f32_e32 v41, 1.0, v43
	v_exp_f32_e64 v42, -v38
	v_exp_f32_e64 v43, -v39
	v_rcp_f32_e32 v40, v40
	v_rcp_f32_e32 v41, v41
	v_add_f32_e32 v42, 1.0, v42
	v_add_f32_e32 v43, 1.0, v43
	v_rcp_f32_e32 v42, v42
	v_rcp_f32_e32 v43, v43
	v_pk_mul_f32 v[34:35], v[38:39], v[34:35]
	v_pk_mul_f32 v[32:33], v[36:37], v[32:33]
	v_pk_mul_f32 v[32:33], v[32:33], v[40:41]
	v_pk_mul_f32 v[34:35], v[34:35], v[42:43]
	v_cvt_pk_bf16_f32 v32, v32, v33
	v_cvt_pk_bf16_f32 v33, v34, v35
	v_exp_f32_e64 v34, -v28
	v_exp_f32_e64 v35, -v29
	v_exp_f32_e64 v36, -v30
	v_exp_f32_e64 v37, -v31
	v_add_f32_e32 v34, 1.0, v34
	v_add_f32_e32 v35, 1.0, v35
	v_add_f32_e32 v36, 1.0, v36
	v_add_f32_e32 v37, 1.0, v37
	v_rcp_f32_e32 v34, v34
	v_rcp_f32_e32 v35, v35
	v_rcp_f32_e32 v36, v36
	v_rcp_f32_e32 v37, v37
	v_pk_mul_f32 v[26:27], v[30:31], v[26:27]
	v_pk_mul_f32 v[24:25], v[28:29], v[24:25]
	global_store_dwordx2 v[48:49], v[32:33], off offset:128
	v_pk_mul_f32 v[24:25], v[24:25], v[34:35]
	v_pk_mul_f32 v[26:27], v[26:27], v[36:37]
	v_cvt_pk_bf16_f32 v24, v24, v25
	v_cvt_pk_bf16_f32 v25, v26, v27
	v_exp_f32_e64 v26, -v20
	v_exp_f32_e64 v27, -v21
	v_add_u32_e32 v32, 0xa0, v165
	v_mad_i64_i32 v[32:33], s[14:15], v32, s70, v[142:143]
	v_lshl_add_u64 v[32:33], v[32:33], 0, v[140:141]
	global_store_dwordx2 v[32:33], v[24:25], off
	v_add_f32_e32 v24, 1.0, v26
	v_add_f32_e32 v25, 1.0, v27
	v_exp_f32_e64 v26, -v22
	v_exp_f32_e64 v27, -v23
	v_rcp_f32_e32 v24, v24
	v_rcp_f32_e32 v25, v25
	v_add_f32_e32 v26, 1.0, v26
	v_add_f32_e32 v27, 1.0, v27
	v_rcp_f32_e32 v26, v26
	v_rcp_f32_e32 v27, v27
	v_pk_mul_f32 v[18:19], v[22:23], v[18:19]
	v_pk_mul_f32 v[16:17], v[20:21], v[16:17]
	v_pk_mul_f32 v[16:17], v[16:17], v[24:25]
	v_pk_mul_f32 v[18:19], v[18:19], v[26:27]
	v_cvt_pk_bf16_f32 v16, v16, v17
	v_cvt_pk_bf16_f32 v17, v18, v19
	v_exp_f32_e64 v18, -v12
	v_exp_f32_e64 v19, -v13
	v_exp_f32_e64 v20, -v14
	v_exp_f32_e64 v21, -v15
	v_add_f32_e32 v18, 1.0, v18
	v_add_f32_e32 v19, 1.0, v19
	v_add_f32_e32 v20, 1.0, v20
	v_add_f32_e32 v21, 1.0, v21
	v_rcp_f32_e32 v18, v18
	v_rcp_f32_e32 v19, v19
	v_rcp_f32_e32 v20, v20
	v_rcp_f32_e32 v21, v21
	v_pk_mul_f32 v[10:11], v[14:15], v[10:11]
	v_pk_mul_f32 v[8:9], v[12:13], v[8:9]
	global_store_dwordx2 v[32:33], v[16:17], off offset:128
	v_pk_mul_f32 v[8:9], v[8:9], v[18:19]
	v_pk_mul_f32 v[10:11], v[10:11], v[20:21]
	v_cvt_pk_bf16_f32 v8, v8, v9
	v_cvt_pk_bf16_f32 v9, v10, v11
	v_exp_f32_e64 v10, -v4
	v_exp_f32_e64 v11, -v5
	v_add_u32_e32 v16, 0xb0, v165
	v_mad_i64_i32 v[16:17], s[14:15], v16, s70, v[142:143]
	v_lshl_add_u64 v[16:17], v[16:17], 0, v[140:141]
	global_store_dwordx2 v[16:17], v[8:9], off
	v_add_f32_e32 v8, 1.0, v10
	v_add_f32_e32 v9, 1.0, v11
	v_exp_f32_e64 v10, -v6
	v_exp_f32_e64 v11, -v7
	v_rcp_f32_e32 v8, v8
	v_rcp_f32_e32 v9, v9
	v_add_f32_e32 v10, 1.0, v10
	v_add_f32_e32 v11, 1.0, v11
	v_rcp_f32_e32 v10, v10
	v_rcp_f32_e32 v11, v11
	v_pk_mul_f32 v[2:3], v[6:7], v[2:3]
	v_pk_mul_f32 v[0:1], v[4:5], v[0:1]
	s_and_b64 vcc, exec, s[2:3]
	v_pk_mul_f32 v[0:1], v[0:1], v[8:9]
	v_pk_mul_f32 v[2:3], v[2:3], v[10:11]
	v_cvt_pk_bf16_f32 v0, v0, v1
	v_cvt_pk_bf16_f32 v1, v2, v3
	s_mov_b32 s74, s71
	s_mov_b32 s73, s72
	s_mov_b64 s[16:17], s[0:1]
	s_mov_b64 s[14:15], s[4:5]
	global_store_dwordx2 v[16:17], v[0:1], off offset:128
	s_cbranch_vccz .LBB0_56
	s_branch .Lgu1_done

; #define PG8_STAGE(bufoff, gbase, voff) do { _Pragma("unroll") for (int _i = 0; _i < 2; ++_i) \
;         __builtin_amdgcn_global_load_lds((const unsigned*)((const char*)(gbase) + (voff)[_i]), (PG8_LAS unsigned*)(lds + (bufoff) + ldsw + _i * 8192), 16, 0, 0); } while (0)
; #define PG8_LDA(dst, b, h) do { _Pragma("unroll") for (int m = 0; m < 4; ++m) _Pragma("unroll") for (int k = 0; k < 2; ++k) dst[m][k] = *(const PG8_LAS bf16x8*)(lds + PG8_SA(b, h) + aoff + m * 2048 + k * 1024); } while (0)
; #define PG8_LDB(dst, b, h) do { _Pragma("unroll") for (int n = 0; n < 2; ++n) _Pragma("unroll") for (int k = 0; k < 2; ++k) dst[n][k] = *(const PG8_LAS bf16x8*)(lds + PG8_SB(b, h) + boff + n * 2048 + k * 1024); } while (0)
; #define PG8_WAIT_V(n) asm volatile("s_waitcnt vmcnt(" #n ")" ::: "memory")
; #define PG8_WAIT_L(n) asm volatile("s_waitcnt lgkmcnt(" #n ")" ::: "memory")
; #define PG8_BAR __builtin_amdgcn_s_barrier()
; template <class Epi, class Sched, bool STAMP = false>
; __device__ __forceinline__ void gemm_phase(PG8_LAS unsigned char* lds, const Gemm g, const Sched& S, const Epi& E, unsigned long long* stamps) {
;     ...
;             PG8_LDB(B0, 0, 0); PG8_SCHED; PG8_LDA(At, 0, 0); PG8_STAGE(PG8_SA(1, 1), a1 + hstep, voffA);
;             PG8_WAIT_L(8); PG8_BAR; PG8_WAIT_L(0); PG8_MMA(0, 0, At, B0); PG8_BAR; PG8_SCHED;
;             PG8_LDB(B1, 0, 1); PG8_STAGE(PG8_SB(0, 0), b2, voffB);
;             PG8_BAR; PG8_WAIT_L(0); PG8_MMA(0, 1, At, B1); PG8_BAR;
;             PG8_LDA(At, 0, 1); PG8_STAGE(PG8_SA(0, 0), a2, voffA);
;             PG8_BAR; PG8_WAIT_L(0); PG8_MMA(1, 0, At, B0); PG8_BAR; PG8_SCHED;
;             PG8_STAGE(PG8_SB(0, 1), b2 + hstep, voffB);
;             PG8_WAIT_V(6); PG8_BAR; PG8_MMA(1, 1, At, B1); PG8_BAR;
;             PG8_LDB(B0, 1, 0); PG8_SCHED; PG8_LDA(At, 1, 0); PG8_STAGE(PG8_SA(0, 1), a2 + hstep, voffA);
;             PG8_WAIT_L(8); PG8_BAR; PG8_WAIT_L(0); PG8_MMA(0, 0, At, B0); PG8_BAR; PG8_SCHED;
;             PG8_LDB(B1, 1, 1); PG8_STAGE(PG8_SB(1, 0), b3, voffB);
;             PG8_BAR; PG8_WAIT_L(0); PG8_MMA(0, 1, At, B1); PG8_BAR;
;             PG8_LDA(At, 1, 1); PG8_STAGE(PG8_SA(1, 0), a3, voffA);
;             PG8_BAR; PG8_WAIT_L(0); PG8_MMA(1, 0, At, B0); PG8_BAR; PG8_SCHED;
;             PG8_STAGE(PG8_SB(1, 1), b3 + hstep, voffB);
;             PG8_WAIT_V(6); PG8_BAR; PG8_MMA(1, 1, At, B1); PG8_BAR;
.Lgu1_half_loop:
	ds_read_b128 v[140:143], v148
	ds_read_b128 v[166:169], v149
	ds_read_b128 v[170:173], v150
	ds_read_b128 v[174:177], v151
	s_add_u32 s16, s14, 0x100
	s_addc_u32 s17, s15, 0
	s_cmp_eq_u32 s77, 12
	s_cselect_b32 s29, s5, s17
	s_cselect_b32 s28, s4, s16
	s_cselect_b32 s19, s1, s76
	s_cselect_b32 s18, s0, s75
	s_mov_b32 m0, s68
	ds_read_b128 v[178:181], v146
	ds_read_b128 v[182:185], v146 offset:1024
	ds_read_b128 v[186:189], v146 offset:2048
	ds_read_b128 v[190:193], v146 offset:3072
	ds_read_b128 v[194:197], v146 offset:4096
	ds_read_b128 v[198:201], v146 offset:5120
	ds_read_b128 v[202:205], v146 offset:6144
	ds_read_b128 v[206:209], v146 offset:7168
	global_load_lds_dwordx4 v132, s[14:15]
	s_mov_b32 m0, s69
	s_nop 0
	global_load_lds_dwordx4 v134, s[14:15]
	s_waitcnt lgkmcnt(8)
	s_barrier
	s_waitcnt lgkmcnt(0)
	s_setprio 1
	s_waitcnt lgkmcnt(0)
	v_mfma_f32_16x16x32_bf16 v[124:127], v[140:143], v[178:181], v[124:127]
	v_mfma_f32_16x16x32_bf16 v[120:123], v[170:173], v[178:181], v[120:123]
	v_mfma_f32_16x16x32_bf16 v[108:111], v[140:143], v[186:189], v[108:111]
	v_mfma_f32_16x16x32_bf16 v[104:107], v[170:173], v[186:189], v[104:107]
	v_mfma_f32_16x16x32_bf16 v[92:95], v[140:143], v[194:197], v[92:95]
	v_mfma_f32_16x16x32_bf16 v[88:91], v[170:173], v[194:197], v[88:91]
	v_mfma_f32_16x16x32_bf16 v[76:79], v[140:143], v[202:205], v[76:79]
	v_mfma_f32_16x16x32_bf16 v[72:75], v[170:173], v[202:205], v[72:75]
	v_mfma_f32_16x16x32_bf16 v[124:127], v[166:169], v[182:185], v[124:127]
	v_mfma_f32_16x16x32_bf16 v[120:123], v[174:177], v[182:185], v[120:123]
	v_mfma_f32_16x16x32_bf16 v[108:111], v[166:169], v[190:193], v[108:111]
	v_mfma_f32_16x16x32_bf16 v[104:107], v[174:177], v[190:193], v[104:107]
	v_mfma_f32_16x16x32_bf16 v[92:95], v[166:169], v[198:201], v[92:95]
	v_mfma_f32_16x16x32_bf16 v[88:91], v[174:177], v[198:201], v[88:91]
	v_mfma_f32_16x16x32_bf16 v[76:79], v[166:169], v[206:209], v[76:79]
	v_mfma_f32_16x16x32_bf16 v[72:75], v[174:177], v[206:209], v[72:75]
	s_setprio 0
	s_barrier
	s_mov_b32 m0, s52
	s_nop 0
	global_load_lds_dwordx4 v130, s[18:19]
	s_mov_b32 m0, s53
	s_nop 0
	global_load_lds_dwordx4 v128, s[18:19]
	s_waitcnt lgkmcnt(0)
	s_barrier
	s_waitcnt lgkmcnt(0)
	s_setprio 1
	s_waitcnt lgkmcnt(0)
	s_setprio 0
	s_mov_b32 m0, s33
	s_barrier
	ds_read_b128 v[178:181], v146 offset:16384
	ds_read_b128 v[182:185], v146 offset:17408
	ds_read_b128 v[186:189], v146 offset:18432
	ds_read_b128 v[190:193], v146 offset:19456
	ds_read_b128 v[194:197], v146 offset:20480
	ds_read_b128 v[198:201], v146 offset:21504
	ds_read_b128 v[202:205], v146 offset:22528
	ds_read_b128 v[206:209], v146 offset:23552
	global_load_lds_dwordx4 v130, s[28:29]
	s_mov_b32 m0, s54
	s_nop 0
	global_load_lds_dwordx4 v128, s[28:29]
	s_add_u32 s14, s18, 0x44000
	s_addc_u32 s15, s19, 0
	s_mov_b32 m0, s55
	s_nop 0
	s_mov_b32 m0, s56
	s_nop 0
	s_waitcnt vmcnt(4)
	s_barrier
	s_waitcnt lgkmcnt(0)
	s_setprio 1
	s_waitcnt lgkmcnt(0)
	v_mfma_f32_16x16x32_bf16 v[60:63], v[140:143], v[178:181], v[60:63]
	v_mfma_f32_16x16x32_bf16 v[56:59], v[170:173], v[178:181], v[56:59]
	v_mfma_f32_16x16x32_bf16 v[44:47], v[140:143], v[186:189], v[44:47]
	v_mfma_f32_16x16x32_bf16 v[40:43], v[170:173], v[186:189], v[40:43]
	v_mfma_f32_16x16x32_bf16 v[28:31], v[140:143], v[194:197], v[28:31]
	v_mfma_f32_16x16x32_bf16 v[24:27], v[170:173], v[194:197], v[24:27]
	v_mfma_f32_16x16x32_bf16 v[12:15], v[140:143], v[202:205], v[12:15]
	v_mfma_f32_16x16x32_bf16 v[8:11], v[170:173], v[202:205], v[8:11]
	v_mfma_f32_16x16x32_bf16 v[60:63], v[166:169], v[182:185], v[60:63]
	v_mfma_f32_16x16x32_bf16 v[56:59], v[174:177], v[182:185], v[56:59]
	v_mfma_f32_16x16x32_bf16 v[44:47], v[166:169], v[190:193], v[44:47]
	v_mfma_f32_16x16x32_bf16 v[40:43], v[174:177], v[190:193], v[40:43]
	v_mfma_f32_16x16x32_bf16 v[28:31], v[166:169], v[198:201], v[28:31]
	v_mfma_f32_16x16x32_bf16 v[24:27], v[174:177], v[198:201], v[24:27]
	v_mfma_f32_16x16x32_bf16 v[12:15], v[166:169], v[206:209], v[12:15]
	v_mfma_f32_16x16x32_bf16 v[8:11], v[174:177], v[206:209], v[8:11]
	s_setprio 0
	s_barrier
	ds_read_b128 v[140:143], v156
	ds_read_b128 v[166:169], v157
	ds_read_b128 v[170:173], v159
	ds_read_b128 v[174:177], v160
	s_add_u32 s14, s28, 0x44000
	s_addc_u32 s15, s29, 0
	s_mov_b32 m0, s57
	ds_read_b128 v[178:181], v146 offset:32768
	ds_read_b128 v[182:185], v146 offset:33792
	ds_read_b128 v[186:189], v146 offset:34816
	ds_read_b128 v[190:193], v146 offset:35840
	ds_read_b128 v[194:197], v146 offset:36864
	ds_read_b128 v[198:201], v146 offset:37888
	ds_read_b128 v[202:205], v146 offset:38912
	ds_read_b128 v[206:209], v146 offset:39936
	global_load_lds_dwordx4 v130, s[14:15]
	s_mov_b32 m0, s58
	s_nop 0
	global_load_lds_dwordx4 v128, s[14:15]
	s_waitcnt lgkmcnt(8)
	s_barrier
	s_waitcnt lgkmcnt(0)
	s_setprio 1
	s_waitcnt lgkmcnt(0)
	v_mfma_f32_16x16x32_bf16 v[124:127], v[140:143], v[178:181], v[124:127]
	v_mfma_f32_16x16x32_bf16 v[120:123], v[170:173], v[178:181], v[120:123]
	v_mfma_f32_16x16x32_bf16 v[108:111], v[140:143], v[186:189], v[108:111]
	v_mfma_f32_16x16x32_bf16 v[104:107], v[170:173], v[186:189], v[104:107]
	v_mfma_f32_16x16x32_bf16 v[92:95], v[140:143], v[194:197], v[92:95]
	v_mfma_f32_16x16x32_bf16 v[88:91], v[170:173], v[194:197], v[88:91]
	v_mfma_f32_16x16x32_bf16 v[76:79], v[140:143], v[202:205], v[76:79]
	v_mfma_f32_16x16x32_bf16 v[72:75], v[170:173], v[202:205], v[72:75]
	v_mfma_f32_16x16x32_bf16 v[124:127], v[166:169], v[182:185], v[124:127]
	v_mfma_f32_16x16x32_bf16 v[120:123], v[174:177], v[182:185], v[120:123]
	v_mfma_f32_16x16x32_bf16 v[108:111], v[166:169], v[190:193], v[108:111]
	v_mfma_f32_16x16x32_bf16 v[104:107], v[174:177], v[190:193], v[104:107]
	v_mfma_f32_16x16x32_bf16 v[92:95], v[166:169], v[198:201], v[92:95]
	v_mfma_f32_16x16x32_bf16 v[88:91], v[174:177], v[198:201], v[88:91]
	v_mfma_f32_16x16x32_bf16 v[76:79], v[166:169], v[206:209], v[76:79]
	v_mfma_f32_16x16x32_bf16 v[72:75], v[174:177], v[206:209], v[72:75]
	s_setprio 0
	s_barrier
; #define PG8_STAGE(bufoff, gbase, voff) do { _Pragma("unroll") for (int _i = 0; _i < 2; ++_i) \
;         __builtin_amdgcn_global_load_lds((const unsigned*)((const char*)(gbase) + (voff)[_i]), (PG8_LAS unsigned*)(lds + (bufoff) + ldsw + _i * 8192), 16, 0, 0); } while (0)
; #define PG8_LDA(dst, b, h) do { _Pragma("unroll") for (int m = 0; m < 4; ++m) _Pragma("unroll") for (int k = 0; k < 2; ++k) dst[m][k] = *(const PG8_LAS bf16x8*)(lds + PG8_SA(b, h) + aoff + m * 2048 + k * 1024); } while (0)
; #define PG8_LDB(dst, b, h) do { _Pragma("unroll") for (int n = 0; n < 2; ++n) _Pragma("unroll") for (int k = 0; k < 2; ++k) dst[n][k] = *(const PG8_LAS bf16x8*)(lds + PG8_SB(b, h) + boff + n * 2048 + k * 1024); } while (0)
; #define PG8_MMA(ai, bj, At, Bt) do { __builtin_amdgcn_s_setprio(1); _Pragma("unroll") for (int m = 0; m < 4; ++m) _Pragma("unroll") for (int n = 0; n < 2; ++n) _Pragma("unroll") for (int k = 0; k < 2; ++k) \
;         acc[ai][bj][m][n] = __builtin_amdgcn_mfma_f32_16x16x32_bf16(Bt[n][k], At[m][k], acc[ai][bj][m][n], 0, 0, 0); __builtin_amdgcn_s_setprio(0); } while (0)
; #define PG8_WAIT_V(n) asm volatile("s_waitcnt vmcnt(" #n ")" ::: "memory")
; #define PG8_WAIT_L(n) asm volatile("s_waitcnt lgkmcnt(" #n ")" ::: "memory")
; #define PG8_BAR __builtin_amdgcn_s_barrier()
; #define PG8_SCHED __builtin_amdgcn_sched_barrier(0)
; template <class Epi, class Sched, bool STAMP = false>
; __device__ __forceinline__ void gemm_phase(PG8_LAS unsigned char* lds, const Gemm g, const Sched& S, const Epi& E, unsigned long long* stamps) {
;     ...
;             PG8_LDB(B0, 1, 0); PG8_SCHED; PG8_LDA(At, 1, 0); PG8_STAGE(PG8_SA(0, 1), a2 + hstep, voffA);
;             PG8_WAIT_L(8); PG8_BAR; PG8_WAIT_L(0); PG8_MMA(0, 0, At, B0); PG8_BAR; PG8_SCHED;
;             PG8_LDB(B1, 1, 1); PG8_STAGE(PG8_SB(1, 0), b3, voffB);
;             PG8_BAR; PG8_WAIT_L(0); PG8_MMA(0, 1, At, B1); PG8_BAR;
;             PG8_LDA(At, 1, 1); PG8_STAGE(PG8_SA(1, 0), a3, voffA);
;             PG8_BAR; PG8_WAIT_L(0); PG8_MMA(1, 0, At, B0); PG8_BAR; PG8_SCHED;
;             PG8_STAGE(PG8_SB(1, 1), b3 + hstep, voffB);
;             PG8_WAIT_V(6); PG8_BAR; PG8_MMA(1, 1, At, B1); PG8_BAR;
;         }
	s_mov_b32 m0, s61
	s_add_u32 s100, s18, 0x80
	s_addc_u32 s101, s19, 0
	global_load_lds_dwordx4 v130, s[100:101]
	s_mov_b32 m0, s62
	s_nop 0
	global_load_lds_dwordx4 v128, s[100:101]
	s_waitcnt lgkmcnt(0)
	s_barrier
	s_waitcnt lgkmcnt(0)
	s_setprio 1
	s_waitcnt lgkmcnt(0)
	s_setprio 0
	s_mov_b32 m0, s63
	s_barrier
	ds_read_b128 v[178:181], v146 offset:49152
	ds_read_b128 v[182:185], v146 offset:50176
	ds_read_b128 v[186:189], v146 offset:51200
	ds_read_b128 v[190:193], v146 offset:52224
	ds_read_b128 v[194:197], v146 offset:53248
	ds_read_b128 v[198:201], v146 offset:54272
	ds_read_b128 v[202:205], v146 offset:55296
	ds_read_b128 v[206:209], v146 offset:56320
	s_add_u32 s100, s28, 0x80
	s_addc_u32 s101, s29, 0
	global_load_lds_dwordx4 v130, s[100:101]
	s_mov_b32 m0, s64
	s_nop 0
	global_load_lds_dwordx4 v128, s[100:101]
	s_add_u32 s14, s18, 0x44080
	s_addc_u32 s15, s19, 0
	s_mov_b32 m0, s65
	s_nop 0
	s_mov_b32 m0, s66
	s_nop 0
	s_waitcnt vmcnt(4)
	s_barrier
	s_waitcnt lgkmcnt(0)
	s_setprio 1
	s_waitcnt lgkmcnt(0)
	v_mfma_f32_16x16x32_bf16 v[60:63], v[140:143], v[178:181], v[60:63]
	v_mfma_f32_16x16x32_bf16 v[56:59], v[170:173], v[178:181], v[56:59]
	v_mfma_f32_16x16x32_bf16 v[44:47], v[140:143], v[186:189], v[44:47]
	v_mfma_f32_16x16x32_bf16 v[40:43], v[170:173], v[186:189], v[40:43]
	v_mfma_f32_16x16x32_bf16 v[28:31], v[140:143], v[194:197], v[28:31]
	v_mfma_f32_16x16x32_bf16 v[24:27], v[170:173], v[194:197], v[24:27]
	v_mfma_f32_16x16x32_bf16 v[12:15], v[140:143], v[202:205], v[12:15]
	v_mfma_f32_16x16x32_bf16 v[8:11], v[170:173], v[202:205], v[8:11]
	v_mfma_f32_16x16x32_bf16 v[60:63], v[166:169], v[182:185], v[60:63]
	v_mfma_f32_16x16x32_bf16 v[56:59], v[174:177], v[182:185], v[56:59]
	v_mfma_f32_16x16x32_bf16 v[44:47], v[166:169], v[190:193], v[44:47]
	v_mfma_f32_16x16x32_bf16 v[40:43], v[174:177], v[190:193], v[40:43]
	v_mfma_f32_16x16x32_bf16 v[28:31], v[166:169], v[198:201], v[28:31]
	v_mfma_f32_16x16x32_bf16 v[24:27], v[174:177], v[198:201], v[24:27]
	v_mfma_f32_16x16x32_bf16 v[12:15], v[166:169], v[206:209], v[12:15]
	v_mfma_f32_16x16x32_bf16 v[8:11], v[174:177], v[206:209], v[8:11]
	s_setprio 0
	s_add_i32 s77, s77, 2
	s_add_u32 s75, s75, 0x100
	s_addc_u32 s76, s76, 0
	s_cmp_gt_u32 s77, 13
	s_mov_b64 s[14:15], s[16:17]
	s_barrier
	s_cbranch_scc0 .Lgu1_half_loop
; DI float ex2(float x) { return __builtin_amdgcn_exp2f(x); }
;     DI void operator()(const f32x4 (&acc)[2][2][4][2], const Unit& u, int wr, int wc, int fr, int fq) const {
;         const int row0 = u.pm * BM + wr * 64 + fr, hcol0 = ((u.pn * BM + wc * 32) >> 1) + 4 * fq;
; #pragma unroll
;         for (int ai = 0; ai < 2; ++ai)
; #pragma unroll
;             for (int m = 0; m < 4; ++m) { u16* rowp = O + (size_t)(row0 + ai * HALF + m * 16) * ldc + hcol0;
; #pragma unroll
;                 for (int bj = 0; bj < 2; ++bj) { const f32x4 g = acc[ai][bj][m][0], up = acc[ai][bj][m][1]; float r[4];
; #pragma unroll
;                     for (int j = 0; j < 4; ++j) r[j] = g[j] * up[j] * __builtin_amdgcn_rcpf(1.f + ex2(-LOG2E * g[j]));
;                     uint2 w = {pack2(r[0], r[1]), pack2(r[2], r[3])}; *(uint2*)(rowp + bj * (HALF / 2)) = w; } }
	v_exp_f32_e64 v168, -v124
	v_exp_f32_e64 v169, -v125
	v_exp_f32_e64 v170, -v126
	v_exp_f32_e64 v171, -v127
	v_add_f32_e32 v168, 1.0, v168
	v_add_f32_e32 v169, 1.0, v169
	v_add_f32_e32 v170, 1.0, v170
	v_add_f32_e32 v171, 1.0, v171
	v_rcp_f32_e32 v168, v168
	v_rcp_f32_e32 v169, v169
	v_rcp_f32_e32 v170, v170
	v_rcp_f32_e32 v171, v171
	s_lshl_b32 s10, s74, 8
	v_pk_mul_f32 v[122:123], v[126:127], v[122:123]
	v_pk_mul_f32 v[120:121], v[124:125], v[120:121]
	s_or_b32 s10, s10, s60
	s_or_b32 s10, s10, s98
	v_pk_mul_f32 v[120:121], v[120:121], v[168:169]
	v_pk_mul_f32 v[122:123], v[122:123], v[170:171]
	s_ashr_i32 s10, s10, 1
	v_cvt_pk_bf16_f32 v120, v120, v121
	v_cvt_pk_bf16_f32 v121, v122, v123
	v_or_b32_e32 v140, s10, v147
	v_lshl_add_u32 v165, s73, 8, v145
	v_ashrrev_i32_e32 v141, 31, v140
	v_mov_b64_e32 v[142:143], s[12:13]
	v_mad_i64_i32 v[166:167], s[14:15], v165, s70, v[142:143]
	v_lshlrev_b64 v[140:141], 1, v[140:141]
	v_lshl_add_u64 v[166:167], v[166:167], 0, v[140:141]
	global_store_dwordx2 v[166:167], v[120:121], off
	v_exp_f32_e64 v114, -v108
	v_exp_f32_e64 v115, -v109
	v_exp_f32_e64 v116, -v110
	v_exp_f32_e64 v117, -v111
	v_add_f32_e32 v114, 1.0, v114
	v_add_f32_e32 v115, 1.0, v115
	v_add_f32_e32 v116, 1.0, v116
	v_add_f32_e32 v117, 1.0, v117
	v_rcp_f32_e32 v114, v114
	v_rcp_f32_e32 v115, v115
	v_rcp_f32_e32 v116, v116
	v_rcp_f32_e32 v117, v117
	v_pk_mul_f32 v[106:107], v[110:111], v[106:107]
	v_pk_mul_f32 v[104:105], v[108:109], v[104:105]
	v_pk_mul_f32 v[104:105], v[104:105], v[114:115]
	v_pk_mul_f32 v[106:107], v[106:107], v[116:117]
	v_cvt_pk_bf16_f32 v104, v104, v105
	v_cvt_pk_bf16_f32 v105, v106, v107
	v_or_b32_e32 v112, 16, v165
	v_mad_i64_i32 v[112:113], s[14:15], v112, s70, v[142:143]
	v_lshl_add_u64 v[112:113], v[112:113], 0, v[140:141]
	global_store_dwordx2 v[112:113], v[104:105], off
	v_exp_f32_e64 v98, -v92
	v_exp_f32_e64 v99, -v93
	v_exp_f32_e64 v100, -v94
	v_exp_f32_e64 v101, -v95
	v_add_f32_e32 v98, 1.0, v98
	v_add_f32_e32 v99, 1.0, v99
	v_add_f32_e32 v100, 1.0, v100
	v_add_f32_e32 v101, 1.0, v101
	v_rcp_f32_e32 v98, v98
	v_rcp_f32_e32 v99, v99
	v_rcp_f32_e32 v100, v100
	v_rcp_f32_e32 v101, v101
	v_pk_mul_f32 v[90:91], v[94:95], v[90:91]
	v_pk_mul_f32 v[88:89], v[92:93], v[88:89]
	v_pk_mul_f32 v[88:89], v[88:89], v[98:99]
	v_pk_mul_f32 v[90:91], v[90:91], v[100:101]
	v_cvt_pk_bf16_f32 v88, v88, v89
	v_cvt_pk_bf16_f32 v89, v90, v91
	v_or_b32_e32 v96, 32, v165
	v_mad_i64_i32 v[96:97], s[14:15], v96, s70, v[142:143]
	v_lshl_add_u64 v[96:97], v[96:97], 0, v[140:141]
	global_store_dwordx2 v[96:97], v[88:89], off
	v_exp_f32_e64 v82, -v76
	v_exp_f32_e64 v83, -v77
	v_exp_f32_e64 v84, -v78
	v_exp_f32_e64 v85, -v79
	v_add_f32_e32 v82, 1.0, v82
	v_add_f32_e32 v83, 1.0, v83
	v_add_f32_e32 v84, 1.0, v84
	v_add_f32_e32 v85, 1.0, v85
	v_rcp_f32_e32 v82, v82
	v_rcp_f32_e32 v83, v83
	v_rcp_f32_e32 v84, v84
	v_rcp_f32_e32 v85, v85
	v_pk_mul_f32 v[74:75], v[78:79], v[74:75]
	v_pk_mul_f32 v[72:73], v[76:77], v[72:73]
	v_pk_mul_f32 v[72:73], v[72:73], v[82:83]
	v_pk_mul_f32 v[74:75], v[74:75], v[84:85]
	v_cvt_pk_bf16_f32 v72, v72, v73
	v_cvt_pk_bf16_f32 v73, v74, v75
	v_or_b32_e32 v80, 48, v165
	v_mad_i64_i32 v[80:81], s[14:15], v80, s70, v[142:143]
	v_lshl_add_u64 v[80:81], v[80:81], 0, v[140:141]
	global_store_dwordx2 v[80:81], v[72:73], off
	v_exp_f32_e64 v66, -v60
	v_exp_f32_e64 v67, -v61
	v_exp_f32_e64 v68, -v62
	v_exp_f32_e64 v69, -v63
	v_add_f32_e32 v66, 1.0, v66
	v_add_f32_e32 v67, 1.0, v67
	v_add_f32_e32 v68, 1.0, v68
	v_add_f32_e32 v69, 1.0, v69
	v_rcp_f32_e32 v66, v66
	v_rcp_f32_e32 v67, v67
	v_rcp_f32_e32 v68, v68
	v_rcp_f32_e32 v69, v69
	v_pk_mul_f32 v[58:59], v[62:63], v[58:59]
	v_pk_mul_f32 v[56:57], v[60:61], v[56:57]
	v_pk_mul_f32 v[56:57], v[56:57], v[66:67]
	v_pk_mul_f32 v[58:59], v[58:59], v[68:69]
	v_cvt_pk_bf16_f32 v56, v56, v57
	v_cvt_pk_bf16_f32 v57, v58, v59
	v_add_u32_e32 v64, 0x80, v165
	v_mad_i64_i32 v[64:65], s[14:15], v64, s70, v[142:143]
	v_lshl_add_u64 v[64:65], v[64:65], 0, v[140:141]
	global_store_dwordx2 v[64:65], v[56:57], off
	v_exp_f32_e64 v50, -v44
	v_exp_f32_e64 v51, -v45
	v_exp_f32_e64 v52, -v46
	v_exp_f32_e64 v53, -v47
	v_add_f32_e32 v50, 1.0, v50
	v_add_f32_e32 v51, 1.0, v51
	v_add_f32_e32 v52, 1.0, v52
	v_add_f32_e32 v53, 1.0, v53
	v_rcp_f32_e32 v50, v50
	v_rcp_f32_e32 v51, v51
	v_rcp_f32_e32 v52, v52
	v_rcp_f32_e32 v53, v53
	v_pk_mul_f32 v[42:43], v[46:47], v[42:43]
	v_pk_mul_f32 v[40:41], v[44:45], v[40:41]
	v_pk_mul_f32 v[40:41], v[40:41], v[50:51]
	v_pk_mul_f32 v[42:43], v[42:43], v[52:53]
	v_cvt_pk_bf16_f32 v40, v40, v41
	v_cvt_pk_bf16_f32 v41, v42, v43
	v_add_u32_e32 v48, 0x90, v165
	v_mad_i64_i32 v[48:49], s[14:15], v48, s70, v[142:143]
	v_lshl_add_u64 v[48:49], v[48:49], 0, v[140:141]
	global_store_dwordx2 v[48:49], v[40:41], off
	v_exp_f32_e64 v34, -v28
	v_exp_f32_e64 v35, -v29
	v_exp_f32_e64 v36, -v30
	v_exp_f32_e64 v37, -v31
	v_add_f32_e32 v34, 1.0, v34
	v_add_f32_e32 v35, 1.0, v35
	v_add_f32_e32 v36, 1.0, v36
	v_add_f32_e32 v37, 1.0, v37
	v_rcp_f32_e32 v34, v34
	v_rcp_f32_e32 v35, v35
	v_rcp_f32_e32 v36, v36
	v_rcp_f32_e32 v37, v37
	v_pk_mul_f32 v[26:27], v[30:31], v[26:27]
	v_pk_mul_f32 v[24:25], v[28:29], v[24:25]
	v_pk_mul_f32 v[24:25], v[24:25], v[34:35]
	v_pk_mul_f32 v[26:27], v[26:27], v[36:37]
	v_cvt_pk_bf16_f32 v24, v24, v25
	v_cvt_pk_bf16_f32 v25, v26, v27
	v_add_u32_e32 v32, 0xa0, v165
	v_mad_i64_i32 v[32:33], s[14:15], v32, s70, v[142:143]
	v_lshl_add_u64 v[32:33], v[32:33], 0, v[140:141]
	global_store_dwordx2 v[32:33], v[24:25], off
	v_exp_f32_e64 v18, -v12
	v_exp_f32_e64 v19, -v13
	v_exp_f32_e64 v20, -v14
	v_exp_f32_e64 v21, -v15
	v_add_f32_e32 v18, 1.0, v18
	v_add_f32_e32 v19, 1.0, v19
	v_add_f32_e32 v20, 1.0, v20
	v_add_f32_e32 v21, 1.0, v21
	v_rcp_f32_e32 v18, v18
	v_rcp_f32_e32 v19, v19
	v_rcp_f32_e32 v20, v20
	v_rcp_f32_e32 v21, v21
	v_pk_mul_f32 v[10:11], v[14:15], v[10:11]
	v_pk_mul_f32 v[8:9], v[12:13], v[8:9]
	v_pk_mul_f32 v[8:9], v[8:9], v[18:19]
	v_pk_mul_f32 v[10:11], v[10:11], v[20:21]
	v_cvt_pk_bf16_f32 v8, v8, v9
	v_cvt_pk_bf16_f32 v9, v10, v11
	v_add_u32_e32 v16, 0xb0, v165
	v_mad_i64_i32 v[16:17], s[14:15], v16, s70, v[142:143]
	v_lshl_add_u64 v[16:17], v[16:17], 0, v[140:141]
	global_store_dwordx2 v[16:17], v[8:9], off
	s_and_b64 vcc, exec, s[2:3]
	s_mov_b32 s74, s71
	s_mov_b32 s73, s72
	s_mov_b64 s[16:17], s[0:1]
	s_mov_b64 s[14:15], s[4:5]

; #define PG8_STAGE(bufoff, gbase, voff) do { _Pragma("unroll") for (int _i = 0; _i < 2; ++_i) \
;         __builtin_amdgcn_global_load_lds((const unsigned*)((const char*)(gbase) + (voff)[_i]), (PG8_LAS unsigned*)(lds + (bufoff) + ldsw + _i * 8192), 16, 0, 0); } while (0)
; #define PG8_LDA(dst, b, h) do { _Pragma("unroll") for (int m = 0; m < 4; ++m) _Pragma("unroll") for (int k = 0; k < 2; ++k) dst[m][k] = *(const PG8_LAS bf16x8*)(lds + PG8_SA(b, h) + aoff + m * 2048 + k * 1024); } while (0)
; #define PG8_LDB(dst, b, h) do { _Pragma("unroll") for (int n = 0; n < 2; ++n) _Pragma("unroll") for (int k = 0; k < 2; ++k) dst[n][k] = *(const PG8_LAS bf16x8*)(lds + PG8_SB(b, h) + boff + n * 2048 + k * 1024); } while (0)
; #define PG8_MMA(ai, bj, At, Bt) do { __builtin_amdgcn_s_setprio(1); _Pragma("unroll") for (int m = 0; m < 4; ++m) _Pragma("unroll") for (int n = 0; n < 2; ++n) _Pragma("unroll") for (int k = 0; k < 2; ++k) \
;         acc[ai][bj][m][n] = __builtin_amdgcn_mfma_f32_16x16x32_bf16(Bt[n][k], At[m][k], acc[ai][bj][m][n], 0, 0, 0); __builtin_amdgcn_s_setprio(0); } while (0)
; #define PG8_BAR __builtin_amdgcn_s_barrier()
; template <class Epi, class Sched, bool STAMP = false>
; __device__ __forceinline__ void gemm_phase(PG8_LAS unsigned char* lds, const Gemm g, const Sched& S, const Epi& E, unsigned long long* stamps) {
;     ...
;         for (int t = 0; t < nt; t += 2) {
;             const bool last = (t == nt - 2);
;             const char* a1 = cA + (size_t)(t + 1) * kstep;
;             const char* a2 = last ? nA : cA + (size_t)(t + 2) * kstep; const char* b2 = last ? nB : cB + (size_t)(t + 2) * kstep;
;             const char* a3 = a2 + kstep; const char* b3 = b2 + kstep;
;             if (last && has_next) S.a_ready(nxt);
;             PG8_LDB(B0, 0, 0); PG8_SCHED; PG8_LDA(At, 0, 0); PG8_STAGE(PG8_SA(1, 1), a1 + hstep, voffA);
;             PG8_WAIT_L(8); PG8_BAR; PG8_WAIT_L(0); PG8_MMA(0, 0, At, B0); PG8_BAR; PG8_SCHED;
;             PG8_LDB(B1, 0, 1); PG8_STAGE(PG8_SB(0, 0), b2, voffB);
;             PG8_BAR; PG8_WAIT_L(0); PG8_MMA(0, 1, At, B1); PG8_BAR;
;             PG8_LDA(At, 0, 1); PG8_STAGE(PG8_SA(0, 0), a2, voffA);
;             PG8_BAR; PG8_WAIT_L(0); PG8_MMA(1, 0, At, B0); PG8_BAR; PG8_SCHED;
;             PG8_STAGE(PG8_SB(0, 1), b2 + hstep, voffB);
;             PG8_WAIT_V(6); PG8_BAR; PG8_MMA(1, 1, At, B1); PG8_BAR;
.LBB0_96:
	s_add_u32 s88, s52, 0x100
	s_addc_u32 s89, s53, 0
	s_mov_b32 s90, -2
	ds_read_b128 v[166:169], v148
	ds_read_b128 v[170:173], v149
	ds_read_b128 v[174:177], v150
	ds_read_b128 v[178:181], v151
	s_add_u32 s52, s34, 0x100
	s_addc_u32 s53, s35, 0
	s_cmp_eq_u32 s90, 40
	s_cselect_b32 s57, s5, s53
	s_cselect_b32 s56, s4, s52
	s_cselect_b32 s55, s1, s89
	s_cselect_b32 s54, s0, s88
	s_mov_b32 m0, s76
	ds_read_b128 v[182:185], v146
	ds_read_b128 v[186:189], v146 offset:1024
	ds_read_b128 v[190:193], v146 offset:2048
	ds_read_b128 v[194:197], v146 offset:3072
	ds_read_b128 v[198:201], v146 offset:4096
	ds_read_b128 v[202:205], v146 offset:5120
	ds_read_b128 v[206:209], v146 offset:6144
	ds_read_b128 v[210:213], v146 offset:7168
	global_load_lds_dwordx4 v136, s[34:35]
	s_mov_b32 m0, s77
	s_nop 0
	global_load_lds_dwordx4 v138, s[34:35]
	s_waitcnt lgkmcnt(8)
	s_barrier
	s_waitcnt lgkmcnt(0)
	s_setprio 1
	s_waitcnt lgkmcnt(0)
	v_mfma_f32_16x16x32_bf16 v[124:127], v[166:169], v[182:185], 0
	v_mfma_f32_16x16x32_bf16 v[120:123], v[174:177], v[182:185], 0
	v_mfma_f32_16x16x32_bf16 v[116:119], v[166:169], v[190:193], 0
	v_mfma_f32_16x16x32_bf16 v[112:115], v[174:177], v[190:193], 0
	v_mfma_f32_16x16x32_bf16 v[100:103], v[166:169], v[198:201], 0
	v_mfma_f32_16x16x32_bf16 v[96:99], v[174:177], v[198:201], 0
	v_mfma_f32_16x16x32_bf16 v[84:87], v[166:169], v[206:209], 0
	v_mfma_f32_16x16x32_bf16 v[80:83], v[174:177], v[206:209], 0
	v_mfma_f32_16x16x32_bf16 v[124:127], v[170:173], v[186:189], v[124:127]
	v_mfma_f32_16x16x32_bf16 v[120:123], v[178:181], v[186:189], v[120:123]
	v_mfma_f32_16x16x32_bf16 v[116:119], v[170:173], v[194:197], v[116:119]
	v_mfma_f32_16x16x32_bf16 v[112:115], v[178:181], v[194:197], v[112:115]
	v_mfma_f32_16x16x32_bf16 v[100:103], v[170:173], v[202:205], v[100:103]
	v_mfma_f32_16x16x32_bf16 v[96:99], v[178:181], v[202:205], v[96:99]
	v_mfma_f32_16x16x32_bf16 v[84:87], v[170:173], v[210:213], v[84:87]
	v_mfma_f32_16x16x32_bf16 v[80:83], v[178:181], v[210:213], v[80:83]
	s_setprio 0
	s_barrier
	s_mov_b32 m0, s61
	ds_read_b128 v[214:217], v152
	ds_read_b128 v[218:221], v153
	ds_read_b128 v[222:225], v154
	ds_read_b128 v[226:229], v155
	global_load_lds_dwordx4 v130, s[54:55]
	s_mov_b32 m0, s62
	s_nop 0
	global_load_lds_dwordx4 v134, s[54:55]
	s_waitcnt lgkmcnt(0)
	s_barrier
	s_waitcnt lgkmcnt(0)
	s_setprio 1
	s_waitcnt lgkmcnt(0)
	v_mfma_f32_16x16x32_bf16 v[108:111], v[214:217], v[182:185], 0
	v_mfma_f32_16x16x32_bf16 v[104:107], v[222:225], v[182:185], 0
	v_mfma_f32_16x16x32_bf16 v[92:95], v[214:217], v[190:193], 0
	v_mfma_f32_16x16x32_bf16 v[88:91], v[222:225], v[190:193], 0
	v_mfma_f32_16x16x32_bf16 v[76:79], v[214:217], v[198:201], 0
	v_mfma_f32_16x16x32_bf16 v[72:75], v[222:225], v[198:201], 0
	v_mfma_f32_16x16x32_bf16 v[68:71], v[214:217], v[206:209], 0
	v_mfma_f32_16x16x32_bf16 v[64:67], v[222:225], v[206:209], 0
	v_mfma_f32_16x16x32_bf16 v[108:111], v[218:221], v[186:189], v[108:111]
	v_mfma_f32_16x16x32_bf16 v[104:107], v[226:229], v[186:189], v[104:107]
	v_mfma_f32_16x16x32_bf16 v[92:95], v[218:221], v[194:197], v[92:95]
	v_mfma_f32_16x16x32_bf16 v[88:91], v[226:229], v[194:197], v[88:91]
	v_mfma_f32_16x16x32_bf16 v[76:79], v[218:221], v[202:205], v[76:79]
	v_mfma_f32_16x16x32_bf16 v[72:75], v[226:229], v[202:205], v[72:75]
	v_mfma_f32_16x16x32_bf16 v[68:71], v[218:221], v[210:213], v[68:71]
	v_mfma_f32_16x16x32_bf16 v[64:67], v[226:229], v[210:213], v[64:67]
	s_setprio 0
	s_mov_b32 m0, s60
	s_barrier
	ds_read_b128 v[182:185], v146 offset:16384
	ds_read_b128 v[186:189], v146 offset:17408
	ds_read_b128 v[190:193], v146 offset:18432
	ds_read_b128 v[194:197], v146 offset:19456
	ds_read_b128 v[198:201], v146 offset:20480
	ds_read_b128 v[202:205], v146 offset:21504
	ds_read_b128 v[206:209], v146 offset:22528
	ds_read_b128 v[210:213], v146 offset:23552
	global_load_lds_dwordx4 v128, s[56:57]
	s_mov_b32 m0, s63
	s_nop 0
	global_load_lds_dwordx4 v132, s[56:57]
	s_add_u32 s34, s54, 0xb4000
	s_addc_u32 s35, s55, 0
	s_mov_b32 m0, s64
	s_nop 0
	global_load_lds_dwordx4 v130, s[34:35]
	s_mov_b32 m0, s65
	s_nop 0
	global_load_lds_dwordx4 v134, s[34:35]
	s_waitcnt vmcnt(6)
	s_barrier
	s_waitcnt lgkmcnt(0)
	s_setprio 1
	s_waitcnt lgkmcnt(0)
	v_mfma_f32_16x16x32_bf16 v[60:63], v[166:169], v[182:185], 0
	v_mfma_f32_16x16x32_bf16 v[56:59], v[174:177], v[182:185], 0
	v_mfma_f32_16x16x32_bf16 v[52:55], v[166:169], v[190:193], 0
	v_mfma_f32_16x16x32_bf16 v[48:51], v[174:177], v[190:193], 0
	v_mfma_f32_16x16x32_bf16 v[36:39], v[166:169], v[198:201], 0
	v_mfma_f32_16x16x32_bf16 v[32:35], v[174:177], v[198:201], 0
	v_mfma_f32_16x16x32_bf16 v[20:23], v[166:169], v[206:209], 0
	v_mfma_f32_16x16x32_bf16 v[16:19], v[174:177], v[206:209], 0
	v_mfma_f32_16x16x32_bf16 v[60:63], v[170:173], v[186:189], v[60:63]
	v_mfma_f32_16x16x32_bf16 v[56:59], v[178:181], v[186:189], v[56:59]
	v_mfma_f32_16x16x32_bf16 v[52:55], v[170:173], v[194:197], v[52:55]
	v_mfma_f32_16x16x32_bf16 v[48:51], v[178:181], v[194:197], v[48:51]
	v_mfma_f32_16x16x32_bf16 v[36:39], v[170:173], v[202:205], v[36:39]
	v_mfma_f32_16x16x32_bf16 v[32:35], v[178:181], v[202:205], v[32:35]
	v_mfma_f32_16x16x32_bf16 v[20:23], v[170:173], v[210:213], v[20:23]
	v_mfma_f32_16x16x32_bf16 v[16:19], v[178:181], v[210:213], v[16:19]
	v_mfma_f32_16x16x32_bf16 v[44:47], v[214:217], v[182:185], 0
	v_mfma_f32_16x16x32_bf16 v[40:43], v[222:225], v[182:185], 0
	v_mfma_f32_16x16x32_bf16 v[28:31], v[214:217], v[190:193], 0
	v_mfma_f32_16x16x32_bf16 v[24:27], v[222:225], v[190:193], 0
	v_mfma_f32_16x16x32_bf16 v[12:15], v[214:217], v[198:201], 0
	v_mfma_f32_16x16x32_bf16 v[8:11], v[222:225], v[198:201], 0
	v_mfma_f32_16x16x32_bf16 v[4:7], v[214:217], v[206:209], 0
	v_mfma_f32_16x16x32_bf16 v[0:3], v[222:225], v[206:209], 0
	v_mfma_f32_16x16x32_bf16 v[44:47], v[218:221], v[186:189], v[44:47]
	v_mfma_f32_16x16x32_bf16 v[40:43], v[226:229], v[186:189], v[40:43]
	v_mfma_f32_16x16x32_bf16 v[28:31], v[218:221], v[194:197], v[28:31]
	v_mfma_f32_16x16x32_bf16 v[24:27], v[226:229], v[194:197], v[24:27]
	v_mfma_f32_16x16x32_bf16 v[12:15], v[218:221], v[202:205], v[12:15]
	v_mfma_f32_16x16x32_bf16 v[8:11], v[226:229], v[202:205], v[8:11]
	v_mfma_f32_16x16x32_bf16 v[4:7], v[218:221], v[210:213], v[4:7]
	v_mfma_f32_16x16x32_bf16 v[0:3], v[226:229], v[210:213], v[0:3]
	s_setprio 0
	s_barrier
	s_branch .Lzp2_mid
; #define PG8_STAGE(bufoff, gbase, voff) do { _Pragma("unroll") for (int _i = 0; _i < 2; ++_i) \
;         __builtin_amdgcn_global_load_lds((const unsigned*)((const char*)(gbase) + (voff)[_i]), (PG8_LAS unsigned*)(lds + (bufoff) + ldsw + _i * 8192), 16, 0, 0); } while (0)
; #define PG8_LDA(dst, b, h) do { _Pragma("unroll") for (int m = 0; m < 4; ++m) _Pragma("unroll") for (int k = 0; k < 2; ++k) dst[m][k] = *(const PG8_LAS bf16x8*)(lds + PG8_SA(b, h) + aoff + m * 2048 + k * 1024); } while (0)
; #define PG8_LDB(dst, b, h) do { _Pragma("unroll") for (int n = 0; n < 2; ++n) _Pragma("unroll") for (int k = 0; k < 2; ++k) dst[n][k] = *(const PG8_LAS bf16x8*)(lds + PG8_SB(b, h) + boff + n * 2048 + k * 1024); } while (0)
; #define PG8_WAIT_V(n) asm volatile("s_waitcnt vmcnt(" #n ")" ::: "memory")
; #define PG8_WAIT_L(n) asm volatile("s_waitcnt lgkmcnt(" #n ")" ::: "memory")
; #define PG8_BAR __builtin_amdgcn_s_barrier()
; template <class Epi, class Sched, bool STAMP = false>
; __device__ __forceinline__ void gemm_phase(PG8_LAS unsigned char* lds, const Gemm g, const Sched& S, const Epi& E, unsigned long long* stamps) {
;     ...
;             PG8_LDB(B0, 0, 0); PG8_SCHED; PG8_LDA(At, 0, 0); PG8_STAGE(PG8_SA(1, 1), a1 + hstep, voffA);
;             PG8_WAIT_L(8); PG8_BAR; PG8_WAIT_L(0); PG8_MMA(0, 0, At, B0); PG8_BAR; PG8_SCHED;
;             PG8_LDB(B1, 0, 1); PG8_STAGE(PG8_SB(0, 0), b2, voffB);
;             PG8_BAR; PG8_WAIT_L(0); PG8_MMA(0, 1, At, B1); PG8_BAR;
;             PG8_LDA(At, 0, 1); PG8_STAGE(PG8_SA(0, 0), a2, voffA);
;             PG8_BAR; PG8_WAIT_L(0); PG8_MMA(1, 0, At, B0); PG8_BAR; PG8_SCHED;
;             PG8_STAGE(PG8_SB(0, 1), b2 + hstep, voffB);
;             PG8_WAIT_V(6); PG8_BAR; PG8_MMA(1, 1, At, B1); PG8_BAR;
;             PG8_LDB(B0, 1, 0); PG8_SCHED; PG8_LDA(At, 1, 0); PG8_STAGE(PG8_SA(0, 1), a2 + hstep, voffA);
;             PG8_WAIT_L(8); PG8_BAR; PG8_WAIT_L(0); PG8_MMA(0, 0, At, B0); PG8_BAR; PG8_SCHED;
;             PG8_LDB(B1, 1, 1); PG8_STAGE(PG8_SB(1, 0), b3, voffB);
;             PG8_BAR; PG8_WAIT_L(0); PG8_MMA(0, 1, At, B1); PG8_BAR;
;             PG8_LDA(At, 1, 1); PG8_STAGE(PG8_SA(1, 0), a3, voffA);
;             PG8_BAR; PG8_WAIT_L(0); PG8_MMA(1, 0, At, B0); PG8_BAR; PG8_SCHED;
;             PG8_STAGE(PG8_SB(1, 1), b3 + hstep, voffB);
;             PG8_WAIT_V(6); PG8_BAR; PG8_MMA(1, 1, At, B1); PG8_BAR;
.LBB0_97:
	ds_read_b128 v[166:169], v148
	ds_read_b128 v[170:173], v149
	ds_read_b128 v[174:177], v150
	ds_read_b128 v[178:181], v151
	s_add_u32 s52, s34, 0x100
	s_addc_u32 s53, s35, 0
	s_cmp_eq_u32 s90, 40
	s_cselect_b32 s57, s5, s53
	s_cselect_b32 s56, s4, s52
	s_cselect_b32 s55, s1, s89
	s_cselect_b32 s54, s0, s88
	s_mov_b32 m0, s76
	ds_read_b128 v[182:185], v146
	ds_read_b128 v[186:189], v146 offset:1024
	ds_read_b128 v[190:193], v146 offset:2048
	ds_read_b128 v[194:197], v146 offset:3072
	ds_read_b128 v[198:201], v146 offset:4096
	ds_read_b128 v[202:205], v146 offset:5120
	ds_read_b128 v[206:209], v146 offset:6144
	ds_read_b128 v[210:213], v146 offset:7168
	global_load_lds_dwordx4 v136, s[34:35]
	s_mov_b32 m0, s77
	s_nop 0
	global_load_lds_dwordx4 v138, s[34:35]
	s_waitcnt lgkmcnt(8)
	s_barrier
	s_waitcnt lgkmcnt(0)
	s_setprio 1
	s_waitcnt lgkmcnt(0)
	v_mfma_f32_16x16x32_bf16 v[124:127], v[166:169], v[182:185], v[124:127]
	v_mfma_f32_16x16x32_bf16 v[120:123], v[174:177], v[182:185], v[120:123]
	v_mfma_f32_16x16x32_bf16 v[116:119], v[166:169], v[190:193], v[116:119]
	v_mfma_f32_16x16x32_bf16 v[112:115], v[174:177], v[190:193], v[112:115]
	v_mfma_f32_16x16x32_bf16 v[100:103], v[166:169], v[198:201], v[100:103]
	v_mfma_f32_16x16x32_bf16 v[96:99], v[174:177], v[198:201], v[96:99]
	v_mfma_f32_16x16x32_bf16 v[84:87], v[166:169], v[206:209], v[84:87]
	v_mfma_f32_16x16x32_bf16 v[80:83], v[174:177], v[206:209], v[80:83]
	v_mfma_f32_16x16x32_bf16 v[124:127], v[170:173], v[186:189], v[124:127]
	v_mfma_f32_16x16x32_bf16 v[120:123], v[178:181], v[186:189], v[120:123]
	v_mfma_f32_16x16x32_bf16 v[116:119], v[170:173], v[194:197], v[116:119]
	v_mfma_f32_16x16x32_bf16 v[112:115], v[178:181], v[194:197], v[112:115]
	v_mfma_f32_16x16x32_bf16 v[100:103], v[170:173], v[202:205], v[100:103]
	v_mfma_f32_16x16x32_bf16 v[96:99], v[178:181], v[202:205], v[96:99]
	v_mfma_f32_16x16x32_bf16 v[84:87], v[170:173], v[210:213], v[84:87]
	v_mfma_f32_16x16x32_bf16 v[80:83], v[178:181], v[210:213], v[80:83]
	s_setprio 0
	s_barrier
	s_mov_b32 m0, s61
	ds_read_b128 v[214:217], v152
	ds_read_b128 v[218:221], v153
	ds_read_b128 v[222:225], v154
	ds_read_b128 v[226:229], v155
	global_load_lds_dwordx4 v130, s[54:55]
	s_mov_b32 m0, s62
	s_nop 0
	global_load_lds_dwordx4 v134, s[54:55]
	s_waitcnt lgkmcnt(0)
	s_barrier
	s_waitcnt lgkmcnt(0)
	s_setprio 1
	s_waitcnt lgkmcnt(0)
	v_mfma_f32_16x16x32_bf16 v[108:111], v[214:217], v[182:185], v[108:111]
	v_mfma_f32_16x16x32_bf16 v[104:107], v[222:225], v[182:185], v[104:107]
	v_mfma_f32_16x16x32_bf16 v[92:95], v[214:217], v[190:193], v[92:95]
	v_mfma_f32_16x16x32_bf16 v[88:91], v[222:225], v[190:193], v[88:91]
	v_mfma_f32_16x16x32_bf16 v[76:79], v[214:217], v[198:201], v[76:79]
	v_mfma_f32_16x16x32_bf16 v[72:75], v[222:225], v[198:201], v[72:75]
	v_mfma_f32_16x16x32_bf16 v[68:71], v[214:217], v[206:209], v[68:71]
	v_mfma_f32_16x16x32_bf16 v[64:67], v[222:225], v[206:209], v[64:67]
	v_mfma_f32_16x16x32_bf16 v[108:111], v[218:221], v[186:189], v[108:111]
	v_mfma_f32_16x16x32_bf16 v[104:107], v[226:229], v[186:189], v[104:107]
	v_mfma_f32_16x16x32_bf16 v[92:95], v[218:221], v[194:197], v[92:95]
	v_mfma_f32_16x16x32_bf16 v[88:91], v[226:229], v[194:197], v[88:91]
	v_mfma_f32_16x16x32_bf16 v[76:79], v[218:221], v[202:205], v[76:79]
	v_mfma_f32_16x16x32_bf16 v[72:75], v[226:229], v[202:205], v[72:75]
	v_mfma_f32_16x16x32_bf16 v[68:71], v[218:221], v[210:213], v[68:71]
	v_mfma_f32_16x16x32_bf16 v[64:67], v[226:229], v[210:213], v[64:67]
	s_setprio 0
	s_mov_b32 m0, s60
	s_barrier
	ds_read_b128 v[182:185], v146 offset:16384
	ds_read_b128 v[186:189], v146 offset:17408
	ds_read_b128 v[190:193], v146 offset:18432
	ds_read_b128 v[194:197], v146 offset:19456
	ds_read_b128 v[198:201], v146 offset:20480
	ds_read_b128 v[202:205], v146 offset:21504
	ds_read_b128 v[206:209], v146 offset:22528
	ds_read_b128 v[210:213], v146 offset:23552
	global_load_lds_dwordx4 v128, s[56:57]
	s_mov_b32 m0, s63
	s_nop 0
	global_load_lds_dwordx4 v132, s[56:57]
	s_add_u32 s34, s54, 0xb4000
	s_addc_u32 s35, s55, 0
	s_mov_b32 m0, s64
	s_nop 0
	global_load_lds_dwordx4 v130, s[34:35]
	s_mov_b32 m0, s65
	s_nop 0
	global_load_lds_dwordx4 v134, s[34:35]
	s_waitcnt vmcnt(6)
	s_barrier
	s_waitcnt lgkmcnt(0)
	s_setprio 1
	s_waitcnt lgkmcnt(0)
	v_mfma_f32_16x16x32_bf16 v[60:63], v[166:169], v[182:185], v[60:63]
	v_mfma_f32_16x16x32_bf16 v[56:59], v[174:177], v[182:185], v[56:59]
	v_mfma_f32_16x16x32_bf16 v[52:55], v[166:169], v[190:193], v[52:55]
	v_mfma_f32_16x16x32_bf16 v[48:51], v[174:177], v[190:193], v[48:51]
	v_mfma_f32_16x16x32_bf16 v[36:39], v[166:169], v[198:201], v[36:39]
	v_mfma_f32_16x16x32_bf16 v[32:35], v[174:177], v[198:201], v[32:35]
	v_mfma_f32_16x16x32_bf16 v[20:23], v[166:169], v[206:209], v[20:23]
	v_mfma_f32_16x16x32_bf16 v[16:19], v[174:177], v[206:209], v[16:19]
	v_mfma_f32_16x16x32_bf16 v[60:63], v[170:173], v[186:189], v[60:63]
	v_mfma_f32_16x16x32_bf16 v[56:59], v[178:181], v[186:189], v[56:59]
	v_mfma_f32_16x16x32_bf16 v[52:55], v[170:173], v[194:197], v[52:55]
	v_mfma_f32_16x16x32_bf16 v[48:51], v[178:181], v[194:197], v[48:51]
	v_mfma_f32_16x16x32_bf16 v[36:39], v[170:173], v[202:205], v[36:39]
	v_mfma_f32_16x16x32_bf16 v[32:35], v[178:181], v[202:205], v[32:35]
	v_mfma_f32_16x16x32_bf16 v[20:23], v[170:173], v[210:213], v[20:23]
	v_mfma_f32_16x16x32_bf16 v[16:19], v[178:181], v[210:213], v[16:19]
	v_mfma_f32_16x16x32_bf16 v[44:47], v[214:217], v[182:185], v[44:47]
	v_mfma_f32_16x16x32_bf16 v[40:43], v[222:225], v[182:185], v[40:43]
	v_mfma_f32_16x16x32_bf16 v[28:31], v[214:217], v[190:193], v[28:31]
	v_mfma_f32_16x16x32_bf16 v[24:27], v[222:225], v[190:193], v[24:27]
	v_mfma_f32_16x16x32_bf16 v[12:15], v[214:217], v[198:201], v[12:15]
	v_mfma_f32_16x16x32_bf16 v[8:11], v[222:225], v[198:201], v[8:11]
	v_mfma_f32_16x16x32_bf16 v[4:7], v[214:217], v[206:209], v[4:7]
	v_mfma_f32_16x16x32_bf16 v[0:3], v[222:225], v[206:209], v[0:3]
	v_mfma_f32_16x16x32_bf16 v[44:47], v[218:221], v[186:189], v[44:47]
	v_mfma_f32_16x16x32_bf16 v[40:43], v[226:229], v[186:189], v[40:43]
	v_mfma_f32_16x16x32_bf16 v[28:31], v[218:221], v[194:197], v[28:31]
	v_mfma_f32_16x16x32_bf16 v[24:27], v[226:229], v[194:197], v[24:27]
	v_mfma_f32_16x16x32_bf16 v[12:15], v[218:221], v[202:205], v[12:15]
	v_mfma_f32_16x16x32_bf16 v[8:11], v[226:229], v[202:205], v[8:11]
	v_mfma_f32_16x16x32_bf16 v[4:7], v[218:221], v[210:213], v[4:7]
	v_mfma_f32_16x16x32_bf16 v[0:3], v[226:229], v[210:213], v[0:3]
	s_setprio 0
	s_barrier
; #define PG8_STAGE(bufoff, gbase, voff) do { _Pragma("unroll") for (int _i = 0; _i < 2; ++_i) \
;         __builtin_amdgcn_global_load_lds((const unsigned*)((const char*)(gbase) + (voff)[_i]), (PG8_LAS unsigned*)(lds + (bufoff) + ldsw + _i * 8192), 16, 0, 0); } while (0)
; #define PG8_LDA(dst, b, h) do { _Pragma("unroll") for (int m = 0; m < 4; ++m) _Pragma("unroll") for (int k = 0; k < 2; ++k) dst[m][k] = *(const PG8_LAS bf16x8*)(lds + PG8_SA(b, h) + aoff + m * 2048 + k * 1024); } while (0)
; #define PG8_LDB(dst, b, h) do { _Pragma("unroll") for (int n = 0; n < 2; ++n) _Pragma("unroll") for (int k = 0; k < 2; ++k) dst[n][k] = *(const PG8_LAS bf16x8*)(lds + PG8_SB(b, h) + boff + n * 2048 + k * 1024); } while (0)
; #define PG8_MMA(ai, bj, At, Bt) do { __builtin_amdgcn_s_setprio(1); _Pragma("unroll") for (int m = 0; m < 4; ++m) _Pragma("unroll") for (int n = 0; n < 2; ++n) _Pragma("unroll") for (int k = 0; k < 2; ++k) \
;         acc[ai][bj][m][n] = __builtin_amdgcn_mfma_f32_16x16x32_bf16(Bt[n][k], At[m][k], acc[ai][bj][m][n], 0, 0, 0); __builtin_amdgcn_s_setprio(0); } while (0)
; #define PG8_WAIT_V(n) asm volatile("s_waitcnt vmcnt(" #n ")" ::: "memory")
; #define PG8_WAIT_L(n) asm volatile("s_waitcnt lgkmcnt(" #n ")" ::: "memory")
; #define PG8_BAR __builtin_amdgcn_s_barrier()
; #define PG8_SCHED __builtin_amdgcn_sched_barrier(0)
; template <class Epi, class Sched, bool STAMP = false>
; __device__ __forceinline__ void gemm_phase(PG8_LAS unsigned char* lds, const Gemm g, const Sched& S, const Epi& E, unsigned long long* stamps) {
;     ...
;             PG8_LDB(B0, 1, 0); PG8_SCHED; PG8_LDA(At, 1, 0); PG8_STAGE(PG8_SA(0, 1), a2 + hstep, voffA);
;             PG8_WAIT_L(8); PG8_BAR; PG8_WAIT_L(0); PG8_MMA(0, 0, At, B0); PG8_BAR; PG8_SCHED;
;             PG8_LDB(B1, 1, 1); PG8_STAGE(PG8_SB(1, 0), b3, voffB);
;             PG8_BAR; PG8_WAIT_L(0); PG8_MMA(0, 1, At, B1); PG8_BAR;
;             PG8_LDA(At, 1, 1); PG8_STAGE(PG8_SA(1, 0), a3, voffA);
;             PG8_BAR; PG8_WAIT_L(0); PG8_MMA(1, 0, At, B0); PG8_BAR; PG8_SCHED;
;             PG8_STAGE(PG8_SB(1, 1), b3 + hstep, voffB);
;             PG8_WAIT_V(6); PG8_BAR; PG8_MMA(1, 1, At, B1); PG8_BAR;
;         }
.Lzp2_mid:
	ds_read_b128 v[166:169], v156
	ds_read_b128 v[170:173], v157
	ds_read_b128 v[174:177], v159
	ds_read_b128 v[178:181], v160
	s_add_u32 s34, s56, 0xb4000
	s_addc_u32 s35, s57, 0
	s_mov_b32 m0, s66
	ds_read_b128 v[182:185], v146 offset:32768
	ds_read_b128 v[186:189], v146 offset:33792
	ds_read_b128 v[190:193], v146 offset:34816
	ds_read_b128 v[194:197], v146 offset:35840
	ds_read_b128 v[198:201], v146 offset:36864
	ds_read_b128 v[202:205], v146 offset:37888
	ds_read_b128 v[206:209], v146 offset:38912
	ds_read_b128 v[210:213], v146 offset:39936
	global_load_lds_dwordx4 v128, s[34:35]
	s_mov_b32 m0, s67
	s_nop 0
	global_load_lds_dwordx4 v132, s[34:35]
	s_waitcnt lgkmcnt(8)
	s_barrier
	s_waitcnt lgkmcnt(0)
	s_setprio 1
	s_waitcnt lgkmcnt(0)
	v_mfma_f32_16x16x32_bf16 v[124:127], v[166:169], v[182:185], v[124:127]
	v_mfma_f32_16x16x32_bf16 v[120:123], v[174:177], v[182:185], v[120:123]
	v_mfma_f32_16x16x32_bf16 v[116:119], v[166:169], v[190:193], v[116:119]
	v_mfma_f32_16x16x32_bf16 v[112:115], v[174:177], v[190:193], v[112:115]
	v_mfma_f32_16x16x32_bf16 v[100:103], v[166:169], v[198:201], v[100:103]
	v_mfma_f32_16x16x32_bf16 v[96:99], v[174:177], v[198:201], v[96:99]
	v_mfma_f32_16x16x32_bf16 v[84:87], v[166:169], v[206:209], v[84:87]
	v_mfma_f32_16x16x32_bf16 v[80:83], v[174:177], v[206:209], v[80:83]
	v_mfma_f32_16x16x32_bf16 v[124:127], v[170:173], v[186:189], v[124:127]
	v_mfma_f32_16x16x32_bf16 v[120:123], v[178:181], v[186:189], v[120:123]
	v_mfma_f32_16x16x32_bf16 v[116:119], v[170:173], v[194:197], v[116:119]
	v_mfma_f32_16x16x32_bf16 v[112:115], v[178:181], v[194:197], v[112:115]
	v_mfma_f32_16x16x32_bf16 v[100:103], v[170:173], v[202:205], v[100:103]
	v_mfma_f32_16x16x32_bf16 v[96:99], v[178:181], v[202:205], v[96:99]
	v_mfma_f32_16x16x32_bf16 v[84:87], v[170:173], v[210:213], v[84:87]
	v_mfma_f32_16x16x32_bf16 v[80:83], v[178:181], v[210:213], v[80:83]
	s_setprio 0
	s_barrier
	s_mov_b32 m0, s68
	ds_read_b128 v[214:217], v161
	ds_read_b128 v[218:221], v162
	ds_read_b128 v[222:225], v163
	ds_read_b128 v[226:229], v164
	s_add_u32 s100, s54, 0x80
	s_addc_u32 s101, s55, 0
	global_load_lds_dwordx4 v130, s[100:101]
	s_mov_b32 m0, s69
	s_nop 0
	global_load_lds_dwordx4 v134, s[100:101]
	s_waitcnt lgkmcnt(0)
	s_barrier
	s_waitcnt lgkmcnt(0)
	s_setprio 1
	s_waitcnt lgkmcnt(0)
	v_mfma_f32_16x16x32_bf16 v[108:111], v[214:217], v[182:185], v[108:111]
	v_mfma_f32_16x16x32_bf16 v[104:107], v[222:225], v[182:185], v[104:107]
	v_mfma_f32_16x16x32_bf16 v[92:95], v[214:217], v[190:193], v[92:95]
	v_mfma_f32_16x16x32_bf16 v[88:91], v[222:225], v[190:193], v[88:91]
	v_mfma_f32_16x16x32_bf16 v[76:79], v[214:217], v[198:201], v[76:79]
	v_mfma_f32_16x16x32_bf16 v[72:75], v[222:225], v[198:201], v[72:75]
	v_mfma_f32_16x16x32_bf16 v[68:71], v[214:217], v[206:209], v[68:71]
	v_mfma_f32_16x16x32_bf16 v[64:67], v[222:225], v[206:209], v[64:67]
	v_mfma_f32_16x16x32_bf16 v[108:111], v[218:221], v[186:189], v[108:111]
	v_mfma_f32_16x16x32_bf16 v[104:107], v[226:229], v[186:189], v[104:107]
	v_mfma_f32_16x16x32_bf16 v[92:95], v[218:221], v[194:197], v[92:95]
	v_mfma_f32_16x16x32_bf16 v[88:91], v[226:229], v[194:197], v[88:91]
	v_mfma_f32_16x16x32_bf16 v[76:79], v[218:221], v[202:205], v[76:79]
	v_mfma_f32_16x16x32_bf16 v[72:75], v[226:229], v[202:205], v[72:75]
	v_mfma_f32_16x16x32_bf16 v[68:71], v[218:221], v[210:213], v[68:71]
	v_mfma_f32_16x16x32_bf16 v[64:67], v[226:229], v[210:213], v[64:67]
	s_setprio 0
	s_mov_b32 m0, s70
	s_barrier
	ds_read_b128 v[182:185], v146 offset:49152
	ds_read_b128 v[186:189], v146 offset:50176
	ds_read_b128 v[190:193], v146 offset:51200
	ds_read_b128 v[194:197], v146 offset:52224
	ds_read_b128 v[198:201], v146 offset:53248
	ds_read_b128 v[202:205], v146 offset:54272
	ds_read_b128 v[206:209], v146 offset:55296
	ds_read_b128 v[210:213], v146 offset:56320
	s_add_u32 s100, s56, 0x80
	s_addc_u32 s101, s57, 0
	global_load_lds_dwordx4 v128, s[100:101]
	s_mov_b32 m0, s71
	s_nop 0
	global_load_lds_dwordx4 v132, s[100:101]
	s_add_u32 s34, s54, 0xb4080
	s_addc_u32 s35, s55, 0
	s_mov_b32 m0, s72
	s_nop 0
	global_load_lds_dwordx4 v130, s[34:35]
	s_mov_b32 m0, s73
	s_nop 0
	global_load_lds_dwordx4 v134, s[34:35]
	s_waitcnt vmcnt(6)
	s_barrier
	s_waitcnt lgkmcnt(0)
	s_setprio 1
	s_waitcnt lgkmcnt(0)
	v_mfma_f32_16x16x32_bf16 v[60:63], v[166:169], v[182:185], v[60:63]
	v_mfma_f32_16x16x32_bf16 v[56:59], v[174:177], v[182:185], v[56:59]
	v_mfma_f32_16x16x32_bf16 v[52:55], v[166:169], v[190:193], v[52:55]
	v_mfma_f32_16x16x32_bf16 v[48:51], v[174:177], v[190:193], v[48:51]
	v_mfma_f32_16x16x32_bf16 v[36:39], v[166:169], v[198:201], v[36:39]
	v_mfma_f32_16x16x32_bf16 v[32:35], v[174:177], v[198:201], v[32:35]
	v_mfma_f32_16x16x32_bf16 v[20:23], v[166:169], v[206:209], v[20:23]
	v_mfma_f32_16x16x32_bf16 v[16:19], v[174:177], v[206:209], v[16:19]
	v_mfma_f32_16x16x32_bf16 v[60:63], v[170:173], v[186:189], v[60:63]
	v_mfma_f32_16x16x32_bf16 v[56:59], v[178:181], v[186:189], v[56:59]
	v_mfma_f32_16x16x32_bf16 v[52:55], v[170:173], v[194:197], v[52:55]
	v_mfma_f32_16x16x32_bf16 v[48:51], v[178:181], v[194:197], v[48:51]
	v_mfma_f32_16x16x32_bf16 v[36:39], v[170:173], v[202:205], v[36:39]
	v_mfma_f32_16x16x32_bf16 v[32:35], v[178:181], v[202:205], v[32:35]
	v_mfma_f32_16x16x32_bf16 v[20:23], v[170:173], v[210:213], v[20:23]
	v_mfma_f32_16x16x32_bf16 v[16:19], v[178:181], v[210:213], v[16:19]
	v_mfma_f32_16x16x32_bf16 v[44:47], v[214:217], v[182:185], v[44:47]
	v_mfma_f32_16x16x32_bf16 v[40:43], v[222:225], v[182:185], v[40:43]
	v_mfma_f32_16x16x32_bf16 v[28:31], v[214:217], v[190:193], v[28:31]
	v_mfma_f32_16x16x32_bf16 v[24:27], v[222:225], v[190:193], v[24:27]
	v_mfma_f32_16x16x32_bf16 v[12:15], v[214:217], v[198:201], v[12:15]
	v_mfma_f32_16x16x32_bf16 v[8:11], v[222:225], v[198:201], v[8:11]
	v_mfma_f32_16x16x32_bf16 v[4:7], v[214:217], v[206:209], v[4:7]
	v_mfma_f32_16x16x32_bf16 v[0:3], v[222:225], v[206:209], v[0:3]
	v_mfma_f32_16x16x32_bf16 v[44:47], v[218:221], v[186:189], v[44:47]
	v_mfma_f32_16x16x32_bf16 v[40:43], v[226:229], v[186:189], v[40:43]
	v_mfma_f32_16x16x32_bf16 v[28:31], v[218:221], v[194:197], v[28:31]
	v_mfma_f32_16x16x32_bf16 v[24:27], v[226:229], v[194:197], v[24:27]
	v_mfma_f32_16x16x32_bf16 v[12:15], v[218:221], v[202:205], v[12:15]
	v_mfma_f32_16x16x32_bf16 v[8:11], v[226:229], v[202:205], v[8:11]
	v_mfma_f32_16x16x32_bf16 v[4:7], v[218:221], v[210:213], v[4:7]
	v_mfma_f32_16x16x32_bf16 v[0:3], v[226:229], v[210:213], v[0:3]
	s_setprio 0
	s_add_i32 s90, s90, 2
	s_add_u32 s88, s88, 0x100
	s_addc_u32 s89, s89, 0
	s_cmp_gt_u32 s90, 41
	s_mov_b64 s[34:35], s[52:53]
	s_barrier
; #define PG8_WAIT_V(n) asm volatile("s_waitcnt vmcnt(" #n ")" ::: "memory")
; #define PG8_BAR __builtin_amdgcn_s_barrier()
;     DI void operator()(const f32x4 (&acc)[2][2][4][2], const Unit& u, int wr, int wc, int fr, int fq) const {
;         const int row0 = u.pm * BM + wr * 64 + fr, col0 = u.pn * BM + wc * 32 + 8 * fq;
; #pragma unroll
;         for (int ai = 0; ai < 2; ++ai)
; #pragma unroll
;             for (int m = 0; m < 4; ++m) { u16* rowp = O + (size_t)(row0 + ai * HALF + m * 16) * ldc + col0;
; #pragma unroll
;                 for (int bj = 0; bj < 2; ++bj) { const f32x4 v0 = acc[ai][bj][m][0], v1 = acc[ai][bj][m][1];
;                     uint4 w = {pack2(v0[0], v0[1]), pack2(v0[2], v0[3]), pack2(v1[0], v1[1]), pack2(v1[2], v1[3])}; *(uint4*)(rowp + bj * HALF) = w; } }
; template <class Epi, class Sched, bool STAMP = false>
; __device__ __forceinline__ void gemm_phase(PG8_LAS unsigned char* lds, const Gemm g, const Sched& S, const Epi& E, unsigned long long* stamps) {
;     ...
;     PG8_WAIT_V(0);
;     if (wr == 0) PG8_BAR;
;     PG8_BAR;
	s_cbranch_scc0 .LBB0_97
	v_lshl_add_u32 v166, s84, 8, v145
	v_lshl_or_b32 v168, s87, 8, v147
	v_ashrrev_i32_e32 v167, 31, v166
	v_ashrrev_i32_e32 v169, 31, v168
	v_lshlrev_b64 v[170:171], 11, v[166:167]
	v_lshl_add_u64 v[170:171], s[14:15], 0, v[170:171]
	v_lshlrev_b64 v[168:169], 1, v[168:169]
	v_lshl_add_u64 v[170:171], v[170:171], 0, v[168:169]
	v_cvt_pk_bf16_f32 v60, v60, v61
	v_cvt_pk_bf16_f32 v61, v62, v63
	v_cvt_pk_bf16_f32 v62, v56, v57
	v_add_co_u32_e32 v56, vcc, s78, v170
	v_cvt_pk_bf16_f32 v68, v68, v69
	v_cvt_pk_bf16_f32 v69, v70, v71
	v_cvt_pk_bf16_f32 v70, v64, v65
	v_lshl_add_u64 v[64:65], v[170:171], 0, s[16:17]
	v_addc_co_u32_e32 v57, vcc, 0, v171, vcc
	v_cvt_pk_bf16_f32 v44, v44, v45
	v_cvt_pk_bf16_f32 v45, v46, v47
	v_cvt_pk_bf16_f32 v46, v40, v41
	v_cvt_pk_bf16_f32 v47, v42, v43
	v_cvt_pk_bf16_f32 v108, v108, v109
	v_cvt_pk_bf16_f32 v109, v110, v111
	v_cvt_pk_bf16_f32 v110, v104, v105
	v_or_b32_e32 v104, 16, v166
	global_store_dwordx4 v[64:65], v[44:47], off offset:256
	v_ashrrev_i32_e32 v105, 31, v104
	v_cvt_pk_bf16_f32 v92, v92, v93
	v_add_co_u32_e32 v46, vcc, s79, v170
	v_cvt_pk_bf16_f32 v93, v94, v95
	v_cvt_pk_bf16_f32 v94, v88, v89
	v_or_b32_e32 v88, 32, v166
	v_lshl_add_u64 v[44:45], v[170:171], 0, s[18:19]
	v_addc_co_u32_e32 v47, vcc, 0, v171, vcc
	v_cvt_pk_bf16_f32 v28, v28, v29
	v_cvt_pk_bf16_f32 v29, v30, v31
	v_cvt_pk_bf16_f32 v30, v24, v25
	v_cvt_pk_bf16_f32 v31, v26, v27
	v_lshlrev_b64 v[104:105], 11, v[104:105]
	v_ashrrev_i32_e32 v89, 31, v88
	v_cvt_pk_bf16_f32 v76, v76, v77
	v_cvt_pk_bf16_f32 v77, v78, v79
	v_cvt_pk_bf16_f32 v78, v72, v73
	v_or_b32_e32 v72, 48, v166
	global_store_dwordx4 v[44:45], v[28:31], off offset:256
	v_cvt_pk_bf16_f32 v111, v106, v107
	v_lshl_add_u64 v[104:105], s[14:15], 0, v[104:105]
	v_add_co_u32_e32 v30, vcc, s82, v170
	v_lshlrev_b64 v[88:89], 11, v[88:89]
	v_ashrrev_i32_e32 v73, 31, v72
	v_lshl_add_u64 v[28:29], v[170:171], 0, s[28:29]
	v_addc_co_u32_e32 v31, vcc, 0, v171, vcc
	v_cvt_pk_bf16_f32 v12, v12, v13
	v_cvt_pk_bf16_f32 v13, v14, v15
	v_cvt_pk_bf16_f32 v14, v8, v9
	v_cvt_pk_bf16_f32 v15, v10, v11
	global_store_dwordx4 v[170:171], v[108:111], off offset:256
	v_cvt_pk_bf16_f32 v95, v90, v91
	v_lshl_add_u64 v[88:89], s[14:15], 0, v[88:89]
	v_lshl_add_u64 v[108:109], v[104:105], 0, v[168:169]
	v_lshlrev_b64 v[72:73], 11, v[72:73]
	global_store_dwordx4 v[28:29], v[12:15], off offset:256
	global_store_dwordx4 v[108:109], v[92:95], off offset:256
	v_cvt_pk_bf16_f32 v79, v74, v75
	v_add_co_u32_e32 v14, vcc, s83, v170
	v_lshl_add_u64 v[92:93], v[88:89], 0, v[168:169]
	v_lshl_add_u64 v[72:73], s[14:15], 0, v[72:73]
	v_addc_co_u32_e32 v15, vcc, 0, v171, vcc
	v_cvt_pk_bf16_f32 v124, v124, v125
	v_cvt_pk_bf16_f32 v125, v126, v127
	v_cvt_pk_bf16_f32 v126, v120, v121
	v_cvt_pk_bf16_f32 v127, v122, v123
	v_cvt_pk_bf16_f32 v104, v116, v117
	v_cvt_pk_bf16_f32 v105, v118, v119
	v_cvt_pk_bf16_f32 v106, v112, v113
	v_cvt_pk_bf16_f32 v107, v114, v115
	v_cvt_pk_bf16_f32 v88, v100, v101
	v_cvt_pk_bf16_f32 v89, v102, v103
	v_cvt_pk_bf16_f32 v90, v96, v97
	v_cvt_pk_bf16_f32 v91, v98, v99
	global_store_dwordx4 v[92:93], v[76:79], off offset:256
	v_cvt_pk_bf16_f32 v74, v80, v81
	v_cvt_pk_bf16_f32 v75, v82, v83
	v_lshl_add_u64 v[76:77], v[72:73], 0, v[168:169]
	v_cvt_pk_bf16_f32 v72, v84, v85
	v_cvt_pk_bf16_f32 v73, v86, v87
	v_cvt_pk_bf16_f32 v71, v66, v67
	v_cvt_pk_bf16_f32 v63, v58, v59
	v_cvt_pk_bf16_f32 v40, v52, v53
	v_cvt_pk_bf16_f32 v41, v54, v55
	v_cvt_pk_bf16_f32 v42, v48, v49
	v_cvt_pk_bf16_f32 v43, v50, v51
	v_cvt_pk_bf16_f32 v24, v36, v37
	v_cvt_pk_bf16_f32 v25, v38, v39
	v_cvt_pk_bf16_f32 v26, v32, v33
	v_cvt_pk_bf16_f32 v27, v34, v35
	v_lshl_add_u64 v[12:13], v[170:171], 0, s[30:31]
	v_cvt_pk_bf16_f32 v8, v20, v21
	v_cvt_pk_bf16_f32 v9, v22, v23
	v_cvt_pk_bf16_f32 v10, v16, v17
	v_cvt_pk_bf16_f32 v11, v18, v19
	v_cvt_pk_bf16_f32 v4, v4, v5
	v_cvt_pk_bf16_f32 v5, v6, v7
	v_cvt_pk_bf16_f32 v6, v0, v1
	v_cvt_pk_bf16_f32 v7, v2, v3
	s_and_b64 vcc, exec, s[2:3]
	s_mov_b32 s87, s85
	s_mov_b32 s84, s86
	s_mov_b64 s[52:53], s[0:1]
	s_mov_b64 s[34:35], s[4:5]
	global_store_dwordx4 v[170:171], v[124:127], off
	global_store_dwordx4 v[108:109], v[104:107], off
	global_store_dwordx4 v[92:93], v[88:91], off
	global_store_dwordx4 v[76:77], v[72:75], off
	global_store_dwordx4 v[76:77], v[68:71], off offset:256
	global_store_dwordx4 v[56:57], v[60:63], off
	global_store_dwordx4 v[46:47], v[40:43], off
	global_store_dwordx4 v[30:31], v[24:27], off
	global_store_dwordx4 v[14:15], v[8:11], off
	global_store_dwordx4 v[12:13], v[4:7], off offset:256
	s_cbranch_vccz .LBB0_86
	s_waitcnt vmcnt(0)
	s_cmpk_gt_u32 s58, 0xff
	s_cbranch_scc1 .LBB0_101
	s_barrier

; #define PG8_STAGE(bufoff, gbase, voff) do { _Pragma("unroll") for (int _i = 0; _i < 2; ++_i) \
;         __builtin_amdgcn_global_load_lds((const unsigned*)((const char*)(gbase) + (voff)[_i]), (PG8_LAS unsigned*)(lds + (bufoff) + ldsw + _i * 8192), 16, 0, 0); } while (0)
; #define PG8_LDA(dst, b, h) do { _Pragma("unroll") for (int m = 0; m < 4; ++m) _Pragma("unroll") for (int k = 0; k < 2; ++k) dst[m][k] = *(const PG8_LAS bf16x8*)(lds + PG8_SA(b, h) + aoff + m * 2048 + k * 1024); } while (0)
; #define PG8_LDB(dst, b, h) do { _Pragma("unroll") for (int n = 0; n < 2; ++n) _Pragma("unroll") for (int k = 0; k < 2; ++k) dst[n][k] = *(const PG8_LAS bf16x8*)(lds + PG8_SB(b, h) + boff + n * 2048 + k * 1024); } while (0)
; #define PG8_MMA(ai, bj, At, Bt) do { __builtin_amdgcn_s_setprio(1); _Pragma("unroll") for (int m = 0; m < 4; ++m) _Pragma("unroll") for (int n = 0; n < 2; ++n) _Pragma("unroll") for (int k = 0; k < 2; ++k) \
;         acc[ai][bj][m][n] = __builtin_amdgcn_mfma_f32_16x16x32_bf16(Bt[n][k], At[m][k], acc[ai][bj][m][n], 0, 0, 0); __builtin_amdgcn_s_setprio(0); } while (0)
; #define PG8_BAR __builtin_amdgcn_s_barrier()
; template <class Epi, class Sched, bool STAMP = false>
; __device__ __forceinline__ void gemm_phase(PG8_LAS unsigned char* lds, const Gemm g, const Sched& S, const Epi& E, unsigned long long* stamps) {
;     ...
;         for (int t = 0; t < nt; t += 2) {
;             const bool last = (t == nt - 2);
;             const char* a1 = cA + (size_t)(t + 1) * kstep;
;             const char* a2 = last ? nA : cA + (size_t)(t + 2) * kstep; const char* b2 = last ? nB : cB + (size_t)(t + 2) * kstep;
;             const char* a3 = a2 + kstep; const char* b3 = b2 + kstep;
;             if (last && has_next) S.a_ready(nxt);
;             PG8_LDB(B0, 0, 0); PG8_SCHED; PG8_LDA(At, 0, 0); PG8_STAGE(PG8_SA(1, 1), a1 + hstep, voffA);
;             PG8_WAIT_L(8); PG8_BAR; PG8_WAIT_L(0); PG8_MMA(0, 0, At, B0); PG8_BAR; PG8_SCHED;
;             PG8_LDB(B1, 0, 1); PG8_STAGE(PG8_SB(0, 0), b2, voffB);
;             PG8_BAR; PG8_WAIT_L(0); PG8_MMA(0, 1, At, B1); PG8_BAR;
;             PG8_LDA(At, 0, 1); PG8_STAGE(PG8_SA(0, 0), a2, voffA);
;             PG8_BAR; PG8_WAIT_L(0); PG8_MMA(1, 0, At, B0); PG8_BAR; PG8_SCHED;
;             PG8_STAGE(PG8_SB(0, 1), b2 + hstep, voffB);
;             PG8_WAIT_V(6); PG8_BAR; PG8_MMA(1, 1, At, B1); PG8_BAR;
.LBB0_137:
	s_add_u32 s83, s34, 0x100
	s_addc_u32 s84, s35, 0
	s_mov_b32 s85, -2
	s_waitcnt lgkmcnt(0)
	ds_read_b128 v[166:169], v148
	ds_read_b128 v[170:173], v149
	ds_read_b128 v[174:177], v150
	ds_read_b128 v[178:181], v151
	s_add_u32 s34, s28, 0x100
	s_addc_u32 s35, s29, 0
	s_cmp_eq_u32 s85, 12
	s_cselect_b32 s53, s7, s35
	s_cselect_b32 s52, s6, s34
	s_cselect_b32 s37, s1, s84
	s_cselect_b32 s36, s0, s83
	s_mov_b32 m0, s74
	ds_read_b128 v[182:185], v146
	ds_read_b128 v[186:189], v146 offset:1024
	ds_read_b128 v[190:193], v146 offset:2048
	ds_read_b128 v[194:197], v146 offset:3072
	ds_read_b128 v[198:201], v146 offset:4096
	ds_read_b128 v[202:205], v146 offset:5120
	ds_read_b128 v[206:209], v146 offset:6144
	ds_read_b128 v[210:213], v146 offset:7168
	global_load_lds_dwordx4 v136, s[28:29]
	s_mov_b32 m0, s75
	s_nop 0
	global_load_lds_dwordx4 v138, s[28:29]
	s_waitcnt lgkmcnt(8)
	s_barrier
	s_waitcnt lgkmcnt(0)
	s_setprio 1
	s_waitcnt lgkmcnt(0)
	v_mfma_f32_16x16x32_bf16 v[124:127], v[166:169], v[182:185], 0
	v_mfma_f32_16x16x32_bf16 v[120:123], v[174:177], v[182:185], 0
	v_mfma_f32_16x16x32_bf16 v[116:119], v[166:169], v[190:193], 0
	v_mfma_f32_16x16x32_bf16 v[112:115], v[174:177], v[190:193], 0
	v_mfma_f32_16x16x32_bf16 v[108:111], v[166:169], v[198:201], 0
	v_mfma_f32_16x16x32_bf16 v[104:107], v[174:177], v[198:201], 0
	v_mfma_f32_16x16x32_bf16 v[100:103], v[166:169], v[206:209], 0
	v_mfma_f32_16x16x32_bf16 v[96:99], v[174:177], v[206:209], 0
	v_mfma_f32_16x16x32_bf16 v[124:127], v[170:173], v[186:189], v[124:127]
	v_mfma_f32_16x16x32_bf16 v[120:123], v[178:181], v[186:189], v[120:123]
	v_mfma_f32_16x16x32_bf16 v[116:119], v[170:173], v[194:197], v[116:119]
	v_mfma_f32_16x16x32_bf16 v[112:115], v[178:181], v[194:197], v[112:115]
	v_mfma_f32_16x16x32_bf16 v[108:111], v[170:173], v[202:205], v[108:111]
	v_mfma_f32_16x16x32_bf16 v[104:107], v[178:181], v[202:205], v[104:107]
	v_mfma_f32_16x16x32_bf16 v[100:103], v[170:173], v[210:213], v[100:103]
	v_mfma_f32_16x16x32_bf16 v[96:99], v[178:181], v[210:213], v[96:99]
	s_setprio 0
	s_barrier
	s_mov_b32 m0, s58
	ds_read_b128 v[214:217], v152
	ds_read_b128 v[218:221], v153
	ds_read_b128 v[222:225], v154
	ds_read_b128 v[226:229], v155
	global_load_lds_dwordx4 v132, s[36:37]
	s_mov_b32 m0, s59
	s_nop 0
	global_load_lds_dwordx4 v128, s[36:37]
	s_waitcnt lgkmcnt(0)
	s_barrier
	s_waitcnt lgkmcnt(0)
	s_setprio 1
	s_waitcnt lgkmcnt(0)
	v_mfma_f32_16x16x32_bf16 v[60:63], v[214:217], v[182:185], 0
	v_mfma_f32_16x16x32_bf16 v[56:59], v[222:225], v[182:185], 0
	v_mfma_f32_16x16x32_bf16 v[52:55], v[214:217], v[190:193], 0
	v_mfma_f32_16x16x32_bf16 v[48:51], v[222:225], v[190:193], 0
	v_mfma_f32_16x16x32_bf16 v[44:47], v[214:217], v[198:201], 0
	v_mfma_f32_16x16x32_bf16 v[40:43], v[222:225], v[198:201], 0
	v_mfma_f32_16x16x32_bf16 v[36:39], v[214:217], v[206:209], 0
	v_mfma_f32_16x16x32_bf16 v[32:35], v[222:225], v[206:209], 0
	v_mfma_f32_16x16x32_bf16 v[60:63], v[218:221], v[186:189], v[60:63]
	v_mfma_f32_16x16x32_bf16 v[56:59], v[226:229], v[186:189], v[56:59]
	v_mfma_f32_16x16x32_bf16 v[52:55], v[218:221], v[194:197], v[52:55]
	v_mfma_f32_16x16x32_bf16 v[48:51], v[226:229], v[194:197], v[48:51]
	v_mfma_f32_16x16x32_bf16 v[44:47], v[218:221], v[202:205], v[44:47]
	v_mfma_f32_16x16x32_bf16 v[40:43], v[226:229], v[202:205], v[40:43]
	v_mfma_f32_16x16x32_bf16 v[36:39], v[218:221], v[210:213], v[36:39]
	v_mfma_f32_16x16x32_bf16 v[32:35], v[226:229], v[210:213], v[32:35]
	s_setprio 0
	s_mov_b32 m0, s55
	s_barrier
	ds_read_b128 v[182:185], v146 offset:16384
	ds_read_b128 v[186:189], v146 offset:17408
	ds_read_b128 v[190:193], v146 offset:18432
	ds_read_b128 v[194:197], v146 offset:19456
	ds_read_b128 v[198:201], v146 offset:20480
	ds_read_b128 v[202:205], v146 offset:21504
	ds_read_b128 v[206:209], v146 offset:22528
	ds_read_b128 v[210:213], v146 offset:23552
	global_load_lds_dwordx4 v134, s[52:53]
	s_mov_b32 m0, s60
	s_nop 0
	global_load_lds_dwordx4 v130, s[52:53]
	s_add_u32 s28, s36, 0x44000
	s_addc_u32 s29, s37, 0
	s_mov_b32 m0, s61
	s_nop 0
	global_load_lds_dwordx4 v132, s[28:29]
	s_mov_b32 m0, s62
	s_nop 0
	global_load_lds_dwordx4 v128, s[28:29]
	s_waitcnt vmcnt(6)
	s_barrier
	s_waitcnt lgkmcnt(0)
	s_setprio 1
	s_waitcnt lgkmcnt(0)
	v_mfma_f32_16x16x32_bf16 v[92:95], v[166:169], v[182:185], 0
	v_mfma_f32_16x16x32_bf16 v[88:91], v[174:177], v[182:185], 0
	v_mfma_f32_16x16x32_bf16 v[84:87], v[166:169], v[190:193], 0
	v_mfma_f32_16x16x32_bf16 v[80:83], v[174:177], v[190:193], 0
	v_mfma_f32_16x16x32_bf16 v[76:79], v[166:169], v[198:201], 0
	v_mfma_f32_16x16x32_bf16 v[72:75], v[174:177], v[198:201], 0
	v_mfma_f32_16x16x32_bf16 v[68:71], v[166:169], v[206:209], 0
	v_mfma_f32_16x16x32_bf16 v[64:67], v[174:177], v[206:209], 0
	v_mfma_f32_16x16x32_bf16 v[92:95], v[170:173], v[186:189], v[92:95]
	v_mfma_f32_16x16x32_bf16 v[88:91], v[178:181], v[186:189], v[88:91]
	v_mfma_f32_16x16x32_bf16 v[84:87], v[170:173], v[194:197], v[84:87]
	v_mfma_f32_16x16x32_bf16 v[80:83], v[178:181], v[194:197], v[80:83]
	v_mfma_f32_16x16x32_bf16 v[76:79], v[170:173], v[202:205], v[76:79]
	v_mfma_f32_16x16x32_bf16 v[72:75], v[178:181], v[202:205], v[72:75]
	v_mfma_f32_16x16x32_bf16 v[68:71], v[170:173], v[210:213], v[68:71]
	v_mfma_f32_16x16x32_bf16 v[64:67], v[178:181], v[210:213], v[64:67]
	v_mfma_f32_16x16x32_bf16 v[28:31], v[214:217], v[182:185], 0
	v_mfma_f32_16x16x32_bf16 v[24:27], v[222:225], v[182:185], 0
	v_mfma_f32_16x16x32_bf16 v[20:23], v[214:217], v[190:193], 0
	v_mfma_f32_16x16x32_bf16 v[16:19], v[222:225], v[190:193], 0
	v_mfma_f32_16x16x32_bf16 v[12:15], v[214:217], v[198:201], 0
	v_mfma_f32_16x16x32_bf16 v[8:11], v[222:225], v[198:201], 0
	v_mfma_f32_16x16x32_bf16 v[4:7], v[214:217], v[206:209], 0
	v_mfma_f32_16x16x32_bf16 v[0:3], v[222:225], v[206:209], 0
	v_mfma_f32_16x16x32_bf16 v[28:31], v[218:221], v[186:189], v[28:31]
	v_mfma_f32_16x16x32_bf16 v[24:27], v[226:229], v[186:189], v[24:27]
	v_mfma_f32_16x16x32_bf16 v[20:23], v[218:221], v[194:197], v[20:23]
	v_mfma_f32_16x16x32_bf16 v[16:19], v[226:229], v[194:197], v[16:19]
	v_mfma_f32_16x16x32_bf16 v[12:15], v[218:221], v[202:205], v[12:15]
	v_mfma_f32_16x16x32_bf16 v[8:11], v[226:229], v[202:205], v[8:11]
	v_mfma_f32_16x16x32_bf16 v[4:7], v[218:221], v[210:213], v[4:7]
	v_mfma_f32_16x16x32_bf16 v[0:3], v[226:229], v[210:213], v[0:3]
	s_setprio 0
	s_barrier
	s_branch .Lzp3_mid
; #define PG8_STAGE(bufoff, gbase, voff) do { _Pragma("unroll") for (int _i = 0; _i < 2; ++_i) \
;         __builtin_amdgcn_global_load_lds((const unsigned*)((const char*)(gbase) + (voff)[_i]), (PG8_LAS unsigned*)(lds + (bufoff) + ldsw + _i * 8192), 16, 0, 0); } while (0)
; #define PG8_LDA(dst, b, h) do { _Pragma("unroll") for (int m = 0; m < 4; ++m) _Pragma("unroll") for (int k = 0; k < 2; ++k) dst[m][k] = *(const PG8_LAS bf16x8*)(lds + PG8_SA(b, h) + aoff + m * 2048 + k * 1024); } while (0)
; #define PG8_BAR __builtin_amdgcn_s_barrier()
; template <class Epi, class Sched, bool STAMP = false>
; __device__ __forceinline__ void gemm_phase(PG8_LAS unsigned char* lds, const Gemm g, const Sched& S, const Epi& E, unsigned long long* stamps) {
;     ...
;         for (int t = 0; t < nt; t += 2) {
;             const bool last = (t == nt - 2);
;             const char* a1 = cA + (size_t)(t + 1) * kstep;
;             const char* a2 = last ? nA : cA + (size_t)(t + 2) * kstep; const char* b2 = last ? nB : cB + (size_t)(t + 2) * kstep;
;             const char* a3 = a2 + kstep; const char* b3 = b2 + kstep;
;             if (last && has_next) S.a_ready(nxt);
;             PG8_LDB(B0, 0, 0); PG8_SCHED; PG8_LDA(At, 0, 0); PG8_STAGE(PG8_SA(1, 1), a1 + hstep, voffA);
;             PG8_WAIT_L(8); PG8_BAR; PG8_WAIT_L(0); PG8_MMA(0, 0, At, B0); PG8_BAR; PG8_SCHED;
;             PG8_LDB(B1, 0, 1); PG8_STAGE(PG8_SB(0, 0), b2, voffB);
;             PG8_BAR; PG8_WAIT_L(0); PG8_MMA(0, 1, At, B1); PG8_BAR;
;             PG8_LDA(At, 0, 1); PG8_STAGE(PG8_SA(0, 0), a2, voffA);
;             PG8_BAR; PG8_WAIT_L(0); PG8_MMA(1, 0, At, B0); PG8_BAR; PG8_SCHED;
;             PG8_STAGE(PG8_SB(0, 1), b2 + hstep, voffB);
;             PG8_WAIT_V(6); PG8_BAR; PG8_MMA(1, 1, At, B1); PG8_BAR;
;             PG8_LDB(B0, 1, 0); PG8_SCHED; PG8_LDA(At, 1, 0); PG8_STAGE(PG8_SA(0, 1), a2 + hstep, voffA);
;             PG8_WAIT_L(8); PG8_BAR; PG8_WAIT_L(0); PG8_MMA(0, 0, At, B0); PG8_BAR; PG8_SCHED;
;             PG8_LDB(B1, 1, 1); PG8_STAGE(PG8_SB(1, 0), b3, voffB);
;             PG8_BAR; PG8_WAIT_L(0); PG8_MMA(0, 1, At, B1); PG8_BAR;
;             PG8_LDA(At, 1, 1); PG8_STAGE(PG8_SA(1, 0), a3, voffA);
;             PG8_BAR; PG8_WAIT_L(0); PG8_MMA(1, 0, At, B0); PG8_BAR; PG8_SCHED;
;             PG8_STAGE(PG8_SB(1, 1), b3 + hstep, voffB);
;             PG8_WAIT_V(6); PG8_BAR; PG8_MMA(1, 1, At, B1); PG8_BAR;
.LBB0_138:
	ds_read_b128 v[166:169], v148
	ds_read_b128 v[170:173], v149
	ds_read_b128 v[174:177], v150
	ds_read_b128 v[178:181], v151
	s_add_u32 s34, s28, 0x100
	s_addc_u32 s35, s29, 0
	s_cmp_eq_u32 s85, 12
	s_cselect_b32 s53, s7, s35
	s_cselect_b32 s52, s6, s34
	s_cselect_b32 s37, s1, s84
	s_cselect_b32 s36, s0, s83
	s_mov_b32 m0, s74
	ds_read_b128 v[182:185], v146
	ds_read_b128 v[186:189], v146 offset:1024
	ds_read_b128 v[190:193], v146 offset:2048
	ds_read_b128 v[194:197], v146 offset:3072
	ds_read_b128 v[198:201], v146 offset:4096
	ds_read_b128 v[202:205], v146 offset:5120
	ds_read_b128 v[206:209], v146 offset:6144
	ds_read_b128 v[210:213], v146 offset:7168
	global_load_lds_dwordx4 v136, s[28:29]
	s_mov_b32 m0, s75
	s_nop 0
	global_load_lds_dwordx4 v138, s[28:29]
	s_waitcnt lgkmcnt(8)
	s_barrier
	s_waitcnt lgkmcnt(0)
	s_setprio 1
	s_waitcnt lgkmcnt(0)
	v_mfma_f32_16x16x32_bf16 v[124:127], v[166:169], v[182:185], v[124:127]
	v_mfma_f32_16x16x32_bf16 v[120:123], v[174:177], v[182:185], v[120:123]
	v_mfma_f32_16x16x32_bf16 v[116:119], v[166:169], v[190:193], v[116:119]
	v_mfma_f32_16x16x32_bf16 v[112:115], v[174:177], v[190:193], v[112:115]
	v_mfma_f32_16x16x32_bf16 v[108:111], v[166:169], v[198:201], v[108:111]
	v_mfma_f32_16x16x32_bf16 v[104:107], v[174:177], v[198:201], v[104:107]
	v_mfma_f32_16x16x32_bf16 v[100:103], v[166:169], v[206:209], v[100:103]
	v_mfma_f32_16x16x32_bf16 v[96:99], v[174:177], v[206:209], v[96:99]
	v_mfma_f32_16x16x32_bf16 v[124:127], v[170:173], v[186:189], v[124:127]
	v_mfma_f32_16x16x32_bf16 v[120:123], v[178:181], v[186:189], v[120:123]
	v_mfma_f32_16x16x32_bf16 v[116:119], v[170:173], v[194:197], v[116:119]
	v_mfma_f32_16x16x32_bf16 v[112:115], v[178:181], v[194:197], v[112:115]
	v_mfma_f32_16x16x32_bf16 v[108:111], v[170:173], v[202:205], v[108:111]
	v_mfma_f32_16x16x32_bf16 v[104:107], v[178:181], v[202:205], v[104:107]
	v_mfma_f32_16x16x32_bf16 v[100:103], v[170:173], v[210:213], v[100:103]
	v_mfma_f32_16x16x32_bf16 v[96:99], v[178:181], v[210:213], v[96:99]
	s_setprio 0
	s_barrier
	s_mov_b32 m0, s58
	ds_read_b128 v[214:217], v152
	ds_read_b128 v[218:221], v153
	ds_read_b128 v[222:225], v154
	ds_read_b128 v[226:229], v155
	global_load_lds_dwordx4 v132, s[36:37]
	s_mov_b32 m0, s59
	s_nop 0
	global_load_lds_dwordx4 v128, s[36:37]
	s_waitcnt lgkmcnt(0)
	s_barrier
	s_waitcnt lgkmcnt(0)
	s_setprio 1
	s_waitcnt lgkmcnt(0)
	v_mfma_f32_16x16x32_bf16 v[60:63], v[214:217], v[182:185], v[60:63]
	v_mfma_f32_16x16x32_bf16 v[56:59], v[222:225], v[182:185], v[56:59]
	v_mfma_f32_16x16x32_bf16 v[52:55], v[214:217], v[190:193], v[52:55]
	v_mfma_f32_16x16x32_bf16 v[48:51], v[222:225], v[190:193], v[48:51]
	v_mfma_f32_16x16x32_bf16 v[44:47], v[214:217], v[198:201], v[44:47]
	v_mfma_f32_16x16x32_bf16 v[40:43], v[222:225], v[198:201], v[40:43]
	v_mfma_f32_16x16x32_bf16 v[36:39], v[214:217], v[206:209], v[36:39]
	v_mfma_f32_16x16x32_bf16 v[32:35], v[222:225], v[206:209], v[32:35]
	v_mfma_f32_16x16x32_bf16 v[60:63], v[218:221], v[186:189], v[60:63]
	v_mfma_f32_16x16x32_bf16 v[56:59], v[226:229], v[186:189], v[56:59]
	v_mfma_f32_16x16x32_bf16 v[52:55], v[218:221], v[194:197], v[52:55]
	v_mfma_f32_16x16x32_bf16 v[48:51], v[226:229], v[194:197], v[48:51]
	v_mfma_f32_16x16x32_bf16 v[44:47], v[218:221], v[202:205], v[44:47]
	v_mfma_f32_16x16x32_bf16 v[40:43], v[226:229], v[202:205], v[40:43]
	v_mfma_f32_16x16x32_bf16 v[36:39], v[218:221], v[210:213], v[36:39]
	v_mfma_f32_16x16x32_bf16 v[32:35], v[226:229], v[210:213], v[32:35]
	s_setprio 0
	s_mov_b32 m0, s55
	s_barrier
	ds_read_b128 v[182:185], v146 offset:16384
	ds_read_b128 v[186:189], v146 offset:17408
	ds_read_b128 v[190:193], v146 offset:18432
	ds_read_b128 v[194:197], v146 offset:19456
	ds_read_b128 v[198:201], v146 offset:20480
	ds_read_b128 v[202:205], v146 offset:21504
	ds_read_b128 v[206:209], v146 offset:22528
	ds_read_b128 v[210:213], v146 offset:23552
	global_load_lds_dwordx4 v134, s[52:53]
	s_mov_b32 m0, s60
	s_nop 0
	global_load_lds_dwordx4 v130, s[52:53]
	s_add_u32 s28, s36, 0x44000
	s_addc_u32 s29, s37, 0
	s_mov_b32 m0, s61
	s_nop 0
	global_load_lds_dwordx4 v132, s[28:29]
	s_mov_b32 m0, s62
	s_nop 0
	global_load_lds_dwordx4 v128, s[28:29]
	s_waitcnt vmcnt(6)
	s_barrier
	s_waitcnt lgkmcnt(0)
	s_setprio 1
	s_waitcnt lgkmcnt(0)
	v_mfma_f32_16x16x32_bf16 v[92:95], v[166:169], v[182:185], v[92:95]
	v_mfma_f32_16x16x32_bf16 v[88:91], v[174:177], v[182:185], v[88:91]
	v_mfma_f32_16x16x32_bf16 v[84:87], v[166:169], v[190:193], v[84:87]
	v_mfma_f32_16x16x32_bf16 v[80:83], v[174:177], v[190:193], v[80:83]
	v_mfma_f32_16x16x32_bf16 v[76:79], v[166:169], v[198:201], v[76:79]
	v_mfma_f32_16x16x32_bf16 v[72:75], v[174:177], v[198:201], v[72:75]
	v_mfma_f32_16x16x32_bf16 v[68:71], v[166:169], v[206:209], v[68:71]
	v_mfma_f32_16x16x32_bf16 v[64:67], v[174:177], v[206:209], v[64:67]
	v_mfma_f32_16x16x32_bf16 v[92:95], v[170:173], v[186:189], v[92:95]
	v_mfma_f32_16x16x32_bf16 v[88:91], v[178:181], v[186:189], v[88:91]
	v_mfma_f32_16x16x32_bf16 v[84:87], v[170:173], v[194:197], v[84:87]
	v_mfma_f32_16x16x32_bf16 v[80:83], v[178:181], v[194:197], v[80:83]
	v_mfma_f32_16x16x32_bf16 v[76:79], v[170:173], v[202:205], v[76:79]
	v_mfma_f32_16x16x32_bf16 v[72:75], v[178:181], v[202:205], v[72:75]
	v_mfma_f32_16x16x32_bf16 v[68:71], v[170:173], v[210:213], v[68:71]
	v_mfma_f32_16x16x32_bf16 v[64:67], v[178:181], v[210:213], v[64:67]
	v_mfma_f32_16x16x32_bf16 v[28:31], v[214:217], v[182:185], v[28:31]
	v_mfma_f32_16x16x32_bf16 v[24:27], v[222:225], v[182:185], v[24:27]
	v_mfma_f32_16x16x32_bf16 v[20:23], v[214:217], v[190:193], v[20:23]
	v_mfma_f32_16x16x32_bf16 v[16:19], v[222:225], v[190:193], v[16:19]
	v_mfma_f32_16x16x32_bf16 v[12:15], v[214:217], v[198:201], v[12:15]
	v_mfma_f32_16x16x32_bf16 v[8:11], v[222:225], v[198:201], v[8:11]
	v_mfma_f32_16x16x32_bf16 v[4:7], v[214:217], v[206:209], v[4:7]
	v_mfma_f32_16x16x32_bf16 v[0:3], v[222:225], v[206:209], v[0:3]
	v_mfma_f32_16x16x32_bf16 v[28:31], v[218:221], v[186:189], v[28:31]
	v_mfma_f32_16x16x32_bf16 v[24:27], v[226:229], v[186:189], v[24:27]
	v_mfma_f32_16x16x32_bf16 v[20:23], v[218:221], v[194:197], v[20:23]
	v_mfma_f32_16x16x32_bf16 v[16:19], v[226:229], v[194:197], v[16:19]
	v_mfma_f32_16x16x32_bf16 v[12:15], v[218:221], v[202:205], v[12:15]
	v_mfma_f32_16x16x32_bf16 v[8:11], v[226:229], v[202:205], v[8:11]
	v_mfma_f32_16x16x32_bf16 v[4:7], v[218:221], v[210:213], v[4:7]
	v_mfma_f32_16x16x32_bf16 v[0:3], v[226:229], v[210:213], v[0:3]
	s_setprio 0
	s_barrier
; #define PG8_STAGE(bufoff, gbase, voff) do { _Pragma("unroll") for (int _i = 0; _i < 2; ++_i) \
;         __builtin_amdgcn_global_load_lds((const unsigned*)((const char*)(gbase) + (voff)[_i]), (PG8_LAS unsigned*)(lds + (bufoff) + ldsw + _i * 8192), 16, 0, 0); } while (0)
; #define PG8_LDA(dst, b, h) do { _Pragma("unroll") for (int m = 0; m < 4; ++m) _Pragma("unroll") for (int k = 0; k < 2; ++k) dst[m][k] = *(const PG8_LAS bf16x8*)(lds + PG8_SA(b, h) + aoff + m * 2048 + k * 1024); } while (0)
; #define PG8_BAR __builtin_amdgcn_s_barrier()
; template <class Epi, class Sched, bool STAMP = false>
; __device__ __forceinline__ void gemm_phase(PG8_LAS unsigned char* lds, const Gemm g, const Sched& S, const Epi& E, unsigned long long* stamps) {
;     ...
;         for (int t = 0; t < nt; t += 2) {
;             const bool last = (t == nt - 2);
;             const char* a1 = cA + (size_t)(t + 1) * kstep;
;             const char* a2 = last ? nA : cA + (size_t)(t + 2) * kstep; const char* b2 = last ? nB : cB + (size_t)(t + 2) * kstep;
;             const char* a3 = a2 + kstep; const char* b3 = b2 + kstep;
;             if (last && has_next) S.a_ready(nxt);
;             PG8_LDB(B0, 0, 0); PG8_SCHED; PG8_LDA(At, 0, 0); PG8_STAGE(PG8_SA(1, 1), a1 + hstep, voffA);
;             PG8_WAIT_L(8); PG8_BAR; PG8_WAIT_L(0); PG8_MMA(0, 0, At, B0); PG8_BAR; PG8_SCHED;
;             PG8_LDB(B1, 0, 1); PG8_STAGE(PG8_SB(0, 0), b2, voffB);
;             PG8_BAR; PG8_WAIT_L(0); PG8_MMA(0, 1, At, B1); PG8_BAR;
;             PG8_LDA(At, 0, 1); PG8_STAGE(PG8_SA(0, 0), a2, voffA);
;             PG8_BAR; PG8_WAIT_L(0); PG8_MMA(1, 0, At, B0); PG8_BAR; PG8_SCHED;
;             PG8_STAGE(PG8_SB(0, 1), b2 + hstep, voffB);
;             PG8_WAIT_V(6); PG8_BAR; PG8_MMA(1, 1, At, B1); PG8_BAR;
;             PG8_LDB(B0, 1, 0); PG8_SCHED; PG8_LDA(At, 1, 0); PG8_STAGE(PG8_SA(0, 1), a2 + hstep, voffA);
;             PG8_WAIT_L(8); PG8_BAR; PG8_WAIT_L(0); PG8_MMA(0, 0, At, B0); PG8_BAR; PG8_SCHED;
;             PG8_LDB(B1, 1, 1); PG8_STAGE(PG8_SB(1, 0), b3, voffB);
;             PG8_BAR; PG8_WAIT_L(0); PG8_MMA(0, 1, At, B1); PG8_BAR;
;             PG8_LDA(At, 1, 1); PG8_STAGE(PG8_SA(1, 0), a3, voffA);
;             PG8_BAR; PG8_WAIT_L(0); PG8_MMA(1, 0, At, B0); PG8_BAR; PG8_SCHED;
;             PG8_STAGE(PG8_SB(1, 1), b3 + hstep, voffB);
;             PG8_WAIT_V(6); PG8_BAR; PG8_MMA(1, 1, At, B1); PG8_BAR;
.Lzp3_mid:
	ds_read_b128 v[166:169], v156
	ds_read_b128 v[170:173], v157
	ds_read_b128 v[174:177], v159
	ds_read_b128 v[178:181], v160
	s_add_u32 s28, s52, 0x44000
	s_addc_u32 s29, s53, 0
	s_mov_b32 m0, s63
	ds_read_b128 v[182:185], v146 offset:32768
	ds_read_b128 v[186:189], v146 offset:33792
	ds_read_b128 v[190:193], v146 offset:34816
	ds_read_b128 v[194:197], v146 offset:35840
	ds_read_b128 v[198:201], v146 offset:36864
	ds_read_b128 v[202:205], v146 offset:37888
	ds_read_b128 v[206:209], v146 offset:38912
	ds_read_b128 v[210:213], v146 offset:39936
	global_load_lds_dwordx4 v134, s[28:29]
	s_mov_b32 m0, s64
	s_nop 0
	global_load_lds_dwordx4 v130, s[28:29]
	s_waitcnt lgkmcnt(8)
	s_barrier
	s_waitcnt lgkmcnt(0)
	s_setprio 1
	s_waitcnt lgkmcnt(0)
	v_mfma_f32_16x16x32_bf16 v[124:127], v[166:169], v[182:185], v[124:127]
	v_mfma_f32_16x16x32_bf16 v[120:123], v[174:177], v[182:185], v[120:123]
	v_mfma_f32_16x16x32_bf16 v[116:119], v[166:169], v[190:193], v[116:119]
	v_mfma_f32_16x16x32_bf16 v[112:115], v[174:177], v[190:193], v[112:115]
	v_mfma_f32_16x16x32_bf16 v[108:111], v[166:169], v[198:201], v[108:111]
	v_mfma_f32_16x16x32_bf16 v[104:107], v[174:177], v[198:201], v[104:107]
	v_mfma_f32_16x16x32_bf16 v[100:103], v[166:169], v[206:209], v[100:103]
	v_mfma_f32_16x16x32_bf16 v[96:99], v[174:177], v[206:209], v[96:99]
	v_mfma_f32_16x16x32_bf16 v[124:127], v[170:173], v[186:189], v[124:127]
	v_mfma_f32_16x16x32_bf16 v[120:123], v[178:181], v[186:189], v[120:123]
	v_mfma_f32_16x16x32_bf16 v[116:119], v[170:173], v[194:197], v[116:119]
	v_mfma_f32_16x16x32_bf16 v[112:115], v[178:181], v[194:197], v[112:115]
	v_mfma_f32_16x16x32_bf16 v[108:111], v[170:173], v[202:205], v[108:111]
	v_mfma_f32_16x16x32_bf16 v[104:107], v[178:181], v[202:205], v[104:107]
	v_mfma_f32_16x16x32_bf16 v[100:103], v[170:173], v[210:213], v[100:103]
	v_mfma_f32_16x16x32_bf16 v[96:99], v[178:181], v[210:213], v[96:99]
	s_setprio 0
	s_barrier
	s_mov_b32 m0, s67
	ds_read_b128 v[214:217], v161
	ds_read_b128 v[218:221], v162
	ds_read_b128 v[222:225], v163
	ds_read_b128 v[226:229], v164
	s_add_u32 s100, s36, 0x80
	s_addc_u32 s101, s37, 0
	global_load_lds_dwordx4 v132, s[100:101]
	s_mov_b32 m0, s68
	s_nop 0
	global_load_lds_dwordx4 v128, s[100:101]
	s_waitcnt lgkmcnt(0)
	s_barrier
	s_waitcnt lgkmcnt(0)
	s_setprio 1
	s_waitcnt lgkmcnt(0)
	v_mfma_f32_16x16x32_bf16 v[60:63], v[214:217], v[182:185], v[60:63]
	v_mfma_f32_16x16x32_bf16 v[56:59], v[222:225], v[182:185], v[56:59]
	v_mfma_f32_16x16x32_bf16 v[52:55], v[214:217], v[190:193], v[52:55]
	v_mfma_f32_16x16x32_bf16 v[48:51], v[222:225], v[190:193], v[48:51]
	v_mfma_f32_16x16x32_bf16 v[44:47], v[214:217], v[198:201], v[44:47]
	v_mfma_f32_16x16x32_bf16 v[40:43], v[222:225], v[198:201], v[40:43]
	v_mfma_f32_16x16x32_bf16 v[36:39], v[214:217], v[206:209], v[36:39]
	v_mfma_f32_16x16x32_bf16 v[32:35], v[222:225], v[206:209], v[32:35]
	v_mfma_f32_16x16x32_bf16 v[60:63], v[218:221], v[186:189], v[60:63]
	v_mfma_f32_16x16x32_bf16 v[56:59], v[226:229], v[186:189], v[56:59]
	v_mfma_f32_16x16x32_bf16 v[52:55], v[218:221], v[194:197], v[52:55]
	v_mfma_f32_16x16x32_bf16 v[48:51], v[226:229], v[194:197], v[48:51]
	v_mfma_f32_16x16x32_bf16 v[44:47], v[218:221], v[202:205], v[44:47]
	v_mfma_f32_16x16x32_bf16 v[40:43], v[226:229], v[202:205], v[40:43]
	v_mfma_f32_16x16x32_bf16 v[36:39], v[218:221], v[210:213], v[36:39]
	v_mfma_f32_16x16x32_bf16 v[32:35], v[226:229], v[210:213], v[32:35]
	s_setprio 0
	s_mov_b32 m0, s69
	s_barrier
	ds_read_b128 v[182:185], v146 offset:49152
	ds_read_b128 v[186:189], v146 offset:50176
	ds_read_b128 v[190:193], v146 offset:51200
	ds_read_b128 v[194:197], v146 offset:52224
	ds_read_b128 v[198:201], v146 offset:53248
	ds_read_b128 v[202:205], v146 offset:54272
	ds_read_b128 v[206:209], v146 offset:55296
	ds_read_b128 v[210:213], v146 offset:56320
	s_add_u32 s100, s52, 0x80
	s_addc_u32 s101, s53, 0
	global_load_lds_dwordx4 v134, s[100:101]
	s_mov_b32 m0, s70
	s_nop 0
	global_load_lds_dwordx4 v130, s[100:101]
	s_add_u32 s28, s36, 0x44080
	s_addc_u32 s29, s37, 0
	s_mov_b32 m0, s71
	s_nop 0
	global_load_lds_dwordx4 v132, s[28:29]
	s_mov_b32 m0, s72
	s_nop 0
	global_load_lds_dwordx4 v128, s[28:29]
	s_waitcnt vmcnt(6)
	s_barrier
	s_waitcnt lgkmcnt(0)
	s_setprio 1
	s_waitcnt lgkmcnt(0)
	v_mfma_f32_16x16x32_bf16 v[92:95], v[166:169], v[182:185], v[92:95]
	v_mfma_f32_16x16x32_bf16 v[88:91], v[174:177], v[182:185], v[88:91]
	v_mfma_f32_16x16x32_bf16 v[84:87], v[166:169], v[190:193], v[84:87]
	v_mfma_f32_16x16x32_bf16 v[80:83], v[174:177], v[190:193], v[80:83]
	v_mfma_f32_16x16x32_bf16 v[76:79], v[166:169], v[198:201], v[76:79]
	v_mfma_f32_16x16x32_bf16 v[72:75], v[174:177], v[198:201], v[72:75]
	v_mfma_f32_16x16x32_bf16 v[68:71], v[166:169], v[206:209], v[68:71]
	v_mfma_f32_16x16x32_bf16 v[64:67], v[174:177], v[206:209], v[64:67]
	v_mfma_f32_16x16x32_bf16 v[92:95], v[170:173], v[186:189], v[92:95]
	v_mfma_f32_16x16x32_bf16 v[88:91], v[178:181], v[186:189], v[88:91]
	v_mfma_f32_16x16x32_bf16 v[84:87], v[170:173], v[194:197], v[84:87]
	v_mfma_f32_16x16x32_bf16 v[80:83], v[178:181], v[194:197], v[80:83]
	v_mfma_f32_16x16x32_bf16 v[76:79], v[170:173], v[202:205], v[76:79]
	v_mfma_f32_16x16x32_bf16 v[72:75], v[178:181], v[202:205], v[72:75]
	v_mfma_f32_16x16x32_bf16 v[68:71], v[170:173], v[210:213], v[68:71]
	v_mfma_f32_16x16x32_bf16 v[64:67], v[178:181], v[210:213], v[64:67]
	v_mfma_f32_16x16x32_bf16 v[28:31], v[214:217], v[182:185], v[28:31]
	v_mfma_f32_16x16x32_bf16 v[24:27], v[222:225], v[182:185], v[24:27]
	v_mfma_f32_16x16x32_bf16 v[20:23], v[214:217], v[190:193], v[20:23]
	v_mfma_f32_16x16x32_bf16 v[16:19], v[222:225], v[190:193], v[16:19]
	v_mfma_f32_16x16x32_bf16 v[12:15], v[214:217], v[198:201], v[12:15]
	v_mfma_f32_16x16x32_bf16 v[8:11], v[222:225], v[198:201], v[8:11]
	v_mfma_f32_16x16x32_bf16 v[4:7], v[214:217], v[206:209], v[4:7]
	v_mfma_f32_16x16x32_bf16 v[0:3], v[222:225], v[206:209], v[0:3]
	v_mfma_f32_16x16x32_bf16 v[28:31], v[218:221], v[186:189], v[28:31]
	v_mfma_f32_16x16x32_bf16 v[24:27], v[226:229], v[186:189], v[24:27]
	v_mfma_f32_16x16x32_bf16 v[20:23], v[218:221], v[194:197], v[20:23]
	v_mfma_f32_16x16x32_bf16 v[16:19], v[226:229], v[194:197], v[16:19]
	v_mfma_f32_16x16x32_bf16 v[12:15], v[218:221], v[202:205], v[12:15]
	v_mfma_f32_16x16x32_bf16 v[8:11], v[226:229], v[202:205], v[8:11]
	v_mfma_f32_16x16x32_bf16 v[4:7], v[218:221], v[210:213], v[4:7]
	v_mfma_f32_16x16x32_bf16 v[0:3], v[226:229], v[210:213], v[0:3]
	s_setprio 0
	s_add_i32 s85, s85, 2
	s_add_u32 s83, s83, 0x100
	s_addc_u32 s84, s84, 0
	s_cmp_gt_u32 s85, 13
	s_mov_b64 s[28:29], s[34:35]
	s_barrier
;     DI void operator()(const f32x4 (&acc)[2][2][4][2], const Unit& u, int wr, int wc, int fr, int fq) const {
;         const int row0 = u.pm * BM + wr * 64 + fr, col0 = u.pn * BM + wc * 32 + 8 * fq;
; #pragma unroll
;         for (int ai = 0; ai < 2; ++ai)
; #pragma unroll
;             for (int m = 0; m < 4; ++m) { u16* rowp = O + (size_t)(row0 + ai * HALF + m * 16) * ldc + col0;
; #pragma unroll
;                 for (int bj = 0; bj < 2; ++bj) { const f32x4 v0 = acc[ai][bj][m][0], v1 = acc[ai][bj][m][1];
;                     uint4 w = {pack2(v0[0], v0[1]), pack2(v0[2], v0[3]), pack2(v1[0], v1[1]), pack2(v1[2], v1[3])}; *(uint4*)(rowp + bj * HALF) = w; } }
;         if (kmaxp) {
; #pragma unroll
;             for (int bj = 0; bj < 2; ++bj) {
;                 const int cb = u.pn * BM + bj * HALF + wc * 32;
;                 const bool isA = (cb >= 384 && cb < 768), isB = (cb >= 1408 && cb < 1664);
;                 if (isA || isB) {
	s_cbranch_scc0 .LBB0_138
	s_lshl_b32 s52, s79, 8
	v_or_b32_e32 v166, s52, v147
	v_lshl_add_u32 v176, s82, 8, v145
	v_ashrrev_i32_e32 v167, 31, v166
	v_mov_b64_e32 v[170:171], s[12:13]
	v_mad_i64_i32 v[168:169], s[28:29], v176, s76, v[170:171]
	v_lshlrev_b64 v[172:173], 1, v[166:167]
	v_lshl_add_u64 v[174:175], v[168:169], 0, v[172:173]
	v_cvt_pk_bf16_f32 v166, v124, v125
	v_cvt_pk_bf16_f32 v167, v126, v127
	v_cvt_pk_bf16_f32 v168, v120, v121
	v_cvt_pk_bf16_f32 v169, v122, v123
	global_store_dwordx4 v[174:175], v[166:169], off
	s_or_b32 s10, s52, s66
	s_nop 0
	v_cvt_pk_bf16_f32 v166, v60, v61
	v_cvt_pk_bf16_f32 v167, v62, v63
	v_cvt_pk_bf16_f32 v168, v56, v57
	v_cvt_pk_bf16_f32 v169, v58, v59
	global_store_dwordx4 v[174:175], v[166:169], off offset:256
	s_nop 1
	v_or_b32_e32 v166, 16, v176
	v_mad_i64_i32 v[166:167], s[28:29], v166, s76, v[170:171]
	v_lshl_add_u64 v[174:175], v[166:167], 0, v[172:173]
	v_cvt_pk_bf16_f32 v166, v116, v117
	v_cvt_pk_bf16_f32 v167, v118, v119
	v_cvt_pk_bf16_f32 v168, v112, v113
	v_cvt_pk_bf16_f32 v169, v114, v115
	global_store_dwordx4 v[174:175], v[166:169], off
	s_nop 1
	v_cvt_pk_bf16_f32 v166, v52, v53
	v_cvt_pk_bf16_f32 v167, v54, v55
	v_cvt_pk_bf16_f32 v168, v48, v49
	v_cvt_pk_bf16_f32 v169, v50, v51
	global_store_dwordx4 v[174:175], v[166:169], off offset:256
	s_nop 1
	v_or_b32_e32 v166, 32, v176
	v_mad_i64_i32 v[166:167], s[28:29], v166, s76, v[170:171]
	v_lshl_add_u64 v[174:175], v[166:167], 0, v[172:173]
	v_cvt_pk_bf16_f32 v166, v108, v109
	v_cvt_pk_bf16_f32 v167, v110, v111
	v_cvt_pk_bf16_f32 v168, v104, v105
	v_cvt_pk_bf16_f32 v169, v106, v107
	global_store_dwordx4 v[174:175], v[166:169], off
	s_nop 1
	v_cvt_pk_bf16_f32 v166, v44, v45
	v_cvt_pk_bf16_f32 v167, v46, v47
	v_cvt_pk_bf16_f32 v168, v40, v41
	v_cvt_pk_bf16_f32 v169, v42, v43
	global_store_dwordx4 v[174:175], v[166:169], off offset:256
	s_nop 1
	v_or_b32_e32 v166, 48, v176
	v_mad_i64_i32 v[166:167], s[28:29], v166, s76, v[170:171]
	v_lshl_add_u64 v[174:175], v[166:167], 0, v[172:173]
	v_cvt_pk_bf16_f32 v166, v100, v101
	v_cvt_pk_bf16_f32 v167, v102, v103
	v_cvt_pk_bf16_f32 v168, v96, v97
	v_cvt_pk_bf16_f32 v169, v98, v99
	global_store_dwordx4 v[174:175], v[166:169], off
	s_nop 1
	v_cvt_pk_bf16_f32 v166, v36, v37
	v_cvt_pk_bf16_f32 v167, v38, v39
	v_cvt_pk_bf16_f32 v168, v32, v33
	v_cvt_pk_bf16_f32 v169, v34, v35
	global_store_dwordx4 v[174:175], v[166:169], off offset:256
	s_nop 1
	v_add_u32_e32 v166, 0x80, v176
	v_mad_i64_i32 v[166:167], s[28:29], v166, s76, v[170:171]
	v_lshl_add_u64 v[174:175], v[166:167], 0, v[172:173]
	v_cvt_pk_bf16_f32 v166, v92, v93
	v_cvt_pk_bf16_f32 v167, v94, v95
	v_cvt_pk_bf16_f32 v168, v88, v89
	v_cvt_pk_bf16_f32 v169, v90, v91
	global_store_dwordx4 v[174:175], v[166:169], off
	s_nop 1
	v_cvt_pk_bf16_f32 v166, v28, v29
	v_cvt_pk_bf16_f32 v167, v30, v31
	v_cvt_pk_bf16_f32 v168, v24, v25
	v_cvt_pk_bf16_f32 v169, v26, v27
	global_store_dwordx4 v[174:175], v[166:169], off offset:256
	s_nop 1
	v_add_u32_e32 v166, 0x90, v176
	v_mad_i64_i32 v[166:167], s[28:29], v166, s76, v[170:171]
	v_lshl_add_u64 v[174:175], v[166:167], 0, v[172:173]
	v_cvt_pk_bf16_f32 v166, v84, v85
	v_cvt_pk_bf16_f32 v167, v86, v87
	v_cvt_pk_bf16_f32 v168, v80, v81
	v_cvt_pk_bf16_f32 v169, v82, v83
	global_store_dwordx4 v[174:175], v[166:169], off
	s_nop 1
	v_cvt_pk_bf16_f32 v166, v20, v21
	v_cvt_pk_bf16_f32 v167, v22, v23
	v_cvt_pk_bf16_f32 v168, v16, v17
	v_cvt_pk_bf16_f32 v169, v18, v19
	global_store_dwordx4 v[174:175], v[166:169], off offset:256
	s_nop 1
	v_add_u32_e32 v166, 0xa0, v176
	v_mad_i64_i32 v[166:167], s[28:29], v166, s76, v[170:171]
	v_lshl_add_u64 v[174:175], v[166:167], 0, v[172:173]
	v_cvt_pk_bf16_f32 v166, v76, v77
	v_cvt_pk_bf16_f32 v167, v78, v79
	v_cvt_pk_bf16_f32 v168, v72, v73
	v_cvt_pk_bf16_f32 v169, v74, v75
	global_store_dwordx4 v[174:175], v[166:169], off
	s_nop 1
	v_cvt_pk_bf16_f32 v166, v12, v13
	v_cvt_pk_bf16_f32 v167, v14, v15
	v_cvt_pk_bf16_f32 v168, v8, v9
	v_cvt_pk_bf16_f32 v169, v10, v11
	global_store_dwordx4 v[174:175], v[166:169], off offset:256
	s_nop 1
	v_add_u32_e32 v166, 0xb0, v176
	v_mad_i64_i32 v[166:167], s[28:29], v166, s76, v[170:171]
	s_add_i32 s28, s52, 0xfffffe80
	s_cmpk_gt_u32 s28, 0x17f
	s_cselect_b64 s[28:29], -1, 0
	s_add_i32 s34, s52, 0xfffffa80
	s_cmpk_gt_u32 s34, 0xff
	s_cselect_b64 s[34:35], -1, 0
	v_lshl_add_u64 v[170:171], v[166:167], 0, v[172:173]
	v_cvt_pk_bf16_f32 v166, v68, v69
	v_cvt_pk_bf16_f32 v167, v70, v71
	v_cvt_pk_bf16_f32 v168, v64, v65
	v_cvt_pk_bf16_f32 v169, v66, v67
	s_and_b64 s[34:35], s[28:29], s[34:35]
	global_store_dwordx4 v[170:171], v[166:169], off
	s_and_b64 vcc, exec, s[34:35]
	s_nop 0
	v_cvt_pk_bf16_f32 v166, v4, v5
	v_cvt_pk_bf16_f32 v167, v6, v7
	v_cvt_pk_bf16_f32 v168, v0, v1
	v_cvt_pk_bf16_f32 v169, v2, v3
	global_store_dwordx4 v[170:171], v[166:169], off offset:256
	s_cbranch_vccnz .LBB0_150
;     DI void operator()(const f32x4 (&acc)[2][2][4][2], const Unit& u, int wr, int wc, int fr, int fq) const {
;     ...
;                     float mx = 0.f;
; #pragma unroll
;                     for (int ai = 0; ai < 2; ++ai)
; #pragma unroll
;                         for (int m = 0; m < 4; ++m) {
;                             const f32x4 a = acc[ai][bj][m][0], b = acc[ai][bj][m][1];
;                             float s0 = a[0] * a[0] + a[1] * a[1] + a[2] * a[2] + a[3] * a[3] + b[0] * b[0] + b[1] * b[1] + b[2] * b[2] + b[3] * b[3];
;                             s0 += __shfl_xor(s0, 16);
;                             s0 += __shfl_xor(s0, 32);
;                             mx = fmaxf(mx, s0);
;                         }
; #pragma unroll
;                     for (int o = 1; o <= 8; o <<= 1) mx = fmaxf(mx, __shfl_xor(mx, o));
;                     if ((threadIdx.x & 63) == 0) atomicMax((unsigned*)kmaxp + (isA ? ((cb - 384) >> 5) : (12 + ((cb - 1408) >> 5))), __float_as_uint(mx));
	v_mul_f32_e32 v125, v125, v125
	v_mul_f32_e32 v117, v117, v117
	v_fmac_f32_e32 v125, v124, v124
	v_fmac_f32_e32 v117, v116, v116
	v_mul_f32_e32 v109, v109, v109
	v_mul_f32_e32 v101, v101, v101
	v_fmac_f32_e32 v125, v126, v126
	v_fmac_f32_e32 v117, v118, v118
	v_fmac_f32_e32 v109, v108, v108
	v_fmac_f32_e32 v101, v100, v100
	v_and_b32_e32 v167, 64, v165
	v_fmac_f32_e32 v125, v127, v127
	v_fmac_f32_e32 v117, v119, v119
	v_fmac_f32_e32 v109, v110, v110
	v_fmac_f32_e32 v101, v102, v102
	v_xor_b32_e32 v166, 16, v165
	v_add_u32_e32 v167, 64, v167
	v_fmac_f32_e32 v125, v120, v120
	v_fmac_f32_e32 v117, v112, v112
	v_fmac_f32_e32 v109, v111, v111
	v_fmac_f32_e32 v101, v103, v103
	v_cmp_lt_i32_e32 vcc, v166, v167
	v_fmac_f32_e32 v125, v121, v121
	v_fmac_f32_e32 v117, v113, v113
	v_fmac_f32_e32 v109, v104, v104
	v_fmac_f32_e32 v101, v96, v96
	v_cndmask_b32_e32 v166, v165, v166, vcc
	v_fmac_f32_e32 v125, v122, v122
	v_fmac_f32_e32 v117, v114, v114
	v_fmac_f32_e32 v109, v105, v105
	v_fmac_f32_e32 v101, v97, v97
	v_lshlrev_b32_e32 v166, 2, v166
	v_fmac_f32_e32 v125, v123, v123
	v_fmac_f32_e32 v117, v115, v115
	v_fmac_f32_e32 v109, v106, v106
	v_fmac_f32_e32 v101, v98, v98
	v_mul_f32_e32 v93, v93, v93
	v_mul_f32_e32 v85, v85, v85
	ds_bpermute_b32 v120, v166, v125
	ds_bpermute_b32 v112, v166, v117
	v_fmac_f32_e32 v109, v107, v107
	v_fmac_f32_e32 v101, v99, v99
	v_fmac_f32_e32 v93, v92, v92
	v_fmac_f32_e32 v85, v84, v84
	v_mul_f32_e32 v77, v77, v77
	v_mul_f32_e32 v69, v69, v69
	ds_bpermute_b32 v104, v166, v109
	ds_bpermute_b32 v96, v166, v101
	v_fmac_f32_e32 v93, v94, v94
	v_fmac_f32_e32 v85, v86, v86
	v_fmac_f32_e32 v77, v76, v76
	v_fmac_f32_e32 v69, v68, v68
	v_xor_b32_e32 v168, 32, v165
	v_fmac_f32_e32 v93, v95, v95
	v_fmac_f32_e32 v85, v87, v87
	v_fmac_f32_e32 v77, v78, v78
	v_fmac_f32_e32 v69, v70, v70
	v_cmp_lt_i32_e32 vcc, v168, v167
	v_fmac_f32_e32 v93, v88, v88
	v_fmac_f32_e32 v85, v80, v80
	v_fmac_f32_e32 v77, v79, v79
	v_fmac_f32_e32 v69, v71, v71
	v_cndmask_b32_e32 v113, v165, v168, vcc
	v_fmac_f32_e32 v93, v89, v89
	v_fmac_f32_e32 v85, v81, v81
	v_fmac_f32_e32 v77, v72, v72
	v_fmac_f32_e32 v69, v64, v64
	v_lshlrev_b32_e32 v113, 2, v113
	s_waitcnt lgkmcnt(0)
	v_add_f32_e32 v114, v125, v120
	v_add_f32_e32 v112, v117, v112
	v_fmac_f32_e32 v93, v90, v90
	v_fmac_f32_e32 v85, v82, v82
	v_fmac_f32_e32 v77, v73, v73
	v_fmac_f32_e32 v69, v65, v65
	ds_bpermute_b32 v115, v113, v114
	ds_bpermute_b32 v116, v113, v112
	v_add_f32_e32 v99, v109, v104
	v_add_f32_e32 v96, v101, v96
	v_fmac_f32_e32 v93, v91, v91
	v_fmac_f32_e32 v85, v83, v83
	v_fmac_f32_e32 v77, v74, v74
	v_fmac_f32_e32 v69, v66, v66
	ds_bpermute_b32 v100, v113, v99
	ds_bpermute_b32 v101, v113, v96
	ds_bpermute_b32 v88, v166, v93
	ds_bpermute_b32 v80, v166, v85
	v_fmac_f32_e32 v77, v75, v75
	v_fmac_f32_e32 v69, v67, v67
	ds_bpermute_b32 v72, v166, v77
	ds_bpermute_b32 v64, v166, v69
	s_waitcnt lgkmcnt(0)
	v_add_f32_e32 v97, v114, v115
	v_add_f32_e32 v98, v112, v116
	v_max3_f32 v89, v97, 0, v98
	v_add_f32_e32 v90, v99, v100
	v_add_f32_e32 v91, v96, v101
	v_add_f32_e32 v88, v93, v88
	v_add_f32_e32 v65, v85, v80
	v_max3_f32 v89, v89, v90, v91
	ds_bpermute_b32 v90, v113, v88
	ds_bpermute_b32 v66, v113, v65
	v_add_f32_e32 v67, v77, v72
	v_add_f32_e32 v64, v69, v64
	ds_bpermute_b32 v68, v113, v67
	ds_bpermute_b32 v69, v113, v64
	s_waitcnt lgkmcnt(0)
	v_add_f32_e32 v70, v88, v90
	v_add_f32_e32 v65, v65, v66
	v_max3_f32 v65, v89, v70, v65
	v_add_f32_e32 v66, v67, v68
	v_add_f32_e32 v64, v64, v69
	v_max3_f32 v64, v65, v66, v64
	v_xor_b32_e32 v65, 1, v165
	v_cmp_lt_i32_e32 vcc, v65, v167
	s_nop 1
	v_cndmask_b32_e32 v65, v165, v65, vcc
	v_lshlrev_b32_e32 v65, 2, v65
	ds_bpermute_b32 v65, v65, v64
	s_waitcnt lgkmcnt(0)
	v_max_f32_e32 v65, v65, v65
	v_max_f32_e32 v64, v64, v65
	v_xor_b32_e32 v65, 2, v165
	v_cmp_lt_i32_e32 vcc, v65, v167
	s_nop 1
	v_cndmask_b32_e32 v65, v165, v65, vcc
	v_lshlrev_b32_e32 v65, 2, v65
	ds_bpermute_b32 v65, v65, v64
	s_waitcnt lgkmcnt(0)
	v_max_f32_e32 v65, v65, v65
	v_max_f32_e32 v64, v64, v65
	v_xor_b32_e32 v65, 4, v165
	v_cmp_lt_i32_e32 vcc, v65, v167
	s_nop 1
	v_cndmask_b32_e32 v65, v165, v65, vcc
	v_lshlrev_b32_e32 v65, 2, v65
	ds_bpermute_b32 v65, v65, v64
	s_waitcnt lgkmcnt(0)
	v_max_f32_e32 v65, v65, v65
	v_max_f32_e32 v64, v64, v65
	v_xor_b32_e32 v65, 8, v165
	v_cmp_lt_i32_e32 vcc, v65, v167
	s_nop 1
	v_cndmask_b32_e32 v65, v165, v65, vcc
	v_lshlrev_b32_e32 v65, 2, v65
	ds_bpermute_b32 v65, v65, v64
	s_and_saveexec_b64 s[34:35], s[2:3]
	s_cbranch_execz .LBB0_149
	s_mov_b64 s[36:37], -1
	s_and_b64 vcc, exec, s[28:29]
	s_cbranch_vccz .LBB0_143
	s_add_i32 s28, s10, 0xfffffa80
	s_ashr_i32 s28, s28, 5
	s_add_i32 s28, s28, 12
	s_mov_b64 s[36:37], 0

; #define PG8_STAGE(bufoff, gbase, voff) do { _Pragma("unroll") for (int _i = 0; _i < 2; ++_i) \
;         __builtin_amdgcn_global_load_lds((const unsigned*)((const char*)(gbase) + (voff)[_i]), (PG8_LAS unsigned*)(lds + (bufoff) + ldsw + _i * 8192), 16, 0, 0); } while (0)
; template <class Epi, class Sched, bool STAMP = false>
; __device__ __forceinline__ void gemm_phase(PG8_LAS unsigned char* lds, const Gemm g, const Sched& S, const Epi& E, unsigned long long* stamps) {
;     ...
;     for (;;) {
;         const bool has_next = S.next(ui + 1, nxt);
;         const char* nA = has_next ? (const char*)g.A + (size_t)nxt.pm * tstep : cA; const char* nB = has_next ? (const char*)g.Bt + (size_t)nxt.pn * tstep : cB;
;         for (int t = 0; t < nt; t += 2) {
;             const bool last = (t == nt - 2);
;             const char* a1 = cA + (size_t)(t + 1) * kstep;
;             const char* a2 = last ? nA : cA + (size_t)(t + 2) * kstep; const char* b2 = last ? nB : cB + (size_t)(t + 2) * kstep;
;             const char* a3 = a2 + kstep; const char* b3 = b2 + kstep;
;             if (last && has_next) S.a_ready(nxt);
;             PG8_LDB(B0, 0, 0); PG8_SCHED; PG8_LDA(At, 0, 0); PG8_STAGE(PG8_SA(1, 1), a1 + hstep, voffA);
;             PG8_WAIT_L(8); PG8_BAR; PG8_WAIT_L(0); PG8_MMA(0, 0, At, B0); PG8_BAR; PG8_SCHED;
;             PG8_LDB(B1, 0, 1); PG8_STAGE(PG8_SB(0, 0), b2, voffB);
;             PG8_BAR; PG8_WAIT_L(0); PG8_MMA(0, 1, At, B1); PG8_BAR;
;             PG8_LDA(At, 0, 1); PG8_STAGE(PG8_SA(0, 0), a2, voffA);
;             PG8_BAR; PG8_WAIT_L(0); PG8_MMA(1, 0, At, B0); PG8_BAR; PG8_SCHED;
;             PG8_STAGE(PG8_SB(0, 1), b2 + hstep, voffB);
;             PG8_WAIT_V(6); PG8_BAR; PG8_MMA(1, 1, At, B1); PG8_BAR;
;             PG8_LDB(B0, 1, 0); PG8_SCHED; PG8_LDA(At, 1, 0); PG8_STAGE(PG8_SA(0, 1), a2 + hstep, voffA);
;             PG8_WAIT_L(8); PG8_BAR; PG8_WAIT_L(0); PG8_MMA(0, 0, At, B0); PG8_BAR; PG8_SCHED;
;             PG8_LDB(B1, 1, 1); PG8_STAGE(PG8_SB(1, 0), b3, voffB);
;             PG8_BAR; PG8_WAIT_L(0); PG8_MMA(0, 1, At, B1); PG8_BAR;
;             PG8_LDA(At, 1, 1); PG8_STAGE(PG8_SA(1, 0), a3, voffA);
;             PG8_BAR; PG8_WAIT_L(0); PG8_MMA(1, 0, At, B0); PG8_BAR; PG8_SCHED;
;             PG8_STAGE(PG8_SB(1, 1), b3 + hstep, voffB);
;             PG8_WAIT_V(6); PG8_BAR; PG8_MMA(1, 1, At, B1); PG8_BAR;
.LBB0_311:
	s_add_u32 s94, s58, 0x100
	s_addc_u32 s95, s59, 0
	s_mov_b32 s96, -2
	ds_read_b128 v[170:173], v147
	ds_read_b128 v[174:177], v148
	ds_read_b128 v[178:181], v149
	ds_read_b128 v[182:185], v150
	s_add_u32 s58, s56, 0x100
	s_addc_u32 s59, s57, 0
	s_cmp_eq_u32 s96, 12
	s_cselect_b32 s63, s5, s59
	s_cselect_b32 s62, s4, s58
	s_cselect_b32 s61, s1, s95
	s_cselect_b32 s60, s0, s94
	s_mov_b32 m0, s84
	ds_read_b128 v[186:189], v145
	ds_read_b128 v[190:193], v145 offset:1024
	ds_read_b128 v[194:197], v145 offset:2048
	ds_read_b128 v[198:201], v145 offset:3072
	ds_read_b128 v[202:205], v145 offset:4096
	ds_read_b128 v[206:209], v145 offset:5120
	ds_read_b128 v[210:213], v145 offset:6144
	ds_read_b128 v[214:217], v145 offset:7168
	global_load_lds_dwordx4 v136, s[56:57]
	s_mov_b32 m0, s85
	s_nop 0
	global_load_lds_dwordx4 v138, s[56:57]
	s_waitcnt lgkmcnt(8)
	s_barrier
	s_waitcnt lgkmcnt(0)
	s_setprio 1
	s_waitcnt lgkmcnt(0)
	v_mfma_f32_16x16x32_bf16 v[124:127], v[170:173], v[186:189], 0
	v_mfma_f32_16x16x32_bf16 v[120:123], v[178:181], v[186:189], 0
	v_mfma_f32_16x16x32_bf16 v[116:119], v[170:173], v[194:197], 0
	v_mfma_f32_16x16x32_bf16 v[112:115], v[178:181], v[194:197], 0
	v_mfma_f32_16x16x32_bf16 v[100:103], v[170:173], v[202:205], 0
	v_mfma_f32_16x16x32_bf16 v[96:99], v[178:181], v[202:205], 0
	v_mfma_f32_16x16x32_bf16 v[84:87], v[170:173], v[210:213], 0
	v_mfma_f32_16x16x32_bf16 v[80:83], v[178:181], v[210:213], 0
	v_mfma_f32_16x16x32_bf16 v[124:127], v[174:177], v[190:193], v[124:127]
	v_mfma_f32_16x16x32_bf16 v[120:123], v[182:185], v[190:193], v[120:123]
	v_mfma_f32_16x16x32_bf16 v[116:119], v[174:177], v[198:201], v[116:119]
	v_mfma_f32_16x16x32_bf16 v[112:115], v[182:185], v[198:201], v[112:115]
	v_mfma_f32_16x16x32_bf16 v[100:103], v[174:177], v[206:209], v[100:103]
	v_mfma_f32_16x16x32_bf16 v[96:99], v[182:185], v[206:209], v[96:99]
	v_mfma_f32_16x16x32_bf16 v[84:87], v[174:177], v[214:217], v[84:87]
	v_mfma_f32_16x16x32_bf16 v[80:83], v[182:185], v[214:217], v[80:83]
	s_setprio 0
	s_barrier
	s_mov_b32 m0, s67
	ds_read_b128 v[218:221], v151
	ds_read_b128 v[222:225], v152
	ds_read_b128 v[226:229], v153
	ds_read_b128 v[230:233], v154
	global_load_lds_dwordx4 v130, s[60:61]
	s_mov_b32 m0, s68
	s_nop 0
	global_load_lds_dwordx4 v134, s[60:61]
	s_waitcnt lgkmcnt(0)
	s_barrier
	s_waitcnt lgkmcnt(0)
	s_setprio 1
	s_waitcnt lgkmcnt(0)
	v_mfma_f32_16x16x32_bf16 v[108:111], v[218:221], v[186:189], 0
	v_mfma_f32_16x16x32_bf16 v[104:107], v[226:229], v[186:189], 0
	v_mfma_f32_16x16x32_bf16 v[92:95], v[218:221], v[194:197], 0
	v_mfma_f32_16x16x32_bf16 v[88:91], v[226:229], v[194:197], 0
	v_mfma_f32_16x16x32_bf16 v[76:79], v[218:221], v[202:205], 0
	v_mfma_f32_16x16x32_bf16 v[72:75], v[226:229], v[202:205], 0
	v_mfma_f32_16x16x32_bf16 v[68:71], v[218:221], v[210:213], 0
	v_mfma_f32_16x16x32_bf16 v[64:67], v[226:229], v[210:213], 0
	v_mfma_f32_16x16x32_bf16 v[108:111], v[222:225], v[190:193], v[108:111]
	v_mfma_f32_16x16x32_bf16 v[104:107], v[230:233], v[190:193], v[104:107]
	v_mfma_f32_16x16x32_bf16 v[92:95], v[222:225], v[198:201], v[92:95]
	v_mfma_f32_16x16x32_bf16 v[88:91], v[230:233], v[198:201], v[88:91]
	v_mfma_f32_16x16x32_bf16 v[76:79], v[222:225], v[206:209], v[76:79]
	v_mfma_f32_16x16x32_bf16 v[72:75], v[230:233], v[206:209], v[72:75]
	v_mfma_f32_16x16x32_bf16 v[68:71], v[222:225], v[214:217], v[68:71]
	v_mfma_f32_16x16x32_bf16 v[64:67], v[230:233], v[214:217], v[64:67]
	s_setprio 0
	s_mov_b32 m0, s66
	s_barrier
	ds_read_b128 v[186:189], v145 offset:16384
	ds_read_b128 v[190:193], v145 offset:17408
	ds_read_b128 v[194:197], v145 offset:18432
	ds_read_b128 v[198:201], v145 offset:19456
	ds_read_b128 v[202:205], v145 offset:20480
	ds_read_b128 v[206:209], v145 offset:21504
	ds_read_b128 v[210:213], v145 offset:22528
	ds_read_b128 v[214:217], v145 offset:23552
	global_load_lds_dwordx4 v128, s[62:63]
	s_mov_b32 m0, s69
	s_nop 0
	global_load_lds_dwordx4 v132, s[62:63]
	s_add_u32 s56, s60, 0x44000
	s_addc_u32 s57, s61, 0
	s_mov_b32 m0, s70
	s_nop 0
	global_load_lds_dwordx4 v130, s[56:57]
	s_mov_b32 m0, s71
	s_nop 0
	global_load_lds_dwordx4 v134, s[56:57]
	s_waitcnt vmcnt(6)
	s_barrier
	s_waitcnt lgkmcnt(0)
	s_setprio 1
	s_waitcnt lgkmcnt(0)
	v_mfma_f32_16x16x32_bf16 v[60:63], v[170:173], v[186:189], 0
	v_mfma_f32_16x16x32_bf16 v[56:59], v[178:181], v[186:189], 0
	v_mfma_f32_16x16x32_bf16 v[52:55], v[170:173], v[194:197], 0
	v_mfma_f32_16x16x32_bf16 v[48:51], v[178:181], v[194:197], 0
	v_mfma_f32_16x16x32_bf16 v[36:39], v[170:173], v[202:205], 0
	v_mfma_f32_16x16x32_bf16 v[32:35], v[178:181], v[202:205], 0
	v_mfma_f32_16x16x32_bf16 v[20:23], v[170:173], v[210:213], 0
	v_mfma_f32_16x16x32_bf16 v[16:19], v[178:181], v[210:213], 0
	v_mfma_f32_16x16x32_bf16 v[60:63], v[174:177], v[190:193], v[60:63]
	v_mfma_f32_16x16x32_bf16 v[56:59], v[182:185], v[190:193], v[56:59]
	v_mfma_f32_16x16x32_bf16 v[52:55], v[174:177], v[198:201], v[52:55]
	v_mfma_f32_16x16x32_bf16 v[48:51], v[182:185], v[198:201], v[48:51]
	v_mfma_f32_16x16x32_bf16 v[36:39], v[174:177], v[206:209], v[36:39]
	v_mfma_f32_16x16x32_bf16 v[32:35], v[182:185], v[206:209], v[32:35]
	v_mfma_f32_16x16x32_bf16 v[20:23], v[174:177], v[214:217], v[20:23]
	v_mfma_f32_16x16x32_bf16 v[16:19], v[182:185], v[214:217], v[16:19]
	v_mfma_f32_16x16x32_bf16 v[44:47], v[218:221], v[186:189], 0
	v_mfma_f32_16x16x32_bf16 v[40:43], v[226:229], v[186:189], 0
	v_mfma_f32_16x16x32_bf16 v[28:31], v[218:221], v[194:197], 0
	v_mfma_f32_16x16x32_bf16 v[24:27], v[226:229], v[194:197], 0
	v_mfma_f32_16x16x32_bf16 v[12:15], v[218:221], v[202:205], 0
	v_mfma_f32_16x16x32_bf16 v[8:11], v[226:229], v[202:205], 0
	v_mfma_f32_16x16x32_bf16 v[4:7], v[218:221], v[210:213], 0
	v_mfma_f32_16x16x32_bf16 v[0:3], v[226:229], v[210:213], 0
	v_mfma_f32_16x16x32_bf16 v[44:47], v[222:225], v[190:193], v[44:47]
	v_mfma_f32_16x16x32_bf16 v[40:43], v[230:233], v[190:193], v[40:43]
	v_mfma_f32_16x16x32_bf16 v[28:31], v[222:225], v[198:201], v[28:31]
	v_mfma_f32_16x16x32_bf16 v[24:27], v[230:233], v[198:201], v[24:27]
	v_mfma_f32_16x16x32_bf16 v[12:15], v[222:225], v[206:209], v[12:15]
	v_mfma_f32_16x16x32_bf16 v[8:11], v[230:233], v[206:209], v[8:11]
	v_mfma_f32_16x16x32_bf16 v[4:7], v[222:225], v[214:217], v[4:7]
	v_mfma_f32_16x16x32_bf16 v[0:3], v[230:233], v[214:217], v[0:3]
	s_setprio 0
	s_barrier
	s_branch .Lzp4_mid
; #define PG8_STAGE(bufoff, gbase, voff) do { _Pragma("unroll") for (int _i = 0; _i < 2; ++_i) \
;         __builtin_amdgcn_global_load_lds((const unsigned*)((const char*)(gbase) + (voff)[_i]), (PG8_LAS unsigned*)(lds + (bufoff) + ldsw + _i * 8192), 16, 0, 0); } while (0)
; #define PG8_LDA(dst, b, h) do { _Pragma("unroll") for (int m = 0; m < 4; ++m) _Pragma("unroll") for (int k = 0; k < 2; ++k) dst[m][k] = *(const PG8_LAS bf16x8*)(lds + PG8_SA(b, h) + aoff + m * 2048 + k * 1024); } while (0)
; #define PG8_BAR __builtin_amdgcn_s_barrier()
; template <class Epi, class Sched, bool STAMP = false>
; __device__ __forceinline__ void gemm_phase(PG8_LAS unsigned char* lds, const Gemm g, const Sched& S, const Epi& E, unsigned long long* stamps) {
;     ...
;         for (int t = 0; t < nt; t += 2) {
;             const bool last = (t == nt - 2);
;             const char* a1 = cA + (size_t)(t + 1) * kstep;
;             const char* a2 = last ? nA : cA + (size_t)(t + 2) * kstep; const char* b2 = last ? nB : cB + (size_t)(t + 2) * kstep;
;             const char* a3 = a2 + kstep; const char* b3 = b2 + kstep;
;             if (last && has_next) S.a_ready(nxt);
;             PG8_LDB(B0, 0, 0); PG8_SCHED; PG8_LDA(At, 0, 0); PG8_STAGE(PG8_SA(1, 1), a1 + hstep, voffA);
;             PG8_WAIT_L(8); PG8_BAR; PG8_WAIT_L(0); PG8_MMA(0, 0, At, B0); PG8_BAR; PG8_SCHED;
;             PG8_LDB(B1, 0, 1); PG8_STAGE(PG8_SB(0, 0), b2, voffB);
;             PG8_BAR; PG8_WAIT_L(0); PG8_MMA(0, 1, At, B1); PG8_BAR;
;             PG8_LDA(At, 0, 1); PG8_STAGE(PG8_SA(0, 0), a2, voffA);
;             PG8_BAR; PG8_WAIT_L(0); PG8_MMA(1, 0, At, B0); PG8_BAR; PG8_SCHED;
;             PG8_STAGE(PG8_SB(0, 1), b2 + hstep, voffB);
;             PG8_WAIT_V(6); PG8_BAR; PG8_MMA(1, 1, At, B1); PG8_BAR;
;             PG8_LDB(B0, 1, 0); PG8_SCHED; PG8_LDA(At, 1, 0); PG8_STAGE(PG8_SA(0, 1), a2 + hstep, voffA);
;             PG8_WAIT_L(8); PG8_BAR; PG8_WAIT_L(0); PG8_MMA(0, 0, At, B0); PG8_BAR; PG8_SCHED;
;             PG8_LDB(B1, 1, 1); PG8_STAGE(PG8_SB(1, 0), b3, voffB);
;             PG8_BAR; PG8_WAIT_L(0); PG8_MMA(0, 1, At, B1); PG8_BAR;
;             PG8_LDA(At, 1, 1); PG8_STAGE(PG8_SA(1, 0), a3, voffA);
;             PG8_BAR; PG8_WAIT_L(0); PG8_MMA(1, 0, At, B0); PG8_BAR; PG8_SCHED;
;             PG8_STAGE(PG8_SB(1, 1), b3 + hstep, voffB);
;             PG8_WAIT_V(6); PG8_BAR; PG8_MMA(1, 1, At, B1); PG8_BAR;
.LBB0_312:
	ds_read_b128 v[170:173], v147
	ds_read_b128 v[174:177], v148
	ds_read_b128 v[178:181], v149
	ds_read_b128 v[182:185], v150
	s_add_u32 s58, s56, 0x100
	s_addc_u32 s59, s57, 0
	s_cmp_eq_u32 s96, 12
	s_cselect_b32 s63, s5, s59
	s_cselect_b32 s62, s4, s58
	s_cselect_b32 s61, s1, s95
	s_cselect_b32 s60, s0, s94
	s_mov_b32 m0, s84
	ds_read_b128 v[186:189], v145
	ds_read_b128 v[190:193], v145 offset:1024
	ds_read_b128 v[194:197], v145 offset:2048
	ds_read_b128 v[198:201], v145 offset:3072
	ds_read_b128 v[202:205], v145 offset:4096
	ds_read_b128 v[206:209], v145 offset:5120
	ds_read_b128 v[210:213], v145 offset:6144
	ds_read_b128 v[214:217], v145 offset:7168
	global_load_lds_dwordx4 v136, s[56:57]
	s_mov_b32 m0, s85
	s_nop 0
	global_load_lds_dwordx4 v138, s[56:57]
	s_waitcnt lgkmcnt(8)
	s_barrier
	s_waitcnt lgkmcnt(0)
	s_setprio 1
	s_waitcnt lgkmcnt(0)
	v_mfma_f32_16x16x32_bf16 v[124:127], v[170:173], v[186:189], v[124:127]
	v_mfma_f32_16x16x32_bf16 v[120:123], v[178:181], v[186:189], v[120:123]
	v_mfma_f32_16x16x32_bf16 v[116:119], v[170:173], v[194:197], v[116:119]
	v_mfma_f32_16x16x32_bf16 v[112:115], v[178:181], v[194:197], v[112:115]
	v_mfma_f32_16x16x32_bf16 v[100:103], v[170:173], v[202:205], v[100:103]
	v_mfma_f32_16x16x32_bf16 v[96:99], v[178:181], v[202:205], v[96:99]
	v_mfma_f32_16x16x32_bf16 v[84:87], v[170:173], v[210:213], v[84:87]
	v_mfma_f32_16x16x32_bf16 v[80:83], v[178:181], v[210:213], v[80:83]
	v_mfma_f32_16x16x32_bf16 v[124:127], v[174:177], v[190:193], v[124:127]
	v_mfma_f32_16x16x32_bf16 v[120:123], v[182:185], v[190:193], v[120:123]
	v_mfma_f32_16x16x32_bf16 v[116:119], v[174:177], v[198:201], v[116:119]
	v_mfma_f32_16x16x32_bf16 v[112:115], v[182:185], v[198:201], v[112:115]
	v_mfma_f32_16x16x32_bf16 v[100:103], v[174:177], v[206:209], v[100:103]
	v_mfma_f32_16x16x32_bf16 v[96:99], v[182:185], v[206:209], v[96:99]
	v_mfma_f32_16x16x32_bf16 v[84:87], v[174:177], v[214:217], v[84:87]
	v_mfma_f32_16x16x32_bf16 v[80:83], v[182:185], v[214:217], v[80:83]
	s_setprio 0
	s_barrier
	s_mov_b32 m0, s67
	ds_read_b128 v[218:221], v151
	ds_read_b128 v[222:225], v152
	ds_read_b128 v[226:229], v153
	ds_read_b128 v[230:233], v154
	global_load_lds_dwordx4 v130, s[60:61]
	s_mov_b32 m0, s68
	s_nop 0
	global_load_lds_dwordx4 v134, s[60:61]
	s_waitcnt lgkmcnt(0)
	s_barrier
	s_waitcnt lgkmcnt(0)
	s_setprio 1
	s_waitcnt lgkmcnt(0)
	v_mfma_f32_16x16x32_bf16 v[108:111], v[218:221], v[186:189], v[108:111]
	v_mfma_f32_16x16x32_bf16 v[104:107], v[226:229], v[186:189], v[104:107]
	v_mfma_f32_16x16x32_bf16 v[92:95], v[218:221], v[194:197], v[92:95]
	v_mfma_f32_16x16x32_bf16 v[88:91], v[226:229], v[194:197], v[88:91]
	v_mfma_f32_16x16x32_bf16 v[76:79], v[218:221], v[202:205], v[76:79]
	v_mfma_f32_16x16x32_bf16 v[72:75], v[226:229], v[202:205], v[72:75]
	v_mfma_f32_16x16x32_bf16 v[68:71], v[218:221], v[210:213], v[68:71]
	v_mfma_f32_16x16x32_bf16 v[64:67], v[226:229], v[210:213], v[64:67]
	v_mfma_f32_16x16x32_bf16 v[108:111], v[222:225], v[190:193], v[108:111]
	v_mfma_f32_16x16x32_bf16 v[104:107], v[230:233], v[190:193], v[104:107]
	v_mfma_f32_16x16x32_bf16 v[92:95], v[222:225], v[198:201], v[92:95]
	v_mfma_f32_16x16x32_bf16 v[88:91], v[230:233], v[198:201], v[88:91]
	v_mfma_f32_16x16x32_bf16 v[76:79], v[222:225], v[206:209], v[76:79]
	v_mfma_f32_16x16x32_bf16 v[72:75], v[230:233], v[206:209], v[72:75]
	v_mfma_f32_16x16x32_bf16 v[68:71], v[222:225], v[214:217], v[68:71]
	v_mfma_f32_16x16x32_bf16 v[64:67], v[230:233], v[214:217], v[64:67]
	s_setprio 0
	s_mov_b32 m0, s66
	s_barrier
	ds_read_b128 v[186:189], v145 offset:16384
	ds_read_b128 v[190:193], v145 offset:17408
	ds_read_b128 v[194:197], v145 offset:18432
	ds_read_b128 v[198:201], v145 offset:19456
	ds_read_b128 v[202:205], v145 offset:20480
	ds_read_b128 v[206:209], v145 offset:21504
	ds_read_b128 v[210:213], v145 offset:22528
	ds_read_b128 v[214:217], v145 offset:23552
	global_load_lds_dwordx4 v128, s[62:63]
	s_mov_b32 m0, s69
	s_nop 0
	global_load_lds_dwordx4 v132, s[62:63]
	s_add_u32 s56, s60, 0x44000
	s_addc_u32 s57, s61, 0
	s_mov_b32 m0, s70
	s_nop 0
	global_load_lds_dwordx4 v130, s[56:57]
	s_mov_b32 m0, s71
	s_nop 0
	global_load_lds_dwordx4 v134, s[56:57]
	s_waitcnt vmcnt(6)
	s_barrier
	s_waitcnt lgkmcnt(0)
	s_setprio 1
	s_waitcnt lgkmcnt(0)
	v_mfma_f32_16x16x32_bf16 v[60:63], v[170:173], v[186:189], v[60:63]
	v_mfma_f32_16x16x32_bf16 v[56:59], v[178:181], v[186:189], v[56:59]
	v_mfma_f32_16x16x32_bf16 v[52:55], v[170:173], v[194:197], v[52:55]
	v_mfma_f32_16x16x32_bf16 v[48:51], v[178:181], v[194:197], v[48:51]
	v_mfma_f32_16x16x32_bf16 v[36:39], v[170:173], v[202:205], v[36:39]
	v_mfma_f32_16x16x32_bf16 v[32:35], v[178:181], v[202:205], v[32:35]
	v_mfma_f32_16x16x32_bf16 v[20:23], v[170:173], v[210:213], v[20:23]
	v_mfma_f32_16x16x32_bf16 v[16:19], v[178:181], v[210:213], v[16:19]
	v_mfma_f32_16x16x32_bf16 v[60:63], v[174:177], v[190:193], v[60:63]
	v_mfma_f32_16x16x32_bf16 v[56:59], v[182:185], v[190:193], v[56:59]
	v_mfma_f32_16x16x32_bf16 v[52:55], v[174:177], v[198:201], v[52:55]
	v_mfma_f32_16x16x32_bf16 v[48:51], v[182:185], v[198:201], v[48:51]
	v_mfma_f32_16x16x32_bf16 v[36:39], v[174:177], v[206:209], v[36:39]
	v_mfma_f32_16x16x32_bf16 v[32:35], v[182:185], v[206:209], v[32:35]
	v_mfma_f32_16x16x32_bf16 v[20:23], v[174:177], v[214:217], v[20:23]
	v_mfma_f32_16x16x32_bf16 v[16:19], v[182:185], v[214:217], v[16:19]
	v_mfma_f32_16x16x32_bf16 v[44:47], v[218:221], v[186:189], v[44:47]
	v_mfma_f32_16x16x32_bf16 v[40:43], v[226:229], v[186:189], v[40:43]
	v_mfma_f32_16x16x32_bf16 v[28:31], v[218:221], v[194:197], v[28:31]
	v_mfma_f32_16x16x32_bf16 v[24:27], v[226:229], v[194:197], v[24:27]
	v_mfma_f32_16x16x32_bf16 v[12:15], v[218:221], v[202:205], v[12:15]
	v_mfma_f32_16x16x32_bf16 v[8:11], v[226:229], v[202:205], v[8:11]
	v_mfma_f32_16x16x32_bf16 v[4:7], v[218:221], v[210:213], v[4:7]
	v_mfma_f32_16x16x32_bf16 v[0:3], v[226:229], v[210:213], v[0:3]
	v_mfma_f32_16x16x32_bf16 v[44:47], v[222:225], v[190:193], v[44:47]
	v_mfma_f32_16x16x32_bf16 v[40:43], v[230:233], v[190:193], v[40:43]
	v_mfma_f32_16x16x32_bf16 v[28:31], v[222:225], v[198:201], v[28:31]
	v_mfma_f32_16x16x32_bf16 v[24:27], v[230:233], v[198:201], v[24:27]
	v_mfma_f32_16x16x32_bf16 v[12:15], v[222:225], v[206:209], v[12:15]
	v_mfma_f32_16x16x32_bf16 v[8:11], v[230:233], v[206:209], v[8:11]
	v_mfma_f32_16x16x32_bf16 v[4:7], v[222:225], v[214:217], v[4:7]
	v_mfma_f32_16x16x32_bf16 v[0:3], v[230:233], v[214:217], v[0:3]
	s_setprio 0
	s_barrier
; #define PG8_STAGE(bufoff, gbase, voff) do { _Pragma("unroll") for (int _i = 0; _i < 2; ++_i) \
;         __builtin_amdgcn_global_load_lds((const unsigned*)((const char*)(gbase) + (voff)[_i]), (PG8_LAS unsigned*)(lds + (bufoff) + ldsw + _i * 8192), 16, 0, 0); } while (0)
; #define PG8_LDA(dst, b, h) do { _Pragma("unroll") for (int m = 0; m < 4; ++m) _Pragma("unroll") for (int k = 0; k < 2; ++k) dst[m][k] = *(const PG8_LAS bf16x8*)(lds + PG8_SA(b, h) + aoff + m * 2048 + k * 1024); } while (0)
; #define PG8_BAR __builtin_amdgcn_s_barrier()
; template <class Epi, class Sched, bool STAMP = false>
; __device__ __forceinline__ void gemm_phase(PG8_LAS unsigned char* lds, const Gemm g, const Sched& S, const Epi& E, unsigned long long* stamps) {
;     ...
;         for (int t = 0; t < nt; t += 2) {
;             const bool last = (t == nt - 2);
;             const char* a1 = cA + (size_t)(t + 1) * kstep;
;             const char* a2 = last ? nA : cA + (size_t)(t + 2) * kstep; const char* b2 = last ? nB : cB + (size_t)(t + 2) * kstep;
;             const char* a3 = a2 + kstep; const char* b3 = b2 + kstep;
;             if (last && has_next) S.a_ready(nxt);
;             PG8_LDB(B0, 0, 0); PG8_SCHED; PG8_LDA(At, 0, 0); PG8_STAGE(PG8_SA(1, 1), a1 + hstep, voffA);
;             PG8_WAIT_L(8); PG8_BAR; PG8_WAIT_L(0); PG8_MMA(0, 0, At, B0); PG8_BAR; PG8_SCHED;
;             PG8_LDB(B1, 0, 1); PG8_STAGE(PG8_SB(0, 0), b2, voffB);
;             PG8_BAR; PG8_WAIT_L(0); PG8_MMA(0, 1, At, B1); PG8_BAR;
;             PG8_LDA(At, 0, 1); PG8_STAGE(PG8_SA(0, 0), a2, voffA);
;             PG8_BAR; PG8_WAIT_L(0); PG8_MMA(1, 0, At, B0); PG8_BAR; PG8_SCHED;
;             PG8_STAGE(PG8_SB(0, 1), b2 + hstep, voffB);
;             PG8_WAIT_V(6); PG8_BAR; PG8_MMA(1, 1, At, B1); PG8_BAR;
;             PG8_LDB(B0, 1, 0); PG8_SCHED; PG8_LDA(At, 1, 0); PG8_STAGE(PG8_SA(0, 1), a2 + hstep, voffA);
;             PG8_WAIT_L(8); PG8_BAR; PG8_WAIT_L(0); PG8_MMA(0, 0, At, B0); PG8_BAR; PG8_SCHED;
;             PG8_LDB(B1, 1, 1); PG8_STAGE(PG8_SB(1, 0), b3, voffB);
;             PG8_BAR; PG8_WAIT_L(0); PG8_MMA(0, 1, At, B1); PG8_BAR;
;             PG8_LDA(At, 1, 1); PG8_STAGE(PG8_SA(1, 0), a3, voffA);
;             PG8_BAR; PG8_WAIT_L(0); PG8_MMA(1, 0, At, B0); PG8_BAR; PG8_SCHED;
;             PG8_STAGE(PG8_SB(1, 1), b3 + hstep, voffB);
;             PG8_WAIT_V(6); PG8_BAR; PG8_MMA(1, 1, At, B1); PG8_BAR;
.Lzp4_mid:
	ds_read_b128 v[170:173], v155
	ds_read_b128 v[174:177], v156
	ds_read_b128 v[178:181], v157
	ds_read_b128 v[182:185], v165
	s_add_u32 s56, s62, 0x44000
	s_addc_u32 s57, s63, 0
	s_mov_b32 m0, s72
	ds_read_b128 v[186:189], v145 offset:32768
	ds_read_b128 v[190:193], v145 offset:33792
	ds_read_b128 v[194:197], v145 offset:34816
	ds_read_b128 v[198:201], v145 offset:35840
	ds_read_b128 v[202:205], v145 offset:36864
	ds_read_b128 v[206:209], v145 offset:37888
	ds_read_b128 v[210:213], v145 offset:38912
	ds_read_b128 v[214:217], v145 offset:39936
	global_load_lds_dwordx4 v128, s[56:57]
	s_mov_b32 m0, s73
	s_nop 0
	global_load_lds_dwordx4 v132, s[56:57]
	s_waitcnt lgkmcnt(8)
	s_barrier
	s_waitcnt lgkmcnt(0)
	s_setprio 1
	s_waitcnt lgkmcnt(0)
	v_mfma_f32_16x16x32_bf16 v[124:127], v[170:173], v[186:189], v[124:127]
	v_mfma_f32_16x16x32_bf16 v[120:123], v[178:181], v[186:189], v[120:123]
	v_mfma_f32_16x16x32_bf16 v[116:119], v[170:173], v[194:197], v[116:119]
	v_mfma_f32_16x16x32_bf16 v[112:115], v[178:181], v[194:197], v[112:115]
	v_mfma_f32_16x16x32_bf16 v[100:103], v[170:173], v[202:205], v[100:103]
	v_mfma_f32_16x16x32_bf16 v[96:99], v[178:181], v[202:205], v[96:99]
	v_mfma_f32_16x16x32_bf16 v[84:87], v[170:173], v[210:213], v[84:87]
	v_mfma_f32_16x16x32_bf16 v[80:83], v[178:181], v[210:213], v[80:83]
	v_mfma_f32_16x16x32_bf16 v[124:127], v[174:177], v[190:193], v[124:127]
	v_mfma_f32_16x16x32_bf16 v[120:123], v[182:185], v[190:193], v[120:123]
	v_mfma_f32_16x16x32_bf16 v[116:119], v[174:177], v[198:201], v[116:119]
	v_mfma_f32_16x16x32_bf16 v[112:115], v[182:185], v[198:201], v[112:115]
	v_mfma_f32_16x16x32_bf16 v[100:103], v[174:177], v[206:209], v[100:103]
	v_mfma_f32_16x16x32_bf16 v[96:99], v[182:185], v[206:209], v[96:99]
	v_mfma_f32_16x16x32_bf16 v[84:87], v[174:177], v[214:217], v[84:87]
	v_mfma_f32_16x16x32_bf16 v[80:83], v[182:185], v[214:217], v[80:83]
	s_setprio 0
	s_barrier
	s_mov_b32 m0, s74
	ds_read_b128 v[218:221], v166
	ds_read_b128 v[222:225], v167
	ds_read_b128 v[226:229], v168
	ds_read_b128 v[230:233], v169
	s_add_u32 s100, s60, 0x80
	s_addc_u32 s101, s61, 0
	global_load_lds_dwordx4 v130, s[100:101]
	s_mov_b32 m0, s75
	s_nop 0
	global_load_lds_dwordx4 v134, s[100:101]
	s_waitcnt lgkmcnt(0)
	s_barrier
	s_waitcnt lgkmcnt(0)
	s_setprio 1
	s_waitcnt lgkmcnt(0)
	v_mfma_f32_16x16x32_bf16 v[108:111], v[218:221], v[186:189], v[108:111]
	v_mfma_f32_16x16x32_bf16 v[104:107], v[226:229], v[186:189], v[104:107]
	v_mfma_f32_16x16x32_bf16 v[92:95], v[218:221], v[194:197], v[92:95]
	v_mfma_f32_16x16x32_bf16 v[88:91], v[226:229], v[194:197], v[88:91]
	v_mfma_f32_16x16x32_bf16 v[76:79], v[218:221], v[202:205], v[76:79]
	v_mfma_f32_16x16x32_bf16 v[72:75], v[226:229], v[202:205], v[72:75]
	v_mfma_f32_16x16x32_bf16 v[68:71], v[218:221], v[210:213], v[68:71]
	v_mfma_f32_16x16x32_bf16 v[64:67], v[226:229], v[210:213], v[64:67]
	v_mfma_f32_16x16x32_bf16 v[108:111], v[222:225], v[190:193], v[108:111]
	v_mfma_f32_16x16x32_bf16 v[104:107], v[230:233], v[190:193], v[104:107]
	v_mfma_f32_16x16x32_bf16 v[92:95], v[222:225], v[198:201], v[92:95]
	v_mfma_f32_16x16x32_bf16 v[88:91], v[230:233], v[198:201], v[88:91]
	v_mfma_f32_16x16x32_bf16 v[76:79], v[222:225], v[206:209], v[76:79]
	v_mfma_f32_16x16x32_bf16 v[72:75], v[230:233], v[206:209], v[72:75]
	v_mfma_f32_16x16x32_bf16 v[68:71], v[222:225], v[214:217], v[68:71]
	v_mfma_f32_16x16x32_bf16 v[64:67], v[230:233], v[214:217], v[64:67]
	s_setprio 0
	s_mov_b32 m0, s76
	s_barrier
	ds_read_b128 v[186:189], v145 offset:49152
	ds_read_b128 v[190:193], v145 offset:50176
	ds_read_b128 v[194:197], v145 offset:51200
	ds_read_b128 v[198:201], v145 offset:52224
	ds_read_b128 v[202:205], v145 offset:53248
	ds_read_b128 v[206:209], v145 offset:54272
	ds_read_b128 v[210:213], v145 offset:55296
	ds_read_b128 v[214:217], v145 offset:56320
	s_add_u32 s100, s62, 0x80
	s_addc_u32 s101, s63, 0
	global_load_lds_dwordx4 v128, s[100:101]
	s_mov_b32 m0, s77
	s_nop 0
	global_load_lds_dwordx4 v132, s[100:101]
	s_add_u32 s56, s60, 0x44080
	s_addc_u32 s57, s61, 0
	s_mov_b32 m0, s78
	s_nop 0
	global_load_lds_dwordx4 v130, s[56:57]
	s_mov_b32 m0, s79
	s_nop 0
	global_load_lds_dwordx4 v134, s[56:57]
	s_waitcnt vmcnt(6)
	s_barrier
	s_waitcnt lgkmcnt(0)
	s_setprio 1
	s_waitcnt lgkmcnt(0)
	v_mfma_f32_16x16x32_bf16 v[60:63], v[170:173], v[186:189], v[60:63]
	v_mfma_f32_16x16x32_bf16 v[56:59], v[178:181], v[186:189], v[56:59]
	v_mfma_f32_16x16x32_bf16 v[52:55], v[170:173], v[194:197], v[52:55]
	v_mfma_f32_16x16x32_bf16 v[48:51], v[178:181], v[194:197], v[48:51]
	v_mfma_f32_16x16x32_bf16 v[36:39], v[170:173], v[202:205], v[36:39]
	v_mfma_f32_16x16x32_bf16 v[32:35], v[178:181], v[202:205], v[32:35]
	v_mfma_f32_16x16x32_bf16 v[20:23], v[170:173], v[210:213], v[20:23]
	v_mfma_f32_16x16x32_bf16 v[16:19], v[178:181], v[210:213], v[16:19]
	v_mfma_f32_16x16x32_bf16 v[60:63], v[174:177], v[190:193], v[60:63]
	v_mfma_f32_16x16x32_bf16 v[56:59], v[182:185], v[190:193], v[56:59]
	v_mfma_f32_16x16x32_bf16 v[52:55], v[174:177], v[198:201], v[52:55]
	v_mfma_f32_16x16x32_bf16 v[48:51], v[182:185], v[198:201], v[48:51]
	v_mfma_f32_16x16x32_bf16 v[36:39], v[174:177], v[206:209], v[36:39]
	v_mfma_f32_16x16x32_bf16 v[32:35], v[182:185], v[206:209], v[32:35]
	v_mfma_f32_16x16x32_bf16 v[20:23], v[174:177], v[214:217], v[20:23]
	v_mfma_f32_16x16x32_bf16 v[16:19], v[182:185], v[214:217], v[16:19]
	v_mfma_f32_16x16x32_bf16 v[44:47], v[218:221], v[186:189], v[44:47]
	v_mfma_f32_16x16x32_bf16 v[40:43], v[226:229], v[186:189], v[40:43]
	v_mfma_f32_16x16x32_bf16 v[28:31], v[218:221], v[194:197], v[28:31]
	v_mfma_f32_16x16x32_bf16 v[24:27], v[226:229], v[194:197], v[24:27]
	v_mfma_f32_16x16x32_bf16 v[12:15], v[218:221], v[202:205], v[12:15]
	v_mfma_f32_16x16x32_bf16 v[8:11], v[226:229], v[202:205], v[8:11]
	v_mfma_f32_16x16x32_bf16 v[4:7], v[218:221], v[210:213], v[4:7]
	v_mfma_f32_16x16x32_bf16 v[0:3], v[226:229], v[210:213], v[0:3]
	v_mfma_f32_16x16x32_bf16 v[44:47], v[222:225], v[190:193], v[44:47]
	v_mfma_f32_16x16x32_bf16 v[40:43], v[230:233], v[190:193], v[40:43]
	v_mfma_f32_16x16x32_bf16 v[28:31], v[222:225], v[198:201], v[28:31]
	v_mfma_f32_16x16x32_bf16 v[24:27], v[230:233], v[198:201], v[24:27]
	v_mfma_f32_16x16x32_bf16 v[12:15], v[222:225], v[206:209], v[12:15]
	v_mfma_f32_16x16x32_bf16 v[8:11], v[230:233], v[206:209], v[8:11]
	v_mfma_f32_16x16x32_bf16 v[4:7], v[222:225], v[214:217], v[4:7]
	v_mfma_f32_16x16x32_bf16 v[0:3], v[230:233], v[214:217], v[0:3]
	s_setprio 0
	s_add_i32 s96, s96, 2
	s_add_u32 s94, s94, 0x100
	s_addc_u32 s95, s95, 0
	s_cmp_gt_u32 s96, 13
	s_mov_b64 s[56:57], s[58:59]
	s_barrier
; #define PG8_WAIT_V(n) asm volatile("s_waitcnt vmcnt(" #n ")" ::: "memory")
; #define PG8_BAR __builtin_amdgcn_s_barrier()
;     DI void operator()(const f32x4 (&acc)[2][2][4][2], const Unit& u, int wr, int wc, int fr, int fq) const {
;         const int row0 = u.pm * BM + wr * 64 + fr, col0 = u.pn * BM + wc * 32 + 8 * fq;
; #pragma unroll
;         for (int ai = 0; ai < 2; ++ai)
; #pragma unroll
;             for (int m = 0; m < 4; ++m) { u16* rowp = O + (size_t)(row0 + ai * HALF + m * 16) * ldc + col0;
; #pragma unroll
;                 for (int bj = 0; bj < 2; ++bj) { const f32x4 v0 = acc[ai][bj][m][0], v1 = acc[ai][bj][m][1];
;                     uint4 w = {pack2(v0[0], v0[1]), pack2(v0[2], v0[3]), pack2(v1[0], v1[1]), pack2(v1[2], v1[3])}; *(uint4*)(rowp + bj * HALF) = w; } }
; template <class Epi, class Sched, bool STAMP = false>
; __device__ __forceinline__ void gemm_phase(PG8_LAS unsigned char* lds, const Gemm g, const Sched& S, const Epi& E, unsigned long long* stamps) {
;     ...
;         if (!has_next) break;
; #pragma unroll
;         for (int a = 0; a < 2; ++a)
; #pragma unroll
;             for (int b = 0; b < 2; ++b)
; #pragma unroll
;                 for (int m = 0; m < 4; ++m)
; #pragma unroll
;                     for (int n = 0; n < 2; ++n) acc[a][b][m][n] = (f32x4){0.f, 0.f, 0.f, 0.f};
;         cur = nxt; cA = nA; cB = nB; ++ui;
;     }
;     PG8_WAIT_V(0);
;     if (wr == 0) PG8_BAR;
;     PG8_BAR;
	s_cbranch_scc0 .LBB0_312
	v_lshl_add_u32 v170, s90, 8, v144
	v_lshl_or_b32 v172, s93, 8, v146
	v_ashrrev_i32_e32 v171, 31, v170
	v_ashrrev_i32_e32 v173, 31, v172
	v_lshlrev_b64 v[174:175], 11, v[170:171]
	v_lshl_add_u64 v[174:175], s[14:15], 0, v[174:175]
	v_lshlrev_b64 v[172:173], 1, v[172:173]
	v_lshl_add_u64 v[174:175], v[174:175], 0, v[172:173]
	v_cvt_pk_bf16_f32 v60, v60, v61
	v_cvt_pk_bf16_f32 v61, v62, v63
	v_cvt_pk_bf16_f32 v62, v56, v57
	v_add_co_u32_e32 v56, vcc, s86, v174
	v_cvt_pk_bf16_f32 v68, v68, v69
	v_cvt_pk_bf16_f32 v69, v70, v71
	v_cvt_pk_bf16_f32 v70, v64, v65
	v_lshl_add_u64 v[64:65], v[174:175], 0, s[34:35]
	v_addc_co_u32_e32 v57, vcc, 0, v175, vcc
	v_cvt_pk_bf16_f32 v44, v44, v45
	v_cvt_pk_bf16_f32 v45, v46, v47
	v_cvt_pk_bf16_f32 v46, v40, v41
	v_cvt_pk_bf16_f32 v47, v42, v43
	v_cvt_pk_bf16_f32 v108, v108, v109
	v_cvt_pk_bf16_f32 v109, v110, v111
	v_cvt_pk_bf16_f32 v110, v104, v105
	v_or_b32_e32 v104, 16, v170
	global_store_dwordx4 v[64:65], v[44:47], off offset:256
	v_ashrrev_i32_e32 v105, 31, v104
	v_cvt_pk_bf16_f32 v92, v92, v93
	v_add_co_u32_e32 v46, vcc, s87, v174
	v_cvt_pk_bf16_f32 v93, v94, v95
	v_cvt_pk_bf16_f32 v94, v88, v89
	v_or_b32_e32 v88, 32, v170
	v_lshl_add_u64 v[44:45], v[174:175], 0, s[36:37]
	v_addc_co_u32_e32 v47, vcc, 0, v175, vcc
	v_cvt_pk_bf16_f32 v28, v28, v29
	v_cvt_pk_bf16_f32 v29, v30, v31
	v_cvt_pk_bf16_f32 v30, v24, v25
	v_cvt_pk_bf16_f32 v31, v26, v27
	v_lshlrev_b64 v[104:105], 11, v[104:105]
	v_ashrrev_i32_e32 v89, 31, v88
	v_cvt_pk_bf16_f32 v76, v76, v77
	v_cvt_pk_bf16_f32 v77, v78, v79
	v_cvt_pk_bf16_f32 v78, v72, v73
	v_or_b32_e32 v72, 48, v170
	global_store_dwordx4 v[44:45], v[28:31], off offset:256
	v_cvt_pk_bf16_f32 v111, v106, v107
	v_lshl_add_u64 v[104:105], s[14:15], 0, v[104:105]
	v_add_co_u32_e32 v30, vcc, s88, v174
	v_lshlrev_b64 v[88:89], 11, v[88:89]
	v_ashrrev_i32_e32 v73, 31, v72
	v_lshl_add_u64 v[28:29], v[174:175], 0, s[52:53]
	v_addc_co_u32_e32 v31, vcc, 0, v175, vcc
	v_cvt_pk_bf16_f32 v12, v12, v13
	v_cvt_pk_bf16_f32 v13, v14, v15
	v_cvt_pk_bf16_f32 v14, v8, v9
	v_cvt_pk_bf16_f32 v15, v10, v11
	global_store_dwordx4 v[174:175], v[108:111], off offset:256
	v_cvt_pk_bf16_f32 v95, v90, v91
	v_lshl_add_u64 v[88:89], s[14:15], 0, v[88:89]
	v_lshl_add_u64 v[108:109], v[104:105], 0, v[172:173]
	v_lshlrev_b64 v[72:73], 11, v[72:73]
	global_store_dwordx4 v[28:29], v[12:15], off offset:256
	global_store_dwordx4 v[108:109], v[92:95], off offset:256
	v_cvt_pk_bf16_f32 v79, v74, v75
	v_add_co_u32_e32 v14, vcc, s89, v174
	v_lshl_add_u64 v[92:93], v[88:89], 0, v[172:173]
	v_lshl_add_u64 v[72:73], s[14:15], 0, v[72:73]
	v_addc_co_u32_e32 v15, vcc, 0, v175, vcc
	v_cvt_pk_bf16_f32 v124, v124, v125
	v_cvt_pk_bf16_f32 v125, v126, v127
	v_cvt_pk_bf16_f32 v126, v120, v121
	v_cvt_pk_bf16_f32 v127, v122, v123
	v_cvt_pk_bf16_f32 v104, v116, v117
	v_cvt_pk_bf16_f32 v105, v118, v119
	v_cvt_pk_bf16_f32 v106, v112, v113
	v_cvt_pk_bf16_f32 v107, v114, v115
	v_cvt_pk_bf16_f32 v88, v100, v101
	v_cvt_pk_bf16_f32 v89, v102, v103
	v_cvt_pk_bf16_f32 v90, v96, v97
	v_cvt_pk_bf16_f32 v91, v98, v99
	global_store_dwordx4 v[92:93], v[76:79], off offset:256
	v_cvt_pk_bf16_f32 v74, v80, v81
	v_cvt_pk_bf16_f32 v75, v82, v83
	v_lshl_add_u64 v[76:77], v[72:73], 0, v[172:173]
	v_cvt_pk_bf16_f32 v72, v84, v85
	v_cvt_pk_bf16_f32 v73, v86, v87
	v_cvt_pk_bf16_f32 v71, v66, v67
	v_cvt_pk_bf16_f32 v63, v58, v59
	v_cvt_pk_bf16_f32 v40, v52, v53
	v_cvt_pk_bf16_f32 v41, v54, v55
	v_cvt_pk_bf16_f32 v42, v48, v49
	v_cvt_pk_bf16_f32 v43, v50, v51
	v_cvt_pk_bf16_f32 v24, v36, v37
	v_cvt_pk_bf16_f32 v25, v38, v39
	v_cvt_pk_bf16_f32 v26, v32, v33
	v_cvt_pk_bf16_f32 v27, v34, v35
	v_lshl_add_u64 v[12:13], v[174:175], 0, s[54:55]
	v_cvt_pk_bf16_f32 v8, v20, v21
	v_cvt_pk_bf16_f32 v9, v22, v23
	v_cvt_pk_bf16_f32 v10, v16, v17
	v_cvt_pk_bf16_f32 v11, v18, v19
	v_cvt_pk_bf16_f32 v4, v4, v5
	v_cvt_pk_bf16_f32 v5, v6, v7
	v_cvt_pk_bf16_f32 v6, v0, v1
	v_cvt_pk_bf16_f32 v7, v2, v3
	s_and_b64 vcc, exec, s[2:3]
	s_mov_b32 s93, s91
	s_mov_b32 s90, s92
	s_mov_b64 s[58:59], s[0:1]
	s_mov_b64 s[56:57], s[4:5]
	global_store_dwordx4 v[174:175], v[124:127], off
	global_store_dwordx4 v[108:109], v[104:107], off
	global_store_dwordx4 v[92:93], v[88:91], off
	global_store_dwordx4 v[76:77], v[72:75], off
	global_store_dwordx4 v[76:77], v[68:71], off offset:256
	global_store_dwordx4 v[56:57], v[60:63], off
	global_store_dwordx4 v[46:47], v[40:43], off
	global_store_dwordx4 v[30:31], v[24:27], off
	global_store_dwordx4 v[14:15], v[8:11], off
	global_store_dwordx4 v[12:13], v[4:7], off offset:256
	s_cbranch_vccz .LBB0_301
	s_waitcnt vmcnt(0)
	s_cmpk_gt_u32 s64, 0xff
	s_cbranch_scc1 .LBB0_316
	s_barrier

; #define PG8_STAGE(bufoff, gbase, voff) do { _Pragma("unroll") for (int _i = 0; _i < 2; ++_i) \
;         __builtin_amdgcn_global_load_lds((const unsigned*)((const char*)(gbase) + (voff)[_i]), (PG8_LAS unsigned*)(lds + (bufoff) + ldsw + _i * 8192), 16, 0, 0); } while (0)
; template <class Epi, class Sched, bool STAMP = false>
; __device__ __forceinline__ void gemm_phase(PG8_LAS unsigned char* lds, const Gemm g, const Sched& S, const Epi& E, unsigned long long* stamps) {
;     ...
;     for (;;) {
;         const bool has_next = S.next(ui + 1, nxt);
;         const char* nA = has_next ? (const char*)g.A + (size_t)nxt.pm * tstep : cA; const char* nB = has_next ? (const char*)g.Bt + (size_t)nxt.pn * tstep : cB;
;         for (int t = 0; t < nt; t += 2) {
;             const bool last = (t == nt - 2);
;             const char* a1 = cA + (size_t)(t + 1) * kstep;
;             const char* a2 = last ? nA : cA + (size_t)(t + 2) * kstep; const char* b2 = last ? nB : cB + (size_t)(t + 2) * kstep;
;             const char* a3 = a2 + kstep; const char* b3 = b2 + kstep;
;             if (last && has_next) S.a_ready(nxt);
;             PG8_LDB(B0, 0, 0); PG8_SCHED; PG8_LDA(At, 0, 0); PG8_STAGE(PG8_SA(1, 1), a1 + hstep, voffA);
;             PG8_WAIT_L(8); PG8_BAR; PG8_WAIT_L(0); PG8_MMA(0, 0, At, B0); PG8_BAR; PG8_SCHED;
;             PG8_LDB(B1, 0, 1); PG8_STAGE(PG8_SB(0, 0), b2, voffB);
;             PG8_BAR; PG8_WAIT_L(0); PG8_MMA(0, 1, At, B1); PG8_BAR;
;             PG8_LDA(At, 0, 1); PG8_STAGE(PG8_SA(0, 0), a2, voffA);
;             PG8_BAR; PG8_WAIT_L(0); PG8_MMA(1, 0, At, B0); PG8_BAR; PG8_SCHED;
;             PG8_STAGE(PG8_SB(0, 1), b2 + hstep, voffB);
;             PG8_WAIT_V(6); PG8_BAR; PG8_MMA(1, 1, At, B1); PG8_BAR;
;             PG8_LDB(B0, 1, 0); PG8_SCHED; PG8_LDA(At, 1, 0); PG8_STAGE(PG8_SA(0, 1), a2 + hstep, voffA);
;             PG8_WAIT_L(8); PG8_BAR; PG8_WAIT_L(0); PG8_MMA(0, 0, At, B0); PG8_BAR; PG8_SCHED;
;             PG8_LDB(B1, 1, 1); PG8_STAGE(PG8_SB(1, 0), b3, voffB);
;             PG8_BAR; PG8_WAIT_L(0); PG8_MMA(0, 1, At, B1); PG8_BAR;
;             PG8_LDA(At, 1, 1); PG8_STAGE(PG8_SA(1, 0), a3, voffA);
;             PG8_BAR; PG8_WAIT_L(0); PG8_MMA(1, 0, At, B0); PG8_BAR; PG8_SCHED;
;             PG8_STAGE(PG8_SB(1, 1), b3 + hstep, voffB);
;             PG8_WAIT_V(6); PG8_BAR; PG8_MMA(1, 1, At, B1); PG8_BAR;
.LBB0_350:
	s_add_u32 s87, s36, 0x100
	s_addc_u32 s88, s37, 0
	s_mov_b32 s89, -2
	s_cmp_eq_u32 s68, s99
	s_cbranch_scc1 .Lgu2_half_loop_z
	ds_read_b128 v[140:143], v147
	ds_read_b128 v[170:173], v148
	ds_read_b128 v[174:177], v149
	ds_read_b128 v[178:181], v150
	s_add_u32 s36, s34, 0x100
	s_addc_u32 s37, s35, 0
	s_cmp_eq_u32 s89, 12
	s_cselect_b32 s55, s5, s37
	s_cselect_b32 s54, s4, s36
	s_cselect_b32 s53, s1, s88
	s_cselect_b32 s52, s0, s87
	s_mov_b32 m0, s78
	ds_read_b128 v[182:185], v145
	ds_read_b128 v[186:189], v145 offset:1024
	ds_read_b128 v[190:193], v145 offset:2048
	ds_read_b128 v[194:197], v145 offset:3072
	ds_read_b128 v[198:201], v145 offset:4096
	ds_read_b128 v[202:205], v145 offset:5120
	ds_read_b128 v[206:209], v145 offset:6144
	ds_read_b128 v[210:213], v145 offset:7168
	global_load_lds_dwordx4 v132, s[34:35]
	s_mov_b32 m0, s79
	s_nop 0
	global_load_lds_dwordx4 v134, s[34:35]
	s_waitcnt lgkmcnt(8)
	s_barrier
	s_waitcnt lgkmcnt(0)
	s_setprio 1
	s_waitcnt lgkmcnt(0)
	v_mfma_f32_16x16x32_bf16 v[124:127], v[140:143], v[182:185], 0
	v_mfma_f32_16x16x32_bf16 v[120:123], v[174:177], v[182:185], 0
	v_mfma_f32_16x16x32_bf16 v[108:111], v[140:143], v[190:193], 0
	v_mfma_f32_16x16x32_bf16 v[104:107], v[174:177], v[190:193], 0
	v_mfma_f32_16x16x32_bf16 v[92:95], v[140:143], v[198:201], 0
	v_mfma_f32_16x16x32_bf16 v[88:91], v[174:177], v[198:201], 0
	v_mfma_f32_16x16x32_bf16 v[76:79], v[140:143], v[206:209], 0
	v_mfma_f32_16x16x32_bf16 v[72:75], v[174:177], v[206:209], 0
	v_mfma_f32_16x16x32_bf16 v[124:127], v[170:173], v[186:189], v[124:127]
	v_mfma_f32_16x16x32_bf16 v[120:123], v[178:181], v[186:189], v[120:123]
	v_mfma_f32_16x16x32_bf16 v[108:111], v[170:173], v[194:197], v[108:111]
	v_mfma_f32_16x16x32_bf16 v[104:107], v[178:181], v[194:197], v[104:107]
	v_mfma_f32_16x16x32_bf16 v[92:95], v[170:173], v[202:205], v[92:95]
	v_mfma_f32_16x16x32_bf16 v[88:91], v[178:181], v[202:205], v[88:91]
	v_mfma_f32_16x16x32_bf16 v[76:79], v[170:173], v[210:213], v[76:79]
	v_mfma_f32_16x16x32_bf16 v[72:75], v[178:181], v[210:213], v[72:75]
	s_setprio 0
	s_barrier
	s_mov_b32 m0, s61
	ds_read_b128 v[214:217], v151
	ds_read_b128 v[218:221], v152
	ds_read_b128 v[222:225], v153
	ds_read_b128 v[226:229], v154
	global_load_lds_dwordx4 v130, s[52:53]
	s_mov_b32 m0, s62
	s_nop 0
	global_load_lds_dwordx4 v128, s[52:53]
	s_waitcnt lgkmcnt(0)
	s_barrier
	s_waitcnt lgkmcnt(0)
	s_setprio 1
	s_waitcnt lgkmcnt(0)
	v_mfma_f32_16x16x32_bf16 v[116:119], v[214:217], v[182:185], 0
	v_mfma_f32_16x16x32_bf16 v[112:115], v[222:225], v[182:185], 0
	v_mfma_f32_16x16x32_bf16 v[100:103], v[214:217], v[190:193], 0
	v_mfma_f32_16x16x32_bf16 v[96:99], v[222:225], v[190:193], 0
	v_mfma_f32_16x16x32_bf16 v[84:87], v[214:217], v[198:201], 0
	v_mfma_f32_16x16x32_bf16 v[80:83], v[222:225], v[198:201], 0
	v_mfma_f32_16x16x32_bf16 v[68:71], v[214:217], v[206:209], 0
	v_mfma_f32_16x16x32_bf16 v[64:67], v[222:225], v[206:209], 0
	v_mfma_f32_16x16x32_bf16 v[116:119], v[218:221], v[186:189], v[116:119]
	v_mfma_f32_16x16x32_bf16 v[112:115], v[226:229], v[186:189], v[112:115]
	v_mfma_f32_16x16x32_bf16 v[100:103], v[218:221], v[194:197], v[100:103]
	v_mfma_f32_16x16x32_bf16 v[96:99], v[226:229], v[194:197], v[96:99]
	v_mfma_f32_16x16x32_bf16 v[84:87], v[218:221], v[202:205], v[84:87]
	v_mfma_f32_16x16x32_bf16 v[80:83], v[226:229], v[202:205], v[80:83]
	v_mfma_f32_16x16x32_bf16 v[68:71], v[218:221], v[210:213], v[68:71]
	v_mfma_f32_16x16x32_bf16 v[64:67], v[226:229], v[210:213], v[64:67]
	s_setprio 0
	s_mov_b32 m0, s58
	s_barrier
	ds_read_b128 v[182:185], v145 offset:16384
	ds_read_b128 v[186:189], v145 offset:17408
	ds_read_b128 v[190:193], v145 offset:18432
	ds_read_b128 v[194:197], v145 offset:19456
	ds_read_b128 v[198:201], v145 offset:20480
	ds_read_b128 v[202:205], v145 offset:21504
	ds_read_b128 v[206:209], v145 offset:22528
	ds_read_b128 v[210:213], v145 offset:23552
	global_load_lds_dwordx4 v130, s[54:55]
	s_mov_b32 m0, s63
	s_nop 0
	global_load_lds_dwordx4 v128, s[54:55]
	s_add_u32 s34, s52, 0x44000
	s_addc_u32 s35, s53, 0
	s_mov_b32 m0, s64
	s_nop 0
	global_load_lds_dwordx4 v130, s[34:35]
	s_mov_b32 m0, s65
	s_nop 0
	global_load_lds_dwordx4 v128, s[34:35]
	s_waitcnt vmcnt(6)
	s_barrier
	s_waitcnt lgkmcnt(0)
	s_setprio 1
	s_waitcnt lgkmcnt(0)
	v_mfma_f32_16x16x32_bf16 v[60:63], v[140:143], v[182:185], 0
	v_mfma_f32_16x16x32_bf16 v[56:59], v[174:177], v[182:185], 0
	v_mfma_f32_16x16x32_bf16 v[44:47], v[140:143], v[190:193], 0
	v_mfma_f32_16x16x32_bf16 v[40:43], v[174:177], v[190:193], 0
	v_mfma_f32_16x16x32_bf16 v[28:31], v[140:143], v[198:201], 0
	v_mfma_f32_16x16x32_bf16 v[24:27], v[174:177], v[198:201], 0
	v_mfma_f32_16x16x32_bf16 v[12:15], v[140:143], v[206:209], 0
	v_mfma_f32_16x16x32_bf16 v[8:11], v[174:177], v[206:209], 0
	v_mfma_f32_16x16x32_bf16 v[60:63], v[170:173], v[186:189], v[60:63]
	v_mfma_f32_16x16x32_bf16 v[56:59], v[178:181], v[186:189], v[56:59]
	v_mfma_f32_16x16x32_bf16 v[44:47], v[170:173], v[194:197], v[44:47]
	v_mfma_f32_16x16x32_bf16 v[40:43], v[178:181], v[194:197], v[40:43]
	v_mfma_f32_16x16x32_bf16 v[28:31], v[170:173], v[202:205], v[28:31]
	v_mfma_f32_16x16x32_bf16 v[24:27], v[178:181], v[202:205], v[24:27]
	v_mfma_f32_16x16x32_bf16 v[12:15], v[170:173], v[210:213], v[12:15]
	v_mfma_f32_16x16x32_bf16 v[8:11], v[178:181], v[210:213], v[8:11]
	v_mfma_f32_16x16x32_bf16 v[52:55], v[214:217], v[182:185], 0
	v_mfma_f32_16x16x32_bf16 v[48:51], v[222:225], v[182:185], 0
	v_mfma_f32_16x16x32_bf16 v[36:39], v[214:217], v[190:193], 0
	v_mfma_f32_16x16x32_bf16 v[32:35], v[222:225], v[190:193], 0
	v_mfma_f32_16x16x32_bf16 v[20:23], v[214:217], v[198:201], 0
	v_mfma_f32_16x16x32_bf16 v[16:19], v[222:225], v[198:201], 0
	v_mfma_f32_16x16x32_bf16 v[4:7], v[214:217], v[206:209], 0
	v_mfma_f32_16x16x32_bf16 v[0:3], v[222:225], v[206:209], 0
	v_mfma_f32_16x16x32_bf16 v[52:55], v[218:221], v[186:189], v[52:55]
	v_mfma_f32_16x16x32_bf16 v[48:51], v[226:229], v[186:189], v[48:51]
	v_mfma_f32_16x16x32_bf16 v[36:39], v[218:221], v[194:197], v[36:39]
	v_mfma_f32_16x16x32_bf16 v[32:35], v[226:229], v[194:197], v[32:35]
	v_mfma_f32_16x16x32_bf16 v[20:23], v[218:221], v[202:205], v[20:23]
	v_mfma_f32_16x16x32_bf16 v[16:19], v[226:229], v[202:205], v[16:19]
	v_mfma_f32_16x16x32_bf16 v[4:7], v[218:221], v[210:213], v[4:7]
	v_mfma_f32_16x16x32_bf16 v[0:3], v[226:229], v[210:213], v[0:3]
	s_setprio 0
	s_barrier
	s_branch .Lzp5_mid
; #define PG8_STAGE(bufoff, gbase, voff) do { _Pragma("unroll") for (int _i = 0; _i < 2; ++_i) \
;         __builtin_amdgcn_global_load_lds((const unsigned*)((const char*)(gbase) + (voff)[_i]), (PG8_LAS unsigned*)(lds + (bufoff) + ldsw + _i * 8192), 16, 0, 0); } while (0)
; #define PG8_LDA(dst, b, h) do { _Pragma("unroll") for (int m = 0; m < 4; ++m) _Pragma("unroll") for (int k = 0; k < 2; ++k) dst[m][k] = *(const PG8_LAS bf16x8*)(lds + PG8_SA(b, h) + aoff + m * 2048 + k * 1024); } while (0)
; #define PG8_BAR __builtin_amdgcn_s_barrier()
; template <class Epi, class Sched, bool STAMP = false>
; __device__ __forceinline__ void gemm_phase(PG8_LAS unsigned char* lds, const Gemm g, const Sched& S, const Epi& E, unsigned long long* stamps) {
;     ...
;         for (int t = 0; t < nt; t += 2) {
;             const bool last = (t == nt - 2);
;             const char* a1 = cA + (size_t)(t + 1) * kstep;
;             const char* a2 = last ? nA : cA + (size_t)(t + 2) * kstep; const char* b2 = last ? nB : cB + (size_t)(t + 2) * kstep;
;             const char* a3 = a2 + kstep; const char* b3 = b2 + kstep;
;             if (last && has_next) S.a_ready(nxt);
;             PG8_LDB(B0, 0, 0); PG8_SCHED; PG8_LDA(At, 0, 0); PG8_STAGE(PG8_SA(1, 1), a1 + hstep, voffA);
;             PG8_WAIT_L(8); PG8_BAR; PG8_WAIT_L(0); PG8_MMA(0, 0, At, B0); PG8_BAR; PG8_SCHED;
;             PG8_LDB(B1, 0, 1); PG8_STAGE(PG8_SB(0, 0), b2, voffB);
;             PG8_BAR; PG8_WAIT_L(0); PG8_MMA(0, 1, At, B1); PG8_BAR;
;             PG8_LDA(At, 0, 1); PG8_STAGE(PG8_SA(0, 0), a2, voffA);
;             PG8_BAR; PG8_WAIT_L(0); PG8_MMA(1, 0, At, B0); PG8_BAR; PG8_SCHED;
;             PG8_STAGE(PG8_SB(0, 1), b2 + hstep, voffB);
;             PG8_WAIT_V(6); PG8_BAR; PG8_MMA(1, 1, At, B1); PG8_BAR;
;             PG8_LDB(B0, 1, 0); PG8_SCHED; PG8_LDA(At, 1, 0); PG8_STAGE(PG8_SA(0, 1), a2 + hstep, voffA);
;             PG8_WAIT_L(8); PG8_BAR; PG8_WAIT_L(0); PG8_MMA(0, 0, At, B0); PG8_BAR; PG8_SCHED;
;             PG8_LDB(B1, 1, 1); PG8_STAGE(PG8_SB(1, 0), b3, voffB);
;             PG8_BAR; PG8_WAIT_L(0); PG8_MMA(0, 1, At, B1); PG8_BAR;
;             PG8_LDA(At, 1, 1); PG8_STAGE(PG8_SA(1, 0), a3, voffA);
;             PG8_BAR; PG8_WAIT_L(0); PG8_MMA(1, 0, At, B0); PG8_BAR; PG8_SCHED;
;             PG8_STAGE(PG8_SB(1, 1), b3 + hstep, voffB);
;             PG8_WAIT_V(6); PG8_BAR; PG8_MMA(1, 1, At, B1); PG8_BAR;
.LBB0_351:
	ds_read_b128 v[140:143], v147
	ds_read_b128 v[170:173], v148
	ds_read_b128 v[174:177], v149
	ds_read_b128 v[178:181], v150
	s_add_u32 s36, s34, 0x100
	s_addc_u32 s37, s35, 0
	s_cmp_eq_u32 s89, 12
	s_cselect_b32 s55, s5, s37
	s_cselect_b32 s54, s4, s36
	s_cselect_b32 s53, s1, s88
	s_cselect_b32 s52, s0, s87
	s_mov_b32 m0, s78
	ds_read_b128 v[182:185], v145
	ds_read_b128 v[186:189], v145 offset:1024
	ds_read_b128 v[190:193], v145 offset:2048
	ds_read_b128 v[194:197], v145 offset:3072
	ds_read_b128 v[198:201], v145 offset:4096
	ds_read_b128 v[202:205], v145 offset:5120
	ds_read_b128 v[206:209], v145 offset:6144
	ds_read_b128 v[210:213], v145 offset:7168
	global_load_lds_dwordx4 v132, s[34:35]
	s_mov_b32 m0, s79
	s_nop 0
	global_load_lds_dwordx4 v134, s[34:35]
	s_waitcnt lgkmcnt(8)
	s_barrier
	s_waitcnt lgkmcnt(0)
	s_setprio 1
	s_waitcnt lgkmcnt(0)
	v_mfma_f32_16x16x32_bf16 v[124:127], v[140:143], v[182:185], v[124:127]
	v_mfma_f32_16x16x32_bf16 v[120:123], v[174:177], v[182:185], v[120:123]
	v_mfma_f32_16x16x32_bf16 v[108:111], v[140:143], v[190:193], v[108:111]
	v_mfma_f32_16x16x32_bf16 v[104:107], v[174:177], v[190:193], v[104:107]
	v_mfma_f32_16x16x32_bf16 v[92:95], v[140:143], v[198:201], v[92:95]
	v_mfma_f32_16x16x32_bf16 v[88:91], v[174:177], v[198:201], v[88:91]
	v_mfma_f32_16x16x32_bf16 v[76:79], v[140:143], v[206:209], v[76:79]
	v_mfma_f32_16x16x32_bf16 v[72:75], v[174:177], v[206:209], v[72:75]
	v_mfma_f32_16x16x32_bf16 v[124:127], v[170:173], v[186:189], v[124:127]
	v_mfma_f32_16x16x32_bf16 v[120:123], v[178:181], v[186:189], v[120:123]
	v_mfma_f32_16x16x32_bf16 v[108:111], v[170:173], v[194:197], v[108:111]
	v_mfma_f32_16x16x32_bf16 v[104:107], v[178:181], v[194:197], v[104:107]
	v_mfma_f32_16x16x32_bf16 v[92:95], v[170:173], v[202:205], v[92:95]
	v_mfma_f32_16x16x32_bf16 v[88:91], v[178:181], v[202:205], v[88:91]
	v_mfma_f32_16x16x32_bf16 v[76:79], v[170:173], v[210:213], v[76:79]
	v_mfma_f32_16x16x32_bf16 v[72:75], v[178:181], v[210:213], v[72:75]
	s_setprio 0
	s_barrier
	s_mov_b32 m0, s61
	ds_read_b128 v[214:217], v151
	ds_read_b128 v[218:221], v152
	ds_read_b128 v[222:225], v153
	ds_read_b128 v[226:229], v154
	global_load_lds_dwordx4 v130, s[52:53]
	s_mov_b32 m0, s62
	s_nop 0
	global_load_lds_dwordx4 v128, s[52:53]
	s_waitcnt lgkmcnt(0)
	s_barrier
	s_waitcnt lgkmcnt(0)
	s_setprio 1
	s_waitcnt lgkmcnt(0)
	v_mfma_f32_16x16x32_bf16 v[116:119], v[214:217], v[182:185], v[116:119]
	v_mfma_f32_16x16x32_bf16 v[112:115], v[222:225], v[182:185], v[112:115]
	v_mfma_f32_16x16x32_bf16 v[100:103], v[214:217], v[190:193], v[100:103]
	v_mfma_f32_16x16x32_bf16 v[96:99], v[222:225], v[190:193], v[96:99]
	v_mfma_f32_16x16x32_bf16 v[84:87], v[214:217], v[198:201], v[84:87]
	v_mfma_f32_16x16x32_bf16 v[80:83], v[222:225], v[198:201], v[80:83]
	v_mfma_f32_16x16x32_bf16 v[68:71], v[214:217], v[206:209], v[68:71]
	v_mfma_f32_16x16x32_bf16 v[64:67], v[222:225], v[206:209], v[64:67]
	v_mfma_f32_16x16x32_bf16 v[116:119], v[218:221], v[186:189], v[116:119]
	v_mfma_f32_16x16x32_bf16 v[112:115], v[226:229], v[186:189], v[112:115]
	v_mfma_f32_16x16x32_bf16 v[100:103], v[218:221], v[194:197], v[100:103]
	v_mfma_f32_16x16x32_bf16 v[96:99], v[226:229], v[194:197], v[96:99]
	v_mfma_f32_16x16x32_bf16 v[84:87], v[218:221], v[202:205], v[84:87]
	v_mfma_f32_16x16x32_bf16 v[80:83], v[226:229], v[202:205], v[80:83]
	v_mfma_f32_16x16x32_bf16 v[68:71], v[218:221], v[210:213], v[68:71]
	v_mfma_f32_16x16x32_bf16 v[64:67], v[226:229], v[210:213], v[64:67]
	s_setprio 0
	s_mov_b32 m0, s58
	s_barrier
	ds_read_b128 v[182:185], v145 offset:16384
	ds_read_b128 v[186:189], v145 offset:17408
	ds_read_b128 v[190:193], v145 offset:18432
	ds_read_b128 v[194:197], v145 offset:19456
	ds_read_b128 v[198:201], v145 offset:20480
	ds_read_b128 v[202:205], v145 offset:21504
	ds_read_b128 v[206:209], v145 offset:22528
	ds_read_b128 v[210:213], v145 offset:23552
	global_load_lds_dwordx4 v130, s[54:55]
	s_mov_b32 m0, s63
	s_nop 0
	global_load_lds_dwordx4 v128, s[54:55]
	s_add_u32 s34, s52, 0x44000
	s_addc_u32 s35, s53, 0
	s_mov_b32 m0, s64
	s_nop 0
	global_load_lds_dwordx4 v130, s[34:35]
	s_mov_b32 m0, s65
	s_nop 0
	global_load_lds_dwordx4 v128, s[34:35]
	s_waitcnt vmcnt(6)
	s_barrier
	s_waitcnt lgkmcnt(0)
	s_setprio 1
	s_waitcnt lgkmcnt(0)
	v_mfma_f32_16x16x32_bf16 v[60:63], v[140:143], v[182:185], v[60:63]
	v_mfma_f32_16x16x32_bf16 v[56:59], v[174:177], v[182:185], v[56:59]
	v_mfma_f32_16x16x32_bf16 v[44:47], v[140:143], v[190:193], v[44:47]
	v_mfma_f32_16x16x32_bf16 v[40:43], v[174:177], v[190:193], v[40:43]
	v_mfma_f32_16x16x32_bf16 v[28:31], v[140:143], v[198:201], v[28:31]
	v_mfma_f32_16x16x32_bf16 v[24:27], v[174:177], v[198:201], v[24:27]
	v_mfma_f32_16x16x32_bf16 v[12:15], v[140:143], v[206:209], v[12:15]
	v_mfma_f32_16x16x32_bf16 v[8:11], v[174:177], v[206:209], v[8:11]
	v_mfma_f32_16x16x32_bf16 v[60:63], v[170:173], v[186:189], v[60:63]
	v_mfma_f32_16x16x32_bf16 v[56:59], v[178:181], v[186:189], v[56:59]
	v_mfma_f32_16x16x32_bf16 v[44:47], v[170:173], v[194:197], v[44:47]
	v_mfma_f32_16x16x32_bf16 v[40:43], v[178:181], v[194:197], v[40:43]
	v_mfma_f32_16x16x32_bf16 v[28:31], v[170:173], v[202:205], v[28:31]
	v_mfma_f32_16x16x32_bf16 v[24:27], v[178:181], v[202:205], v[24:27]
	v_mfma_f32_16x16x32_bf16 v[12:15], v[170:173], v[210:213], v[12:15]
	v_mfma_f32_16x16x32_bf16 v[8:11], v[178:181], v[210:213], v[8:11]
	v_mfma_f32_16x16x32_bf16 v[52:55], v[214:217], v[182:185], v[52:55]
	v_mfma_f32_16x16x32_bf16 v[48:51], v[222:225], v[182:185], v[48:51]
	v_mfma_f32_16x16x32_bf16 v[36:39], v[214:217], v[190:193], v[36:39]
	v_mfma_f32_16x16x32_bf16 v[32:35], v[222:225], v[190:193], v[32:35]
	v_mfma_f32_16x16x32_bf16 v[20:23], v[214:217], v[198:201], v[20:23]
	v_mfma_f32_16x16x32_bf16 v[16:19], v[222:225], v[198:201], v[16:19]
	v_mfma_f32_16x16x32_bf16 v[4:7], v[214:217], v[206:209], v[4:7]
	v_mfma_f32_16x16x32_bf16 v[0:3], v[222:225], v[206:209], v[0:3]
	v_mfma_f32_16x16x32_bf16 v[52:55], v[218:221], v[186:189], v[52:55]
	v_mfma_f32_16x16x32_bf16 v[48:51], v[226:229], v[186:189], v[48:51]
	v_mfma_f32_16x16x32_bf16 v[36:39], v[218:221], v[194:197], v[36:39]
	v_mfma_f32_16x16x32_bf16 v[32:35], v[226:229], v[194:197], v[32:35]
	v_mfma_f32_16x16x32_bf16 v[20:23], v[218:221], v[202:205], v[20:23]
	v_mfma_f32_16x16x32_bf16 v[16:19], v[226:229], v[202:205], v[16:19]
	v_mfma_f32_16x16x32_bf16 v[4:7], v[218:221], v[210:213], v[4:7]
	v_mfma_f32_16x16x32_bf16 v[0:3], v[226:229], v[210:213], v[0:3]
	s_setprio 0
	s_barrier
; #define PG8_STAGE(bufoff, gbase, voff) do { _Pragma("unroll") for (int _i = 0; _i < 2; ++_i) \
;         __builtin_amdgcn_global_load_lds((const unsigned*)((const char*)(gbase) + (voff)[_i]), (PG8_LAS unsigned*)(lds + (bufoff) + ldsw + _i * 8192), 16, 0, 0); } while (0)
; #define PG8_LDA(dst, b, h) do { _Pragma("unroll") for (int m = 0; m < 4; ++m) _Pragma("unroll") for (int k = 0; k < 2; ++k) dst[m][k] = *(const PG8_LAS bf16x8*)(lds + PG8_SA(b, h) + aoff + m * 2048 + k * 1024); } while (0)
; #define PG8_BAR __builtin_amdgcn_s_barrier()
; template <class Epi, class Sched, bool STAMP = false>
; __device__ __forceinline__ void gemm_phase(PG8_LAS unsigned char* lds, const Gemm g, const Sched& S, const Epi& E, unsigned long long* stamps) {
;     ...
;         for (int t = 0; t < nt; t += 2) {
;             const bool last = (t == nt - 2);
;             const char* a1 = cA + (size_t)(t + 1) * kstep;
;             const char* a2 = last ? nA : cA + (size_t)(t + 2) * kstep; const char* b2 = last ? nB : cB + (size_t)(t + 2) * kstep;
;             const char* a3 = a2 + kstep; const char* b3 = b2 + kstep;
;             if (last && has_next) S.a_ready(nxt);
;             PG8_LDB(B0, 0, 0); PG8_SCHED; PG8_LDA(At, 0, 0); PG8_STAGE(PG8_SA(1, 1), a1 + hstep, voffA);
;             PG8_WAIT_L(8); PG8_BAR; PG8_WAIT_L(0); PG8_MMA(0, 0, At, B0); PG8_BAR; PG8_SCHED;
;             PG8_LDB(B1, 0, 1); PG8_STAGE(PG8_SB(0, 0), b2, voffB);
;             PG8_BAR; PG8_WAIT_L(0); PG8_MMA(0, 1, At, B1); PG8_BAR;
;             PG8_LDA(At, 0, 1); PG8_STAGE(PG8_SA(0, 0), a2, voffA);
;             PG8_BAR; PG8_WAIT_L(0); PG8_MMA(1, 0, At, B0); PG8_BAR; PG8_SCHED;
;             PG8_STAGE(PG8_SB(0, 1), b2 + hstep, voffB);
;             PG8_WAIT_V(6); PG8_BAR; PG8_MMA(1, 1, At, B1); PG8_BAR;
;             PG8_LDB(B0, 1, 0); PG8_SCHED; PG8_LDA(At, 1, 0); PG8_STAGE(PG8_SA(0, 1), a2 + hstep, voffA);
;             PG8_WAIT_L(8); PG8_BAR; PG8_WAIT_L(0); PG8_MMA(0, 0, At, B0); PG8_BAR; PG8_SCHED;
;             PG8_LDB(B1, 1, 1); PG8_STAGE(PG8_SB(1, 0), b3, voffB);
;             PG8_BAR; PG8_WAIT_L(0); PG8_MMA(0, 1, At, B1); PG8_BAR;
;             PG8_LDA(At, 1, 1); PG8_STAGE(PG8_SA(1, 0), a3, voffA);
;             PG8_BAR; PG8_WAIT_L(0); PG8_MMA(1, 0, At, B0); PG8_BAR; PG8_SCHED;
;             PG8_STAGE(PG8_SB(1, 1), b3 + hstep, voffB);
;             PG8_WAIT_V(6); PG8_BAR; PG8_MMA(1, 1, At, B1); PG8_BAR;
.Lzp5_mid:
	ds_read_b128 v[140:143], v155
	ds_read_b128 v[170:173], v156
	ds_read_b128 v[174:177], v157
	ds_read_b128 v[178:181], v165
	s_add_u32 s34, s54, 0x44000
	s_addc_u32 s35, s55, 0
	s_mov_b32 m0, s66
	ds_read_b128 v[182:185], v145 offset:32768
	ds_read_b128 v[186:189], v145 offset:33792
	ds_read_b128 v[190:193], v145 offset:34816
	ds_read_b128 v[194:197], v145 offset:35840
	ds_read_b128 v[198:201], v145 offset:36864
	ds_read_b128 v[202:205], v145 offset:37888
	ds_read_b128 v[206:209], v145 offset:38912
	ds_read_b128 v[210:213], v145 offset:39936
	global_load_lds_dwordx4 v130, s[34:35]
	s_mov_b32 m0, s67
	s_nop 0
	global_load_lds_dwordx4 v128, s[34:35]
	s_waitcnt lgkmcnt(8)
	s_barrier
	s_waitcnt lgkmcnt(0)
	s_setprio 1
	s_waitcnt lgkmcnt(0)
	v_mfma_f32_16x16x32_bf16 v[124:127], v[140:143], v[182:185], v[124:127]
	v_mfma_f32_16x16x32_bf16 v[120:123], v[174:177], v[182:185], v[120:123]
	v_mfma_f32_16x16x32_bf16 v[108:111], v[140:143], v[190:193], v[108:111]
	v_mfma_f32_16x16x32_bf16 v[104:107], v[174:177], v[190:193], v[104:107]
	v_mfma_f32_16x16x32_bf16 v[92:95], v[140:143], v[198:201], v[92:95]
	v_mfma_f32_16x16x32_bf16 v[88:91], v[174:177], v[198:201], v[88:91]
	v_mfma_f32_16x16x32_bf16 v[76:79], v[140:143], v[206:209], v[76:79]
	v_mfma_f32_16x16x32_bf16 v[72:75], v[174:177], v[206:209], v[72:75]
	v_mfma_f32_16x16x32_bf16 v[124:127], v[170:173], v[186:189], v[124:127]
	v_mfma_f32_16x16x32_bf16 v[120:123], v[178:181], v[186:189], v[120:123]
	v_mfma_f32_16x16x32_bf16 v[108:111], v[170:173], v[194:197], v[108:111]
	v_mfma_f32_16x16x32_bf16 v[104:107], v[178:181], v[194:197], v[104:107]
	v_mfma_f32_16x16x32_bf16 v[92:95], v[170:173], v[202:205], v[92:95]
	v_mfma_f32_16x16x32_bf16 v[88:91], v[178:181], v[202:205], v[88:91]
	v_mfma_f32_16x16x32_bf16 v[76:79], v[170:173], v[210:213], v[76:79]
	v_mfma_f32_16x16x32_bf16 v[72:75], v[178:181], v[210:213], v[72:75]
	s_setprio 0
	s_barrier
	s_mov_b32 m0, s70
	ds_read_b128 v[214:217], v166
	ds_read_b128 v[218:221], v167
	ds_read_b128 v[222:225], v168
	ds_read_b128 v[226:229], v169
	s_add_u32 s100, s52, 0x80
	s_addc_u32 s101, s53, 0
	global_load_lds_dwordx4 v130, s[100:101]
	s_mov_b32 m0, s71
	s_nop 0
	global_load_lds_dwordx4 v128, s[100:101]
	s_waitcnt lgkmcnt(0)
	s_barrier
	s_waitcnt lgkmcnt(0)
	s_setprio 1
	s_waitcnt lgkmcnt(0)
	v_mfma_f32_16x16x32_bf16 v[116:119], v[214:217], v[182:185], v[116:119]
	v_mfma_f32_16x16x32_bf16 v[112:115], v[222:225], v[182:185], v[112:115]
	v_mfma_f32_16x16x32_bf16 v[100:103], v[214:217], v[190:193], v[100:103]
	v_mfma_f32_16x16x32_bf16 v[96:99], v[222:225], v[190:193], v[96:99]
	v_mfma_f32_16x16x32_bf16 v[84:87], v[214:217], v[198:201], v[84:87]
	v_mfma_f32_16x16x32_bf16 v[80:83], v[222:225], v[198:201], v[80:83]
	v_mfma_f32_16x16x32_bf16 v[68:71], v[214:217], v[206:209], v[68:71]
	v_mfma_f32_16x16x32_bf16 v[64:67], v[222:225], v[206:209], v[64:67]
	v_mfma_f32_16x16x32_bf16 v[116:119], v[218:221], v[186:189], v[116:119]
	v_mfma_f32_16x16x32_bf16 v[112:115], v[226:229], v[186:189], v[112:115]
	v_mfma_f32_16x16x32_bf16 v[100:103], v[218:221], v[194:197], v[100:103]
	v_mfma_f32_16x16x32_bf16 v[96:99], v[226:229], v[194:197], v[96:99]
	v_mfma_f32_16x16x32_bf16 v[84:87], v[218:221], v[202:205], v[84:87]
	v_mfma_f32_16x16x32_bf16 v[80:83], v[226:229], v[202:205], v[80:83]
	v_mfma_f32_16x16x32_bf16 v[68:71], v[218:221], v[210:213], v[68:71]
	v_mfma_f32_16x16x32_bf16 v[64:67], v[226:229], v[210:213], v[64:67]
	s_setprio 0
	s_mov_b32 m0, s73
	s_barrier
	ds_read_b128 v[182:185], v145 offset:49152
	ds_read_b128 v[186:189], v145 offset:50176
	ds_read_b128 v[190:193], v145 offset:51200
	ds_read_b128 v[194:197], v145 offset:52224
	ds_read_b128 v[198:201], v145 offset:53248
	ds_read_b128 v[202:205], v145 offset:54272
	ds_read_b128 v[206:209], v145 offset:55296
	ds_read_b128 v[210:213], v145 offset:56320
	s_add_u32 s100, s54, 0x80
	s_addc_u32 s101, s55, 0
	global_load_lds_dwordx4 v130, s[100:101]
	s_mov_b32 m0, s74
	s_nop 0
	global_load_lds_dwordx4 v128, s[100:101]
	s_add_u32 s34, s52, 0x44080
	s_addc_u32 s35, s53, 0
	s_mov_b32 m0, s75
	s_nop 0
	global_load_lds_dwordx4 v130, s[34:35]
	s_mov_b32 m0, s76
	s_nop 0
	global_load_lds_dwordx4 v128, s[34:35]
	s_waitcnt vmcnt(6)
	s_barrier
	s_waitcnt lgkmcnt(0)
	s_setprio 1
	s_waitcnt lgkmcnt(0)
	v_mfma_f32_16x16x32_bf16 v[60:63], v[140:143], v[182:185], v[60:63]
	v_mfma_f32_16x16x32_bf16 v[56:59], v[174:177], v[182:185], v[56:59]
	v_mfma_f32_16x16x32_bf16 v[44:47], v[140:143], v[190:193], v[44:47]
	v_mfma_f32_16x16x32_bf16 v[40:43], v[174:177], v[190:193], v[40:43]
	v_mfma_f32_16x16x32_bf16 v[28:31], v[140:143], v[198:201], v[28:31]
	v_mfma_f32_16x16x32_bf16 v[24:27], v[174:177], v[198:201], v[24:27]
	v_mfma_f32_16x16x32_bf16 v[12:15], v[140:143], v[206:209], v[12:15]
	v_mfma_f32_16x16x32_bf16 v[8:11], v[174:177], v[206:209], v[8:11]
	v_mfma_f32_16x16x32_bf16 v[60:63], v[170:173], v[186:189], v[60:63]
	v_mfma_f32_16x16x32_bf16 v[56:59], v[178:181], v[186:189], v[56:59]
	v_mfma_f32_16x16x32_bf16 v[44:47], v[170:173], v[194:197], v[44:47]
	v_mfma_f32_16x16x32_bf16 v[40:43], v[178:181], v[194:197], v[40:43]
	v_mfma_f32_16x16x32_bf16 v[28:31], v[170:173], v[202:205], v[28:31]
	v_mfma_f32_16x16x32_bf16 v[24:27], v[178:181], v[202:205], v[24:27]
	v_mfma_f32_16x16x32_bf16 v[12:15], v[170:173], v[210:213], v[12:15]
	v_mfma_f32_16x16x32_bf16 v[8:11], v[178:181], v[210:213], v[8:11]
	v_mfma_f32_16x16x32_bf16 v[52:55], v[214:217], v[182:185], v[52:55]
	v_mfma_f32_16x16x32_bf16 v[48:51], v[222:225], v[182:185], v[48:51]
	v_mfma_f32_16x16x32_bf16 v[36:39], v[214:217], v[190:193], v[36:39]
	v_mfma_f32_16x16x32_bf16 v[32:35], v[222:225], v[190:193], v[32:35]
	v_mfma_f32_16x16x32_bf16 v[20:23], v[214:217], v[198:201], v[20:23]
	v_mfma_f32_16x16x32_bf16 v[16:19], v[222:225], v[198:201], v[16:19]
	v_mfma_f32_16x16x32_bf16 v[4:7], v[214:217], v[206:209], v[4:7]
	v_mfma_f32_16x16x32_bf16 v[0:3], v[222:225], v[206:209], v[0:3]
	v_mfma_f32_16x16x32_bf16 v[52:55], v[218:221], v[186:189], v[52:55]
	v_mfma_f32_16x16x32_bf16 v[48:51], v[226:229], v[186:189], v[48:51]
	v_mfma_f32_16x16x32_bf16 v[36:39], v[218:221], v[194:197], v[36:39]
	v_mfma_f32_16x16x32_bf16 v[32:35], v[226:229], v[194:197], v[32:35]
	v_mfma_f32_16x16x32_bf16 v[20:23], v[218:221], v[202:205], v[20:23]
	v_mfma_f32_16x16x32_bf16 v[16:19], v[226:229], v[202:205], v[16:19]
	v_mfma_f32_16x16x32_bf16 v[4:7], v[218:221], v[210:213], v[4:7]
	v_mfma_f32_16x16x32_bf16 v[0:3], v[226:229], v[210:213], v[0:3]
	s_setprio 0
	s_add_i32 s89, s89, 2
	s_add_u32 s87, s87, 0x100
	s_addc_u32 s88, s88, 0
	s_cmp_gt_u32 s89, 13
	s_mov_b64 s[34:35], s[36:37]
	s_barrier
; DI float ex2(float x) { return __builtin_amdgcn_exp2f(x); }
;     DI void operator()(const f32x4 (&acc)[2][2][4][2], const Unit& u, int wr, int wc, int fr, int fq) const {
;         const int row0 = u.pm * BM + wr * 64 + fr, hcol0 = ((u.pn * BM + wc * 32) >> 1) + 4 * fq;
; #pragma unroll
;         for (int ai = 0; ai < 2; ++ai)
; #pragma unroll
;             for (int m = 0; m < 4; ++m) { u16* rowp = O + (size_t)(row0 + ai * HALF + m * 16) * ldc + hcol0;
; #pragma unroll
;                 for (int bj = 0; bj < 2; ++bj) { const f32x4 g = acc[ai][bj][m][0], up = acc[ai][bj][m][1]; float r[4];
; #pragma unroll
;                     for (int j = 0; j < 4; ++j) r[j] = g[j] * up[j] * __builtin_amdgcn_rcpf(1.f + ex2(-LOG2E * g[j]));
;                     uint2 w = {pack2(r[0], r[1]), pack2(r[2], r[3])}; *(uint2*)(rowp + bj * (HALF / 2)) = w; } }
	s_cbranch_scc0 .LBB0_351
	v_exp_f32_e64 v171, -v124
	v_exp_f32_e64 v175, -v125
	s_lshl_b32 s10, s86, 8
	v_add_f32_e32 v171, 1.0, v171
	v_rcp_f32_e32 v174, v171
	v_add_f32_e32 v171, 1.0, v175
	v_exp_f32_e64 v176, -v126
	v_exp_f32_e64 v177, -v127
	v_rcp_f32_e32 v175, v171
	v_add_f32_e32 v171, 1.0, v176
	v_rcp_f32_e32 v176, v171
	v_add_f32_e32 v171, 1.0, v177
	v_rcp_f32_e32 v177, v171
	v_pk_mul_f32 v[122:123], v[126:127], v[122:123]
	v_pk_mul_f32 v[120:121], v[124:125], v[120:121]
	s_or_b32 s10, s10, s69
	v_pk_mul_f32 v[120:121], v[120:121], v[174:175]
	v_pk_mul_f32 v[122:123], v[122:123], v[176:177]
	s_ashr_i32 s10, s10, 1
	v_cvt_pk_bf16_f32 v120, v120, v121
	v_cvt_pk_bf16_f32 v121, v122, v123
	v_or_b32_e32 v140, s10, v146
	v_exp_f32_e64 v122, -v116
	v_exp_f32_e64 v123, -v117
	v_lshl_add_u32 v170, s85, 8, v144
	v_ashrrev_i32_e32 v141, 31, v140
	v_mov_b64_e32 v[142:143], s[12:13]
	v_mad_i64_i32 v[172:173], s[34:35], v170, s82, v[142:143]
	v_lshlrev_b64 v[140:141], 1, v[140:141]
	v_lshl_add_u64 v[172:173], v[172:173], 0, v[140:141]
	global_store_dwordx2 v[172:173], v[120:121], off
	v_add_f32_e32 v120, 1.0, v122
	v_add_f32_e32 v121, 1.0, v123
	v_exp_f32_e64 v122, -v118
	v_exp_f32_e64 v123, -v119
	v_rcp_f32_e32 v120, v120
	v_rcp_f32_e32 v121, v121
	v_add_f32_e32 v122, 1.0, v122
	v_add_f32_e32 v123, 1.0, v123
	v_rcp_f32_e32 v122, v122
	v_rcp_f32_e32 v123, v123
	v_pk_mul_f32 v[114:115], v[118:119], v[114:115]
	v_pk_mul_f32 v[112:113], v[116:117], v[112:113]
	v_pk_mul_f32 v[112:113], v[112:113], v[120:121]
	v_pk_mul_f32 v[114:115], v[114:115], v[122:123]
	v_cvt_pk_bf16_f32 v112, v112, v113
	v_cvt_pk_bf16_f32 v113, v114, v115
	v_exp_f32_e64 v114, -v108
	v_exp_f32_e64 v115, -v109
	v_exp_f32_e64 v116, -v110
	v_exp_f32_e64 v117, -v111
	v_add_f32_e32 v114, 1.0, v114
	v_add_f32_e32 v115, 1.0, v115
	v_add_f32_e32 v116, 1.0, v116
	v_add_f32_e32 v117, 1.0, v117
	v_rcp_f32_e32 v114, v114
	v_rcp_f32_e32 v115, v115
	v_rcp_f32_e32 v116, v116
	v_rcp_f32_e32 v117, v117
	v_pk_mul_f32 v[106:107], v[110:111], v[106:107]
	v_pk_mul_f32 v[104:105], v[108:109], v[104:105]
	global_store_dwordx2 v[172:173], v[112:113], off offset:128
	v_pk_mul_f32 v[104:105], v[104:105], v[114:115]
	v_pk_mul_f32 v[106:107], v[106:107], v[116:117]
	v_cvt_pk_bf16_f32 v104, v104, v105
	v_cvt_pk_bf16_f32 v105, v106, v107
	v_exp_f32_e64 v106, -v100
	v_exp_f32_e64 v107, -v101
	v_or_b32_e32 v112, 16, v170
	v_mad_i64_i32 v[112:113], s[34:35], v112, s82, v[142:143]
	v_lshl_add_u64 v[112:113], v[112:113], 0, v[140:141]
	global_store_dwordx2 v[112:113], v[104:105], off
	v_add_f32_e32 v104, 1.0, v106
	v_add_f32_e32 v105, 1.0, v107
	v_exp_f32_e64 v106, -v102
	v_exp_f32_e64 v107, -v103
	v_rcp_f32_e32 v104, v104
	v_rcp_f32_e32 v105, v105
	v_add_f32_e32 v106, 1.0, v106
	v_add_f32_e32 v107, 1.0, v107
	v_rcp_f32_e32 v106, v106
	v_rcp_f32_e32 v107, v107
	v_pk_mul_f32 v[98:99], v[102:103], v[98:99]
	v_pk_mul_f32 v[96:97], v[100:101], v[96:97]
	v_pk_mul_f32 v[96:97], v[96:97], v[104:105]
	v_pk_mul_f32 v[98:99], v[98:99], v[106:107]
	v_cvt_pk_bf16_f32 v96, v96, v97
	v_cvt_pk_bf16_f32 v97, v98, v99
	v_exp_f32_e64 v98, -v92
	v_exp_f32_e64 v99, -v93
	v_exp_f32_e64 v100, -v94
	v_exp_f32_e64 v101, -v95
	v_add_f32_e32 v98, 1.0, v98
	v_add_f32_e32 v99, 1.0, v99
	v_add_f32_e32 v100, 1.0, v100
	v_add_f32_e32 v101, 1.0, v101
	v_rcp_f32_e32 v98, v98
	v_rcp_f32_e32 v99, v99
	v_rcp_f32_e32 v100, v100
	v_rcp_f32_e32 v101, v101
	v_pk_mul_f32 v[90:91], v[94:95], v[90:91]
	v_pk_mul_f32 v[88:89], v[92:93], v[88:89]
	global_store_dwordx2 v[112:113], v[96:97], off offset:128
	v_pk_mul_f32 v[88:89], v[88:89], v[98:99]
	v_pk_mul_f32 v[90:91], v[90:91], v[100:101]
	v_cvt_pk_bf16_f32 v88, v88, v89
	v_cvt_pk_bf16_f32 v89, v90, v91
	v_exp_f32_e64 v90, -v84
	v_exp_f32_e64 v91, -v85
	v_or_b32_e32 v96, 32, v170
	v_mad_i64_i32 v[96:97], s[34:35], v96, s82, v[142:143]
	v_lshl_add_u64 v[96:97], v[96:97], 0, v[140:141]
	global_store_dwordx2 v[96:97], v[88:89], off
	v_add_f32_e32 v88, 1.0, v90
	v_add_f32_e32 v89, 1.0, v91
	v_exp_f32_e64 v90, -v86
	v_exp_f32_e64 v91, -v87
	v_rcp_f32_e32 v88, v88
	v_rcp_f32_e32 v89, v89
	v_add_f32_e32 v90, 1.0, v90
	v_add_f32_e32 v91, 1.0, v91
	v_rcp_f32_e32 v90, v90
	v_rcp_f32_e32 v91, v91
	v_pk_mul_f32 v[82:83], v[86:87], v[82:83]
	v_pk_mul_f32 v[80:81], v[84:85], v[80:81]
	v_pk_mul_f32 v[80:81], v[80:81], v[88:89]
	v_pk_mul_f32 v[82:83], v[82:83], v[90:91]
	v_cvt_pk_bf16_f32 v80, v80, v81
	v_cvt_pk_bf16_f32 v81, v82, v83
	v_exp_f32_e64 v82, -v76
	v_exp_f32_e64 v83, -v77
	v_exp_f32_e64 v84, -v78
	v_exp_f32_e64 v85, -v79
	v_add_f32_e32 v82, 1.0, v82
	v_add_f32_e32 v83, 1.0, v83
	v_add_f32_e32 v84, 1.0, v84
	v_add_f32_e32 v85, 1.0, v85
	v_rcp_f32_e32 v82, v82
	v_rcp_f32_e32 v83, v83
	v_rcp_f32_e32 v84, v84
	v_rcp_f32_e32 v85, v85
	v_pk_mul_f32 v[74:75], v[78:79], v[74:75]
	v_pk_mul_f32 v[72:73], v[76:77], v[72:73]
	global_store_dwordx2 v[96:97], v[80:81], off offset:128
	v_pk_mul_f32 v[72:73], v[72:73], v[82:83]
	v_pk_mul_f32 v[74:75], v[74:75], v[84:85]
	v_cvt_pk_bf16_f32 v72, v72, v73
	v_cvt_pk_bf16_f32 v73, v74, v75
	v_exp_f32_e64 v74, -v68
	v_exp_f32_e64 v75, -v69
	v_or_b32_e32 v80, 48, v170
	v_mad_i64_i32 v[80:81], s[34:35], v80, s82, v[142:143]
	v_lshl_add_u64 v[80:81], v[80:81], 0, v[140:141]
	global_store_dwordx2 v[80:81], v[72:73], off
	v_add_f32_e32 v72, 1.0, v74
	v_add_f32_e32 v73, 1.0, v75
	v_exp_f32_e64 v74, -v70
	v_exp_f32_e64 v75, -v71
	v_rcp_f32_e32 v72, v72
	v_rcp_f32_e32 v73, v73
	v_add_f32_e32 v74, 1.0, v74
	v_add_f32_e32 v75, 1.0, v75
	v_rcp_f32_e32 v74, v74
	v_rcp_f32_e32 v75, v75
	v_pk_mul_f32 v[66:67], v[70:71], v[66:67]
	v_pk_mul_f32 v[64:65], v[68:69], v[64:65]
; DI float ex2(float x) { return __builtin_amdgcn_exp2f(x); }
;     DI void operator()(const f32x4 (&acc)[2][2][4][2], const Unit& u, int wr, int wc, int fr, int fq) const {
;         const int row0 = u.pm * BM + wr * 64 + fr, hcol0 = ((u.pn * BM + wc * 32) >> 1) + 4 * fq;
; #pragma unroll
;         for (int ai = 0; ai < 2; ++ai)
; #pragma unroll
;             for (int m = 0; m < 4; ++m) { u16* rowp = O + (size_t)(row0 + ai * HALF + m * 16) * ldc + hcol0;
; #pragma unroll
;                 for (int bj = 0; bj < 2; ++bj) { const f32x4 g = acc[ai][bj][m][0], up = acc[ai][bj][m][1]; float r[4];
; #pragma unroll
;                     for (int j = 0; j < 4; ++j) r[j] = g[j] * up[j] * __builtin_amdgcn_rcpf(1.f + ex2(-LOG2E * g[j]));
;                     uint2 w = {pack2(r[0], r[1]), pack2(r[2], r[3])}; *(uint2*)(rowp + bj * (HALF / 2)) = w; } }
	v_pk_mul_f32 v[64:65], v[64:65], v[72:73]
	v_pk_mul_f32 v[66:67], v[66:67], v[74:75]
	v_cvt_pk_bf16_f32 v64, v64, v65
	v_cvt_pk_bf16_f32 v65, v66, v67
	v_exp_f32_e64 v66, -v60
	v_exp_f32_e64 v67, -v61
	v_exp_f32_e64 v68, -v62
	v_exp_f32_e64 v69, -v63
	v_add_f32_e32 v66, 1.0, v66
	v_add_f32_e32 v67, 1.0, v67
	v_add_f32_e32 v68, 1.0, v68
	v_add_f32_e32 v69, 1.0, v69
	v_rcp_f32_e32 v66, v66
	v_rcp_f32_e32 v67, v67
	v_rcp_f32_e32 v68, v68
	v_rcp_f32_e32 v69, v69
	v_pk_mul_f32 v[58:59], v[62:63], v[58:59]
	v_pk_mul_f32 v[56:57], v[60:61], v[56:57]
	global_store_dwordx2 v[80:81], v[64:65], off offset:128
	v_pk_mul_f32 v[56:57], v[56:57], v[66:67]
	v_pk_mul_f32 v[58:59], v[58:59], v[68:69]
	v_cvt_pk_bf16_f32 v56, v56, v57
	v_cvt_pk_bf16_f32 v57, v58, v59
	v_exp_f32_e64 v58, -v52
	v_exp_f32_e64 v59, -v53
	v_add_u32_e32 v64, 0x80, v170
	v_mad_i64_i32 v[64:65], s[34:35], v64, s82, v[142:143]
	v_lshl_add_u64 v[64:65], v[64:65], 0, v[140:141]
	global_store_dwordx2 v[64:65], v[56:57], off
	v_add_f32_e32 v56, 1.0, v58
	v_add_f32_e32 v57, 1.0, v59
	v_exp_f32_e64 v58, -v54
	v_exp_f32_e64 v59, -v55
	v_rcp_f32_e32 v56, v56
	v_rcp_f32_e32 v57, v57
	v_add_f32_e32 v58, 1.0, v58
	v_add_f32_e32 v59, 1.0, v59
	v_rcp_f32_e32 v58, v58
	v_rcp_f32_e32 v59, v59
	v_pk_mul_f32 v[50:51], v[54:55], v[50:51]
	v_pk_mul_f32 v[48:49], v[52:53], v[48:49]
	v_pk_mul_f32 v[48:49], v[48:49], v[56:57]
	v_pk_mul_f32 v[50:51], v[50:51], v[58:59]
	v_cvt_pk_bf16_f32 v48, v48, v49
	v_cvt_pk_bf16_f32 v49, v50, v51
	v_exp_f32_e64 v50, -v44
	v_exp_f32_e64 v51, -v45
	v_exp_f32_e64 v52, -v46
	v_exp_f32_e64 v53, -v47
	v_add_f32_e32 v50, 1.0, v50
	v_add_f32_e32 v51, 1.0, v51
	v_add_f32_e32 v52, 1.0, v52
	v_add_f32_e32 v53, 1.0, v53
	v_rcp_f32_e32 v50, v50
	v_rcp_f32_e32 v51, v51
	v_rcp_f32_e32 v52, v52
	v_rcp_f32_e32 v53, v53
	v_pk_mul_f32 v[42:43], v[46:47], v[42:43]
	v_pk_mul_f32 v[40:41], v[44:45], v[40:41]
	global_store_dwordx2 v[64:65], v[48:49], off offset:128
	v_pk_mul_f32 v[40:41], v[40:41], v[50:51]
	v_pk_mul_f32 v[42:43], v[42:43], v[52:53]
	v_cvt_pk_bf16_f32 v40, v40, v41
	v_cvt_pk_bf16_f32 v41, v42, v43
	v_exp_f32_e64 v42, -v36
	v_exp_f32_e64 v43, -v37
	v_add_u32_e32 v48, 0x90, v170
	v_mad_i64_i32 v[48:49], s[34:35], v48, s82, v[142:143]
	v_lshl_add_u64 v[48:49], v[48:49], 0, v[140:141]
	global_store_dwordx2 v[48:49], v[40:41], off
	v_add_f32_e32 v40, 1.0, v42
	v_add_f32_e32 v41, 1.0, v43
	v_exp_f32_e64 v42, -v38
	v_exp_f32_e64 v43, -v39
	v_rcp_f32_e32 v40, v40
	v_rcp_f32_e32 v41, v41
	v_add_f32_e32 v42, 1.0, v42
	v_add_f32_e32 v43, 1.0, v43
	v_rcp_f32_e32 v42, v42
	v_rcp_f32_e32 v43, v43
	v_pk_mul_f32 v[34:35], v[38:39], v[34:35]
	v_pk_mul_f32 v[32:33], v[36:37], v[32:33]
	v_pk_mul_f32 v[32:33], v[32:33], v[40:41]
	v_pk_mul_f32 v[34:35], v[34:35], v[42:43]
	v_cvt_pk_bf16_f32 v32, v32, v33
	v_cvt_pk_bf16_f32 v33, v34, v35
	v_exp_f32_e64 v34, -v28
	v_exp_f32_e64 v35, -v29
	v_exp_f32_e64 v36, -v30
	v_exp_f32_e64 v37, -v31
	v_add_f32_e32 v34, 1.0, v34
	v_add_f32_e32 v35, 1.0, v35
	v_add_f32_e32 v36, 1.0, v36
	v_add_f32_e32 v37, 1.0, v37
	v_rcp_f32_e32 v34, v34
	v_rcp_f32_e32 v35, v35
	v_rcp_f32_e32 v36, v36
	v_rcp_f32_e32 v37, v37
	v_pk_mul_f32 v[26:27], v[30:31], v[26:27]
	v_pk_mul_f32 v[24:25], v[28:29], v[24:25]
	global_store_dwordx2 v[48:49], v[32:33], off offset:128
	v_pk_mul_f32 v[24:25], v[24:25], v[34:35]
	v_pk_mul_f32 v[26:27], v[26:27], v[36:37]
	v_cvt_pk_bf16_f32 v24, v24, v25
	v_cvt_pk_bf16_f32 v25, v26, v27
	v_exp_f32_e64 v26, -v20
	v_exp_f32_e64 v27, -v21
	v_add_u32_e32 v32, 0xa0, v170
	v_mad_i64_i32 v[32:33], s[34:35], v32, s82, v[142:143]
	v_lshl_add_u64 v[32:33], v[32:33], 0, v[140:141]
	global_store_dwordx2 v[32:33], v[24:25], off
	v_add_f32_e32 v24, 1.0, v26
	v_add_f32_e32 v25, 1.0, v27
	v_exp_f32_e64 v26, -v22
	v_exp_f32_e64 v27, -v23
	v_rcp_f32_e32 v24, v24
	v_rcp_f32_e32 v25, v25
	v_add_f32_e32 v26, 1.0, v26
	v_add_f32_e32 v27, 1.0, v27
	v_rcp_f32_e32 v26, v26
	v_rcp_f32_e32 v27, v27
	v_pk_mul_f32 v[18:19], v[22:23], v[18:19]
	v_pk_mul_f32 v[16:17], v[20:21], v[16:17]
	v_pk_mul_f32 v[16:17], v[16:17], v[24:25]
	v_pk_mul_f32 v[18:19], v[18:19], v[26:27]
	v_cvt_pk_bf16_f32 v16, v16, v17
	v_cvt_pk_bf16_f32 v17, v18, v19
	v_exp_f32_e64 v18, -v12
	v_exp_f32_e64 v19, -v13
	v_exp_f32_e64 v20, -v14
	v_exp_f32_e64 v21, -v15
	v_add_f32_e32 v18, 1.0, v18
	v_add_f32_e32 v19, 1.0, v19
	v_add_f32_e32 v20, 1.0, v20
	v_add_f32_e32 v21, 1.0, v21
	v_rcp_f32_e32 v18, v18
	v_rcp_f32_e32 v19, v19
	v_rcp_f32_e32 v20, v20
	v_rcp_f32_e32 v21, v21
	v_pk_mul_f32 v[10:11], v[14:15], v[10:11]
	v_pk_mul_f32 v[8:9], v[12:13], v[8:9]
	global_store_dwordx2 v[32:33], v[16:17], off offset:128
	v_pk_mul_f32 v[8:9], v[8:9], v[18:19]
	v_pk_mul_f32 v[10:11], v[10:11], v[20:21]
	v_cvt_pk_bf16_f32 v8, v8, v9
	v_cvt_pk_bf16_f32 v9, v10, v11
	v_exp_f32_e64 v10, -v4
	v_exp_f32_e64 v11, -v5
	v_add_u32_e32 v16, 0xb0, v170
	v_mad_i64_i32 v[16:17], s[34:35], v16, s82, v[142:143]
	v_lshl_add_u64 v[16:17], v[16:17], 0, v[140:141]
	global_store_dwordx2 v[16:17], v[8:9], off
	v_add_f32_e32 v8, 1.0, v10
	v_add_f32_e32 v9, 1.0, v11
	v_exp_f32_e64 v10, -v6
	v_exp_f32_e64 v11, -v7
	v_rcp_f32_e32 v8, v8
	v_rcp_f32_e32 v9, v9
	v_add_f32_e32 v10, 1.0, v10
	v_add_f32_e32 v11, 1.0, v11
	v_rcp_f32_e32 v10, v10
	v_rcp_f32_e32 v11, v11
	v_pk_mul_f32 v[2:3], v[6:7], v[2:3]
	v_pk_mul_f32 v[0:1], v[4:5], v[0:1]
	s_and_b64 vcc, exec, s[2:3]
	v_pk_mul_f32 v[0:1], v[0:1], v[8:9]
	v_pk_mul_f32 v[2:3], v[2:3], v[10:11]
	v_cvt_pk_bf16_f32 v0, v0, v1
	v_cvt_pk_bf16_f32 v1, v2, v3
	s_mov_b32 s86, s83
	s_mov_b32 s85, s84
	s_mov_b64 s[36:37], s[0:1]
	s_mov_b64 s[34:35], s[4:5]
	global_store_dwordx2 v[16:17], v[0:1], off offset:128
	s_cbranch_vccz .LBB0_344
	s_branch .Lgu2_done

; #define PG8_STAGE(bufoff, gbase, voff) do { _Pragma("unroll") for (int _i = 0; _i < 2; ++_i) \
;         __builtin_amdgcn_global_load_lds((const unsigned*)((const char*)(gbase) + (voff)[_i]), (PG8_LAS unsigned*)(lds + (bufoff) + ldsw + _i * 8192), 16, 0, 0); } while (0)
; #define PG8_LDA(dst, b, h) do { _Pragma("unroll") for (int m = 0; m < 4; ++m) _Pragma("unroll") for (int k = 0; k < 2; ++k) dst[m][k] = *(const PG8_LAS bf16x8*)(lds + PG8_SA(b, h) + aoff + m * 2048 + k * 1024); } while (0)
; #define PG8_BAR __builtin_amdgcn_s_barrier()
; template <class Epi, class Sched, bool STAMP = false>
; __device__ __forceinline__ void gemm_phase(PG8_LAS unsigned char* lds, const Gemm g, const Sched& S, const Epi& E, unsigned long long* stamps) {
;     ...
;         for (int t = 0; t < nt; t += 2) {
;             const bool last = (t == nt - 2);
;             const char* a1 = cA + (size_t)(t + 1) * kstep;
;             const char* a2 = last ? nA : cA + (size_t)(t + 2) * kstep; const char* b2 = last ? nB : cB + (size_t)(t + 2) * kstep;
;             const char* a3 = a2 + kstep; const char* b3 = b2 + kstep;
;             if (last && has_next) S.a_ready(nxt);
;             PG8_LDB(B0, 0, 0); PG8_SCHED; PG8_LDA(At, 0, 0); PG8_STAGE(PG8_SA(1, 1), a1 + hstep, voffA);
;             PG8_WAIT_L(8); PG8_BAR; PG8_WAIT_L(0); PG8_MMA(0, 0, At, B0); PG8_BAR; PG8_SCHED;
;             PG8_LDB(B1, 0, 1); PG8_STAGE(PG8_SB(0, 0), b2, voffB);
;             PG8_BAR; PG8_WAIT_L(0); PG8_MMA(0, 1, At, B1); PG8_BAR;
;             PG8_LDA(At, 0, 1); PG8_STAGE(PG8_SA(0, 0), a2, voffA);
;             PG8_BAR; PG8_WAIT_L(0); PG8_MMA(1, 0, At, B0); PG8_BAR; PG8_SCHED;
;             PG8_STAGE(PG8_SB(0, 1), b2 + hstep, voffB);
;             PG8_WAIT_V(6); PG8_BAR; PG8_MMA(1, 1, At, B1); PG8_BAR;
;             PG8_LDB(B0, 1, 0); PG8_SCHED; PG8_LDA(At, 1, 0); PG8_STAGE(PG8_SA(0, 1), a2 + hstep, voffA);
;             PG8_WAIT_L(8); PG8_BAR; PG8_WAIT_L(0); PG8_MMA(0, 0, At, B0); PG8_BAR; PG8_SCHED;
;             PG8_LDB(B1, 1, 1); PG8_STAGE(PG8_SB(1, 0), b3, voffB);
;             PG8_BAR; PG8_WAIT_L(0); PG8_MMA(0, 1, At, B1); PG8_BAR;
;             PG8_LDA(At, 1, 1); PG8_STAGE(PG8_SA(1, 0), a3, voffA);
;             PG8_BAR; PG8_WAIT_L(0); PG8_MMA(1, 0, At, B0); PG8_BAR; PG8_SCHED;
;             PG8_STAGE(PG8_SB(1, 1), b3 + hstep, voffB);
;             PG8_WAIT_V(6); PG8_BAR; PG8_MMA(1, 1, At, B1); PG8_BAR;
.Lgu2_half_loop:
	ds_read_b128 v[140:143], v147
	ds_read_b128 v[170:173], v148
	ds_read_b128 v[174:177], v149
	ds_read_b128 v[178:181], v150
	s_add_u32 s36, s34, 0x100
	s_addc_u32 s37, s35, 0
	s_cmp_eq_u32 s89, 12
	s_cselect_b32 s55, s5, s37
	s_cselect_b32 s54, s4, s36
	s_cselect_b32 s53, s1, s88
	s_cselect_b32 s52, s0, s87
	s_mov_b32 m0, s78
	ds_read_b128 v[182:185], v145
	ds_read_b128 v[186:189], v145 offset:1024
	ds_read_b128 v[190:193], v145 offset:2048
	ds_read_b128 v[194:197], v145 offset:3072
	ds_read_b128 v[198:201], v145 offset:4096
	ds_read_b128 v[202:205], v145 offset:5120
	ds_read_b128 v[206:209], v145 offset:6144
	ds_read_b128 v[210:213], v145 offset:7168
	global_load_lds_dwordx4 v132, s[34:35]
	s_mov_b32 m0, s79
	s_nop 0
	global_load_lds_dwordx4 v134, s[34:35]
	s_waitcnt lgkmcnt(8)
	s_barrier
	s_waitcnt lgkmcnt(0)
	s_setprio 1
	s_waitcnt lgkmcnt(0)
	v_mfma_f32_16x16x32_bf16 v[124:127], v[140:143], v[182:185], v[124:127]
	v_mfma_f32_16x16x32_bf16 v[120:123], v[174:177], v[182:185], v[120:123]
	v_mfma_f32_16x16x32_bf16 v[108:111], v[140:143], v[190:193], v[108:111]
	v_mfma_f32_16x16x32_bf16 v[104:107], v[174:177], v[190:193], v[104:107]
	v_mfma_f32_16x16x32_bf16 v[92:95], v[140:143], v[198:201], v[92:95]
	v_mfma_f32_16x16x32_bf16 v[88:91], v[174:177], v[198:201], v[88:91]
	v_mfma_f32_16x16x32_bf16 v[76:79], v[140:143], v[206:209], v[76:79]
	v_mfma_f32_16x16x32_bf16 v[72:75], v[174:177], v[206:209], v[72:75]
	v_mfma_f32_16x16x32_bf16 v[124:127], v[170:173], v[186:189], v[124:127]
	v_mfma_f32_16x16x32_bf16 v[120:123], v[178:181], v[186:189], v[120:123]
	v_mfma_f32_16x16x32_bf16 v[108:111], v[170:173], v[194:197], v[108:111]
	v_mfma_f32_16x16x32_bf16 v[104:107], v[178:181], v[194:197], v[104:107]
	v_mfma_f32_16x16x32_bf16 v[92:95], v[170:173], v[202:205], v[92:95]
	v_mfma_f32_16x16x32_bf16 v[88:91], v[178:181], v[202:205], v[88:91]
	v_mfma_f32_16x16x32_bf16 v[76:79], v[170:173], v[210:213], v[76:79]
	v_mfma_f32_16x16x32_bf16 v[72:75], v[178:181], v[210:213], v[72:75]
	s_setprio 0
	s_barrier
	s_mov_b32 m0, s61
	s_nop 0
	global_load_lds_dwordx4 v130, s[52:53]
	s_mov_b32 m0, s62
	s_nop 0
	global_load_lds_dwordx4 v128, s[52:53]
	s_waitcnt lgkmcnt(0)
	s_barrier
	s_waitcnt lgkmcnt(0)
	s_setprio 1
	s_waitcnt lgkmcnt(0)
	s_setprio 0
	s_mov_b32 m0, s58
	s_barrier
	ds_read_b128 v[182:185], v145 offset:16384
	ds_read_b128 v[186:189], v145 offset:17408
	ds_read_b128 v[190:193], v145 offset:18432
	ds_read_b128 v[194:197], v145 offset:19456
	ds_read_b128 v[198:201], v145 offset:20480
	ds_read_b128 v[202:205], v145 offset:21504
	ds_read_b128 v[206:209], v145 offset:22528
	ds_read_b128 v[210:213], v145 offset:23552
	global_load_lds_dwordx4 v130, s[54:55]
	s_mov_b32 m0, s63
	s_nop 0
	global_load_lds_dwordx4 v128, s[54:55]
	s_add_u32 s34, s52, 0x44000
	s_addc_u32 s35, s53, 0
	s_mov_b32 m0, s64
	s_nop 0
	s_mov_b32 m0, s65
	s_nop 0
	s_waitcnt vmcnt(4)
	s_barrier
	s_waitcnt lgkmcnt(0)
	s_setprio 1
	s_waitcnt lgkmcnt(0)
	v_mfma_f32_16x16x32_bf16 v[60:63], v[140:143], v[182:185], v[60:63]
	v_mfma_f32_16x16x32_bf16 v[56:59], v[174:177], v[182:185], v[56:59]
	v_mfma_f32_16x16x32_bf16 v[44:47], v[140:143], v[190:193], v[44:47]
	v_mfma_f32_16x16x32_bf16 v[40:43], v[174:177], v[190:193], v[40:43]
	v_mfma_f32_16x16x32_bf16 v[28:31], v[140:143], v[198:201], v[28:31]
	v_mfma_f32_16x16x32_bf16 v[24:27], v[174:177], v[198:201], v[24:27]
	v_mfma_f32_16x16x32_bf16 v[12:15], v[140:143], v[206:209], v[12:15]
	v_mfma_f32_16x16x32_bf16 v[8:11], v[174:177], v[206:209], v[8:11]
	v_mfma_f32_16x16x32_bf16 v[60:63], v[170:173], v[186:189], v[60:63]
	v_mfma_f32_16x16x32_bf16 v[56:59], v[178:181], v[186:189], v[56:59]
	v_mfma_f32_16x16x32_bf16 v[44:47], v[170:173], v[194:197], v[44:47]
	v_mfma_f32_16x16x32_bf16 v[40:43], v[178:181], v[194:197], v[40:43]
	v_mfma_f32_16x16x32_bf16 v[28:31], v[170:173], v[202:205], v[28:31]
	v_mfma_f32_16x16x32_bf16 v[24:27], v[178:181], v[202:205], v[24:27]
	v_mfma_f32_16x16x32_bf16 v[12:15], v[170:173], v[210:213], v[12:15]
	v_mfma_f32_16x16x32_bf16 v[8:11], v[178:181], v[210:213], v[8:11]
	s_setprio 0
	s_barrier
	ds_read_b128 v[140:143], v155
	ds_read_b128 v[170:173], v156
	ds_read_b128 v[174:177], v157
	ds_read_b128 v[178:181], v165
	s_add_u32 s34, s54, 0x44000
	s_addc_u32 s35, s55, 0
	s_mov_b32 m0, s66
	ds_read_b128 v[182:185], v145 offset:32768
	ds_read_b128 v[186:189], v145 offset:33792
	ds_read_b128 v[190:193], v145 offset:34816
	ds_read_b128 v[194:197], v145 offset:35840
	ds_read_b128 v[198:201], v145 offset:36864
	ds_read_b128 v[202:205], v145 offset:37888
	ds_read_b128 v[206:209], v145 offset:38912
	ds_read_b128 v[210:213], v145 offset:39936
	global_load_lds_dwordx4 v130, s[34:35]
	s_mov_b32 m0, s67
	s_nop 0
	global_load_lds_dwordx4 v128, s[34:35]
	s_waitcnt lgkmcnt(8)
	s_barrier
	s_waitcnt lgkmcnt(0)
	s_setprio 1
	s_waitcnt lgkmcnt(0)
	v_mfma_f32_16x16x32_bf16 v[124:127], v[140:143], v[182:185], v[124:127]
	v_mfma_f32_16x16x32_bf16 v[120:123], v[174:177], v[182:185], v[120:123]
	v_mfma_f32_16x16x32_bf16 v[108:111], v[140:143], v[190:193], v[108:111]
	v_mfma_f32_16x16x32_bf16 v[104:107], v[174:177], v[190:193], v[104:107]
	v_mfma_f32_16x16x32_bf16 v[92:95], v[140:143], v[198:201], v[92:95]
	v_mfma_f32_16x16x32_bf16 v[88:91], v[174:177], v[198:201], v[88:91]
	v_mfma_f32_16x16x32_bf16 v[76:79], v[140:143], v[206:209], v[76:79]
	v_mfma_f32_16x16x32_bf16 v[72:75], v[174:177], v[206:209], v[72:75]
	v_mfma_f32_16x16x32_bf16 v[124:127], v[170:173], v[186:189], v[124:127]
	v_mfma_f32_16x16x32_bf16 v[120:123], v[178:181], v[186:189], v[120:123]
	v_mfma_f32_16x16x32_bf16 v[108:111], v[170:173], v[194:197], v[108:111]
	v_mfma_f32_16x16x32_bf16 v[104:107], v[178:181], v[194:197], v[104:107]
	v_mfma_f32_16x16x32_bf16 v[92:95], v[170:173], v[202:205], v[92:95]
	v_mfma_f32_16x16x32_bf16 v[88:91], v[178:181], v[202:205], v[88:91]
	v_mfma_f32_16x16x32_bf16 v[76:79], v[170:173], v[210:213], v[76:79]
	v_mfma_f32_16x16x32_bf16 v[72:75], v[178:181], v[210:213], v[72:75]
	s_setprio 0
	s_barrier
; #define PG8_STAGE(bufoff, gbase, voff) do { _Pragma("unroll") for (int _i = 0; _i < 2; ++_i) \
;         __builtin_amdgcn_global_load_lds((const unsigned*)((const char*)(gbase) + (voff)[_i]), (PG8_LAS unsigned*)(lds + (bufoff) + ldsw + _i * 8192), 16, 0, 0); } while (0)
; #define PG8_LDA(dst, b, h) do { _Pragma("unroll") for (int m = 0; m < 4; ++m) _Pragma("unroll") for (int k = 0; k < 2; ++k) dst[m][k] = *(const PG8_LAS bf16x8*)(lds + PG8_SA(b, h) + aoff + m * 2048 + k * 1024); } while (0)
; #define PG8_BAR __builtin_amdgcn_s_barrier()
; template <class Epi, class Sched, bool STAMP = false>
; __device__ __forceinline__ void gemm_phase(PG8_LAS unsigned char* lds, const Gemm g, const Sched& S, const Epi& E, unsigned long long* stamps) {
;     ...
;         for (int t = 0; t < nt; t += 2) {
;             const bool last = (t == nt - 2);
;             const char* a1 = cA + (size_t)(t + 1) * kstep;
;             const char* a2 = last ? nA : cA + (size_t)(t + 2) * kstep; const char* b2 = last ? nB : cB + (size_t)(t + 2) * kstep;
;             const char* a3 = a2 + kstep; const char* b3 = b2 + kstep;
;             if (last && has_next) S.a_ready(nxt);
;             PG8_LDB(B0, 0, 0); PG8_SCHED; PG8_LDA(At, 0, 0); PG8_STAGE(PG8_SA(1, 1), a1 + hstep, voffA);
;             PG8_WAIT_L(8); PG8_BAR; PG8_WAIT_L(0); PG8_MMA(0, 0, At, B0); PG8_BAR; PG8_SCHED;
;             PG8_LDB(B1, 0, 1); PG8_STAGE(PG8_SB(0, 0), b2, voffB);
;             PG8_BAR; PG8_WAIT_L(0); PG8_MMA(0, 1, At, B1); PG8_BAR;
;             PG8_LDA(At, 0, 1); PG8_STAGE(PG8_SA(0, 0), a2, voffA);
;             PG8_BAR; PG8_WAIT_L(0); PG8_MMA(1, 0, At, B0); PG8_BAR; PG8_SCHED;
;             PG8_STAGE(PG8_SB(0, 1), b2 + hstep, voffB);
;             PG8_WAIT_V(6); PG8_BAR; PG8_MMA(1, 1, At, B1); PG8_BAR;
;             PG8_LDB(B0, 1, 0); PG8_SCHED; PG8_LDA(At, 1, 0); PG8_STAGE(PG8_SA(0, 1), a2 + hstep, voffA);
;             PG8_WAIT_L(8); PG8_BAR; PG8_WAIT_L(0); PG8_MMA(0, 0, At, B0); PG8_BAR; PG8_SCHED;
;             PG8_LDB(B1, 1, 1); PG8_STAGE(PG8_SB(1, 0), b3, voffB);
;             PG8_BAR; PG8_WAIT_L(0); PG8_MMA(0, 1, At, B1); PG8_BAR;
;             PG8_LDA(At, 1, 1); PG8_STAGE(PG8_SA(1, 0), a3, voffA);
;             PG8_BAR; PG8_WAIT_L(0); PG8_MMA(1, 0, At, B0); PG8_BAR; PG8_SCHED;
;             PG8_STAGE(PG8_SB(1, 1), b3 + hstep, voffB);
;             PG8_WAIT_V(6); PG8_BAR; PG8_MMA(1, 1, At, B1); PG8_BAR;
	s_mov_b32 m0, s70
	s_add_u32 s100, s52, 0x80
	s_addc_u32 s101, s53, 0
	global_load_lds_dwordx4 v130, s[100:101]
	s_mov_b32 m0, s71
	s_nop 0
	global_load_lds_dwordx4 v128, s[100:101]
	s_waitcnt lgkmcnt(0)
	s_barrier
	s_waitcnt lgkmcnt(0)
	s_setprio 1
	s_waitcnt lgkmcnt(0)
	s_setprio 0
	s_mov_b32 m0, s73
	s_barrier
	ds_read_b128 v[182:185], v145 offset:49152
	ds_read_b128 v[186:189], v145 offset:50176
	ds_read_b128 v[190:193], v145 offset:51200
	ds_read_b128 v[194:197], v145 offset:52224
	ds_read_b128 v[198:201], v145 offset:53248
	ds_read_b128 v[202:205], v145 offset:54272
	ds_read_b128 v[206:209], v145 offset:55296
	ds_read_b128 v[210:213], v145 offset:56320
	s_add_u32 s100, s54, 0x80
	s_addc_u32 s101, s55, 0
	global_load_lds_dwordx4 v130, s[100:101]
	s_mov_b32 m0, s74
	s_nop 0
	global_load_lds_dwordx4 v128, s[100:101]
	s_add_u32 s34, s52, 0x44080
	s_addc_u32 s35, s53, 0
	s_mov_b32 m0, s75
	s_nop 0
	s_mov_b32 m0, s76
	s_nop 0
	s_waitcnt vmcnt(4)
	s_barrier
	s_waitcnt lgkmcnt(0)
	s_setprio 1
	s_waitcnt lgkmcnt(0)
	v_mfma_f32_16x16x32_bf16 v[60:63], v[140:143], v[182:185], v[60:63]
	v_mfma_f32_16x16x32_bf16 v[56:59], v[174:177], v[182:185], v[56:59]
	v_mfma_f32_16x16x32_bf16 v[44:47], v[140:143], v[190:193], v[44:47]
	v_mfma_f32_16x16x32_bf16 v[40:43], v[174:177], v[190:193], v[40:43]
	v_mfma_f32_16x16x32_bf16 v[28:31], v[140:143], v[198:201], v[28:31]
	v_mfma_f32_16x16x32_bf16 v[24:27], v[174:177], v[198:201], v[24:27]
	v_mfma_f32_16x16x32_bf16 v[12:15], v[140:143], v[206:209], v[12:15]
	v_mfma_f32_16x16x32_bf16 v[8:11], v[174:177], v[206:209], v[8:11]
	v_mfma_f32_16x16x32_bf16 v[60:63], v[170:173], v[186:189], v[60:63]
	v_mfma_f32_16x16x32_bf16 v[56:59], v[178:181], v[186:189], v[56:59]
	v_mfma_f32_16x16x32_bf16 v[44:47], v[170:173], v[194:197], v[44:47]
	v_mfma_f32_16x16x32_bf16 v[40:43], v[178:181], v[194:197], v[40:43]
	v_mfma_f32_16x16x32_bf16 v[28:31], v[170:173], v[202:205], v[28:31]
	v_mfma_f32_16x16x32_bf16 v[24:27], v[178:181], v[202:205], v[24:27]
	v_mfma_f32_16x16x32_bf16 v[12:15], v[170:173], v[210:213], v[12:15]
	v_mfma_f32_16x16x32_bf16 v[8:11], v[178:181], v[210:213], v[8:11]
	s_setprio 0
	s_add_i32 s89, s89, 2
	s_add_u32 s87, s87, 0x100
	s_addc_u32 s88, s88, 0
	s_cmp_gt_u32 s89, 13
	s_mov_b64 s[34:35], s[36:37]
	s_barrier
	s_cbranch_scc0 .Lgu2_half_loop
; DI float ex2(float x) { return __builtin_amdgcn_exp2f(x); }
;     DI void operator()(const f32x4 (&acc)[2][2][4][2], const Unit& u, int wr, int wc, int fr, int fq) const {
;         const int row0 = u.pm * BM + wr * 64 + fr, hcol0 = ((u.pn * BM + wc * 32) >> 1) + 4 * fq;
; #pragma unroll
;         for (int ai = 0; ai < 2; ++ai)
; #pragma unroll
;             for (int m = 0; m < 4; ++m) { u16* rowp = O + (size_t)(row0 + ai * HALF + m * 16) * ldc + hcol0;
; #pragma unroll
;                 for (int bj = 0; bj < 2; ++bj) { const f32x4 g = acc[ai][bj][m][0], up = acc[ai][bj][m][1]; float r[4];
; #pragma unroll
;                     for (int j = 0; j < 4; ++j) r[j] = g[j] * up[j] * __builtin_amdgcn_rcpf(1.f + ex2(-LOG2E * g[j]));
;                     uint2 w = {pack2(r[0], r[1]), pack2(r[2], r[3])}; *(uint2*)(rowp + bj * (HALF / 2)) = w; } }
	v_exp_f32_e64 v171, -v124
	v_exp_f32_e64 v175, -v125
	s_lshl_b32 s10, s86, 8
	v_add_f32_e32 v171, 1.0, v171
	v_rcp_f32_e32 v174, v171
	v_add_f32_e32 v171, 1.0, v175
	v_exp_f32_e64 v176, -v126
	v_exp_f32_e64 v177, -v127
	v_rcp_f32_e32 v175, v171
	v_add_f32_e32 v171, 1.0, v176
	v_rcp_f32_e32 v176, v171
	v_add_f32_e32 v171, 1.0, v177
	v_rcp_f32_e32 v177, v171
	v_pk_mul_f32 v[122:123], v[126:127], v[122:123]
	v_pk_mul_f32 v[120:121], v[124:125], v[120:121]
	s_or_b32 s10, s10, s69
	s_or_b32 s10, s10, s98
	v_pk_mul_f32 v[120:121], v[120:121], v[174:175]
	v_pk_mul_f32 v[122:123], v[122:123], v[176:177]
	s_ashr_i32 s10, s10, 1
	v_cvt_pk_bf16_f32 v120, v120, v121
	v_cvt_pk_bf16_f32 v121, v122, v123
	v_or_b32_e32 v140, s10, v146
	v_lshl_add_u32 v170, s85, 8, v144
	v_ashrrev_i32_e32 v141, 31, v140
	v_mov_b64_e32 v[142:143], s[12:13]
	v_mad_i64_i32 v[172:173], s[34:35], v170, s82, v[142:143]
	v_lshlrev_b64 v[140:141], 1, v[140:141]
	v_lshl_add_u64 v[172:173], v[172:173], 0, v[140:141]
	global_store_dwordx2 v[172:173], v[120:121], off
	v_exp_f32_e64 v114, -v108
	v_exp_f32_e64 v115, -v109
	v_exp_f32_e64 v116, -v110
	v_exp_f32_e64 v117, -v111
	v_add_f32_e32 v114, 1.0, v114
	v_add_f32_e32 v115, 1.0, v115
	v_add_f32_e32 v116, 1.0, v116
	v_add_f32_e32 v117, 1.0, v117
	v_rcp_f32_e32 v114, v114
	v_rcp_f32_e32 v115, v115
	v_rcp_f32_e32 v116, v116
	v_rcp_f32_e32 v117, v117
	v_pk_mul_f32 v[106:107], v[110:111], v[106:107]
	v_pk_mul_f32 v[104:105], v[108:109], v[104:105]
	v_pk_mul_f32 v[104:105], v[104:105], v[114:115]
	v_pk_mul_f32 v[106:107], v[106:107], v[116:117]
	v_cvt_pk_bf16_f32 v104, v104, v105
	v_cvt_pk_bf16_f32 v105, v106, v107
	v_or_b32_e32 v112, 16, v170
	v_mad_i64_i32 v[112:113], s[34:35], v112, s82, v[142:143]
	v_lshl_add_u64 v[112:113], v[112:113], 0, v[140:141]
	global_store_dwordx2 v[112:113], v[104:105], off
	v_exp_f32_e64 v98, -v92
	v_exp_f32_e64 v99, -v93
	v_exp_f32_e64 v100, -v94
	v_exp_f32_e64 v101, -v95
	v_add_f32_e32 v98, 1.0, v98
	v_add_f32_e32 v99, 1.0, v99
	v_add_f32_e32 v100, 1.0, v100
	v_add_f32_e32 v101, 1.0, v101
	v_rcp_f32_e32 v98, v98
	v_rcp_f32_e32 v99, v99
	v_rcp_f32_e32 v100, v100
	v_rcp_f32_e32 v101, v101
	v_pk_mul_f32 v[90:91], v[94:95], v[90:91]
	v_pk_mul_f32 v[88:89], v[92:93], v[88:89]
	v_pk_mul_f32 v[88:89], v[88:89], v[98:99]
	v_pk_mul_f32 v[90:91], v[90:91], v[100:101]
	v_cvt_pk_bf16_f32 v88, v88, v89
	v_cvt_pk_bf16_f32 v89, v90, v91
	v_or_b32_e32 v96, 32, v170
	v_mad_i64_i32 v[96:97], s[34:35], v96, s82, v[142:143]
	v_lshl_add_u64 v[96:97], v[96:97], 0, v[140:141]
	global_store_dwordx2 v[96:97], v[88:89], off
	v_exp_f32_e64 v82, -v76
	v_exp_f32_e64 v83, -v77
	v_exp_f32_e64 v84, -v78
	v_exp_f32_e64 v85, -v79
	v_add_f32_e32 v82, 1.0, v82
	v_add_f32_e32 v83, 1.0, v83
	v_add_f32_e32 v84, 1.0, v84
	v_add_f32_e32 v85, 1.0, v85
	v_rcp_f32_e32 v82, v82
	v_rcp_f32_e32 v83, v83
	v_rcp_f32_e32 v84, v84
	v_rcp_f32_e32 v85, v85
	v_pk_mul_f32 v[74:75], v[78:79], v[74:75]
	v_pk_mul_f32 v[72:73], v[76:77], v[72:73]
	v_pk_mul_f32 v[72:73], v[72:73], v[82:83]
	v_pk_mul_f32 v[74:75], v[74:75], v[84:85]
	v_cvt_pk_bf16_f32 v72, v72, v73
	v_cvt_pk_bf16_f32 v73, v74, v75
	v_or_b32_e32 v80, 48, v170
	v_mad_i64_i32 v[80:81], s[34:35], v80, s82, v[142:143]
	v_lshl_add_u64 v[80:81], v[80:81], 0, v[140:141]
	global_store_dwordx2 v[80:81], v[72:73], off
	v_exp_f32_e64 v66, -v60
	v_exp_f32_e64 v67, -v61
	v_exp_f32_e64 v68, -v62
	v_exp_f32_e64 v69, -v63
	v_add_f32_e32 v66, 1.0, v66
	v_add_f32_e32 v67, 1.0, v67
	v_add_f32_e32 v68, 1.0, v68
	v_add_f32_e32 v69, 1.0, v69
	v_rcp_f32_e32 v66, v66
	v_rcp_f32_e32 v67, v67
	v_rcp_f32_e32 v68, v68
	v_rcp_f32_e32 v69, v69
	v_pk_mul_f32 v[58:59], v[62:63], v[58:59]
	v_pk_mul_f32 v[56:57], v[60:61], v[56:57]
	v_pk_mul_f32 v[56:57], v[56:57], v[66:67]
	v_pk_mul_f32 v[58:59], v[58:59], v[68:69]
	v_cvt_pk_bf16_f32 v56, v56, v57
	v_cvt_pk_bf16_f32 v57, v58, v59
	v_add_u32_e32 v64, 0x80, v170
	v_mad_i64_i32 v[64:65], s[34:35], v64, s82, v[142:143]
	v_lshl_add_u64 v[64:65], v[64:65], 0, v[140:141]
	global_store_dwordx2 v[64:65], v[56:57], off
	v_exp_f32_e64 v50, -v44
	v_exp_f32_e64 v51, -v45
	v_exp_f32_e64 v52, -v46
	v_exp_f32_e64 v53, -v47
	v_add_f32_e32 v50, 1.0, v50
	v_add_f32_e32 v51, 1.0, v51
	v_add_f32_e32 v52, 1.0, v52
	v_add_f32_e32 v53, 1.0, v53
	v_rcp_f32_e32 v50, v50
	v_rcp_f32_e32 v51, v51
	v_rcp_f32_e32 v52, v52
	v_rcp_f32_e32 v53, v53
	v_pk_mul_f32 v[42:43], v[46:47], v[42:43]
	v_pk_mul_f32 v[40:41], v[44:45], v[40:41]
	v_pk_mul_f32 v[40:41], v[40:41], v[50:51]
	v_pk_mul_f32 v[42:43], v[42:43], v[52:53]
	v_cvt_pk_bf16_f32 v40, v40, v41
	v_cvt_pk_bf16_f32 v41, v42, v43
	v_add_u32_e32 v48, 0x90, v170
	v_mad_i64_i32 v[48:49], s[34:35], v48, s82, v[142:143]
	v_lshl_add_u64 v[48:49], v[48:49], 0, v[140:141]
	global_store_dwordx2 v[48:49], v[40:41], off
	v_exp_f32_e64 v34, -v28
	v_exp_f32_e64 v35, -v29
	v_exp_f32_e64 v36, -v30
	v_exp_f32_e64 v37, -v31
	v_add_f32_e32 v34, 1.0, v34
	v_add_f32_e32 v35, 1.0, v35
	v_add_f32_e32 v36, 1.0, v36
	v_add_f32_e32 v37, 1.0, v37
	v_rcp_f32_e32 v34, v34
	v_rcp_f32_e32 v35, v35
	v_rcp_f32_e32 v36, v36
	v_rcp_f32_e32 v37, v37
	v_pk_mul_f32 v[26:27], v[30:31], v[26:27]
	v_pk_mul_f32 v[24:25], v[28:29], v[24:25]
	v_pk_mul_f32 v[24:25], v[24:25], v[34:35]
	v_pk_mul_f32 v[26:27], v[26:27], v[36:37]
	v_cvt_pk_bf16_f32 v24, v24, v25
	v_cvt_pk_bf16_f32 v25, v26, v27
	v_add_u32_e32 v32, 0xa0, v170
	v_mad_i64_i32 v[32:33], s[34:35], v32, s82, v[142:143]
	v_lshl_add_u64 v[32:33], v[32:33], 0, v[140:141]
	global_store_dwordx2 v[32:33], v[24:25], off
	v_exp_f32_e64 v18, -v12
	v_exp_f32_e64 v19, -v13
	v_exp_f32_e64 v20, -v14
	v_exp_f32_e64 v21, -v15
	v_add_f32_e32 v18, 1.0, v18
	v_add_f32_e32 v19, 1.0, v19
	v_add_f32_e32 v20, 1.0, v20
	v_add_f32_e32 v21, 1.0, v21
	v_rcp_f32_e32 v18, v18
	v_rcp_f32_e32 v19, v19
	v_rcp_f32_e32 v20, v20
	v_rcp_f32_e32 v21, v21
	v_pk_mul_f32 v[10:11], v[14:15], v[10:11]
	v_pk_mul_f32 v[8:9], v[12:13], v[8:9]
	v_pk_mul_f32 v[8:9], v[8:9], v[18:19]
	v_pk_mul_f32 v[10:11], v[10:11], v[20:21]
	v_cvt_pk_bf16_f32 v8, v8, v9
	v_cvt_pk_bf16_f32 v9, v10, v11
	v_add_u32_e32 v16, 0xb0, v170
	v_mad_i64_i32 v[16:17], s[34:35], v16, s82, v[142:143]
	v_lshl_add_u64 v[16:17], v[16:17], 0, v[140:141]
	global_store_dwordx2 v[16:17], v[8:9], off
	s_and_b64 vcc, exec, s[2:3]
	s_mov_b32 s86, s83
	s_mov_b32 s85, s84
	s_mov_b64 s[36:37], s[0:1]
	s_mov_b64 s[34:35], s[4:5]

; #define PG8_STAGE(bufoff, gbase, voff) do { _Pragma("unroll") for (int _i = 0; _i < 2; ++_i) \
;         __builtin_amdgcn_global_load_lds((const unsigned*)((const char*)(gbase) + (voff)[_i]), (PG8_LAS unsigned*)(lds + (bufoff) + ldsw + _i * 8192), 16, 0, 0); } while (0)
; template <class Epi, class Sched, bool STAMP = false>
; __device__ __forceinline__ void gemm_phase(PG8_LAS unsigned char* lds, const Gemm g, const Sched& S, const Epi& E, unsigned long long* stamps) {
;     ...
;     for (;;) {
;         const bool has_next = S.next(ui + 1, nxt);
;         const char* nA = has_next ? (const char*)g.A + (size_t)nxt.pm * tstep : cA; const char* nB = has_next ? (const char*)g.Bt + (size_t)nxt.pn * tstep : cB;
;         for (int t = 0; t < nt; t += 2) {
;             const bool last = (t == nt - 2);
;             const char* a1 = cA + (size_t)(t + 1) * kstep;
;             const char* a2 = last ? nA : cA + (size_t)(t + 2) * kstep; const char* b2 = last ? nB : cB + (size_t)(t + 2) * kstep;
;             const char* a3 = a2 + kstep; const char* b3 = b2 + kstep;
;             if (last && has_next) S.a_ready(nxt);
;             PG8_LDB(B0, 0, 0); PG8_SCHED; PG8_LDA(At, 0, 0); PG8_STAGE(PG8_SA(1, 1), a1 + hstep, voffA);
;             PG8_WAIT_L(8); PG8_BAR; PG8_WAIT_L(0); PG8_MMA(0, 0, At, B0); PG8_BAR; PG8_SCHED;
;             PG8_LDB(B1, 0, 1); PG8_STAGE(PG8_SB(0, 0), b2, voffB);
;             PG8_BAR; PG8_WAIT_L(0); PG8_MMA(0, 1, At, B1); PG8_BAR;
;             PG8_LDA(At, 0, 1); PG8_STAGE(PG8_SA(0, 0), a2, voffA);
;             PG8_BAR; PG8_WAIT_L(0); PG8_MMA(1, 0, At, B0); PG8_BAR; PG8_SCHED;
;             PG8_STAGE(PG8_SB(0, 1), b2 + hstep, voffB);
;             PG8_WAIT_V(6); PG8_BAR; PG8_MMA(1, 1, At, B1); PG8_BAR;
;             PG8_LDB(B0, 1, 0); PG8_SCHED; PG8_LDA(At, 1, 0); PG8_STAGE(PG8_SA(0, 1), a2 + hstep, voffA);
;             PG8_WAIT_L(8); PG8_BAR; PG8_WAIT_L(0); PG8_MMA(0, 0, At, B0); PG8_BAR; PG8_SCHED;
;             PG8_LDB(B1, 1, 1); PG8_STAGE(PG8_SB(1, 0), b3, voffB);
;             PG8_BAR; PG8_WAIT_L(0); PG8_MMA(0, 1, At, B1); PG8_BAR;
;             PG8_LDA(At, 1, 1); PG8_STAGE(PG8_SA(1, 0), a3, voffA);
;             PG8_BAR; PG8_WAIT_L(0); PG8_MMA(1, 0, At, B0); PG8_BAR; PG8_SCHED;
;             PG8_STAGE(PG8_SB(1, 1), b3 + hstep, voffB);
;             PG8_WAIT_V(6); PG8_BAR; PG8_MMA(1, 1, At, B1); PG8_BAR;
.LBB0_384:
	s_add_u32 vcc_lo, s58, 0x100
	s_addc_u32 vcc_hi, s59, 0
	s_mov_b32 s10, -2
	ds_read_b128 v[170:173], v147
	ds_read_b128 v[174:177], v148
	ds_read_b128 v[178:181], v149
	ds_read_b128 v[182:185], v150
	s_add_u32 s58, s56, 0x100
	s_addc_u32 s59, s57, 0
	s_cmp_eq_u32 s10, 40
	s_cselect_b32 s63, s5, s59
	s_cselect_b32 s62, s4, s58
	s_cselect_b32 s61, s1, vcc_hi
	s_cselect_b32 s60, s0, vcc_lo
	s_mov_b32 m0, s88
	ds_read_b128 v[186:189], v145
	ds_read_b128 v[190:193], v145 offset:1024
	ds_read_b128 v[194:197], v145 offset:2048
	ds_read_b128 v[198:201], v145 offset:3072
	ds_read_b128 v[202:205], v145 offset:4096
	ds_read_b128 v[206:209], v145 offset:5120
	ds_read_b128 v[210:213], v145 offset:6144
	ds_read_b128 v[214:217], v145 offset:7168
	global_load_lds_dwordx4 v136, s[56:57]
	s_mov_b32 m0, s89
	s_nop 0
	global_load_lds_dwordx4 v138, s[56:57]
	s_waitcnt lgkmcnt(8)
	s_barrier
	s_waitcnt lgkmcnt(0)
	s_setprio 1
	s_waitcnt lgkmcnt(0)
	v_mfma_f32_16x16x32_bf16 v[124:127], v[170:173], v[186:189], 0
	v_mfma_f32_16x16x32_bf16 v[120:123], v[178:181], v[186:189], 0
	v_mfma_f32_16x16x32_bf16 v[116:119], v[170:173], v[194:197], 0
	v_mfma_f32_16x16x32_bf16 v[112:115], v[178:181], v[194:197], 0
	v_mfma_f32_16x16x32_bf16 v[100:103], v[170:173], v[202:205], 0
	v_mfma_f32_16x16x32_bf16 v[96:99], v[178:181], v[202:205], 0
	v_mfma_f32_16x16x32_bf16 v[84:87], v[170:173], v[210:213], 0
	v_mfma_f32_16x16x32_bf16 v[80:83], v[178:181], v[210:213], 0
	v_mfma_f32_16x16x32_bf16 v[124:127], v[174:177], v[190:193], v[124:127]
	v_mfma_f32_16x16x32_bf16 v[120:123], v[182:185], v[190:193], v[120:123]
	v_mfma_f32_16x16x32_bf16 v[116:119], v[174:177], v[198:201], v[116:119]
	v_mfma_f32_16x16x32_bf16 v[112:115], v[182:185], v[198:201], v[112:115]
	v_mfma_f32_16x16x32_bf16 v[100:103], v[174:177], v[206:209], v[100:103]
	v_mfma_f32_16x16x32_bf16 v[96:99], v[182:185], v[206:209], v[96:99]
	v_mfma_f32_16x16x32_bf16 v[84:87], v[174:177], v[214:217], v[84:87]
	v_mfma_f32_16x16x32_bf16 v[80:83], v[182:185], v[214:217], v[80:83]
	s_setprio 0
	s_barrier
	s_mov_b32 m0, s68
	ds_read_b128 v[218:221], v151
	ds_read_b128 v[222:225], v152
	ds_read_b128 v[226:229], v153
	ds_read_b128 v[230:233], v154
	global_load_lds_dwordx4 v130, s[60:61]
	s_mov_b32 m0, s69
	s_nop 0
	global_load_lds_dwordx4 v134, s[60:61]
	s_waitcnt lgkmcnt(0)
	s_barrier
	s_waitcnt lgkmcnt(0)
	s_setprio 1
	s_waitcnt lgkmcnt(0)
	v_mfma_f32_16x16x32_bf16 v[108:111], v[218:221], v[186:189], 0
	v_mfma_f32_16x16x32_bf16 v[104:107], v[226:229], v[186:189], 0
	v_mfma_f32_16x16x32_bf16 v[92:95], v[218:221], v[194:197], 0
	v_mfma_f32_16x16x32_bf16 v[88:91], v[226:229], v[194:197], 0
	v_mfma_f32_16x16x32_bf16 v[76:79], v[218:221], v[202:205], 0
	v_mfma_f32_16x16x32_bf16 v[72:75], v[226:229], v[202:205], 0
	v_mfma_f32_16x16x32_bf16 v[68:71], v[218:221], v[210:213], 0
	v_mfma_f32_16x16x32_bf16 v[64:67], v[226:229], v[210:213], 0
	v_mfma_f32_16x16x32_bf16 v[108:111], v[222:225], v[190:193], v[108:111]
	v_mfma_f32_16x16x32_bf16 v[104:107], v[230:233], v[190:193], v[104:107]
	v_mfma_f32_16x16x32_bf16 v[92:95], v[222:225], v[198:201], v[92:95]
	v_mfma_f32_16x16x32_bf16 v[88:91], v[230:233], v[198:201], v[88:91]
	v_mfma_f32_16x16x32_bf16 v[76:79], v[222:225], v[206:209], v[76:79]
	v_mfma_f32_16x16x32_bf16 v[72:75], v[230:233], v[206:209], v[72:75]
	v_mfma_f32_16x16x32_bf16 v[68:71], v[222:225], v[214:217], v[68:71]
	v_mfma_f32_16x16x32_bf16 v[64:67], v[230:233], v[214:217], v[64:67]
	s_setprio 0
	s_mov_b32 m0, s67
	s_barrier
	ds_read_b128 v[186:189], v145 offset:16384
	ds_read_b128 v[190:193], v145 offset:17408
	ds_read_b128 v[194:197], v145 offset:18432
	ds_read_b128 v[198:201], v145 offset:19456
	ds_read_b128 v[202:205], v145 offset:20480
	ds_read_b128 v[206:209], v145 offset:21504
	ds_read_b128 v[210:213], v145 offset:22528
	ds_read_b128 v[214:217], v145 offset:23552
	global_load_lds_dwordx4 v128, s[62:63]
	s_mov_b32 m0, s70
	s_nop 0
	global_load_lds_dwordx4 v132, s[62:63]
	s_add_u32 s56, s60, 0xb4000
	s_addc_u32 s57, s61, 0
	s_mov_b32 m0, s71
	s_nop 0
	global_load_lds_dwordx4 v130, s[56:57]
	s_mov_b32 m0, s75
	s_nop 0
	global_load_lds_dwordx4 v134, s[56:57]
	s_waitcnt vmcnt(6)
	s_barrier
	s_waitcnt lgkmcnt(0)
	s_setprio 1
	s_waitcnt lgkmcnt(0)
	v_mfma_f32_16x16x32_bf16 v[60:63], v[170:173], v[186:189], 0
	v_mfma_f32_16x16x32_bf16 v[56:59], v[178:181], v[186:189], 0
	v_mfma_f32_16x16x32_bf16 v[52:55], v[170:173], v[194:197], 0
	v_mfma_f32_16x16x32_bf16 v[48:51], v[178:181], v[194:197], 0
	v_mfma_f32_16x16x32_bf16 v[36:39], v[170:173], v[202:205], 0
	v_mfma_f32_16x16x32_bf16 v[32:35], v[178:181], v[202:205], 0
	v_mfma_f32_16x16x32_bf16 v[20:23], v[170:173], v[210:213], 0
	v_mfma_f32_16x16x32_bf16 v[16:19], v[178:181], v[210:213], 0
	v_mfma_f32_16x16x32_bf16 v[60:63], v[174:177], v[190:193], v[60:63]
	v_mfma_f32_16x16x32_bf16 v[56:59], v[182:185], v[190:193], v[56:59]
	v_mfma_f32_16x16x32_bf16 v[52:55], v[174:177], v[198:201], v[52:55]
	v_mfma_f32_16x16x32_bf16 v[48:51], v[182:185], v[198:201], v[48:51]
	v_mfma_f32_16x16x32_bf16 v[36:39], v[174:177], v[206:209], v[36:39]
	v_mfma_f32_16x16x32_bf16 v[32:35], v[182:185], v[206:209], v[32:35]
	v_mfma_f32_16x16x32_bf16 v[20:23], v[174:177], v[214:217], v[20:23]
	v_mfma_f32_16x16x32_bf16 v[16:19], v[182:185], v[214:217], v[16:19]
	v_mfma_f32_16x16x32_bf16 v[44:47], v[218:221], v[186:189], 0
	v_mfma_f32_16x16x32_bf16 v[40:43], v[226:229], v[186:189], 0
	v_mfma_f32_16x16x32_bf16 v[28:31], v[218:221], v[194:197], 0
	v_mfma_f32_16x16x32_bf16 v[24:27], v[226:229], v[194:197], 0
	v_mfma_f32_16x16x32_bf16 v[12:15], v[218:221], v[202:205], 0
	v_mfma_f32_16x16x32_bf16 v[8:11], v[226:229], v[202:205], 0
	v_mfma_f32_16x16x32_bf16 v[4:7], v[218:221], v[210:213], 0
	v_mfma_f32_16x16x32_bf16 v[0:3], v[226:229], v[210:213], 0
	v_mfma_f32_16x16x32_bf16 v[44:47], v[222:225], v[190:193], v[44:47]
	v_mfma_f32_16x16x32_bf16 v[40:43], v[230:233], v[190:193], v[40:43]
	v_mfma_f32_16x16x32_bf16 v[28:31], v[222:225], v[198:201], v[28:31]
	v_mfma_f32_16x16x32_bf16 v[24:27], v[230:233], v[198:201], v[24:27]
	v_mfma_f32_16x16x32_bf16 v[12:15], v[222:225], v[206:209], v[12:15]
	v_mfma_f32_16x16x32_bf16 v[8:11], v[230:233], v[206:209], v[8:11]
	v_mfma_f32_16x16x32_bf16 v[4:7], v[222:225], v[214:217], v[4:7]
	v_mfma_f32_16x16x32_bf16 v[0:3], v[230:233], v[214:217], v[0:3]
	s_setprio 0
	s_barrier
	s_branch .Lzp6_mid
; #define PG8_STAGE(bufoff, gbase, voff) do { _Pragma("unroll") for (int _i = 0; _i < 2; ++_i) \
;         __builtin_amdgcn_global_load_lds((const unsigned*)((const char*)(gbase) + (voff)[_i]), (PG8_LAS unsigned*)(lds + (bufoff) + ldsw + _i * 8192), 16, 0, 0); } while (0)
; #define PG8_LDA(dst, b, h) do { _Pragma("unroll") for (int m = 0; m < 4; ++m) _Pragma("unroll") for (int k = 0; k < 2; ++k) dst[m][k] = *(const PG8_LAS bf16x8*)(lds + PG8_SA(b, h) + aoff + m * 2048 + k * 1024); } while (0)
; #define PG8_BAR __builtin_amdgcn_s_barrier()
; template <class Epi, class Sched, bool STAMP = false>
; __device__ __forceinline__ void gemm_phase(PG8_LAS unsigned char* lds, const Gemm g, const Sched& S, const Epi& E, unsigned long long* stamps) {
;     ...
;         for (int t = 0; t < nt; t += 2) {
;             const bool last = (t == nt - 2);
;             const char* a1 = cA + (size_t)(t + 1) * kstep;
;             const char* a2 = last ? nA : cA + (size_t)(t + 2) * kstep; const char* b2 = last ? nB : cB + (size_t)(t + 2) * kstep;
;             const char* a3 = a2 + kstep; const char* b3 = b2 + kstep;
;             if (last && has_next) S.a_ready(nxt);
;             PG8_LDB(B0, 0, 0); PG8_SCHED; PG8_LDA(At, 0, 0); PG8_STAGE(PG8_SA(1, 1), a1 + hstep, voffA);
;             PG8_WAIT_L(8); PG8_BAR; PG8_WAIT_L(0); PG8_MMA(0, 0, At, B0); PG8_BAR; PG8_SCHED;
;             PG8_LDB(B1, 0, 1); PG8_STAGE(PG8_SB(0, 0), b2, voffB);
;             PG8_BAR; PG8_WAIT_L(0); PG8_MMA(0, 1, At, B1); PG8_BAR;
;             PG8_LDA(At, 0, 1); PG8_STAGE(PG8_SA(0, 0), a2, voffA);
;             PG8_BAR; PG8_WAIT_L(0); PG8_MMA(1, 0, At, B0); PG8_BAR; PG8_SCHED;
;             PG8_STAGE(PG8_SB(0, 1), b2 + hstep, voffB);
;             PG8_WAIT_V(6); PG8_BAR; PG8_MMA(1, 1, At, B1); PG8_BAR;
;             PG8_LDB(B0, 1, 0); PG8_SCHED; PG8_LDA(At, 1, 0); PG8_STAGE(PG8_SA(0, 1), a2 + hstep, voffA);
;             PG8_WAIT_L(8); PG8_BAR; PG8_WAIT_L(0); PG8_MMA(0, 0, At, B0); PG8_BAR; PG8_SCHED;
;             PG8_LDB(B1, 1, 1); PG8_STAGE(PG8_SB(1, 0), b3, voffB);
;             PG8_BAR; PG8_WAIT_L(0); PG8_MMA(0, 1, At, B1); PG8_BAR;
;             PG8_LDA(At, 1, 1); PG8_STAGE(PG8_SA(1, 0), a3, voffA);
;             PG8_BAR; PG8_WAIT_L(0); PG8_MMA(1, 0, At, B0); PG8_BAR; PG8_SCHED;
;             PG8_STAGE(PG8_SB(1, 1), b3 + hstep, voffB);
;             PG8_WAIT_V(6); PG8_BAR; PG8_MMA(1, 1, At, B1); PG8_BAR;
.LBB0_385:
	ds_read_b128 v[170:173], v147
	ds_read_b128 v[174:177], v148
	ds_read_b128 v[178:181], v149
	ds_read_b128 v[182:185], v150
	s_add_u32 s58, s56, 0x100
	s_addc_u32 s59, s57, 0
	s_cmp_eq_u32 s10, 40
	s_cselect_b32 s63, s5, s59
	s_cselect_b32 s62, s4, s58
	s_cselect_b32 s61, s1, vcc_hi
	s_cselect_b32 s60, s0, vcc_lo
	s_mov_b32 m0, s88
	ds_read_b128 v[186:189], v145
	ds_read_b128 v[190:193], v145 offset:1024
	ds_read_b128 v[194:197], v145 offset:2048
	ds_read_b128 v[198:201], v145 offset:3072
	ds_read_b128 v[202:205], v145 offset:4096
	ds_read_b128 v[206:209], v145 offset:5120
	ds_read_b128 v[210:213], v145 offset:6144
	ds_read_b128 v[214:217], v145 offset:7168
	global_load_lds_dwordx4 v136, s[56:57]
	s_mov_b32 m0, s89
	s_nop 0
	global_load_lds_dwordx4 v138, s[56:57]
	s_waitcnt lgkmcnt(8)
	s_barrier
	s_waitcnt lgkmcnt(0)
	s_setprio 1
	s_waitcnt lgkmcnt(0)
	v_mfma_f32_16x16x32_bf16 v[124:127], v[170:173], v[186:189], v[124:127]
	v_mfma_f32_16x16x32_bf16 v[120:123], v[178:181], v[186:189], v[120:123]
	v_mfma_f32_16x16x32_bf16 v[116:119], v[170:173], v[194:197], v[116:119]
	v_mfma_f32_16x16x32_bf16 v[112:115], v[178:181], v[194:197], v[112:115]
	v_mfma_f32_16x16x32_bf16 v[100:103], v[170:173], v[202:205], v[100:103]
	v_mfma_f32_16x16x32_bf16 v[96:99], v[178:181], v[202:205], v[96:99]
	v_mfma_f32_16x16x32_bf16 v[84:87], v[170:173], v[210:213], v[84:87]
	v_mfma_f32_16x16x32_bf16 v[80:83], v[178:181], v[210:213], v[80:83]
	v_mfma_f32_16x16x32_bf16 v[124:127], v[174:177], v[190:193], v[124:127]
	v_mfma_f32_16x16x32_bf16 v[120:123], v[182:185], v[190:193], v[120:123]
	v_mfma_f32_16x16x32_bf16 v[116:119], v[174:177], v[198:201], v[116:119]
	v_mfma_f32_16x16x32_bf16 v[112:115], v[182:185], v[198:201], v[112:115]
	v_mfma_f32_16x16x32_bf16 v[100:103], v[174:177], v[206:209], v[100:103]
	v_mfma_f32_16x16x32_bf16 v[96:99], v[182:185], v[206:209], v[96:99]
	v_mfma_f32_16x16x32_bf16 v[84:87], v[174:177], v[214:217], v[84:87]
	v_mfma_f32_16x16x32_bf16 v[80:83], v[182:185], v[214:217], v[80:83]
	s_setprio 0
	s_barrier
	s_mov_b32 m0, s68
	ds_read_b128 v[218:221], v151
	ds_read_b128 v[222:225], v152
	ds_read_b128 v[226:229], v153
	ds_read_b128 v[230:233], v154
	global_load_lds_dwordx4 v130, s[60:61]
	s_mov_b32 m0, s69
	s_nop 0
	global_load_lds_dwordx4 v134, s[60:61]
	s_waitcnt lgkmcnt(0)
	s_barrier
	s_waitcnt lgkmcnt(0)
	s_setprio 1
	s_waitcnt lgkmcnt(0)
	v_mfma_f32_16x16x32_bf16 v[108:111], v[218:221], v[186:189], v[108:111]
	v_mfma_f32_16x16x32_bf16 v[104:107], v[226:229], v[186:189], v[104:107]
	v_mfma_f32_16x16x32_bf16 v[92:95], v[218:221], v[194:197], v[92:95]
	v_mfma_f32_16x16x32_bf16 v[88:91], v[226:229], v[194:197], v[88:91]
	v_mfma_f32_16x16x32_bf16 v[76:79], v[218:221], v[202:205], v[76:79]
	v_mfma_f32_16x16x32_bf16 v[72:75], v[226:229], v[202:205], v[72:75]
	v_mfma_f32_16x16x32_bf16 v[68:71], v[218:221], v[210:213], v[68:71]
	v_mfma_f32_16x16x32_bf16 v[64:67], v[226:229], v[210:213], v[64:67]
	v_mfma_f32_16x16x32_bf16 v[108:111], v[222:225], v[190:193], v[108:111]
	v_mfma_f32_16x16x32_bf16 v[104:107], v[230:233], v[190:193], v[104:107]
	v_mfma_f32_16x16x32_bf16 v[92:95], v[222:225], v[198:201], v[92:95]
	v_mfma_f32_16x16x32_bf16 v[88:91], v[230:233], v[198:201], v[88:91]
	v_mfma_f32_16x16x32_bf16 v[76:79], v[222:225], v[206:209], v[76:79]
	v_mfma_f32_16x16x32_bf16 v[72:75], v[230:233], v[206:209], v[72:75]
	v_mfma_f32_16x16x32_bf16 v[68:71], v[222:225], v[214:217], v[68:71]
	v_mfma_f32_16x16x32_bf16 v[64:67], v[230:233], v[214:217], v[64:67]
	s_setprio 0
	s_mov_b32 m0, s67
	s_barrier
	ds_read_b128 v[186:189], v145 offset:16384
	ds_read_b128 v[190:193], v145 offset:17408
	ds_read_b128 v[194:197], v145 offset:18432
	ds_read_b128 v[198:201], v145 offset:19456
	ds_read_b128 v[202:205], v145 offset:20480
	ds_read_b128 v[206:209], v145 offset:21504
	ds_read_b128 v[210:213], v145 offset:22528
	ds_read_b128 v[214:217], v145 offset:23552
	global_load_lds_dwordx4 v128, s[62:63]
	s_mov_b32 m0, s70
	s_nop 0
	global_load_lds_dwordx4 v132, s[62:63]
	s_add_u32 s56, s60, 0xb4000
	s_addc_u32 s57, s61, 0
	s_mov_b32 m0, s71
	s_nop 0
	global_load_lds_dwordx4 v130, s[56:57]
	s_mov_b32 m0, s75
	s_nop 0
	global_load_lds_dwordx4 v134, s[56:57]
	s_waitcnt vmcnt(6)
	s_barrier
	s_waitcnt lgkmcnt(0)
	s_setprio 1
	s_waitcnt lgkmcnt(0)
	v_mfma_f32_16x16x32_bf16 v[60:63], v[170:173], v[186:189], v[60:63]
	v_mfma_f32_16x16x32_bf16 v[56:59], v[178:181], v[186:189], v[56:59]
	v_mfma_f32_16x16x32_bf16 v[52:55], v[170:173], v[194:197], v[52:55]
	v_mfma_f32_16x16x32_bf16 v[48:51], v[178:181], v[194:197], v[48:51]
	v_mfma_f32_16x16x32_bf16 v[36:39], v[170:173], v[202:205], v[36:39]
	v_mfma_f32_16x16x32_bf16 v[32:35], v[178:181], v[202:205], v[32:35]
	v_mfma_f32_16x16x32_bf16 v[20:23], v[170:173], v[210:213], v[20:23]
	v_mfma_f32_16x16x32_bf16 v[16:19], v[178:181], v[210:213], v[16:19]
	v_mfma_f32_16x16x32_bf16 v[60:63], v[174:177], v[190:193], v[60:63]
	v_mfma_f32_16x16x32_bf16 v[56:59], v[182:185], v[190:193], v[56:59]
	v_mfma_f32_16x16x32_bf16 v[52:55], v[174:177], v[198:201], v[52:55]
	v_mfma_f32_16x16x32_bf16 v[48:51], v[182:185], v[198:201], v[48:51]
	v_mfma_f32_16x16x32_bf16 v[36:39], v[174:177], v[206:209], v[36:39]
	v_mfma_f32_16x16x32_bf16 v[32:35], v[182:185], v[206:209], v[32:35]
	v_mfma_f32_16x16x32_bf16 v[20:23], v[174:177], v[214:217], v[20:23]
	v_mfma_f32_16x16x32_bf16 v[16:19], v[182:185], v[214:217], v[16:19]
	v_mfma_f32_16x16x32_bf16 v[44:47], v[218:221], v[186:189], v[44:47]
	v_mfma_f32_16x16x32_bf16 v[40:43], v[226:229], v[186:189], v[40:43]
	v_mfma_f32_16x16x32_bf16 v[28:31], v[218:221], v[194:197], v[28:31]
	v_mfma_f32_16x16x32_bf16 v[24:27], v[226:229], v[194:197], v[24:27]
	v_mfma_f32_16x16x32_bf16 v[12:15], v[218:221], v[202:205], v[12:15]
	v_mfma_f32_16x16x32_bf16 v[8:11], v[226:229], v[202:205], v[8:11]
	v_mfma_f32_16x16x32_bf16 v[4:7], v[218:221], v[210:213], v[4:7]
	v_mfma_f32_16x16x32_bf16 v[0:3], v[226:229], v[210:213], v[0:3]
	v_mfma_f32_16x16x32_bf16 v[44:47], v[222:225], v[190:193], v[44:47]
	v_mfma_f32_16x16x32_bf16 v[40:43], v[230:233], v[190:193], v[40:43]
	v_mfma_f32_16x16x32_bf16 v[28:31], v[222:225], v[198:201], v[28:31]
	v_mfma_f32_16x16x32_bf16 v[24:27], v[230:233], v[198:201], v[24:27]
	v_mfma_f32_16x16x32_bf16 v[12:15], v[222:225], v[206:209], v[12:15]
	v_mfma_f32_16x16x32_bf16 v[8:11], v[230:233], v[206:209], v[8:11]
	v_mfma_f32_16x16x32_bf16 v[4:7], v[222:225], v[214:217], v[4:7]
	v_mfma_f32_16x16x32_bf16 v[0:3], v[230:233], v[214:217], v[0:3]
	s_setprio 0
	s_barrier
; #define PG8_STAGE(bufoff, gbase, voff) do { _Pragma("unroll") for (int _i = 0; _i < 2; ++_i) \
;         __builtin_amdgcn_global_load_lds((const unsigned*)((const char*)(gbase) + (voff)[_i]), (PG8_LAS unsigned*)(lds + (bufoff) + ldsw + _i * 8192), 16, 0, 0); } while (0)
; #define PG8_LDA(dst, b, h) do { _Pragma("unroll") for (int m = 0; m < 4; ++m) _Pragma("unroll") for (int k = 0; k < 2; ++k) dst[m][k] = *(const PG8_LAS bf16x8*)(lds + PG8_SA(b, h) + aoff + m * 2048 + k * 1024); } while (0)
; #define PG8_BAR __builtin_amdgcn_s_barrier()
; template <class Epi, class Sched, bool STAMP = false>
; __device__ __forceinline__ void gemm_phase(PG8_LAS unsigned char* lds, const Gemm g, const Sched& S, const Epi& E, unsigned long long* stamps) {
;     ...
;         for (int t = 0; t < nt; t += 2) {
;             const bool last = (t == nt - 2);
;             const char* a1 = cA + (size_t)(t + 1) * kstep;
;             const char* a2 = last ? nA : cA + (size_t)(t + 2) * kstep; const char* b2 = last ? nB : cB + (size_t)(t + 2) * kstep;
;             const char* a3 = a2 + kstep; const char* b3 = b2 + kstep;
;             if (last && has_next) S.a_ready(nxt);
;             PG8_LDB(B0, 0, 0); PG8_SCHED; PG8_LDA(At, 0, 0); PG8_STAGE(PG8_SA(1, 1), a1 + hstep, voffA);
;             PG8_WAIT_L(8); PG8_BAR; PG8_WAIT_L(0); PG8_MMA(0, 0, At, B0); PG8_BAR; PG8_SCHED;
;             PG8_LDB(B1, 0, 1); PG8_STAGE(PG8_SB(0, 0), b2, voffB);
;             PG8_BAR; PG8_WAIT_L(0); PG8_MMA(0, 1, At, B1); PG8_BAR;
;             PG8_LDA(At, 0, 1); PG8_STAGE(PG8_SA(0, 0), a2, voffA);
;             PG8_BAR; PG8_WAIT_L(0); PG8_MMA(1, 0, At, B0); PG8_BAR; PG8_SCHED;
;             PG8_STAGE(PG8_SB(0, 1), b2 + hstep, voffB);
;             PG8_WAIT_V(6); PG8_BAR; PG8_MMA(1, 1, At, B1); PG8_BAR;
;             PG8_LDB(B0, 1, 0); PG8_SCHED; PG8_LDA(At, 1, 0); PG8_STAGE(PG8_SA(0, 1), a2 + hstep, voffA);
;             PG8_WAIT_L(8); PG8_BAR; PG8_WAIT_L(0); PG8_MMA(0, 0, At, B0); PG8_BAR; PG8_SCHED;
;             PG8_LDB(B1, 1, 1); PG8_STAGE(PG8_SB(1, 0), b3, voffB);
;             PG8_BAR; PG8_WAIT_L(0); PG8_MMA(0, 1, At, B1); PG8_BAR;
;             PG8_LDA(At, 1, 1); PG8_STAGE(PG8_SA(1, 0), a3, voffA);
;             PG8_BAR; PG8_WAIT_L(0); PG8_MMA(1, 0, At, B0); PG8_BAR; PG8_SCHED;
;             PG8_STAGE(PG8_SB(1, 1), b3 + hstep, voffB);
;             PG8_WAIT_V(6); PG8_BAR; PG8_MMA(1, 1, At, B1); PG8_BAR;
.Lzp6_mid:
	ds_read_b128 v[170:173], v155
	ds_read_b128 v[174:177], v156
	ds_read_b128 v[178:181], v157
	ds_read_b128 v[182:185], v165
	s_add_u32 s56, s62, 0xb4000
	s_addc_u32 s57, s63, 0
	s_mov_b32 m0, s76
	ds_read_b128 v[186:189], v145 offset:32768
	ds_read_b128 v[190:193], v145 offset:33792
	ds_read_b128 v[194:197], v145 offset:34816
	ds_read_b128 v[198:201], v145 offset:35840
	ds_read_b128 v[202:205], v145 offset:36864
	ds_read_b128 v[206:209], v145 offset:37888
	ds_read_b128 v[210:213], v145 offset:38912
	ds_read_b128 v[214:217], v145 offset:39936
	global_load_lds_dwordx4 v128, s[56:57]
	s_mov_b32 m0, s77
	s_nop 0
	global_load_lds_dwordx4 v132, s[56:57]
	s_waitcnt lgkmcnt(8)
	s_barrier
	s_waitcnt lgkmcnt(0)
	s_setprio 1
	s_waitcnt lgkmcnt(0)
	v_mfma_f32_16x16x32_bf16 v[124:127], v[170:173], v[186:189], v[124:127]
	v_mfma_f32_16x16x32_bf16 v[120:123], v[178:181], v[186:189], v[120:123]
	v_mfma_f32_16x16x32_bf16 v[116:119], v[170:173], v[194:197], v[116:119]
	v_mfma_f32_16x16x32_bf16 v[112:115], v[178:181], v[194:197], v[112:115]
	v_mfma_f32_16x16x32_bf16 v[100:103], v[170:173], v[202:205], v[100:103]
	v_mfma_f32_16x16x32_bf16 v[96:99], v[178:181], v[202:205], v[96:99]
	v_mfma_f32_16x16x32_bf16 v[84:87], v[170:173], v[210:213], v[84:87]
	v_mfma_f32_16x16x32_bf16 v[80:83], v[178:181], v[210:213], v[80:83]
	v_mfma_f32_16x16x32_bf16 v[124:127], v[174:177], v[190:193], v[124:127]
	v_mfma_f32_16x16x32_bf16 v[120:123], v[182:185], v[190:193], v[120:123]
	v_mfma_f32_16x16x32_bf16 v[116:119], v[174:177], v[198:201], v[116:119]
	v_mfma_f32_16x16x32_bf16 v[112:115], v[182:185], v[198:201], v[112:115]
	v_mfma_f32_16x16x32_bf16 v[100:103], v[174:177], v[206:209], v[100:103]
	v_mfma_f32_16x16x32_bf16 v[96:99], v[182:185], v[206:209], v[96:99]
	v_mfma_f32_16x16x32_bf16 v[84:87], v[174:177], v[214:217], v[84:87]
	v_mfma_f32_16x16x32_bf16 v[80:83], v[182:185], v[214:217], v[80:83]
	s_setprio 0
	s_barrier
	s_mov_b32 m0, s78
	ds_read_b128 v[218:221], v166
	ds_read_b128 v[222:225], v167
	ds_read_b128 v[226:229], v168
	ds_read_b128 v[230:233], v169
	s_add_u32 s100, s60, 0x80
	s_addc_u32 s101, s61, 0
	global_load_lds_dwordx4 v130, s[100:101]
	s_mov_b32 m0, s79
	s_nop 0
	global_load_lds_dwordx4 v134, s[100:101]
	s_waitcnt lgkmcnt(0)
	s_barrier
	s_waitcnt lgkmcnt(0)
	s_setprio 1
	s_waitcnt lgkmcnt(0)
	v_mfma_f32_16x16x32_bf16 v[108:111], v[218:221], v[186:189], v[108:111]
	v_mfma_f32_16x16x32_bf16 v[104:107], v[226:229], v[186:189], v[104:107]
	v_mfma_f32_16x16x32_bf16 v[92:95], v[218:221], v[194:197], v[92:95]
	v_mfma_f32_16x16x32_bf16 v[88:91], v[226:229], v[194:197], v[88:91]
	v_mfma_f32_16x16x32_bf16 v[76:79], v[218:221], v[202:205], v[76:79]
	v_mfma_f32_16x16x32_bf16 v[72:75], v[226:229], v[202:205], v[72:75]
	v_mfma_f32_16x16x32_bf16 v[68:71], v[218:221], v[210:213], v[68:71]
	v_mfma_f32_16x16x32_bf16 v[64:67], v[226:229], v[210:213], v[64:67]
	v_mfma_f32_16x16x32_bf16 v[108:111], v[222:225], v[190:193], v[108:111]
	v_mfma_f32_16x16x32_bf16 v[104:107], v[230:233], v[190:193], v[104:107]
	v_mfma_f32_16x16x32_bf16 v[92:95], v[222:225], v[198:201], v[92:95]
	v_mfma_f32_16x16x32_bf16 v[88:91], v[230:233], v[198:201], v[88:91]
	v_mfma_f32_16x16x32_bf16 v[76:79], v[222:225], v[206:209], v[76:79]
	v_mfma_f32_16x16x32_bf16 v[72:75], v[230:233], v[206:209], v[72:75]
	v_mfma_f32_16x16x32_bf16 v[68:71], v[222:225], v[214:217], v[68:71]
	v_mfma_f32_16x16x32_bf16 v[64:67], v[230:233], v[214:217], v[64:67]
	s_setprio 0
	s_mov_b32 m0, s82
	s_barrier
	ds_read_b128 v[186:189], v145 offset:49152
	ds_read_b128 v[190:193], v145 offset:50176
	ds_read_b128 v[194:197], v145 offset:51200
	ds_read_b128 v[198:201], v145 offset:52224
	ds_read_b128 v[202:205], v145 offset:53248
	ds_read_b128 v[206:209], v145 offset:54272
	ds_read_b128 v[210:213], v145 offset:55296
	ds_read_b128 v[214:217], v145 offset:56320
	s_add_u32 s100, s62, 0x80
	s_addc_u32 s101, s63, 0
	global_load_lds_dwordx4 v128, s[100:101]
	s_mov_b32 m0, s83
	s_nop 0
	global_load_lds_dwordx4 v132, s[100:101]
	s_add_u32 s56, s60, 0xb4080
	s_addc_u32 s57, s61, 0
	s_mov_b32 m0, s84
	s_nop 0
	global_load_lds_dwordx4 v130, s[56:57]
	s_mov_b32 m0, s85
	s_nop 0
	global_load_lds_dwordx4 v134, s[56:57]
	s_waitcnt vmcnt(6)
	s_barrier
	s_waitcnt lgkmcnt(0)
	s_setprio 1
	s_waitcnt lgkmcnt(0)
	v_mfma_f32_16x16x32_bf16 v[60:63], v[170:173], v[186:189], v[60:63]
	v_mfma_f32_16x16x32_bf16 v[56:59], v[178:181], v[186:189], v[56:59]
	v_mfma_f32_16x16x32_bf16 v[52:55], v[170:173], v[194:197], v[52:55]
	v_mfma_f32_16x16x32_bf16 v[48:51], v[178:181], v[194:197], v[48:51]
	v_mfma_f32_16x16x32_bf16 v[36:39], v[170:173], v[202:205], v[36:39]
	v_mfma_f32_16x16x32_bf16 v[32:35], v[178:181], v[202:205], v[32:35]
	v_mfma_f32_16x16x32_bf16 v[20:23], v[170:173], v[210:213], v[20:23]
	v_mfma_f32_16x16x32_bf16 v[16:19], v[178:181], v[210:213], v[16:19]
	v_mfma_f32_16x16x32_bf16 v[60:63], v[174:177], v[190:193], v[60:63]
	v_mfma_f32_16x16x32_bf16 v[56:59], v[182:185], v[190:193], v[56:59]
	v_mfma_f32_16x16x32_bf16 v[52:55], v[174:177], v[198:201], v[52:55]
	v_mfma_f32_16x16x32_bf16 v[48:51], v[182:185], v[198:201], v[48:51]
	v_mfma_f32_16x16x32_bf16 v[36:39], v[174:177], v[206:209], v[36:39]
	v_mfma_f32_16x16x32_bf16 v[32:35], v[182:185], v[206:209], v[32:35]
	v_mfma_f32_16x16x32_bf16 v[20:23], v[174:177], v[214:217], v[20:23]
	v_mfma_f32_16x16x32_bf16 v[16:19], v[182:185], v[214:217], v[16:19]
	v_mfma_f32_16x16x32_bf16 v[44:47], v[218:221], v[186:189], v[44:47]
	v_mfma_f32_16x16x32_bf16 v[40:43], v[226:229], v[186:189], v[40:43]
	v_mfma_f32_16x16x32_bf16 v[28:31], v[218:221], v[194:197], v[28:31]
	v_mfma_f32_16x16x32_bf16 v[24:27], v[226:229], v[194:197], v[24:27]
	v_mfma_f32_16x16x32_bf16 v[12:15], v[218:221], v[202:205], v[12:15]
	v_mfma_f32_16x16x32_bf16 v[8:11], v[226:229], v[202:205], v[8:11]
	v_mfma_f32_16x16x32_bf16 v[4:7], v[218:221], v[210:213], v[4:7]
	v_mfma_f32_16x16x32_bf16 v[0:3], v[226:229], v[210:213], v[0:3]
	v_mfma_f32_16x16x32_bf16 v[44:47], v[222:225], v[190:193], v[44:47]
	v_mfma_f32_16x16x32_bf16 v[40:43], v[230:233], v[190:193], v[40:43]
	v_mfma_f32_16x16x32_bf16 v[28:31], v[222:225], v[198:201], v[28:31]
	v_mfma_f32_16x16x32_bf16 v[24:27], v[230:233], v[198:201], v[24:27]
	v_mfma_f32_16x16x32_bf16 v[12:15], v[222:225], v[206:209], v[12:15]
	v_mfma_f32_16x16x32_bf16 v[8:11], v[230:233], v[206:209], v[8:11]
	v_mfma_f32_16x16x32_bf16 v[4:7], v[222:225], v[214:217], v[4:7]
	v_mfma_f32_16x16x32_bf16 v[0:3], v[230:233], v[214:217], v[0:3]
	s_setprio 0
	s_add_i32 s10, s10, 2
	s_add_u32 vcc_lo, vcc_lo, 0x100
	s_addc_u32 vcc_hi, vcc_hi, 0
	s_cmp_gt_u32 s10, 41
	s_mov_b64 s[56:57], s[58:59]
	s_barrier
; #define PG8_WAIT_V(n) asm volatile("s_waitcnt vmcnt(" #n ")" ::: "memory")
; #define PG8_BAR __builtin_amdgcn_s_barrier()
;     DI void operator()(const f32x4 (&acc)[2][2][4][2], const Unit& u, int wr, int wc, int fr, int fq) const {
;         const int row0 = u.pm * BM + wr * 64 + fr, col0 = u.pn * BM + wc * 32 + 8 * fq;
; #pragma unroll
;         for (int ai = 0; ai < 2; ++ai)
; #pragma unroll
;             for (int m = 0; m < 4; ++m) { u16* rowp = O + (size_t)(row0 + ai * HALF + m * 16) * ldc + col0;
; #pragma unroll
;                 for (int bj = 0; bj < 2; ++bj) { const f32x4 v0 = acc[ai][bj][m][0], v1 = acc[ai][bj][m][1];
;                     uint4 w = {pack2(v0[0], v0[1]), pack2(v0[2], v0[3]), pack2(v1[0], v1[1]), pack2(v1[2], v1[3])}; *(uint4*)(rowp + bj * HALF) = w; } }
; template <class Epi, class Sched, bool STAMP = false>
; __device__ __forceinline__ void gemm_phase(PG8_LAS unsigned char* lds, const Gemm g, const Sched& S, const Epi& E, unsigned long long* stamps) {
;     ...
;         if (!has_next) break;
; #pragma unroll
;         for (int a = 0; a < 2; ++a)
; #pragma unroll
;             for (int b = 0; b < 2; ++b)
; #pragma unroll
;                 for (int m = 0; m < 4; ++m)
; #pragma unroll
;                     for (int n = 0; n < 2; ++n) acc[a][b][m][n] = (f32x4){0.f, 0.f, 0.f, 0.f};
;         cur = nxt; cA = nA; cB = nB; ++ui;
;     }
;     PG8_WAIT_V(0);
;     if (wr == 0) PG8_BAR;
;     PG8_BAR;
	s_cbranch_scc0 .LBB0_385
	v_lshl_add_u32 v170, s94, 8, v144
	v_lshl_or_b32 v172, s97, 8, v146
	v_ashrrev_i32_e32 v171, 31, v170
	v_ashrrev_i32_e32 v173, 31, v172
	v_lshlrev_b64 v[174:175], 11, v[170:171]
	v_lshl_add_u64 v[174:175], s[14:15], 0, v[174:175]
	v_lshlrev_b64 v[172:173], 1, v[172:173]
	v_lshl_add_u64 v[174:175], v[174:175], 0, v[172:173]
	v_cvt_pk_bf16_f32 v60, v60, v61
	v_cvt_pk_bf16_f32 v61, v62, v63
	v_cvt_pk_bf16_f32 v62, v56, v57
	v_add_co_u32_e32 v56, vcc, s90, v174
	v_cvt_pk_bf16_f32 v68, v68, v69
	v_cvt_pk_bf16_f32 v69, v70, v71
	v_cvt_pk_bf16_f32 v70, v64, v65
	v_lshl_add_u64 v[64:65], v[174:175], 0, s[34:35]
	v_addc_co_u32_e32 v57, vcc, 0, v175, vcc
	v_cvt_pk_bf16_f32 v44, v44, v45
	v_cvt_pk_bf16_f32 v45, v46, v47
	v_cvt_pk_bf16_f32 v46, v40, v41
	v_cvt_pk_bf16_f32 v47, v42, v43
	v_cvt_pk_bf16_f32 v108, v108, v109
	v_cvt_pk_bf16_f32 v109, v110, v111
	v_cvt_pk_bf16_f32 v110, v104, v105
	v_or_b32_e32 v104, 16, v170
	global_store_dwordx4 v[64:65], v[44:47], off offset:256
	v_ashrrev_i32_e32 v105, 31, v104
	v_cvt_pk_bf16_f32 v92, v92, v93
	v_add_co_u32_e32 v46, vcc, s91, v174
	v_cvt_pk_bf16_f32 v93, v94, v95
	v_cvt_pk_bf16_f32 v94, v88, v89
	v_or_b32_e32 v88, 32, v170
	v_lshl_add_u64 v[44:45], v[174:175], 0, s[36:37]
	v_addc_co_u32_e32 v47, vcc, 0, v175, vcc
	v_cvt_pk_bf16_f32 v28, v28, v29
	v_cvt_pk_bf16_f32 v29, v30, v31
	v_cvt_pk_bf16_f32 v30, v24, v25
	v_cvt_pk_bf16_f32 v31, v26, v27
	v_lshlrev_b64 v[104:105], 11, v[104:105]
	v_ashrrev_i32_e32 v89, 31, v88
	v_cvt_pk_bf16_f32 v76, v76, v77
	v_cvt_pk_bf16_f32 v77, v78, v79
	v_cvt_pk_bf16_f32 v78, v72, v73
	v_or_b32_e32 v72, 48, v170
	global_store_dwordx4 v[44:45], v[28:31], off offset:256
	v_cvt_pk_bf16_f32 v111, v106, v107
	v_lshl_add_u64 v[104:105], s[14:15], 0, v[104:105]
	v_add_co_u32_e32 v30, vcc, s92, v174
	v_lshlrev_b64 v[88:89], 11, v[88:89]
	v_ashrrev_i32_e32 v73, 31, v72
	v_lshl_add_u64 v[28:29], v[174:175], 0, s[52:53]
	v_addc_co_u32_e32 v31, vcc, 0, v175, vcc
	v_cvt_pk_bf16_f32 v12, v12, v13
	v_cvt_pk_bf16_f32 v13, v14, v15
	v_cvt_pk_bf16_f32 v14, v8, v9
	v_cvt_pk_bf16_f32 v15, v10, v11
	global_store_dwordx4 v[174:175], v[108:111], off offset:256
	v_cvt_pk_bf16_f32 v95, v90, v91
	v_lshl_add_u64 v[88:89], s[14:15], 0, v[88:89]
	v_lshl_add_u64 v[108:109], v[104:105], 0, v[172:173]
	v_lshlrev_b64 v[72:73], 11, v[72:73]
	global_store_dwordx4 v[28:29], v[12:15], off offset:256
	global_store_dwordx4 v[108:109], v[92:95], off offset:256
	v_cvt_pk_bf16_f32 v79, v74, v75
	v_add_co_u32_e32 v14, vcc, s93, v174
	v_lshl_add_u64 v[92:93], v[88:89], 0, v[172:173]
	v_lshl_add_u64 v[72:73], s[14:15], 0, v[72:73]
	v_addc_co_u32_e32 v15, vcc, 0, v175, vcc
	v_cvt_pk_bf16_f32 v124, v124, v125
	v_cvt_pk_bf16_f32 v125, v126, v127
	v_cvt_pk_bf16_f32 v126, v120, v121
	v_cvt_pk_bf16_f32 v127, v122, v123
	v_cvt_pk_bf16_f32 v104, v116, v117
	v_cvt_pk_bf16_f32 v105, v118, v119
	v_cvt_pk_bf16_f32 v106, v112, v113
	v_cvt_pk_bf16_f32 v107, v114, v115
	v_cvt_pk_bf16_f32 v88, v100, v101
	v_cvt_pk_bf16_f32 v89, v102, v103
	v_cvt_pk_bf16_f32 v90, v96, v97
	v_cvt_pk_bf16_f32 v91, v98, v99
	global_store_dwordx4 v[92:93], v[76:79], off offset:256
	v_cvt_pk_bf16_f32 v74, v80, v81
	v_cvt_pk_bf16_f32 v75, v82, v83
	v_lshl_add_u64 v[76:77], v[72:73], 0, v[172:173]
	v_cvt_pk_bf16_f32 v72, v84, v85
	v_cvt_pk_bf16_f32 v73, v86, v87
	v_cvt_pk_bf16_f32 v71, v66, v67
	v_cvt_pk_bf16_f32 v63, v58, v59
	v_cvt_pk_bf16_f32 v40, v52, v53
	v_cvt_pk_bf16_f32 v41, v54, v55
	v_cvt_pk_bf16_f32 v42, v48, v49
	v_cvt_pk_bf16_f32 v43, v50, v51
	v_cvt_pk_bf16_f32 v24, v36, v37
	v_cvt_pk_bf16_f32 v25, v38, v39
	v_cvt_pk_bf16_f32 v26, v32, v33
	v_cvt_pk_bf16_f32 v27, v34, v35
	v_lshl_add_u64 v[12:13], v[174:175], 0, s[54:55]
	v_cvt_pk_bf16_f32 v8, v20, v21
	v_cvt_pk_bf16_f32 v9, v22, v23
	v_cvt_pk_bf16_f32 v10, v16, v17
	v_cvt_pk_bf16_f32 v11, v18, v19
	v_cvt_pk_bf16_f32 v4, v4, v5
	v_cvt_pk_bf16_f32 v5, v6, v7
	v_cvt_pk_bf16_f32 v6, v0, v1
	v_cvt_pk_bf16_f32 v7, v2, v3
	s_and_b64 vcc, exec, s[2:3]
	s_mov_b32 s97, s95
	s_mov_b32 s94, s96
	s_mov_b64 s[58:59], s[0:1]
	s_mov_b64 s[56:57], s[4:5]
	global_store_dwordx4 v[174:175], v[124:127], off
	global_store_dwordx4 v[108:109], v[104:107], off
	global_store_dwordx4 v[92:93], v[88:91], off
	global_store_dwordx4 v[76:77], v[72:75], off
	global_store_dwordx4 v[76:77], v[68:71], off offset:256
	global_store_dwordx4 v[56:57], v[60:63], off
	global_store_dwordx4 v[46:47], v[40:43], off
	global_store_dwordx4 v[30:31], v[24:27], off
	global_store_dwordx4 v[14:15], v[8:11], off
	global_store_dwordx4 v[12:13], v[4:7], off offset:256
	s_cbranch_vccz .LBB0_374
	s_waitcnt vmcnt(0)
	s_cmpk_gt_u32 s65, 0xff
	s_cbranch_scc1 .LBB0_389
	s_barrier

; #define PG8_STAGE(bufoff, gbase, voff) do { _Pragma("unroll") for (int _i = 0; _i < 2; ++_i) \
;         __builtin_amdgcn_global_load_lds((const unsigned*)((const char*)(gbase) + (voff)[_i]), (PG8_LAS unsigned*)(lds + (bufoff) + ldsw + _i * 8192), 16, 0, 0); } while (0)
; template <class Epi, class Sched, bool STAMP = false>
; __device__ __forceinline__ void gemm_phase(PG8_LAS unsigned char* lds, const Gemm g, const Sched& S, const Epi& E, unsigned long long* stamps) {
;     ...
;     for (;;) {
;         const bool has_next = S.next(ui + 1, nxt);
;         const char* nA = has_next ? (const char*)g.A + (size_t)nxt.pm * tstep : cA; const char* nB = has_next ? (const char*)g.Bt + (size_t)nxt.pn * tstep : cB;
;         for (int t = 0; t < nt; t += 2) {
;             const bool last = (t == nt - 2);
;             const char* a1 = cA + (size_t)(t + 1) * kstep;
;             const char* a2 = last ? nA : cA + (size_t)(t + 2) * kstep; const char* b2 = last ? nB : cB + (size_t)(t + 2) * kstep;
;             const char* a3 = a2 + kstep; const char* b3 = b2 + kstep;
;             if (last && has_next) S.a_ready(nxt);
;             PG8_LDB(B0, 0, 0); PG8_SCHED; PG8_LDA(At, 0, 0); PG8_STAGE(PG8_SA(1, 1), a1 + hstep, voffA);
;             PG8_WAIT_L(8); PG8_BAR; PG8_WAIT_L(0); PG8_MMA(0, 0, At, B0); PG8_BAR; PG8_SCHED;
;             PG8_LDB(B1, 0, 1); PG8_STAGE(PG8_SB(0, 0), b2, voffB);
;             PG8_BAR; PG8_WAIT_L(0); PG8_MMA(0, 1, At, B1); PG8_BAR;
;             PG8_LDA(At, 0, 1); PG8_STAGE(PG8_SA(0, 0), a2, voffA);
;             PG8_BAR; PG8_WAIT_L(0); PG8_MMA(1, 0, At, B0); PG8_BAR; PG8_SCHED;
;             PG8_STAGE(PG8_SB(0, 1), b2 + hstep, voffB);
;             PG8_WAIT_V(6); PG8_BAR; PG8_MMA(1, 1, At, B1); PG8_BAR;
;             PG8_LDB(B0, 1, 0); PG8_SCHED; PG8_LDA(At, 1, 0); PG8_STAGE(PG8_SA(0, 1), a2 + hstep, voffA);
;             PG8_WAIT_L(8); PG8_BAR; PG8_WAIT_L(0); PG8_MMA(0, 0, At, B0); PG8_BAR; PG8_SCHED;
;             PG8_LDB(B1, 1, 1); PG8_STAGE(PG8_SB(1, 0), b3, voffB);
;             PG8_BAR; PG8_WAIT_L(0); PG8_MMA(0, 1, At, B1); PG8_BAR;
;             PG8_LDA(At, 1, 1); PG8_STAGE(PG8_SA(1, 0), a3, voffA);
;             PG8_BAR; PG8_WAIT_L(0); PG8_MMA(1, 0, At, B0); PG8_BAR; PG8_SCHED;
;             PG8_STAGE(PG8_SB(1, 1), b3 + hstep, voffB);
;             PG8_WAIT_V(6); PG8_BAR; PG8_MMA(1, 1, At, B1); PG8_BAR;
;         }
.LBB0_438:
	s_add_u32 s77, s36, 0x100
	s_addc_u32 s78, s37, 0
	s_mov_b32 s10, -2
	s_cmp_eq_u32 s58, s99
	s_cbranch_scc1 .Lgu3_half_loop_z
	ds_read_b128 v[140:143], v147
	ds_read_b128 v[170:173], v148
	ds_read_b128 v[174:177], v149
	ds_read_b128 v[178:181], v150
	s_add_u32 s36, s34, 0x100
	s_addc_u32 s37, s35, 0
	s_cmp_eq_u32 s10, 12
	s_cselect_b32 s43, s5, s37
	s_cselect_b32 s42, s4, s36
	s_cselect_b32 s41, s1, s78
	s_cselect_b32 s40, s0, s77
	s_mov_b32 m0, s67
	ds_read_b128 v[182:185], v145
	ds_read_b128 v[186:189], v145 offset:1024
	ds_read_b128 v[190:193], v145 offset:2048
	ds_read_b128 v[194:197], v145 offset:3072
	ds_read_b128 v[198:201], v145 offset:4096
	ds_read_b128 v[202:205], v145 offset:5120
	ds_read_b128 v[206:209], v145 offset:6144
	ds_read_b128 v[210:213], v145 offset:7168
	global_load_lds_dwordx4 v132, s[34:35]
	s_mov_b32 m0, s68
	s_nop 0
	global_load_lds_dwordx4 v134, s[34:35]
	s_waitcnt lgkmcnt(8)
	s_barrier
	s_waitcnt lgkmcnt(0)
	s_setprio 1
	s_waitcnt lgkmcnt(0)
	v_mfma_f32_16x16x32_bf16 v[124:127], v[140:143], v[182:185], 0
	v_mfma_f32_16x16x32_bf16 v[120:123], v[174:177], v[182:185], 0
	v_mfma_f32_16x16x32_bf16 v[108:111], v[140:143], v[190:193], 0
	v_mfma_f32_16x16x32_bf16 v[104:107], v[174:177], v[190:193], 0
	v_mfma_f32_16x16x32_bf16 v[92:95], v[140:143], v[198:201], 0
	v_mfma_f32_16x16x32_bf16 v[88:91], v[174:177], v[198:201], 0
	v_mfma_f32_16x16x32_bf16 v[76:79], v[140:143], v[206:209], 0
	v_mfma_f32_16x16x32_bf16 v[72:75], v[174:177], v[206:209], 0
	v_mfma_f32_16x16x32_bf16 v[124:127], v[170:173], v[186:189], v[124:127]
	v_mfma_f32_16x16x32_bf16 v[120:123], v[178:181], v[186:189], v[120:123]
	v_mfma_f32_16x16x32_bf16 v[108:111], v[170:173], v[194:197], v[108:111]
	v_mfma_f32_16x16x32_bf16 v[104:107], v[178:181], v[194:197], v[104:107]
	v_mfma_f32_16x16x32_bf16 v[92:95], v[170:173], v[202:205], v[92:95]
	v_mfma_f32_16x16x32_bf16 v[88:91], v[178:181], v[202:205], v[88:91]
	v_mfma_f32_16x16x32_bf16 v[76:79], v[170:173], v[210:213], v[76:79]
	v_mfma_f32_16x16x32_bf16 v[72:75], v[178:181], v[210:213], v[72:75]
	s_setprio 0
	s_barrier
	s_mov_b32 m0, s49
	ds_read_b128 v[214:217], v151
	ds_read_b128 v[218:221], v152
	ds_read_b128 v[222:225], v153
	ds_read_b128 v[226:229], v154
	global_load_lds_dwordx4 v130, s[40:41]
	s_mov_b32 m0, s52
	s_nop 0
	global_load_lds_dwordx4 v128, s[40:41]
	s_waitcnt lgkmcnt(0)
	s_barrier
	s_waitcnt lgkmcnt(0)
	s_setprio 1
	s_waitcnt lgkmcnt(0)
	v_mfma_f32_16x16x32_bf16 v[116:119], v[214:217], v[182:185], 0
	v_mfma_f32_16x16x32_bf16 v[112:115], v[222:225], v[182:185], 0
	v_mfma_f32_16x16x32_bf16 v[100:103], v[214:217], v[190:193], 0
	v_mfma_f32_16x16x32_bf16 v[96:99], v[222:225], v[190:193], 0
	v_mfma_f32_16x16x32_bf16 v[84:87], v[214:217], v[198:201], 0
	v_mfma_f32_16x16x32_bf16 v[80:83], v[222:225], v[198:201], 0
	v_mfma_f32_16x16x32_bf16 v[68:71], v[214:217], v[206:209], 0
	v_mfma_f32_16x16x32_bf16 v[64:67], v[222:225], v[206:209], 0
	v_mfma_f32_16x16x32_bf16 v[116:119], v[218:221], v[186:189], v[116:119]
	v_mfma_f32_16x16x32_bf16 v[112:115], v[226:229], v[186:189], v[112:115]
	v_mfma_f32_16x16x32_bf16 v[100:103], v[218:221], v[194:197], v[100:103]
	v_mfma_f32_16x16x32_bf16 v[96:99], v[226:229], v[194:197], v[96:99]
	v_mfma_f32_16x16x32_bf16 v[84:87], v[218:221], v[202:205], v[84:87]
	v_mfma_f32_16x16x32_bf16 v[80:83], v[226:229], v[202:205], v[80:83]
	v_mfma_f32_16x16x32_bf16 v[68:71], v[218:221], v[210:213], v[68:71]
	v_mfma_f32_16x16x32_bf16 v[64:67], v[226:229], v[210:213], v[64:67]
	s_setprio 0
	s_mov_b32 m0, s46
	s_barrier
	ds_read_b128 v[182:185], v145 offset:16384
	ds_read_b128 v[186:189], v145 offset:17408
	ds_read_b128 v[190:193], v145 offset:18432
	ds_read_b128 v[194:197], v145 offset:19456
	ds_read_b128 v[198:201], v145 offset:20480
	ds_read_b128 v[202:205], v145 offset:21504
	ds_read_b128 v[206:209], v145 offset:22528
	ds_read_b128 v[210:213], v145 offset:23552
	global_load_lds_dwordx4 v130, s[42:43]
	s_mov_b32 m0, s53
	s_nop 0
	global_load_lds_dwordx4 v128, s[42:43]
	s_add_u32 s34, s40, 0x44000
	s_addc_u32 s35, s41, 0
	s_mov_b32 m0, s54
	s_nop 0
	global_load_lds_dwordx4 v130, s[34:35]
	s_mov_b32 m0, s55
	s_nop 0
	global_load_lds_dwordx4 v128, s[34:35]
	s_waitcnt vmcnt(6)
	s_barrier
	s_waitcnt lgkmcnt(0)
	s_setprio 1
	s_waitcnt lgkmcnt(0)
	v_mfma_f32_16x16x32_bf16 v[60:63], v[140:143], v[182:185], 0
	v_mfma_f32_16x16x32_bf16 v[56:59], v[174:177], v[182:185], 0
	v_mfma_f32_16x16x32_bf16 v[44:47], v[140:143], v[190:193], 0
	v_mfma_f32_16x16x32_bf16 v[40:43], v[174:177], v[190:193], 0
	v_mfma_f32_16x16x32_bf16 v[28:31], v[140:143], v[198:201], 0
	v_mfma_f32_16x16x32_bf16 v[24:27], v[174:177], v[198:201], 0
	v_mfma_f32_16x16x32_bf16 v[12:15], v[140:143], v[206:209], 0
	v_mfma_f32_16x16x32_bf16 v[8:11], v[174:177], v[206:209], 0
	v_mfma_f32_16x16x32_bf16 v[60:63], v[170:173], v[186:189], v[60:63]
	v_mfma_f32_16x16x32_bf16 v[56:59], v[178:181], v[186:189], v[56:59]
	v_mfma_f32_16x16x32_bf16 v[44:47], v[170:173], v[194:197], v[44:47]
	v_mfma_f32_16x16x32_bf16 v[40:43], v[178:181], v[194:197], v[40:43]
	v_mfma_f32_16x16x32_bf16 v[28:31], v[170:173], v[202:205], v[28:31]
	v_mfma_f32_16x16x32_bf16 v[24:27], v[178:181], v[202:205], v[24:27]
	v_mfma_f32_16x16x32_bf16 v[12:15], v[170:173], v[210:213], v[12:15]
	v_mfma_f32_16x16x32_bf16 v[8:11], v[178:181], v[210:213], v[8:11]
	v_mfma_f32_16x16x32_bf16 v[52:55], v[214:217], v[182:185], 0
	v_mfma_f32_16x16x32_bf16 v[48:51], v[222:225], v[182:185], 0
	v_mfma_f32_16x16x32_bf16 v[36:39], v[214:217], v[190:193], 0
	v_mfma_f32_16x16x32_bf16 v[32:35], v[222:225], v[190:193], 0
	v_mfma_f32_16x16x32_bf16 v[20:23], v[214:217], v[198:201], 0
	v_mfma_f32_16x16x32_bf16 v[16:19], v[222:225], v[198:201], 0
	v_mfma_f32_16x16x32_bf16 v[4:7], v[214:217], v[206:209], 0
	v_mfma_f32_16x16x32_bf16 v[0:3], v[222:225], v[206:209], 0
	v_mfma_f32_16x16x32_bf16 v[52:55], v[218:221], v[186:189], v[52:55]
	v_mfma_f32_16x16x32_bf16 v[48:51], v[226:229], v[186:189], v[48:51]
	v_mfma_f32_16x16x32_bf16 v[36:39], v[218:221], v[194:197], v[36:39]
	v_mfma_f32_16x16x32_bf16 v[32:35], v[226:229], v[194:197], v[32:35]
	v_mfma_f32_16x16x32_bf16 v[20:23], v[218:221], v[202:205], v[20:23]
	v_mfma_f32_16x16x32_bf16 v[16:19], v[226:229], v[202:205], v[16:19]
	v_mfma_f32_16x16x32_bf16 v[4:7], v[218:221], v[210:213], v[4:7]
	v_mfma_f32_16x16x32_bf16 v[0:3], v[226:229], v[210:213], v[0:3]
	s_setprio 0
	s_barrier
	s_branch .Lzp7_mid
; #define PG8_STAGE(bufoff, gbase, voff) do { _Pragma("unroll") for (int _i = 0; _i < 2; ++_i) \
;         __builtin_amdgcn_global_load_lds((const unsigned*)((const char*)(gbase) + (voff)[_i]), (PG8_LAS unsigned*)(lds + (bufoff) + ldsw + _i * 8192), 16, 0, 0); } while (0)
; #define PG8_LDA(dst, b, h) do { _Pragma("unroll") for (int m = 0; m < 4; ++m) _Pragma("unroll") for (int k = 0; k < 2; ++k) dst[m][k] = *(const PG8_LAS bf16x8*)(lds + PG8_SA(b, h) + aoff + m * 2048 + k * 1024); } while (0)
; template <class Epi, class Sched, bool STAMP = false>
; __device__ __forceinline__ void gemm_phase(PG8_LAS unsigned char* lds, const Gemm g, const Sched& S, const Epi& E, unsigned long long* stamps) {
;     ...
;         for (int t = 0; t < nt; t += 2) {
;             const bool last = (t == nt - 2);
;             const char* a1 = cA + (size_t)(t + 1) * kstep;
;             const char* a2 = last ? nA : cA + (size_t)(t + 2) * kstep; const char* b2 = last ? nB : cB + (size_t)(t + 2) * kstep;
;             const char* a3 = a2 + kstep; const char* b3 = b2 + kstep;
;             if (last && has_next) S.a_ready(nxt);
;             PG8_LDB(B0, 0, 0); PG8_SCHED; PG8_LDA(At, 0, 0); PG8_STAGE(PG8_SA(1, 1), a1 + hstep, voffA);
;             PG8_WAIT_L(8); PG8_BAR; PG8_WAIT_L(0); PG8_MMA(0, 0, At, B0); PG8_BAR; PG8_SCHED;
;             PG8_LDB(B1, 0, 1); PG8_STAGE(PG8_SB(0, 0), b2, voffB);
;             PG8_BAR; PG8_WAIT_L(0); PG8_MMA(0, 1, At, B1); PG8_BAR;
;             PG8_LDA(At, 0, 1); PG8_STAGE(PG8_SA(0, 0), a2, voffA);
;             PG8_BAR; PG8_WAIT_L(0); PG8_MMA(1, 0, At, B0); PG8_BAR; PG8_SCHED;
;             PG8_STAGE(PG8_SB(0, 1), b2 + hstep, voffB);
;             PG8_WAIT_V(6); PG8_BAR; PG8_MMA(1, 1, At, B1); PG8_BAR;
;             PG8_LDB(B0, 1, 0); PG8_SCHED; PG8_LDA(At, 1, 0); PG8_STAGE(PG8_SA(0, 1), a2 + hstep, voffA);
;             PG8_WAIT_L(8); PG8_BAR; PG8_WAIT_L(0); PG8_MMA(0, 0, At, B0); PG8_BAR; PG8_SCHED;
;             PG8_LDB(B1, 1, 1); PG8_STAGE(PG8_SB(1, 0), b3, voffB);
;             PG8_BAR; PG8_WAIT_L(0); PG8_MMA(0, 1, At, B1); PG8_BAR;
;             PG8_LDA(At, 1, 1); PG8_STAGE(PG8_SA(1, 0), a3, voffA);
;             PG8_BAR; PG8_WAIT_L(0); PG8_MMA(1, 0, At, B0); PG8_BAR; PG8_SCHED;
;             PG8_STAGE(PG8_SB(1, 1), b3 + hstep, voffB);
;             PG8_WAIT_V(6); PG8_BAR; PG8_MMA(1, 1, At, B1); PG8_BAR;
;         }
.LBB0_439:
	ds_read_b128 v[140:143], v147
	ds_read_b128 v[170:173], v148
	ds_read_b128 v[174:177], v149
	ds_read_b128 v[178:181], v150
	s_add_u32 s36, s34, 0x100
	s_addc_u32 s37, s35, 0
	s_cmp_eq_u32 s10, 12
	s_cselect_b32 s43, s5, s37
	s_cselect_b32 s42, s4, s36
	s_cselect_b32 s41, s1, s78
	s_cselect_b32 s40, s0, s77
	s_mov_b32 m0, s67
	ds_read_b128 v[182:185], v145
	ds_read_b128 v[186:189], v145 offset:1024
	ds_read_b128 v[190:193], v145 offset:2048
	ds_read_b128 v[194:197], v145 offset:3072
	ds_read_b128 v[198:201], v145 offset:4096
	ds_read_b128 v[202:205], v145 offset:5120
	ds_read_b128 v[206:209], v145 offset:6144
	ds_read_b128 v[210:213], v145 offset:7168
	global_load_lds_dwordx4 v132, s[34:35]
	s_mov_b32 m0, s68
	s_nop 0
	global_load_lds_dwordx4 v134, s[34:35]
	s_waitcnt lgkmcnt(8)
	s_barrier
	s_waitcnt lgkmcnt(0)
	s_setprio 1
	s_waitcnt lgkmcnt(0)
	v_mfma_f32_16x16x32_bf16 v[124:127], v[140:143], v[182:185], v[124:127]
	v_mfma_f32_16x16x32_bf16 v[120:123], v[174:177], v[182:185], v[120:123]
	v_mfma_f32_16x16x32_bf16 v[108:111], v[140:143], v[190:193], v[108:111]
	v_mfma_f32_16x16x32_bf16 v[104:107], v[174:177], v[190:193], v[104:107]
	v_mfma_f32_16x16x32_bf16 v[92:95], v[140:143], v[198:201], v[92:95]
	v_mfma_f32_16x16x32_bf16 v[88:91], v[174:177], v[198:201], v[88:91]
	v_mfma_f32_16x16x32_bf16 v[76:79], v[140:143], v[206:209], v[76:79]
	v_mfma_f32_16x16x32_bf16 v[72:75], v[174:177], v[206:209], v[72:75]
	v_mfma_f32_16x16x32_bf16 v[124:127], v[170:173], v[186:189], v[124:127]
	v_mfma_f32_16x16x32_bf16 v[120:123], v[178:181], v[186:189], v[120:123]
	v_mfma_f32_16x16x32_bf16 v[108:111], v[170:173], v[194:197], v[108:111]
	v_mfma_f32_16x16x32_bf16 v[104:107], v[178:181], v[194:197], v[104:107]
	v_mfma_f32_16x16x32_bf16 v[92:95], v[170:173], v[202:205], v[92:95]
	v_mfma_f32_16x16x32_bf16 v[88:91], v[178:181], v[202:205], v[88:91]
	v_mfma_f32_16x16x32_bf16 v[76:79], v[170:173], v[210:213], v[76:79]
	v_mfma_f32_16x16x32_bf16 v[72:75], v[178:181], v[210:213], v[72:75]
	s_setprio 0
	s_barrier
	s_mov_b32 m0, s49
	ds_read_b128 v[214:217], v151
	ds_read_b128 v[218:221], v152
	ds_read_b128 v[222:225], v153
	ds_read_b128 v[226:229], v154
	global_load_lds_dwordx4 v130, s[40:41]
	s_mov_b32 m0, s52
	s_nop 0
	global_load_lds_dwordx4 v128, s[40:41]
	s_waitcnt lgkmcnt(0)
	s_barrier
	s_waitcnt lgkmcnt(0)
	s_setprio 1
	s_waitcnt lgkmcnt(0)
	v_mfma_f32_16x16x32_bf16 v[116:119], v[214:217], v[182:185], v[116:119]
	v_mfma_f32_16x16x32_bf16 v[112:115], v[222:225], v[182:185], v[112:115]
	v_mfma_f32_16x16x32_bf16 v[100:103], v[214:217], v[190:193], v[100:103]
	v_mfma_f32_16x16x32_bf16 v[96:99], v[222:225], v[190:193], v[96:99]
	v_mfma_f32_16x16x32_bf16 v[84:87], v[214:217], v[198:201], v[84:87]
	v_mfma_f32_16x16x32_bf16 v[80:83], v[222:225], v[198:201], v[80:83]
	v_mfma_f32_16x16x32_bf16 v[68:71], v[214:217], v[206:209], v[68:71]
	v_mfma_f32_16x16x32_bf16 v[64:67], v[222:225], v[206:209], v[64:67]
	v_mfma_f32_16x16x32_bf16 v[116:119], v[218:221], v[186:189], v[116:119]
	v_mfma_f32_16x16x32_bf16 v[112:115], v[226:229], v[186:189], v[112:115]
	v_mfma_f32_16x16x32_bf16 v[100:103], v[218:221], v[194:197], v[100:103]
	v_mfma_f32_16x16x32_bf16 v[96:99], v[226:229], v[194:197], v[96:99]
	v_mfma_f32_16x16x32_bf16 v[84:87], v[218:221], v[202:205], v[84:87]
	v_mfma_f32_16x16x32_bf16 v[80:83], v[226:229], v[202:205], v[80:83]
	v_mfma_f32_16x16x32_bf16 v[68:71], v[218:221], v[210:213], v[68:71]
	v_mfma_f32_16x16x32_bf16 v[64:67], v[226:229], v[210:213], v[64:67]
	s_setprio 0
	s_mov_b32 m0, s46
	s_barrier
	ds_read_b128 v[182:185], v145 offset:16384
	ds_read_b128 v[186:189], v145 offset:17408
	ds_read_b128 v[190:193], v145 offset:18432
	ds_read_b128 v[194:197], v145 offset:19456
	ds_read_b128 v[198:201], v145 offset:20480
	ds_read_b128 v[202:205], v145 offset:21504
	ds_read_b128 v[206:209], v145 offset:22528
	ds_read_b128 v[210:213], v145 offset:23552
	global_load_lds_dwordx4 v130, s[42:43]
	s_mov_b32 m0, s53
	s_nop 0
	global_load_lds_dwordx4 v128, s[42:43]
	s_add_u32 s34, s40, 0x44000
	s_addc_u32 s35, s41, 0
	s_mov_b32 m0, s54
	s_nop 0
	global_load_lds_dwordx4 v130, s[34:35]
	s_mov_b32 m0, s55
	s_nop 0
	global_load_lds_dwordx4 v128, s[34:35]
	s_waitcnt vmcnt(6)
	s_barrier
	s_waitcnt lgkmcnt(0)
	s_setprio 1
	s_waitcnt lgkmcnt(0)
	v_mfma_f32_16x16x32_bf16 v[60:63], v[140:143], v[182:185], v[60:63]
	v_mfma_f32_16x16x32_bf16 v[56:59], v[174:177], v[182:185], v[56:59]
	v_mfma_f32_16x16x32_bf16 v[44:47], v[140:143], v[190:193], v[44:47]
	v_mfma_f32_16x16x32_bf16 v[40:43], v[174:177], v[190:193], v[40:43]
	v_mfma_f32_16x16x32_bf16 v[28:31], v[140:143], v[198:201], v[28:31]
	v_mfma_f32_16x16x32_bf16 v[24:27], v[174:177], v[198:201], v[24:27]
	v_mfma_f32_16x16x32_bf16 v[12:15], v[140:143], v[206:209], v[12:15]
	v_mfma_f32_16x16x32_bf16 v[8:11], v[174:177], v[206:209], v[8:11]
	v_mfma_f32_16x16x32_bf16 v[60:63], v[170:173], v[186:189], v[60:63]
	v_mfma_f32_16x16x32_bf16 v[56:59], v[178:181], v[186:189], v[56:59]
	v_mfma_f32_16x16x32_bf16 v[44:47], v[170:173], v[194:197], v[44:47]
	v_mfma_f32_16x16x32_bf16 v[40:43], v[178:181], v[194:197], v[40:43]
	v_mfma_f32_16x16x32_bf16 v[28:31], v[170:173], v[202:205], v[28:31]
	v_mfma_f32_16x16x32_bf16 v[24:27], v[178:181], v[202:205], v[24:27]
	v_mfma_f32_16x16x32_bf16 v[12:15], v[170:173], v[210:213], v[12:15]
	v_mfma_f32_16x16x32_bf16 v[8:11], v[178:181], v[210:213], v[8:11]
	v_mfma_f32_16x16x32_bf16 v[52:55], v[214:217], v[182:185], v[52:55]
	v_mfma_f32_16x16x32_bf16 v[48:51], v[222:225], v[182:185], v[48:51]
	v_mfma_f32_16x16x32_bf16 v[36:39], v[214:217], v[190:193], v[36:39]
	v_mfma_f32_16x16x32_bf16 v[32:35], v[222:225], v[190:193], v[32:35]
	v_mfma_f32_16x16x32_bf16 v[20:23], v[214:217], v[198:201], v[20:23]
	v_mfma_f32_16x16x32_bf16 v[16:19], v[222:225], v[198:201], v[16:19]
	v_mfma_f32_16x16x32_bf16 v[4:7], v[214:217], v[206:209], v[4:7]
	v_mfma_f32_16x16x32_bf16 v[0:3], v[222:225], v[206:209], v[0:3]
	v_mfma_f32_16x16x32_bf16 v[52:55], v[218:221], v[186:189], v[52:55]
	v_mfma_f32_16x16x32_bf16 v[48:51], v[226:229], v[186:189], v[48:51]
	v_mfma_f32_16x16x32_bf16 v[36:39], v[218:221], v[194:197], v[36:39]
	v_mfma_f32_16x16x32_bf16 v[32:35], v[226:229], v[194:197], v[32:35]
	v_mfma_f32_16x16x32_bf16 v[20:23], v[218:221], v[202:205], v[20:23]
	v_mfma_f32_16x16x32_bf16 v[16:19], v[226:229], v[202:205], v[16:19]
	v_mfma_f32_16x16x32_bf16 v[4:7], v[218:221], v[210:213], v[4:7]
	v_mfma_f32_16x16x32_bf16 v[0:3], v[226:229], v[210:213], v[0:3]
	s_setprio 0
	s_barrier
; #define PG8_STAGE(bufoff, gbase, voff) do { _Pragma("unroll") for (int _i = 0; _i < 2; ++_i) \
;         __builtin_amdgcn_global_load_lds((const unsigned*)((const char*)(gbase) + (voff)[_i]), (PG8_LAS unsigned*)(lds + (bufoff) + ldsw + _i * 8192), 16, 0, 0); } while (0)
; #define PG8_LDA(dst, b, h) do { _Pragma("unroll") for (int m = 0; m < 4; ++m) _Pragma("unroll") for (int k = 0; k < 2; ++k) dst[m][k] = *(const PG8_LAS bf16x8*)(lds + PG8_SA(b, h) + aoff + m * 2048 + k * 1024); } while (0)
; template <class Epi, class Sched, bool STAMP = false>
; __device__ __forceinline__ void gemm_phase(PG8_LAS unsigned char* lds, const Gemm g, const Sched& S, const Epi& E, unsigned long long* stamps) {
;     ...
;         for (int t = 0; t < nt; t += 2) {
;             const bool last = (t == nt - 2);
;             const char* a1 = cA + (size_t)(t + 1) * kstep;
;             const char* a2 = last ? nA : cA + (size_t)(t + 2) * kstep; const char* b2 = last ? nB : cB + (size_t)(t + 2) * kstep;
;             const char* a3 = a2 + kstep; const char* b3 = b2 + kstep;
;             if (last && has_next) S.a_ready(nxt);
;             PG8_LDB(B0, 0, 0); PG8_SCHED; PG8_LDA(At, 0, 0); PG8_STAGE(PG8_SA(1, 1), a1 + hstep, voffA);
;             PG8_WAIT_L(8); PG8_BAR; PG8_WAIT_L(0); PG8_MMA(0, 0, At, B0); PG8_BAR; PG8_SCHED;
;             PG8_LDB(B1, 0, 1); PG8_STAGE(PG8_SB(0, 0), b2, voffB);
;             PG8_BAR; PG8_WAIT_L(0); PG8_MMA(0, 1, At, B1); PG8_BAR;
;             PG8_LDA(At, 0, 1); PG8_STAGE(PG8_SA(0, 0), a2, voffA);
;             PG8_BAR; PG8_WAIT_L(0); PG8_MMA(1, 0, At, B0); PG8_BAR; PG8_SCHED;
;             PG8_STAGE(PG8_SB(0, 1), b2 + hstep, voffB);
;             PG8_WAIT_V(6); PG8_BAR; PG8_MMA(1, 1, At, B1); PG8_BAR;
;             PG8_LDB(B0, 1, 0); PG8_SCHED; PG8_LDA(At, 1, 0); PG8_STAGE(PG8_SA(0, 1), a2 + hstep, voffA);
;             PG8_WAIT_L(8); PG8_BAR; PG8_WAIT_L(0); PG8_MMA(0, 0, At, B0); PG8_BAR; PG8_SCHED;
;             PG8_LDB(B1, 1, 1); PG8_STAGE(PG8_SB(1, 0), b3, voffB);
;             PG8_BAR; PG8_WAIT_L(0); PG8_MMA(0, 1, At, B1); PG8_BAR;
;             PG8_LDA(At, 1, 1); PG8_STAGE(PG8_SA(1, 0), a3, voffA);
;             PG8_BAR; PG8_WAIT_L(0); PG8_MMA(1, 0, At, B0); PG8_BAR; PG8_SCHED;
;             PG8_STAGE(PG8_SB(1, 1), b3 + hstep, voffB);
;             PG8_WAIT_V(6); PG8_BAR; PG8_MMA(1, 1, At, B1); PG8_BAR;
;         }
.Lzp7_mid:
	ds_read_b128 v[140:143], v155
	ds_read_b128 v[170:173], v156
	ds_read_b128 v[174:177], v157
	ds_read_b128 v[178:181], v165
	s_add_u32 s34, s42, 0x44000
	s_addc_u32 s35, s43, 0
	s_mov_b32 m0, s56
	ds_read_b128 v[182:185], v145 offset:32768
	ds_read_b128 v[186:189], v145 offset:33792
	ds_read_b128 v[190:193], v145 offset:34816
	ds_read_b128 v[194:197], v145 offset:35840
	ds_read_b128 v[198:201], v145 offset:36864
	ds_read_b128 v[202:205], v145 offset:37888
	ds_read_b128 v[206:209], v145 offset:38912
	ds_read_b128 v[210:213], v145 offset:39936
	global_load_lds_dwordx4 v130, s[34:35]
	s_mov_b32 m0, s57
	s_nop 0
	global_load_lds_dwordx4 v128, s[34:35]
	s_waitcnt lgkmcnt(8)
	s_barrier
	s_waitcnt lgkmcnt(0)
	s_setprio 1
	s_waitcnt lgkmcnt(0)
	v_mfma_f32_16x16x32_bf16 v[124:127], v[140:143], v[182:185], v[124:127]
	v_mfma_f32_16x16x32_bf16 v[120:123], v[174:177], v[182:185], v[120:123]
	v_mfma_f32_16x16x32_bf16 v[108:111], v[140:143], v[190:193], v[108:111]
	v_mfma_f32_16x16x32_bf16 v[104:107], v[174:177], v[190:193], v[104:107]
	v_mfma_f32_16x16x32_bf16 v[92:95], v[140:143], v[198:201], v[92:95]
	v_mfma_f32_16x16x32_bf16 v[88:91], v[174:177], v[198:201], v[88:91]
	v_mfma_f32_16x16x32_bf16 v[76:79], v[140:143], v[206:209], v[76:79]
	v_mfma_f32_16x16x32_bf16 v[72:75], v[174:177], v[206:209], v[72:75]
	v_mfma_f32_16x16x32_bf16 v[124:127], v[170:173], v[186:189], v[124:127]
	v_mfma_f32_16x16x32_bf16 v[120:123], v[178:181], v[186:189], v[120:123]
	v_mfma_f32_16x16x32_bf16 v[108:111], v[170:173], v[194:197], v[108:111]
	v_mfma_f32_16x16x32_bf16 v[104:107], v[178:181], v[194:197], v[104:107]
	v_mfma_f32_16x16x32_bf16 v[92:95], v[170:173], v[202:205], v[92:95]
	v_mfma_f32_16x16x32_bf16 v[88:91], v[178:181], v[202:205], v[88:91]
	v_mfma_f32_16x16x32_bf16 v[76:79], v[170:173], v[210:213], v[76:79]
	v_mfma_f32_16x16x32_bf16 v[72:75], v[178:181], v[210:213], v[72:75]
	s_setprio 0
	s_barrier
	s_mov_b32 m0, s60
	ds_read_b128 v[214:217], v166
	ds_read_b128 v[218:221], v167
	ds_read_b128 v[222:225], v168
	ds_read_b128 v[226:229], v169
	s_add_u32 s100, s40, 0x80
	s_addc_u32 s101, s41, 0
	global_load_lds_dwordx4 v130, s[100:101]
	s_mov_b32 m0, s61
	s_nop 0
	global_load_lds_dwordx4 v128, s[100:101]
	s_waitcnt lgkmcnt(0)
	s_barrier
	s_waitcnt lgkmcnt(0)
	s_setprio 1
	s_waitcnt lgkmcnt(0)
	v_mfma_f32_16x16x32_bf16 v[116:119], v[214:217], v[182:185], v[116:119]
	v_mfma_f32_16x16x32_bf16 v[112:115], v[222:225], v[182:185], v[112:115]
	v_mfma_f32_16x16x32_bf16 v[100:103], v[214:217], v[190:193], v[100:103]
	v_mfma_f32_16x16x32_bf16 v[96:99], v[222:225], v[190:193], v[96:99]
	v_mfma_f32_16x16x32_bf16 v[84:87], v[214:217], v[198:201], v[84:87]
	v_mfma_f32_16x16x32_bf16 v[80:83], v[222:225], v[198:201], v[80:83]
	v_mfma_f32_16x16x32_bf16 v[68:71], v[214:217], v[206:209], v[68:71]
	v_mfma_f32_16x16x32_bf16 v[64:67], v[222:225], v[206:209], v[64:67]
	v_mfma_f32_16x16x32_bf16 v[116:119], v[218:221], v[186:189], v[116:119]
	v_mfma_f32_16x16x32_bf16 v[112:115], v[226:229], v[186:189], v[112:115]
	v_mfma_f32_16x16x32_bf16 v[100:103], v[218:221], v[194:197], v[100:103]
	v_mfma_f32_16x16x32_bf16 v[96:99], v[226:229], v[194:197], v[96:99]
	v_mfma_f32_16x16x32_bf16 v[84:87], v[218:221], v[202:205], v[84:87]
	v_mfma_f32_16x16x32_bf16 v[80:83], v[226:229], v[202:205], v[80:83]
	v_mfma_f32_16x16x32_bf16 v[68:71], v[218:221], v[210:213], v[68:71]
	v_mfma_f32_16x16x32_bf16 v[64:67], v[226:229], v[210:213], v[64:67]
	s_setprio 0
	s_mov_b32 m0, s62
	s_barrier
	ds_read_b128 v[182:185], v145 offset:49152
	ds_read_b128 v[186:189], v145 offset:50176
	ds_read_b128 v[190:193], v145 offset:51200
	ds_read_b128 v[194:197], v145 offset:52224
	ds_read_b128 v[198:201], v145 offset:53248
	ds_read_b128 v[202:205], v145 offset:54272
	ds_read_b128 v[206:209], v145 offset:55296
	ds_read_b128 v[210:213], v145 offset:56320
	s_add_u32 s100, s42, 0x80
	s_addc_u32 s101, s43, 0
	global_load_lds_dwordx4 v130, s[100:101]
	s_mov_b32 m0, s63
	s_nop 0
	global_load_lds_dwordx4 v128, s[100:101]
	s_add_u32 s34, s40, 0x44080
	s_addc_u32 s35, s41, 0
	s_mov_b32 m0, s64
	s_nop 0
	global_load_lds_dwordx4 v130, s[34:35]
	s_mov_b32 m0, s65
	s_nop 0
	global_load_lds_dwordx4 v128, s[34:35]
	s_waitcnt vmcnt(6)
	s_barrier
	s_waitcnt lgkmcnt(0)
	s_setprio 1
	s_waitcnt lgkmcnt(0)
	v_mfma_f32_16x16x32_bf16 v[60:63], v[140:143], v[182:185], v[60:63]
	v_mfma_f32_16x16x32_bf16 v[56:59], v[174:177], v[182:185], v[56:59]
	v_mfma_f32_16x16x32_bf16 v[44:47], v[140:143], v[190:193], v[44:47]
	v_mfma_f32_16x16x32_bf16 v[40:43], v[174:177], v[190:193], v[40:43]
	v_mfma_f32_16x16x32_bf16 v[28:31], v[140:143], v[198:201], v[28:31]
	v_mfma_f32_16x16x32_bf16 v[24:27], v[174:177], v[198:201], v[24:27]
	v_mfma_f32_16x16x32_bf16 v[12:15], v[140:143], v[206:209], v[12:15]
	v_mfma_f32_16x16x32_bf16 v[8:11], v[174:177], v[206:209], v[8:11]
	v_mfma_f32_16x16x32_bf16 v[60:63], v[170:173], v[186:189], v[60:63]
	v_mfma_f32_16x16x32_bf16 v[56:59], v[178:181], v[186:189], v[56:59]
	v_mfma_f32_16x16x32_bf16 v[44:47], v[170:173], v[194:197], v[44:47]
	v_mfma_f32_16x16x32_bf16 v[40:43], v[178:181], v[194:197], v[40:43]
	v_mfma_f32_16x16x32_bf16 v[28:31], v[170:173], v[202:205], v[28:31]
	v_mfma_f32_16x16x32_bf16 v[24:27], v[178:181], v[202:205], v[24:27]
	v_mfma_f32_16x16x32_bf16 v[12:15], v[170:173], v[210:213], v[12:15]
	v_mfma_f32_16x16x32_bf16 v[8:11], v[178:181], v[210:213], v[8:11]
	v_mfma_f32_16x16x32_bf16 v[52:55], v[214:217], v[182:185], v[52:55]
	v_mfma_f32_16x16x32_bf16 v[48:51], v[222:225], v[182:185], v[48:51]
	v_mfma_f32_16x16x32_bf16 v[36:39], v[214:217], v[190:193], v[36:39]
	v_mfma_f32_16x16x32_bf16 v[32:35], v[222:225], v[190:193], v[32:35]
	v_mfma_f32_16x16x32_bf16 v[20:23], v[214:217], v[198:201], v[20:23]
	v_mfma_f32_16x16x32_bf16 v[16:19], v[222:225], v[198:201], v[16:19]
	v_mfma_f32_16x16x32_bf16 v[4:7], v[214:217], v[206:209], v[4:7]
	v_mfma_f32_16x16x32_bf16 v[0:3], v[222:225], v[206:209], v[0:3]
	v_mfma_f32_16x16x32_bf16 v[52:55], v[218:221], v[186:189], v[52:55]
	v_mfma_f32_16x16x32_bf16 v[48:51], v[226:229], v[186:189], v[48:51]
	v_mfma_f32_16x16x32_bf16 v[36:39], v[218:221], v[194:197], v[36:39]
	v_mfma_f32_16x16x32_bf16 v[32:35], v[226:229], v[194:197], v[32:35]
	v_mfma_f32_16x16x32_bf16 v[20:23], v[218:221], v[202:205], v[20:23]
	v_mfma_f32_16x16x32_bf16 v[16:19], v[226:229], v[202:205], v[16:19]
	v_mfma_f32_16x16x32_bf16 v[4:7], v[218:221], v[210:213], v[4:7]
	v_mfma_f32_16x16x32_bf16 v[0:3], v[226:229], v[210:213], v[0:3]
	s_setprio 0
	s_add_i32 s10, s10, 2
	s_add_u32 s77, s77, 0x100
	s_addc_u32 s78, s78, 0
	s_cmp_gt_u32 s10, 13
	s_mov_b64 s[34:35], s[36:37]
	s_barrier
; DI float ex2(float x) { return __builtin_amdgcn_exp2f(x); }
;     DI void operator()(const f32x4 (&acc)[2][2][4][2], const Unit& u, int wr, int wc, int fr, int fq) const {
;         const int row0 = u.pm * BM + wr * 64 + fr, hcol0 = ((u.pn * BM + wc * 32) >> 1) + 4 * fq;
; #pragma unroll
;         for (int ai = 0; ai < 2; ++ai)
; #pragma unroll
;             for (int m = 0; m < 4; ++m) { u16* rowp = O + (size_t)(row0 + ai * HALF + m * 16) * ldc + hcol0;
; #pragma unroll
;                 for (int bj = 0; bj < 2; ++bj) { const f32x4 g = acc[ai][bj][m][0], up = acc[ai][bj][m][1]; float r[4];
; #pragma unroll
;                     for (int j = 0; j < 4; ++j) r[j] = g[j] * up[j] * __builtin_amdgcn_rcpf(1.f + ex2(-LOG2E * g[j]));
;                     uint2 w = {pack2(r[0], r[1]), pack2(r[2], r[3])}; *(uint2*)(rowp + bj * (HALF / 2)) = w; } }
;     }
	s_cbranch_scc0 .LBB0_439
	v_exp_f32_e64 v171, -v124
	v_exp_f32_e64 v175, -v125
	s_lshl_b32 s10, s76, 8
	v_add_f32_e32 v171, 1.0, v171
	v_rcp_f32_e32 v174, v171
	v_add_f32_e32 v171, 1.0, v175
	v_exp_f32_e64 v176, -v126
	v_exp_f32_e64 v177, -v127
	v_rcp_f32_e32 v175, v171
	v_add_f32_e32 v171, 1.0, v176
	v_rcp_f32_e32 v176, v171
	v_add_f32_e32 v171, 1.0, v177
	v_rcp_f32_e32 v177, v171
	v_pk_mul_f32 v[122:123], v[126:127], v[122:123]
	v_pk_mul_f32 v[120:121], v[124:125], v[120:121]
	s_or_b32 s10, s10, s59
	v_pk_mul_f32 v[120:121], v[120:121], v[174:175]
	v_pk_mul_f32 v[122:123], v[122:123], v[176:177]
	s_ashr_i32 s10, s10, 1
	v_cvt_pk_bf16_f32 v120, v120, v121
	v_cvt_pk_bf16_f32 v121, v122, v123
	v_or_b32_e32 v140, s10, v146
	v_exp_f32_e64 v122, -v116
	v_exp_f32_e64 v123, -v117
	v_lshl_add_u32 v170, s75, 8, v144
	v_ashrrev_i32_e32 v141, 31, v140
	v_mov_b64_e32 v[142:143], s[12:13]
	v_mad_i64_i32 v[172:173], s[34:35], v170, s69, v[142:143]
	v_lshlrev_b64 v[140:141], 1, v[140:141]
	v_lshl_add_u64 v[172:173], v[172:173], 0, v[140:141]
	global_store_dwordx2 v[172:173], v[120:121], off
	v_add_f32_e32 v120, 1.0, v122
	v_add_f32_e32 v121, 1.0, v123
	v_exp_f32_e64 v122, -v118
	v_exp_f32_e64 v123, -v119
	v_rcp_f32_e32 v120, v120
	v_rcp_f32_e32 v121, v121
	v_add_f32_e32 v122, 1.0, v122
	v_add_f32_e32 v123, 1.0, v123
	v_rcp_f32_e32 v122, v122
	v_rcp_f32_e32 v123, v123
	v_pk_mul_f32 v[114:115], v[118:119], v[114:115]
	v_pk_mul_f32 v[112:113], v[116:117], v[112:113]
	v_pk_mul_f32 v[112:113], v[112:113], v[120:121]
	v_pk_mul_f32 v[114:115], v[114:115], v[122:123]
	v_cvt_pk_bf16_f32 v112, v112, v113
	v_cvt_pk_bf16_f32 v113, v114, v115
	v_exp_f32_e64 v114, -v108
	v_exp_f32_e64 v115, -v109
	v_exp_f32_e64 v116, -v110
	v_exp_f32_e64 v117, -v111
	v_add_f32_e32 v114, 1.0, v114
	v_add_f32_e32 v115, 1.0, v115
	v_add_f32_e32 v116, 1.0, v116
	v_add_f32_e32 v117, 1.0, v117
	v_rcp_f32_e32 v114, v114
	v_rcp_f32_e32 v115, v115
	v_rcp_f32_e32 v116, v116
	v_rcp_f32_e32 v117, v117
	v_pk_mul_f32 v[106:107], v[110:111], v[106:107]
	v_pk_mul_f32 v[104:105], v[108:109], v[104:105]
	global_store_dwordx2 v[172:173], v[112:113], off offset:128
	v_pk_mul_f32 v[104:105], v[104:105], v[114:115]
	v_pk_mul_f32 v[106:107], v[106:107], v[116:117]
	v_cvt_pk_bf16_f32 v104, v104, v105
	v_cvt_pk_bf16_f32 v105, v106, v107
	v_exp_f32_e64 v106, -v100
	v_exp_f32_e64 v107, -v101
	v_or_b32_e32 v112, 16, v170
	v_mad_i64_i32 v[112:113], s[34:35], v112, s69, v[142:143]
	v_lshl_add_u64 v[112:113], v[112:113], 0, v[140:141]
	global_store_dwordx2 v[112:113], v[104:105], off
	v_add_f32_e32 v104, 1.0, v106
	v_add_f32_e32 v105, 1.0, v107
	v_exp_f32_e64 v106, -v102
	v_exp_f32_e64 v107, -v103
	v_rcp_f32_e32 v104, v104
	v_rcp_f32_e32 v105, v105
	v_add_f32_e32 v106, 1.0, v106
	v_add_f32_e32 v107, 1.0, v107
	v_rcp_f32_e32 v106, v106
	v_rcp_f32_e32 v107, v107
	v_pk_mul_f32 v[98:99], v[102:103], v[98:99]
	v_pk_mul_f32 v[96:97], v[100:101], v[96:97]
	v_pk_mul_f32 v[96:97], v[96:97], v[104:105]
	v_pk_mul_f32 v[98:99], v[98:99], v[106:107]
	v_cvt_pk_bf16_f32 v96, v96, v97
	v_cvt_pk_bf16_f32 v97, v98, v99
	v_exp_f32_e64 v98, -v92
	v_exp_f32_e64 v99, -v93
	v_exp_f32_e64 v100, -v94
	v_exp_f32_e64 v101, -v95
	v_add_f32_e32 v98, 1.0, v98
	v_add_f32_e32 v99, 1.0, v99
	v_add_f32_e32 v100, 1.0, v100
	v_add_f32_e32 v101, 1.0, v101
	v_rcp_f32_e32 v98, v98
	v_rcp_f32_e32 v99, v99
	v_rcp_f32_e32 v100, v100
	v_rcp_f32_e32 v101, v101
	v_pk_mul_f32 v[90:91], v[94:95], v[90:91]
	v_pk_mul_f32 v[88:89], v[92:93], v[88:89]
	global_store_dwordx2 v[112:113], v[96:97], off offset:128
	v_pk_mul_f32 v[88:89], v[88:89], v[98:99]
	v_pk_mul_f32 v[90:91], v[90:91], v[100:101]
	v_cvt_pk_bf16_f32 v88, v88, v89
	v_cvt_pk_bf16_f32 v89, v90, v91
	v_exp_f32_e64 v90, -v84
	v_exp_f32_e64 v91, -v85
	v_or_b32_e32 v96, 32, v170
	v_mad_i64_i32 v[96:97], s[34:35], v96, s69, v[142:143]
	v_lshl_add_u64 v[96:97], v[96:97], 0, v[140:141]
	global_store_dwordx2 v[96:97], v[88:89], off
	v_add_f32_e32 v88, 1.0, v90
	v_add_f32_e32 v89, 1.0, v91
	v_exp_f32_e64 v90, -v86
	v_exp_f32_e64 v91, -v87
	v_rcp_f32_e32 v88, v88
	v_rcp_f32_e32 v89, v89
	v_add_f32_e32 v90, 1.0, v90
	v_add_f32_e32 v91, 1.0, v91
	v_rcp_f32_e32 v90, v90
	v_rcp_f32_e32 v91, v91
	v_pk_mul_f32 v[82:83], v[86:87], v[82:83]
	v_pk_mul_f32 v[80:81], v[84:85], v[80:81]
	v_pk_mul_f32 v[80:81], v[80:81], v[88:89]
	v_pk_mul_f32 v[82:83], v[82:83], v[90:91]
	v_cvt_pk_bf16_f32 v80, v80, v81
	v_cvt_pk_bf16_f32 v81, v82, v83
	v_exp_f32_e64 v82, -v76
	v_exp_f32_e64 v83, -v77
	v_exp_f32_e64 v84, -v78
	v_exp_f32_e64 v85, -v79
	v_add_f32_e32 v82, 1.0, v82
	v_add_f32_e32 v83, 1.0, v83
	v_add_f32_e32 v84, 1.0, v84
	v_add_f32_e32 v85, 1.0, v85
	v_rcp_f32_e32 v82, v82
	v_rcp_f32_e32 v83, v83
	v_rcp_f32_e32 v84, v84
	v_rcp_f32_e32 v85, v85
	v_pk_mul_f32 v[74:75], v[78:79], v[74:75]
	v_pk_mul_f32 v[72:73], v[76:77], v[72:73]
	global_store_dwordx2 v[96:97], v[80:81], off offset:128
	v_pk_mul_f32 v[72:73], v[72:73], v[82:83]
	v_pk_mul_f32 v[74:75], v[74:75], v[84:85]
	v_cvt_pk_bf16_f32 v72, v72, v73
	v_cvt_pk_bf16_f32 v73, v74, v75
	v_exp_f32_e64 v74, -v68
	v_exp_f32_e64 v75, -v69
	v_or_b32_e32 v80, 48, v170
	v_mad_i64_i32 v[80:81], s[34:35], v80, s69, v[142:143]
	v_lshl_add_u64 v[80:81], v[80:81], 0, v[140:141]
	global_store_dwordx2 v[80:81], v[72:73], off
	v_add_f32_e32 v72, 1.0, v74
	v_add_f32_e32 v73, 1.0, v75
	v_exp_f32_e64 v74, -v70
	v_exp_f32_e64 v75, -v71
	v_rcp_f32_e32 v72, v72
	v_rcp_f32_e32 v73, v73
	v_add_f32_e32 v74, 1.0, v74
	v_add_f32_e32 v75, 1.0, v75
	v_rcp_f32_e32 v74, v74
	v_rcp_f32_e32 v75, v75
	v_pk_mul_f32 v[66:67], v[70:71], v[66:67]
	v_pk_mul_f32 v[64:65], v[68:69], v[64:65]
; DI float ex2(float x) { return __builtin_amdgcn_exp2f(x); }
;     DI void operator()(const f32x4 (&acc)[2][2][4][2], const Unit& u, int wr, int wc, int fr, int fq) const {
;         const int row0 = u.pm * BM + wr * 64 + fr, hcol0 = ((u.pn * BM + wc * 32) >> 1) + 4 * fq;
; #pragma unroll
;         for (int ai = 0; ai < 2; ++ai)
; #pragma unroll
;             for (int m = 0; m < 4; ++m) { u16* rowp = O + (size_t)(row0 + ai * HALF + m * 16) * ldc + hcol0;
; #pragma unroll
;                 for (int bj = 0; bj < 2; ++bj) { const f32x4 g = acc[ai][bj][m][0], up = acc[ai][bj][m][1]; float r[4];
; #pragma unroll
;                     for (int j = 0; j < 4; ++j) r[j] = g[j] * up[j] * __builtin_amdgcn_rcpf(1.f + ex2(-LOG2E * g[j]));
;                     uint2 w = {pack2(r[0], r[1]), pack2(r[2], r[3])}; *(uint2*)(rowp + bj * (HALF / 2)) = w; } }
;     }
; template <class Epi, class Sched, bool STAMP = false>
; __device__ __forceinline__ void gemm_phase(PG8_LAS unsigned char* lds, const Gemm g, const Sched& S, const Epi& E, unsigned long long* stamps) {
;     ...
;         if (!has_next) break;
; #pragma unroll
;         for (int a = 0; a < 2; ++a)
; #pragma unroll
;             for (int b = 0; b < 2; ++b)
; #pragma unroll
;                 for (int m = 0; m < 4; ++m)
; #pragma unroll
;                     for (int n = 0; n < 2; ++n) acc[a][b][m][n] = (f32x4){0.f, 0.f, 0.f, 0.f};
;         cur = nxt; cA = nA; cB = nB; ++ui;
	v_pk_mul_f32 v[64:65], v[64:65], v[72:73]
	v_pk_mul_f32 v[66:67], v[66:67], v[74:75]
	v_cvt_pk_bf16_f32 v64, v64, v65
	v_cvt_pk_bf16_f32 v65, v66, v67
	v_exp_f32_e64 v66, -v60
	v_exp_f32_e64 v67, -v61
	v_exp_f32_e64 v68, -v62
	v_exp_f32_e64 v69, -v63
	v_add_f32_e32 v66, 1.0, v66
	v_add_f32_e32 v67, 1.0, v67
	v_add_f32_e32 v68, 1.0, v68
	v_add_f32_e32 v69, 1.0, v69
	v_rcp_f32_e32 v66, v66
	v_rcp_f32_e32 v67, v67
	v_rcp_f32_e32 v68, v68
	v_rcp_f32_e32 v69, v69
	v_pk_mul_f32 v[58:59], v[62:63], v[58:59]
	v_pk_mul_f32 v[56:57], v[60:61], v[56:57]
	global_store_dwordx2 v[80:81], v[64:65], off offset:128
	v_pk_mul_f32 v[56:57], v[56:57], v[66:67]
	v_pk_mul_f32 v[58:59], v[58:59], v[68:69]
	v_cvt_pk_bf16_f32 v56, v56, v57
	v_cvt_pk_bf16_f32 v57, v58, v59
	v_exp_f32_e64 v58, -v52
	v_exp_f32_e64 v59, -v53
	v_add_u32_e32 v64, 0x80, v170
	v_mad_i64_i32 v[64:65], s[34:35], v64, s69, v[142:143]
	v_lshl_add_u64 v[64:65], v[64:65], 0, v[140:141]
	global_store_dwordx2 v[64:65], v[56:57], off
	v_add_f32_e32 v56, 1.0, v58
	v_add_f32_e32 v57, 1.0, v59
	v_exp_f32_e64 v58, -v54
	v_exp_f32_e64 v59, -v55
	v_rcp_f32_e32 v56, v56
	v_rcp_f32_e32 v57, v57
	v_add_f32_e32 v58, 1.0, v58
	v_add_f32_e32 v59, 1.0, v59
	v_rcp_f32_e32 v58, v58
	v_rcp_f32_e32 v59, v59
	v_pk_mul_f32 v[50:51], v[54:55], v[50:51]
	v_pk_mul_f32 v[48:49], v[52:53], v[48:49]
	v_pk_mul_f32 v[48:49], v[48:49], v[56:57]
	v_pk_mul_f32 v[50:51], v[50:51], v[58:59]
	v_cvt_pk_bf16_f32 v48, v48, v49
	v_cvt_pk_bf16_f32 v49, v50, v51
	v_exp_f32_e64 v50, -v44
	v_exp_f32_e64 v51, -v45
	v_exp_f32_e64 v52, -v46
	v_exp_f32_e64 v53, -v47
	v_add_f32_e32 v50, 1.0, v50
	v_add_f32_e32 v51, 1.0, v51
	v_add_f32_e32 v52, 1.0, v52
	v_add_f32_e32 v53, 1.0, v53
	v_rcp_f32_e32 v50, v50
	v_rcp_f32_e32 v51, v51
	v_rcp_f32_e32 v52, v52
	v_rcp_f32_e32 v53, v53
	v_pk_mul_f32 v[42:43], v[46:47], v[42:43]
	v_pk_mul_f32 v[40:41], v[44:45], v[40:41]
	global_store_dwordx2 v[64:65], v[48:49], off offset:128
	v_pk_mul_f32 v[40:41], v[40:41], v[50:51]
	v_pk_mul_f32 v[42:43], v[42:43], v[52:53]
	v_cvt_pk_bf16_f32 v40, v40, v41
	v_cvt_pk_bf16_f32 v41, v42, v43
	v_exp_f32_e64 v42, -v36
	v_exp_f32_e64 v43, -v37
	v_add_u32_e32 v48, 0x90, v170
	v_mad_i64_i32 v[48:49], s[34:35], v48, s69, v[142:143]
	v_lshl_add_u64 v[48:49], v[48:49], 0, v[140:141]
	global_store_dwordx2 v[48:49], v[40:41], off
	v_add_f32_e32 v40, 1.0, v42
	v_add_f32_e32 v41, 1.0, v43
	v_exp_f32_e64 v42, -v38
	v_exp_f32_e64 v43, -v39
	v_rcp_f32_e32 v40, v40
	v_rcp_f32_e32 v41, v41
	v_add_f32_e32 v42, 1.0, v42
	v_add_f32_e32 v43, 1.0, v43
	v_rcp_f32_e32 v42, v42
	v_rcp_f32_e32 v43, v43
	v_pk_mul_f32 v[34:35], v[38:39], v[34:35]
	v_pk_mul_f32 v[32:33], v[36:37], v[32:33]
	v_pk_mul_f32 v[32:33], v[32:33], v[40:41]
	v_pk_mul_f32 v[34:35], v[34:35], v[42:43]
	v_cvt_pk_bf16_f32 v32, v32, v33
	v_cvt_pk_bf16_f32 v33, v34, v35
	v_exp_f32_e64 v34, -v28
	v_exp_f32_e64 v35, -v29
	v_exp_f32_e64 v36, -v30
	v_exp_f32_e64 v37, -v31
	v_add_f32_e32 v34, 1.0, v34
	v_add_f32_e32 v35, 1.0, v35
	v_add_f32_e32 v36, 1.0, v36
	v_add_f32_e32 v37, 1.0, v37
	v_rcp_f32_e32 v34, v34
	v_rcp_f32_e32 v35, v35
	v_rcp_f32_e32 v36, v36
	v_rcp_f32_e32 v37, v37
	v_pk_mul_f32 v[26:27], v[30:31], v[26:27]
	v_pk_mul_f32 v[24:25], v[28:29], v[24:25]
	global_store_dwordx2 v[48:49], v[32:33], off offset:128
	v_pk_mul_f32 v[24:25], v[24:25], v[34:35]
	v_pk_mul_f32 v[26:27], v[26:27], v[36:37]
	v_cvt_pk_bf16_f32 v24, v24, v25
	v_cvt_pk_bf16_f32 v25, v26, v27
	v_exp_f32_e64 v26, -v20
	v_exp_f32_e64 v27, -v21
	v_add_u32_e32 v32, 0xa0, v170
	v_mad_i64_i32 v[32:33], s[34:35], v32, s69, v[142:143]
	v_lshl_add_u64 v[32:33], v[32:33], 0, v[140:141]
	global_store_dwordx2 v[32:33], v[24:25], off
	v_add_f32_e32 v24, 1.0, v26
	v_add_f32_e32 v25, 1.0, v27
	v_exp_f32_e64 v26, -v22
	v_exp_f32_e64 v27, -v23
	v_rcp_f32_e32 v24, v24
	v_rcp_f32_e32 v25, v25
	v_add_f32_e32 v26, 1.0, v26
	v_add_f32_e32 v27, 1.0, v27
	v_rcp_f32_e32 v26, v26
	v_rcp_f32_e32 v27, v27
	v_pk_mul_f32 v[18:19], v[22:23], v[18:19]
	v_pk_mul_f32 v[16:17], v[20:21], v[16:17]
	v_pk_mul_f32 v[16:17], v[16:17], v[24:25]
	v_pk_mul_f32 v[18:19], v[18:19], v[26:27]
	v_cvt_pk_bf16_f32 v16, v16, v17
	v_cvt_pk_bf16_f32 v17, v18, v19
	v_exp_f32_e64 v18, -v12
	v_exp_f32_e64 v19, -v13
	v_exp_f32_e64 v20, -v14
	v_exp_f32_e64 v21, -v15
	v_add_f32_e32 v18, 1.0, v18
	v_add_f32_e32 v19, 1.0, v19
	v_add_f32_e32 v20, 1.0, v20
	v_add_f32_e32 v21, 1.0, v21
	v_rcp_f32_e32 v18, v18
	v_rcp_f32_e32 v19, v19
	v_rcp_f32_e32 v20, v20
	v_rcp_f32_e32 v21, v21
	v_pk_mul_f32 v[10:11], v[14:15], v[10:11]
	v_pk_mul_f32 v[8:9], v[12:13], v[8:9]
	global_store_dwordx2 v[32:33], v[16:17], off offset:128
	v_pk_mul_f32 v[8:9], v[8:9], v[18:19]
	v_pk_mul_f32 v[10:11], v[10:11], v[20:21]
	v_cvt_pk_bf16_f32 v8, v8, v9
	v_cvt_pk_bf16_f32 v9, v10, v11
	v_exp_f32_e64 v10, -v4
	v_exp_f32_e64 v11, -v5
	v_add_u32_e32 v16, 0xb0, v170
	v_mad_i64_i32 v[16:17], s[34:35], v16, s69, v[142:143]
	v_lshl_add_u64 v[16:17], v[16:17], 0, v[140:141]
	global_store_dwordx2 v[16:17], v[8:9], off
	v_add_f32_e32 v8, 1.0, v10
	v_add_f32_e32 v9, 1.0, v11
	v_exp_f32_e64 v10, -v6
	v_exp_f32_e64 v11, -v7
	v_rcp_f32_e32 v8, v8
	v_rcp_f32_e32 v9, v9
	v_add_f32_e32 v10, 1.0, v10
	v_add_f32_e32 v11, 1.0, v11
	v_rcp_f32_e32 v10, v10
	v_rcp_f32_e32 v11, v11
	v_pk_mul_f32 v[2:3], v[6:7], v[2:3]
	v_pk_mul_f32 v[0:1], v[4:5], v[0:1]
	s_and_b64 vcc, exec, s[2:3]
	v_pk_mul_f32 v[0:1], v[0:1], v[8:9]
	v_pk_mul_f32 v[2:3], v[2:3], v[10:11]
	v_cvt_pk_bf16_f32 v0, v0, v1
	v_cvt_pk_bf16_f32 v1, v2, v3
	s_mov_b32 s76, s70
	s_mov_b32 s75, s71
	s_mov_b64 s[36:37], s[0:1]
	s_mov_b64 s[34:35], s[4:5]
	global_store_dwordx2 v[16:17], v[0:1], off offset:128
	s_cbranch_vccz .LBB0_432
	s_branch .Lgu3_done

; #define PG8_STAGE(bufoff, gbase, voff) do { _Pragma("unroll") for (int _i = 0; _i < 2; ++_i) \
;         __builtin_amdgcn_global_load_lds((const unsigned*)((const char*)(gbase) + (voff)[_i]), (PG8_LAS unsigned*)(lds + (bufoff) + ldsw + _i * 8192), 16, 0, 0); } while (0)
; #define PG8_LDA(dst, b, h) do { _Pragma("unroll") for (int m = 0; m < 4; ++m) _Pragma("unroll") for (int k = 0; k < 2; ++k) dst[m][k] = *(const PG8_LAS bf16x8*)(lds + PG8_SA(b, h) + aoff + m * 2048 + k * 1024); } while (0)
; template <class Epi, class Sched, bool STAMP = false>
; __device__ __forceinline__ void gemm_phase(PG8_LAS unsigned char* lds, const Gemm g, const Sched& S, const Epi& E, unsigned long long* stamps) {
;     ...
;         for (int t = 0; t < nt; t += 2) {
;             const bool last = (t == nt - 2);
;             const char* a1 = cA + (size_t)(t + 1) * kstep;
;             const char* a2 = last ? nA : cA + (size_t)(t + 2) * kstep; const char* b2 = last ? nB : cB + (size_t)(t + 2) * kstep;
;             const char* a3 = a2 + kstep; const char* b3 = b2 + kstep;
;             if (last && has_next) S.a_ready(nxt);
;             PG8_LDB(B0, 0, 0); PG8_SCHED; PG8_LDA(At, 0, 0); PG8_STAGE(PG8_SA(1, 1), a1 + hstep, voffA);
;             PG8_WAIT_L(8); PG8_BAR; PG8_WAIT_L(0); PG8_MMA(0, 0, At, B0); PG8_BAR; PG8_SCHED;
;             PG8_LDB(B1, 0, 1); PG8_STAGE(PG8_SB(0, 0), b2, voffB);
;             PG8_BAR; PG8_WAIT_L(0); PG8_MMA(0, 1, At, B1); PG8_BAR;
;             PG8_LDA(At, 0, 1); PG8_STAGE(PG8_SA(0, 0), a2, voffA);
;             PG8_BAR; PG8_WAIT_L(0); PG8_MMA(1, 0, At, B0); PG8_BAR; PG8_SCHED;
;             PG8_STAGE(PG8_SB(0, 1), b2 + hstep, voffB);
;             PG8_WAIT_V(6); PG8_BAR; PG8_MMA(1, 1, At, B1); PG8_BAR;
;             PG8_LDB(B0, 1, 0); PG8_SCHED; PG8_LDA(At, 1, 0); PG8_STAGE(PG8_SA(0, 1), a2 + hstep, voffA);
;             PG8_WAIT_L(8); PG8_BAR; PG8_WAIT_L(0); PG8_MMA(0, 0, At, B0); PG8_BAR; PG8_SCHED;
;             PG8_LDB(B1, 1, 1); PG8_STAGE(PG8_SB(1, 0), b3, voffB);
;             PG8_BAR; PG8_WAIT_L(0); PG8_MMA(0, 1, At, B1); PG8_BAR;
;             PG8_LDA(At, 1, 1); PG8_STAGE(PG8_SA(1, 0), a3, voffA);
;             PG8_BAR; PG8_WAIT_L(0); PG8_MMA(1, 0, At, B0); PG8_BAR; PG8_SCHED;
;             PG8_STAGE(PG8_SB(1, 1), b3 + hstep, voffB);
;             PG8_WAIT_V(6); PG8_BAR; PG8_MMA(1, 1, At, B1); PG8_BAR;
;         }
.Lgu3_half_loop:
	ds_read_b128 v[140:143], v147
	ds_read_b128 v[170:173], v148
	ds_read_b128 v[174:177], v149
	ds_read_b128 v[178:181], v150
	s_add_u32 s36, s34, 0x100
	s_addc_u32 s37, s35, 0
	s_cmp_eq_u32 s10, 12
	s_cselect_b32 s43, s5, s37
	s_cselect_b32 s42, s4, s36
	s_cselect_b32 s41, s1, s78
	s_cselect_b32 s40, s0, s77
	s_mov_b32 m0, s67
	ds_read_b128 v[182:185], v145
	ds_read_b128 v[186:189], v145 offset:1024
	ds_read_b128 v[190:193], v145 offset:2048
	ds_read_b128 v[194:197], v145 offset:3072
	ds_read_b128 v[198:201], v145 offset:4096
	ds_read_b128 v[202:205], v145 offset:5120
	ds_read_b128 v[206:209], v145 offset:6144
	ds_read_b128 v[210:213], v145 offset:7168
	global_load_lds_dwordx4 v132, s[34:35]
	s_mov_b32 m0, s68
	s_nop 0
	global_load_lds_dwordx4 v134, s[34:35]
	s_waitcnt lgkmcnt(8)
	s_barrier
	s_waitcnt lgkmcnt(0)
	s_setprio 1
	s_waitcnt lgkmcnt(0)
	v_mfma_f32_16x16x32_bf16 v[124:127], v[140:143], v[182:185], v[124:127]
	v_mfma_f32_16x16x32_bf16 v[120:123], v[174:177], v[182:185], v[120:123]
	v_mfma_f32_16x16x32_bf16 v[108:111], v[140:143], v[190:193], v[108:111]
	v_mfma_f32_16x16x32_bf16 v[104:107], v[174:177], v[190:193], v[104:107]
	v_mfma_f32_16x16x32_bf16 v[92:95], v[140:143], v[198:201], v[92:95]
	v_mfma_f32_16x16x32_bf16 v[88:91], v[174:177], v[198:201], v[88:91]
	v_mfma_f32_16x16x32_bf16 v[76:79], v[140:143], v[206:209], v[76:79]
	v_mfma_f32_16x16x32_bf16 v[72:75], v[174:177], v[206:209], v[72:75]
	v_mfma_f32_16x16x32_bf16 v[124:127], v[170:173], v[186:189], v[124:127]
	v_mfma_f32_16x16x32_bf16 v[120:123], v[178:181], v[186:189], v[120:123]
	v_mfma_f32_16x16x32_bf16 v[108:111], v[170:173], v[194:197], v[108:111]
	v_mfma_f32_16x16x32_bf16 v[104:107], v[178:181], v[194:197], v[104:107]
	v_mfma_f32_16x16x32_bf16 v[92:95], v[170:173], v[202:205], v[92:95]
	v_mfma_f32_16x16x32_bf16 v[88:91], v[178:181], v[202:205], v[88:91]
	v_mfma_f32_16x16x32_bf16 v[76:79], v[170:173], v[210:213], v[76:79]
	v_mfma_f32_16x16x32_bf16 v[72:75], v[178:181], v[210:213], v[72:75]
	s_setprio 0
	s_barrier
	s_mov_b32 m0, s49
	s_nop 0
	global_load_lds_dwordx4 v130, s[40:41]
	s_mov_b32 m0, s52
	s_nop 0
	global_load_lds_dwordx4 v128, s[40:41]
	s_waitcnt lgkmcnt(0)
	s_barrier
	s_waitcnt lgkmcnt(0)
	s_setprio 1
	s_waitcnt lgkmcnt(0)
	s_setprio 0
	s_mov_b32 m0, s46
	s_barrier
	ds_read_b128 v[182:185], v145 offset:16384
	ds_read_b128 v[186:189], v145 offset:17408
	ds_read_b128 v[190:193], v145 offset:18432
	ds_read_b128 v[194:197], v145 offset:19456
	ds_read_b128 v[198:201], v145 offset:20480
	ds_read_b128 v[202:205], v145 offset:21504
	ds_read_b128 v[206:209], v145 offset:22528
	ds_read_b128 v[210:213], v145 offset:23552
	global_load_lds_dwordx4 v130, s[42:43]
	s_mov_b32 m0, s53
	s_nop 0
	global_load_lds_dwordx4 v128, s[42:43]
	s_add_u32 s34, s40, 0x44000
	s_addc_u32 s35, s41, 0
	s_mov_b32 m0, s54
	s_nop 0
	s_mov_b32 m0, s55
	s_nop 0
	s_waitcnt vmcnt(4)
	s_barrier
	s_waitcnt lgkmcnt(0)
	s_setprio 1
	s_waitcnt lgkmcnt(0)
	v_mfma_f32_16x16x32_bf16 v[60:63], v[140:143], v[182:185], v[60:63]
	v_mfma_f32_16x16x32_bf16 v[56:59], v[174:177], v[182:185], v[56:59]
	v_mfma_f32_16x16x32_bf16 v[44:47], v[140:143], v[190:193], v[44:47]
	v_mfma_f32_16x16x32_bf16 v[40:43], v[174:177], v[190:193], v[40:43]
	v_mfma_f32_16x16x32_bf16 v[28:31], v[140:143], v[198:201], v[28:31]
	v_mfma_f32_16x16x32_bf16 v[24:27], v[174:177], v[198:201], v[24:27]
	v_mfma_f32_16x16x32_bf16 v[12:15], v[140:143], v[206:209], v[12:15]
	v_mfma_f32_16x16x32_bf16 v[8:11], v[174:177], v[206:209], v[8:11]
	v_mfma_f32_16x16x32_bf16 v[60:63], v[170:173], v[186:189], v[60:63]
	v_mfma_f32_16x16x32_bf16 v[56:59], v[178:181], v[186:189], v[56:59]
	v_mfma_f32_16x16x32_bf16 v[44:47], v[170:173], v[194:197], v[44:47]
	v_mfma_f32_16x16x32_bf16 v[40:43], v[178:181], v[194:197], v[40:43]
	v_mfma_f32_16x16x32_bf16 v[28:31], v[170:173], v[202:205], v[28:31]
	v_mfma_f32_16x16x32_bf16 v[24:27], v[178:181], v[202:205], v[24:27]
	v_mfma_f32_16x16x32_bf16 v[12:15], v[170:173], v[210:213], v[12:15]
	v_mfma_f32_16x16x32_bf16 v[8:11], v[178:181], v[210:213], v[8:11]
	s_setprio 0
	s_barrier
	ds_read_b128 v[140:143], v155
	ds_read_b128 v[170:173], v156
	ds_read_b128 v[174:177], v157
	ds_read_b128 v[178:181], v165
	s_add_u32 s34, s42, 0x44000
	s_addc_u32 s35, s43, 0
	s_mov_b32 m0, s56
	ds_read_b128 v[182:185], v145 offset:32768
	ds_read_b128 v[186:189], v145 offset:33792
	ds_read_b128 v[190:193], v145 offset:34816
	ds_read_b128 v[194:197], v145 offset:35840
	ds_read_b128 v[198:201], v145 offset:36864
	ds_read_b128 v[202:205], v145 offset:37888
	ds_read_b128 v[206:209], v145 offset:38912
	ds_read_b128 v[210:213], v145 offset:39936
	global_load_lds_dwordx4 v130, s[34:35]
	s_mov_b32 m0, s57
	s_nop 0
	global_load_lds_dwordx4 v128, s[34:35]
	s_waitcnt lgkmcnt(8)
	s_barrier
	s_waitcnt lgkmcnt(0)
	s_setprio 1
	s_waitcnt lgkmcnt(0)
	v_mfma_f32_16x16x32_bf16 v[124:127], v[140:143], v[182:185], v[124:127]
	v_mfma_f32_16x16x32_bf16 v[120:123], v[174:177], v[182:185], v[120:123]
	v_mfma_f32_16x16x32_bf16 v[108:111], v[140:143], v[190:193], v[108:111]
	v_mfma_f32_16x16x32_bf16 v[104:107], v[174:177], v[190:193], v[104:107]
	v_mfma_f32_16x16x32_bf16 v[92:95], v[140:143], v[198:201], v[92:95]
	v_mfma_f32_16x16x32_bf16 v[88:91], v[174:177], v[198:201], v[88:91]
	v_mfma_f32_16x16x32_bf16 v[76:79], v[140:143], v[206:209], v[76:79]
	v_mfma_f32_16x16x32_bf16 v[72:75], v[174:177], v[206:209], v[72:75]
	v_mfma_f32_16x16x32_bf16 v[124:127], v[170:173], v[186:189], v[124:127]
	v_mfma_f32_16x16x32_bf16 v[120:123], v[178:181], v[186:189], v[120:123]
	v_mfma_f32_16x16x32_bf16 v[108:111], v[170:173], v[194:197], v[108:111]
	v_mfma_f32_16x16x32_bf16 v[104:107], v[178:181], v[194:197], v[104:107]
	v_mfma_f32_16x16x32_bf16 v[92:95], v[170:173], v[202:205], v[92:95]
	v_mfma_f32_16x16x32_bf16 v[88:91], v[178:181], v[202:205], v[88:91]
	v_mfma_f32_16x16x32_bf16 v[76:79], v[170:173], v[210:213], v[76:79]
	v_mfma_f32_16x16x32_bf16 v[72:75], v[178:181], v[210:213], v[72:75]
	s_setprio 0
	s_barrier
; #define PG8_STAGE(bufoff, gbase, voff) do { _Pragma("unroll") for (int _i = 0; _i < 2; ++_i) \
;         __builtin_amdgcn_global_load_lds((const unsigned*)((const char*)(gbase) + (voff)[_i]), (PG8_LAS unsigned*)(lds + (bufoff) + ldsw + _i * 8192), 16, 0, 0); } while (0)
; #define PG8_LDA(dst, b, h) do { _Pragma("unroll") for (int m = 0; m < 4; ++m) _Pragma("unroll") for (int k = 0; k < 2; ++k) dst[m][k] = *(const PG8_LAS bf16x8*)(lds + PG8_SA(b, h) + aoff + m * 2048 + k * 1024); } while (0)
; template <class Epi, class Sched, bool STAMP = false>
; __device__ __forceinline__ void gemm_phase(PG8_LAS unsigned char* lds, const Gemm g, const Sched& S, const Epi& E, unsigned long long* stamps) {
;     ...
;         for (int t = 0; t < nt; t += 2) {
;             const bool last = (t == nt - 2);
;             const char* a1 = cA + (size_t)(t + 1) * kstep;
;             const char* a2 = last ? nA : cA + (size_t)(t + 2) * kstep; const char* b2 = last ? nB : cB + (size_t)(t + 2) * kstep;
;             const char* a3 = a2 + kstep; const char* b3 = b2 + kstep;
;             if (last && has_next) S.a_ready(nxt);
;             PG8_LDB(B0, 0, 0); PG8_SCHED; PG8_LDA(At, 0, 0); PG8_STAGE(PG8_SA(1, 1), a1 + hstep, voffA);
;             PG8_WAIT_L(8); PG8_BAR; PG8_WAIT_L(0); PG8_MMA(0, 0, At, B0); PG8_BAR; PG8_SCHED;
;             PG8_LDB(B1, 0, 1); PG8_STAGE(PG8_SB(0, 0), b2, voffB);
;             PG8_BAR; PG8_WAIT_L(0); PG8_MMA(0, 1, At, B1); PG8_BAR;
;             PG8_LDA(At, 0, 1); PG8_STAGE(PG8_SA(0, 0), a2, voffA);
;             PG8_BAR; PG8_WAIT_L(0); PG8_MMA(1, 0, At, B0); PG8_BAR; PG8_SCHED;
;             PG8_STAGE(PG8_SB(0, 1), b2 + hstep, voffB);
;             PG8_WAIT_V(6); PG8_BAR; PG8_MMA(1, 1, At, B1); PG8_BAR;
;             PG8_LDB(B0, 1, 0); PG8_SCHED; PG8_LDA(At, 1, 0); PG8_STAGE(PG8_SA(0, 1), a2 + hstep, voffA);
;             PG8_WAIT_L(8); PG8_BAR; PG8_WAIT_L(0); PG8_MMA(0, 0, At, B0); PG8_BAR; PG8_SCHED;
;             PG8_LDB(B1, 1, 1); PG8_STAGE(PG8_SB(1, 0), b3, voffB);
;             PG8_BAR; PG8_WAIT_L(0); PG8_MMA(0, 1, At, B1); PG8_BAR;
;             PG8_LDA(At, 1, 1); PG8_STAGE(PG8_SA(1, 0), a3, voffA);
;             PG8_BAR; PG8_WAIT_L(0); PG8_MMA(1, 0, At, B0); PG8_BAR; PG8_SCHED;
;             PG8_STAGE(PG8_SB(1, 1), b3 + hstep, voffB);
;             PG8_WAIT_V(6); PG8_BAR; PG8_MMA(1, 1, At, B1); PG8_BAR;
;         }
	s_mov_b32 m0, s60
	s_add_u32 s100, s40, 0x80
	s_addc_u32 s101, s41, 0
	global_load_lds_dwordx4 v130, s[100:101]
	s_mov_b32 m0, s61
	s_nop 0
	global_load_lds_dwordx4 v128, s[100:101]
	s_waitcnt lgkmcnt(0)
	s_barrier
	s_waitcnt lgkmcnt(0)
	s_setprio 1
	s_waitcnt lgkmcnt(0)
	s_setprio 0
	s_mov_b32 m0, s62
	s_barrier
	ds_read_b128 v[182:185], v145 offset:49152
	ds_read_b128 v[186:189], v145 offset:50176
	ds_read_b128 v[190:193], v145 offset:51200
	ds_read_b128 v[194:197], v145 offset:52224
	ds_read_b128 v[198:201], v145 offset:53248
	ds_read_b128 v[202:205], v145 offset:54272
	ds_read_b128 v[206:209], v145 offset:55296
	ds_read_b128 v[210:213], v145 offset:56320
	s_add_u32 s100, s42, 0x80
	s_addc_u32 s101, s43, 0
	global_load_lds_dwordx4 v130, s[100:101]
	s_mov_b32 m0, s63
	s_nop 0
	global_load_lds_dwordx4 v128, s[100:101]
	s_add_u32 s34, s40, 0x44080
	s_addc_u32 s35, s41, 0
	s_mov_b32 m0, s64
	s_nop 0
	s_mov_b32 m0, s65
	s_nop 0
	s_waitcnt vmcnt(4)
	s_barrier
	s_waitcnt lgkmcnt(0)
	s_setprio 1
	s_waitcnt lgkmcnt(0)
	v_mfma_f32_16x16x32_bf16 v[60:63], v[140:143], v[182:185], v[60:63]
	v_mfma_f32_16x16x32_bf16 v[56:59], v[174:177], v[182:185], v[56:59]
	v_mfma_f32_16x16x32_bf16 v[44:47], v[140:143], v[190:193], v[44:47]
	v_mfma_f32_16x16x32_bf16 v[40:43], v[174:177], v[190:193], v[40:43]
	v_mfma_f32_16x16x32_bf16 v[28:31], v[140:143], v[198:201], v[28:31]
	v_mfma_f32_16x16x32_bf16 v[24:27], v[174:177], v[198:201], v[24:27]
	v_mfma_f32_16x16x32_bf16 v[12:15], v[140:143], v[206:209], v[12:15]
	v_mfma_f32_16x16x32_bf16 v[8:11], v[174:177], v[206:209], v[8:11]
	v_mfma_f32_16x16x32_bf16 v[60:63], v[170:173], v[186:189], v[60:63]
	v_mfma_f32_16x16x32_bf16 v[56:59], v[178:181], v[186:189], v[56:59]
	v_mfma_f32_16x16x32_bf16 v[44:47], v[170:173], v[194:197], v[44:47]
	v_mfma_f32_16x16x32_bf16 v[40:43], v[178:181], v[194:197], v[40:43]
	v_mfma_f32_16x16x32_bf16 v[28:31], v[170:173], v[202:205], v[28:31]
	v_mfma_f32_16x16x32_bf16 v[24:27], v[178:181], v[202:205], v[24:27]
	v_mfma_f32_16x16x32_bf16 v[12:15], v[170:173], v[210:213], v[12:15]
	v_mfma_f32_16x16x32_bf16 v[8:11], v[178:181], v[210:213], v[8:11]
	s_setprio 0
	s_add_i32 s10, s10, 2
	s_add_u32 s77, s77, 0x100
	s_addc_u32 s78, s78, 0
	s_cmp_gt_u32 s10, 13
	s_mov_b64 s[34:35], s[36:37]
	s_barrier
	s_cbranch_scc0 .Lgu3_half_loop
; DI float ex2(float x) { return __builtin_amdgcn_exp2f(x); }
;     DI void operator()(const f32x4 (&acc)[2][2][4][2], const Unit& u, int wr, int wc, int fr, int fq) const {
;         const int row0 = u.pm * BM + wr * 64 + fr, hcol0 = ((u.pn * BM + wc * 32) >> 1) + 4 * fq;
; #pragma unroll
;         for (int ai = 0; ai < 2; ++ai)
; #pragma unroll
;             for (int m = 0; m < 4; ++m) { u16* rowp = O + (size_t)(row0 + ai * HALF + m * 16) * ldc + hcol0;
; #pragma unroll
;                 for (int bj = 0; bj < 2; ++bj) { const f32x4 g = acc[ai][bj][m][0], up = acc[ai][bj][m][1]; float r[4];
; #pragma unroll
;                     for (int j = 0; j < 4; ++j) r[j] = g[j] * up[j] * __builtin_amdgcn_rcpf(1.f + ex2(-LOG2E * g[j]));
;                     uint2 w = {pack2(r[0], r[1]), pack2(r[2], r[3])}; *(uint2*)(rowp + bj * (HALF / 2)) = w; } }
;     }
	v_exp_f32_e64 v171, -v124
	v_exp_f32_e64 v175, -v125
	s_lshl_b32 s10, s76, 8
	v_add_f32_e32 v171, 1.0, v171
	v_rcp_f32_e32 v174, v171
	v_add_f32_e32 v171, 1.0, v175
	v_exp_f32_e64 v176, -v126
	v_exp_f32_e64 v177, -v127
	v_rcp_f32_e32 v175, v171
	v_add_f32_e32 v171, 1.0, v176
	v_rcp_f32_e32 v176, v171
	v_add_f32_e32 v171, 1.0, v177
	v_rcp_f32_e32 v177, v171
	v_pk_mul_f32 v[122:123], v[126:127], v[122:123]
	v_pk_mul_f32 v[120:121], v[124:125], v[120:121]
	s_or_b32 s10, s10, s59
	s_or_b32 s10, s10, s98
	v_pk_mul_f32 v[120:121], v[120:121], v[174:175]
	v_pk_mul_f32 v[122:123], v[122:123], v[176:177]
	s_ashr_i32 s10, s10, 1
	v_cvt_pk_bf16_f32 v120, v120, v121
	v_cvt_pk_bf16_f32 v121, v122, v123
	v_or_b32_e32 v140, s10, v146
	v_lshl_add_u32 v170, s75, 8, v144
	v_ashrrev_i32_e32 v141, 31, v140
	v_mov_b64_e32 v[142:143], s[12:13]
	v_mad_i64_i32 v[172:173], s[34:35], v170, s69, v[142:143]
	v_lshlrev_b64 v[140:141], 1, v[140:141]
	v_lshl_add_u64 v[172:173], v[172:173], 0, v[140:141]
	global_store_dwordx2 v[172:173], v[120:121], off
	v_exp_f32_e64 v114, -v108
	v_exp_f32_e64 v115, -v109
	v_exp_f32_e64 v116, -v110
	v_exp_f32_e64 v117, -v111
	v_add_f32_e32 v114, 1.0, v114
	v_add_f32_e32 v115, 1.0, v115
	v_add_f32_e32 v116, 1.0, v116
	v_add_f32_e32 v117, 1.0, v117
	v_rcp_f32_e32 v114, v114
	v_rcp_f32_e32 v115, v115
	v_rcp_f32_e32 v116, v116
	v_rcp_f32_e32 v117, v117
	v_pk_mul_f32 v[106:107], v[110:111], v[106:107]
	v_pk_mul_f32 v[104:105], v[108:109], v[104:105]
	v_pk_mul_f32 v[104:105], v[104:105], v[114:115]
	v_pk_mul_f32 v[106:107], v[106:107], v[116:117]
	v_cvt_pk_bf16_f32 v104, v104, v105
	v_cvt_pk_bf16_f32 v105, v106, v107
	v_or_b32_e32 v112, 16, v170
	v_mad_i64_i32 v[112:113], s[34:35], v112, s69, v[142:143]
	v_lshl_add_u64 v[112:113], v[112:113], 0, v[140:141]
	global_store_dwordx2 v[112:113], v[104:105], off
	v_exp_f32_e64 v98, -v92
	v_exp_f32_e64 v99, -v93
	v_exp_f32_e64 v100, -v94
	v_exp_f32_e64 v101, -v95
	v_add_f32_e32 v98, 1.0, v98
	v_add_f32_e32 v99, 1.0, v99
	v_add_f32_e32 v100, 1.0, v100
	v_add_f32_e32 v101, 1.0, v101
	v_rcp_f32_e32 v98, v98
	v_rcp_f32_e32 v99, v99
	v_rcp_f32_e32 v100, v100
	v_rcp_f32_e32 v101, v101
	v_pk_mul_f32 v[90:91], v[94:95], v[90:91]
	v_pk_mul_f32 v[88:89], v[92:93], v[88:89]
	v_pk_mul_f32 v[88:89], v[88:89], v[98:99]
	v_pk_mul_f32 v[90:91], v[90:91], v[100:101]
	v_cvt_pk_bf16_f32 v88, v88, v89
	v_cvt_pk_bf16_f32 v89, v90, v91
	v_or_b32_e32 v96, 32, v170
	v_mad_i64_i32 v[96:97], s[34:35], v96, s69, v[142:143]
	v_lshl_add_u64 v[96:97], v[96:97], 0, v[140:141]
	global_store_dwordx2 v[96:97], v[88:89], off
	v_exp_f32_e64 v82, -v76
	v_exp_f32_e64 v83, -v77
	v_exp_f32_e64 v84, -v78
	v_exp_f32_e64 v85, -v79
	v_add_f32_e32 v82, 1.0, v82
	v_add_f32_e32 v83, 1.0, v83
	v_add_f32_e32 v84, 1.0, v84
	v_add_f32_e32 v85, 1.0, v85
	v_rcp_f32_e32 v82, v82
	v_rcp_f32_e32 v83, v83
	v_rcp_f32_e32 v84, v84
	v_rcp_f32_e32 v85, v85
	v_pk_mul_f32 v[74:75], v[78:79], v[74:75]
	v_pk_mul_f32 v[72:73], v[76:77], v[72:73]
	v_pk_mul_f32 v[72:73], v[72:73], v[82:83]
	v_pk_mul_f32 v[74:75], v[74:75], v[84:85]
	v_cvt_pk_bf16_f32 v72, v72, v73
	v_cvt_pk_bf16_f32 v73, v74, v75
	v_or_b32_e32 v80, 48, v170
	v_mad_i64_i32 v[80:81], s[34:35], v80, s69, v[142:143]
	v_lshl_add_u64 v[80:81], v[80:81], 0, v[140:141]
	global_store_dwordx2 v[80:81], v[72:73], off
	v_exp_f32_e64 v66, -v60
	v_exp_f32_e64 v67, -v61
	v_exp_f32_e64 v68, -v62
	v_exp_f32_e64 v69, -v63
	v_add_f32_e32 v66, 1.0, v66
	v_add_f32_e32 v67, 1.0, v67
	v_add_f32_e32 v68, 1.0, v68
	v_add_f32_e32 v69, 1.0, v69
	v_rcp_f32_e32 v66, v66
	v_rcp_f32_e32 v67, v67
	v_rcp_f32_e32 v68, v68
	v_rcp_f32_e32 v69, v69
	v_pk_mul_f32 v[58:59], v[62:63], v[58:59]
	v_pk_mul_f32 v[56:57], v[60:61], v[56:57]
	v_pk_mul_f32 v[56:57], v[56:57], v[66:67]
	v_pk_mul_f32 v[58:59], v[58:59], v[68:69]
	v_cvt_pk_bf16_f32 v56, v56, v57
	v_cvt_pk_bf16_f32 v57, v58, v59
	v_add_u32_e32 v64, 0x80, v170
	v_mad_i64_i32 v[64:65], s[34:35], v64, s69, v[142:143]
	v_lshl_add_u64 v[64:65], v[64:65], 0, v[140:141]
	global_store_dwordx2 v[64:65], v[56:57], off
	v_exp_f32_e64 v50, -v44
	v_exp_f32_e64 v51, -v45
	v_exp_f32_e64 v52, -v46
	v_exp_f32_e64 v53, -v47
	v_add_f32_e32 v50, 1.0, v50
	v_add_f32_e32 v51, 1.0, v51
	v_add_f32_e32 v52, 1.0, v52
	v_add_f32_e32 v53, 1.0, v53
	v_rcp_f32_e32 v50, v50
	v_rcp_f32_e32 v51, v51
	v_rcp_f32_e32 v52, v52
	v_rcp_f32_e32 v53, v53
	v_pk_mul_f32 v[42:43], v[46:47], v[42:43]
	v_pk_mul_f32 v[40:41], v[44:45], v[40:41]
	v_pk_mul_f32 v[40:41], v[40:41], v[50:51]
	v_pk_mul_f32 v[42:43], v[42:43], v[52:53]
	v_cvt_pk_bf16_f32 v40, v40, v41
	v_cvt_pk_bf16_f32 v41, v42, v43
	v_add_u32_e32 v48, 0x90, v170
	v_mad_i64_i32 v[48:49], s[34:35], v48, s69, v[142:143]
	v_lshl_add_u64 v[48:49], v[48:49], 0, v[140:141]
	global_store_dwordx2 v[48:49], v[40:41], off
	v_exp_f32_e64 v34, -v28
	v_exp_f32_e64 v35, -v29
	v_exp_f32_e64 v36, -v30
	v_exp_f32_e64 v37, -v31
	v_add_f32_e32 v34, 1.0, v34
	v_add_f32_e32 v35, 1.0, v35
	v_add_f32_e32 v36, 1.0, v36
	v_add_f32_e32 v37, 1.0, v37
	v_rcp_f32_e32 v34, v34
	v_rcp_f32_e32 v35, v35
	v_rcp_f32_e32 v36, v36
	v_rcp_f32_e32 v37, v37
	v_pk_mul_f32 v[26:27], v[30:31], v[26:27]
	v_pk_mul_f32 v[24:25], v[28:29], v[24:25]
	v_pk_mul_f32 v[24:25], v[24:25], v[34:35]
	v_pk_mul_f32 v[26:27], v[26:27], v[36:37]
	v_cvt_pk_bf16_f32 v24, v24, v25
	v_cvt_pk_bf16_f32 v25, v26, v27
	v_add_u32_e32 v32, 0xa0, v170
	v_mad_i64_i32 v[32:33], s[34:35], v32, s69, v[142:143]
	v_lshl_add_u64 v[32:33], v[32:33], 0, v[140:141]
	global_store_dwordx2 v[32:33], v[24:25], off
	v_exp_f32_e64 v18, -v12
	v_exp_f32_e64 v19, -v13
	v_exp_f32_e64 v20, -v14
	v_exp_f32_e64 v21, -v15
	v_add_f32_e32 v18, 1.0, v18
	v_add_f32_e32 v19, 1.0, v19
	v_add_f32_e32 v20, 1.0, v20
	v_add_f32_e32 v21, 1.0, v21
	v_rcp_f32_e32 v18, v18
	v_rcp_f32_e32 v19, v19
	v_rcp_f32_e32 v20, v20
	v_rcp_f32_e32 v21, v21
	v_pk_mul_f32 v[10:11], v[14:15], v[10:11]
	v_pk_mul_f32 v[8:9], v[12:13], v[8:9]
	v_pk_mul_f32 v[8:9], v[8:9], v[18:19]
	v_pk_mul_f32 v[10:11], v[10:11], v[20:21]
	v_cvt_pk_bf16_f32 v8, v8, v9
	v_cvt_pk_bf16_f32 v9, v10, v11
	v_add_u32_e32 v16, 0xb0, v170
	v_mad_i64_i32 v[16:17], s[34:35], v16, s69, v[142:143]
	v_lshl_add_u64 v[16:17], v[16:17], 0, v[140:141]
	global_store_dwordx2 v[16:17], v[8:9], off
	s_and_b64 vcc, exec, s[2:3]
	s_mov_b32 s76, s70
	s_mov_b32 s75, s71
	s_mov_b64 s[36:37], s[0:1]
	s_mov_b64 s[34:35], s[4:5]

; #define PG8_STAGE(bufoff, gbase, voff) do { _Pragma("unroll") for (int _i = 0; _i < 2; ++_i) \
;         __builtin_amdgcn_global_load_lds((const unsigned*)((const char*)(gbase) + (voff)[_i]), (PG8_LAS unsigned*)(lds + (bufoff) + ldsw + _i * 8192), 16, 0, 0); } while (0)
; template <class Epi, class Sched, bool STAMP = false>
; __device__ __forceinline__ void gemm_phase(PG8_LAS unsigned char* lds, const Gemm g, const Sched& S, const Epi& E, unsigned long long* stamps) {
;     ...
;     for (;;) {
;         const bool has_next = S.next(ui + 1, nxt);
;         const char* nA = has_next ? (const char*)g.A + (size_t)nxt.pm * tstep : cA; const char* nB = has_next ? (const char*)g.Bt + (size_t)nxt.pn * tstep : cB;
;         for (int t = 0; t < nt; t += 2) {
;             const bool last = (t == nt - 2);
;             const char* a1 = cA + (size_t)(t + 1) * kstep;
;             const char* a2 = last ? nA : cA + (size_t)(t + 2) * kstep; const char* b2 = last ? nB : cB + (size_t)(t + 2) * kstep;
;             const char* a3 = a2 + kstep; const char* b3 = b2 + kstep;
;             if (last && has_next) S.a_ready(nxt);
;             PG8_LDB(B0, 0, 0); PG8_SCHED; PG8_LDA(At, 0, 0); PG8_STAGE(PG8_SA(1, 1), a1 + hstep, voffA);
;             PG8_WAIT_L(8); PG8_BAR; PG8_WAIT_L(0); PG8_MMA(0, 0, At, B0); PG8_BAR; PG8_SCHED;
;             PG8_LDB(B1, 0, 1); PG8_STAGE(PG8_SB(0, 0), b2, voffB);
;             PG8_BAR; PG8_WAIT_L(0); PG8_MMA(0, 1, At, B1); PG8_BAR;
;             PG8_LDA(At, 0, 1); PG8_STAGE(PG8_SA(0, 0), a2, voffA);
;             PG8_BAR; PG8_WAIT_L(0); PG8_MMA(1, 0, At, B0); PG8_BAR; PG8_SCHED;
;             PG8_STAGE(PG8_SB(0, 1), b2 + hstep, voffB);
;             PG8_WAIT_V(6); PG8_BAR; PG8_MMA(1, 1, At, B1); PG8_BAR;
;             PG8_LDB(B0, 1, 0); PG8_SCHED; PG8_LDA(At, 1, 0); PG8_STAGE(PG8_SA(0, 1), a2 + hstep, voffA);
;             PG8_WAIT_L(8); PG8_BAR; PG8_WAIT_L(0); PG8_MMA(0, 0, At, B0); PG8_BAR; PG8_SCHED;
;             PG8_LDB(B1, 1, 1); PG8_STAGE(PG8_SB(1, 0), b3, voffB);
;             PG8_BAR; PG8_WAIT_L(0); PG8_MMA(0, 1, At, B1); PG8_BAR;
;             PG8_LDA(At, 1, 1); PG8_STAGE(PG8_SA(1, 0), a3, voffA);
;             PG8_BAR; PG8_WAIT_L(0); PG8_MMA(1, 0, At, B0); PG8_BAR; PG8_SCHED;
;             PG8_STAGE(PG8_SB(1, 1), b3 + hstep, voffB);
;             PG8_WAIT_V(6); PG8_BAR; PG8_MMA(1, 1, At, B1); PG8_BAR;
;         }
.LBB0_472:
	s_add_u32 s88, s46, 0x100
	s_addc_u32 s89, s47, 0
	s_mov_b32 s10, -2
	ds_read_b128 v[170:173], v147
	ds_read_b128 v[174:177], v148
	ds_read_b128 v[178:181], v149
	ds_read_b128 v[182:185], v150
	s_add_u32 s46, s44, 0x100
	s_addc_u32 s47, s45, 0
	s_cmp_eq_u32 s10, 40
	s_cselect_b32 s53, s5, s47
	s_cselect_b32 s52, s4, s46
	s_cselect_b32 s49, s1, s89
	s_cselect_b32 s48, s0, s88
	s_mov_b32 m0, s76
	ds_read_b128 v[186:189], v145
	ds_read_b128 v[190:193], v145 offset:1024
	ds_read_b128 v[194:197], v145 offset:2048
	ds_read_b128 v[198:201], v145 offset:3072
	ds_read_b128 v[202:205], v145 offset:4096
	ds_read_b128 v[206:209], v145 offset:5120
	ds_read_b128 v[210:213], v145 offset:6144
	ds_read_b128 v[214:217], v145 offset:7168
	global_load_lds_dwordx4 v136, s[44:45]
	s_mov_b32 m0, s77
	s_nop 0
	global_load_lds_dwordx4 v138, s[44:45]
	s_waitcnt lgkmcnt(8)
	s_barrier
	s_waitcnt lgkmcnt(0)
	s_setprio 1
	s_waitcnt lgkmcnt(0)
	v_mfma_f32_16x16x32_bf16 v[124:127], v[170:173], v[186:189], 0
	v_mfma_f32_16x16x32_bf16 v[120:123], v[178:181], v[186:189], 0
	v_mfma_f32_16x16x32_bf16 v[116:119], v[170:173], v[194:197], 0
	v_mfma_f32_16x16x32_bf16 v[112:115], v[178:181], v[194:197], 0
	v_mfma_f32_16x16x32_bf16 v[100:103], v[170:173], v[202:205], 0
	v_mfma_f32_16x16x32_bf16 v[96:99], v[178:181], v[202:205], 0
	v_mfma_f32_16x16x32_bf16 v[84:87], v[170:173], v[210:213], 0
	v_mfma_f32_16x16x32_bf16 v[80:83], v[178:181], v[210:213], 0
	v_mfma_f32_16x16x32_bf16 v[124:127], v[174:177], v[190:193], v[124:127]
	v_mfma_f32_16x16x32_bf16 v[120:123], v[182:185], v[190:193], v[120:123]
	v_mfma_f32_16x16x32_bf16 v[116:119], v[174:177], v[198:201], v[116:119]
	v_mfma_f32_16x16x32_bf16 v[112:115], v[182:185], v[198:201], v[112:115]
	v_mfma_f32_16x16x32_bf16 v[100:103], v[174:177], v[206:209], v[100:103]
	v_mfma_f32_16x16x32_bf16 v[96:99], v[182:185], v[206:209], v[96:99]
	v_mfma_f32_16x16x32_bf16 v[84:87], v[174:177], v[214:217], v[84:87]
	v_mfma_f32_16x16x32_bf16 v[80:83], v[182:185], v[214:217], v[80:83]
	s_setprio 0
	s_barrier
	s_mov_b32 m0, s58
	ds_read_b128 v[218:221], v151
	ds_read_b128 v[222:225], v152
	ds_read_b128 v[226:229], v153
	ds_read_b128 v[230:233], v154
	global_load_lds_dwordx4 v130, s[48:49]
	s_mov_b32 m0, s59
	s_nop 0
	global_load_lds_dwordx4 v134, s[48:49]
	s_waitcnt lgkmcnt(0)
	s_barrier
	s_waitcnt lgkmcnt(0)
	s_setprio 1
	s_waitcnt lgkmcnt(0)
	v_mfma_f32_16x16x32_bf16 v[108:111], v[218:221], v[186:189], 0
	v_mfma_f32_16x16x32_bf16 v[104:107], v[226:229], v[186:189], 0
	v_mfma_f32_16x16x32_bf16 v[92:95], v[218:221], v[194:197], 0
	v_mfma_f32_16x16x32_bf16 v[88:91], v[226:229], v[194:197], 0
	v_mfma_f32_16x16x32_bf16 v[76:79], v[218:221], v[202:205], 0
	v_mfma_f32_16x16x32_bf16 v[72:75], v[226:229], v[202:205], 0
	v_mfma_f32_16x16x32_bf16 v[68:71], v[218:221], v[210:213], 0
	v_mfma_f32_16x16x32_bf16 v[64:67], v[226:229], v[210:213], 0
	v_mfma_f32_16x16x32_bf16 v[108:111], v[222:225], v[190:193], v[108:111]
	v_mfma_f32_16x16x32_bf16 v[104:107], v[230:233], v[190:193], v[104:107]
	v_mfma_f32_16x16x32_bf16 v[92:95], v[222:225], v[198:201], v[92:95]
	v_mfma_f32_16x16x32_bf16 v[88:91], v[230:233], v[198:201], v[88:91]
	v_mfma_f32_16x16x32_bf16 v[76:79], v[222:225], v[206:209], v[76:79]
	v_mfma_f32_16x16x32_bf16 v[72:75], v[230:233], v[206:209], v[72:75]
	v_mfma_f32_16x16x32_bf16 v[68:71], v[222:225], v[214:217], v[68:71]
	v_mfma_f32_16x16x32_bf16 v[64:67], v[230:233], v[214:217], v[64:67]
	s_setprio 0
	s_mov_b32 m0, s57
	s_barrier
	ds_read_b128 v[186:189], v145 offset:16384
	ds_read_b128 v[190:193], v145 offset:17408
	ds_read_b128 v[194:197], v145 offset:18432
	ds_read_b128 v[198:201], v145 offset:19456
	ds_read_b128 v[202:205], v145 offset:20480
	ds_read_b128 v[206:209], v145 offset:21504
	ds_read_b128 v[210:213], v145 offset:22528
	ds_read_b128 v[214:217], v145 offset:23552
	global_load_lds_dwordx4 v128, s[52:53]
	s_mov_b32 m0, s60
	s_nop 0
	global_load_lds_dwordx4 v132, s[52:53]
	s_add_u32 s44, s48, 0xb4000
	s_addc_u32 s45, s49, 0
	s_mov_b32 m0, s61
	s_nop 0
	global_load_lds_dwordx4 v130, s[44:45]
	s_mov_b32 m0, s62
	s_nop 0
	global_load_lds_dwordx4 v134, s[44:45]
	s_waitcnt vmcnt(6)
	s_barrier
	s_waitcnt lgkmcnt(0)
	s_setprio 1
	s_waitcnt lgkmcnt(0)
	v_mfma_f32_16x16x32_bf16 v[60:63], v[170:173], v[186:189], 0
	v_mfma_f32_16x16x32_bf16 v[56:59], v[178:181], v[186:189], 0
	v_mfma_f32_16x16x32_bf16 v[52:55], v[170:173], v[194:197], 0
	v_mfma_f32_16x16x32_bf16 v[48:51], v[178:181], v[194:197], 0
	v_mfma_f32_16x16x32_bf16 v[36:39], v[170:173], v[202:205], 0
	v_mfma_f32_16x16x32_bf16 v[32:35], v[178:181], v[202:205], 0
	v_mfma_f32_16x16x32_bf16 v[20:23], v[170:173], v[210:213], 0
	v_mfma_f32_16x16x32_bf16 v[16:19], v[178:181], v[210:213], 0
	v_mfma_f32_16x16x32_bf16 v[60:63], v[174:177], v[190:193], v[60:63]
	v_mfma_f32_16x16x32_bf16 v[56:59], v[182:185], v[190:193], v[56:59]
	v_mfma_f32_16x16x32_bf16 v[52:55], v[174:177], v[198:201], v[52:55]
	v_mfma_f32_16x16x32_bf16 v[48:51], v[182:185], v[198:201], v[48:51]
	v_mfma_f32_16x16x32_bf16 v[36:39], v[174:177], v[206:209], v[36:39]
	v_mfma_f32_16x16x32_bf16 v[32:35], v[182:185], v[206:209], v[32:35]
	v_mfma_f32_16x16x32_bf16 v[20:23], v[174:177], v[214:217], v[20:23]
	v_mfma_f32_16x16x32_bf16 v[16:19], v[182:185], v[214:217], v[16:19]
	v_mfma_f32_16x16x32_bf16 v[44:47], v[218:221], v[186:189], 0
	v_mfma_f32_16x16x32_bf16 v[40:43], v[226:229], v[186:189], 0
	v_mfma_f32_16x16x32_bf16 v[28:31], v[218:221], v[194:197], 0
	v_mfma_f32_16x16x32_bf16 v[24:27], v[226:229], v[194:197], 0
	v_mfma_f32_16x16x32_bf16 v[12:15], v[218:221], v[202:205], 0
	v_mfma_f32_16x16x32_bf16 v[8:11], v[226:229], v[202:205], 0
	v_mfma_f32_16x16x32_bf16 v[4:7], v[218:221], v[210:213], 0
	v_mfma_f32_16x16x32_bf16 v[0:3], v[226:229], v[210:213], 0
	v_mfma_f32_16x16x32_bf16 v[44:47], v[222:225], v[190:193], v[44:47]
	v_mfma_f32_16x16x32_bf16 v[40:43], v[230:233], v[190:193], v[40:43]
	v_mfma_f32_16x16x32_bf16 v[28:31], v[222:225], v[198:201], v[28:31]
	v_mfma_f32_16x16x32_bf16 v[24:27], v[230:233], v[198:201], v[24:27]
	v_mfma_f32_16x16x32_bf16 v[12:15], v[222:225], v[206:209], v[12:15]
	v_mfma_f32_16x16x32_bf16 v[8:11], v[230:233], v[206:209], v[8:11]
	v_mfma_f32_16x16x32_bf16 v[4:7], v[222:225], v[214:217], v[4:7]
	v_mfma_f32_16x16x32_bf16 v[0:3], v[230:233], v[214:217], v[0:3]
	s_setprio 0
	s_barrier
	s_branch .Lzp8_mid
; #define PG8_STAGE(bufoff, gbase, voff) do { _Pragma("unroll") for (int _i = 0; _i < 2; ++_i) \
;         __builtin_amdgcn_global_load_lds((const unsigned*)((const char*)(gbase) + (voff)[_i]), (PG8_LAS unsigned*)(lds + (bufoff) + ldsw + _i * 8192), 16, 0, 0); } while (0)
; #define PG8_LDA(dst, b, h) do { _Pragma("unroll") for (int m = 0; m < 4; ++m) _Pragma("unroll") for (int k = 0; k < 2; ++k) dst[m][k] = *(const PG8_LAS bf16x8*)(lds + PG8_SA(b, h) + aoff + m * 2048 + k * 1024); } while (0)
; template <class Epi, class Sched, bool STAMP = false>
; __device__ __forceinline__ void gemm_phase(PG8_LAS unsigned char* lds, const Gemm g, const Sched& S, const Epi& E, unsigned long long* stamps) {
;     ...
;         for (int t = 0; t < nt; t += 2) {
;             const bool last = (t == nt - 2);
;             const char* a1 = cA + (size_t)(t + 1) * kstep;
;             const char* a2 = last ? nA : cA + (size_t)(t + 2) * kstep; const char* b2 = last ? nB : cB + (size_t)(t + 2) * kstep;
;             const char* a3 = a2 + kstep; const char* b3 = b2 + kstep;
;             if (last && has_next) S.a_ready(nxt);
;             PG8_LDB(B0, 0, 0); PG8_SCHED; PG8_LDA(At, 0, 0); PG8_STAGE(PG8_SA(1, 1), a1 + hstep, voffA);
;             PG8_WAIT_L(8); PG8_BAR; PG8_WAIT_L(0); PG8_MMA(0, 0, At, B0); PG8_BAR; PG8_SCHED;
;             PG8_LDB(B1, 0, 1); PG8_STAGE(PG8_SB(0, 0), b2, voffB);
;             PG8_BAR; PG8_WAIT_L(0); PG8_MMA(0, 1, At, B1); PG8_BAR;
;             PG8_LDA(At, 0, 1); PG8_STAGE(PG8_SA(0, 0), a2, voffA);
;             PG8_BAR; PG8_WAIT_L(0); PG8_MMA(1, 0, At, B0); PG8_BAR; PG8_SCHED;
;             PG8_STAGE(PG8_SB(0, 1), b2 + hstep, voffB);
;             PG8_WAIT_V(6); PG8_BAR; PG8_MMA(1, 1, At, B1); PG8_BAR;
;             PG8_LDB(B0, 1, 0); PG8_SCHED; PG8_LDA(At, 1, 0); PG8_STAGE(PG8_SA(0, 1), a2 + hstep, voffA);
;             PG8_WAIT_L(8); PG8_BAR; PG8_WAIT_L(0); PG8_MMA(0, 0, At, B0); PG8_BAR; PG8_SCHED;
;             PG8_LDB(B1, 1, 1); PG8_STAGE(PG8_SB(1, 0), b3, voffB);
;             PG8_BAR; PG8_WAIT_L(0); PG8_MMA(0, 1, At, B1); PG8_BAR;
;             PG8_LDA(At, 1, 1); PG8_STAGE(PG8_SA(1, 0), a3, voffA);
;             PG8_BAR; PG8_WAIT_L(0); PG8_MMA(1, 0, At, B0); PG8_BAR; PG8_SCHED;
;             PG8_STAGE(PG8_SB(1, 1), b3 + hstep, voffB);
;             PG8_WAIT_V(6); PG8_BAR; PG8_MMA(1, 1, At, B1); PG8_BAR;
;         }
.LBB0_473:
	ds_read_b128 v[170:173], v147
	ds_read_b128 v[174:177], v148
	ds_read_b128 v[178:181], v149
	ds_read_b128 v[182:185], v150
	s_add_u32 s46, s44, 0x100
	s_addc_u32 s47, s45, 0
	s_cmp_eq_u32 s10, 40
	s_cselect_b32 s53, s5, s47
	s_cselect_b32 s52, s4, s46
	s_cselect_b32 s49, s1, s89
	s_cselect_b32 s48, s0, s88
	s_mov_b32 m0, s76
	ds_read_b128 v[186:189], v145
	ds_read_b128 v[190:193], v145 offset:1024
	ds_read_b128 v[194:197], v145 offset:2048
	ds_read_b128 v[198:201], v145 offset:3072
	ds_read_b128 v[202:205], v145 offset:4096
	ds_read_b128 v[206:209], v145 offset:5120
	ds_read_b128 v[210:213], v145 offset:6144
	ds_read_b128 v[214:217], v145 offset:7168
	global_load_lds_dwordx4 v136, s[44:45]
	s_mov_b32 m0, s77
	s_nop 0
	global_load_lds_dwordx4 v138, s[44:45]
	s_waitcnt lgkmcnt(8)
	s_barrier
	s_waitcnt lgkmcnt(0)
	s_setprio 1
	s_waitcnt lgkmcnt(0)
	v_mfma_f32_16x16x32_bf16 v[124:127], v[170:173], v[186:189], v[124:127]
	v_mfma_f32_16x16x32_bf16 v[120:123], v[178:181], v[186:189], v[120:123]
	v_mfma_f32_16x16x32_bf16 v[116:119], v[170:173], v[194:197], v[116:119]
	v_mfma_f32_16x16x32_bf16 v[112:115], v[178:181], v[194:197], v[112:115]
	v_mfma_f32_16x16x32_bf16 v[100:103], v[170:173], v[202:205], v[100:103]
	v_mfma_f32_16x16x32_bf16 v[96:99], v[178:181], v[202:205], v[96:99]
	v_mfma_f32_16x16x32_bf16 v[84:87], v[170:173], v[210:213], v[84:87]
	v_mfma_f32_16x16x32_bf16 v[80:83], v[178:181], v[210:213], v[80:83]
	v_mfma_f32_16x16x32_bf16 v[124:127], v[174:177], v[190:193], v[124:127]
	v_mfma_f32_16x16x32_bf16 v[120:123], v[182:185], v[190:193], v[120:123]
	v_mfma_f32_16x16x32_bf16 v[116:119], v[174:177], v[198:201], v[116:119]
	v_mfma_f32_16x16x32_bf16 v[112:115], v[182:185], v[198:201], v[112:115]
	v_mfma_f32_16x16x32_bf16 v[100:103], v[174:177], v[206:209], v[100:103]
	v_mfma_f32_16x16x32_bf16 v[96:99], v[182:185], v[206:209], v[96:99]
	v_mfma_f32_16x16x32_bf16 v[84:87], v[174:177], v[214:217], v[84:87]
	v_mfma_f32_16x16x32_bf16 v[80:83], v[182:185], v[214:217], v[80:83]
	s_setprio 0
	s_barrier
	s_mov_b32 m0, s58
	ds_read_b128 v[218:221], v151
	ds_read_b128 v[222:225], v152
	ds_read_b128 v[226:229], v153
	ds_read_b128 v[230:233], v154
	global_load_lds_dwordx4 v130, s[48:49]
	s_mov_b32 m0, s59
	s_nop 0
	global_load_lds_dwordx4 v134, s[48:49]
	s_waitcnt lgkmcnt(0)
	s_barrier
	s_waitcnt lgkmcnt(0)
	s_setprio 1
	s_waitcnt lgkmcnt(0)
	v_mfma_f32_16x16x32_bf16 v[108:111], v[218:221], v[186:189], v[108:111]
	v_mfma_f32_16x16x32_bf16 v[104:107], v[226:229], v[186:189], v[104:107]
	v_mfma_f32_16x16x32_bf16 v[92:95], v[218:221], v[194:197], v[92:95]
	v_mfma_f32_16x16x32_bf16 v[88:91], v[226:229], v[194:197], v[88:91]
	v_mfma_f32_16x16x32_bf16 v[76:79], v[218:221], v[202:205], v[76:79]
	v_mfma_f32_16x16x32_bf16 v[72:75], v[226:229], v[202:205], v[72:75]
	v_mfma_f32_16x16x32_bf16 v[68:71], v[218:221], v[210:213], v[68:71]
	v_mfma_f32_16x16x32_bf16 v[64:67], v[226:229], v[210:213], v[64:67]
	v_mfma_f32_16x16x32_bf16 v[108:111], v[222:225], v[190:193], v[108:111]
	v_mfma_f32_16x16x32_bf16 v[104:107], v[230:233], v[190:193], v[104:107]
	v_mfma_f32_16x16x32_bf16 v[92:95], v[222:225], v[198:201], v[92:95]
	v_mfma_f32_16x16x32_bf16 v[88:91], v[230:233], v[198:201], v[88:91]
	v_mfma_f32_16x16x32_bf16 v[76:79], v[222:225], v[206:209], v[76:79]
	v_mfma_f32_16x16x32_bf16 v[72:75], v[230:233], v[206:209], v[72:75]
	v_mfma_f32_16x16x32_bf16 v[68:71], v[222:225], v[214:217], v[68:71]
	v_mfma_f32_16x16x32_bf16 v[64:67], v[230:233], v[214:217], v[64:67]
	s_setprio 0
	s_mov_b32 m0, s57
	s_barrier
	ds_read_b128 v[186:189], v145 offset:16384
	ds_read_b128 v[190:193], v145 offset:17408
	ds_read_b128 v[194:197], v145 offset:18432
	ds_read_b128 v[198:201], v145 offset:19456
	ds_read_b128 v[202:205], v145 offset:20480
	ds_read_b128 v[206:209], v145 offset:21504
	ds_read_b128 v[210:213], v145 offset:22528
	ds_read_b128 v[214:217], v145 offset:23552
	global_load_lds_dwordx4 v128, s[52:53]
	s_mov_b32 m0, s60
	s_nop 0
	global_load_lds_dwordx4 v132, s[52:53]
	s_add_u32 s44, s48, 0xb4000
	s_addc_u32 s45, s49, 0
	s_mov_b32 m0, s61
	s_nop 0
	global_load_lds_dwordx4 v130, s[44:45]
	s_mov_b32 m0, s62
	s_nop 0
	global_load_lds_dwordx4 v134, s[44:45]
	s_waitcnt vmcnt(6)
	s_barrier
	s_waitcnt lgkmcnt(0)
	s_setprio 1
	s_waitcnt lgkmcnt(0)
	v_mfma_f32_16x16x32_bf16 v[60:63], v[170:173], v[186:189], v[60:63]
	v_mfma_f32_16x16x32_bf16 v[56:59], v[178:181], v[186:189], v[56:59]
	v_mfma_f32_16x16x32_bf16 v[52:55], v[170:173], v[194:197], v[52:55]
	v_mfma_f32_16x16x32_bf16 v[48:51], v[178:181], v[194:197], v[48:51]
	v_mfma_f32_16x16x32_bf16 v[36:39], v[170:173], v[202:205], v[36:39]
	v_mfma_f32_16x16x32_bf16 v[32:35], v[178:181], v[202:205], v[32:35]
	v_mfma_f32_16x16x32_bf16 v[20:23], v[170:173], v[210:213], v[20:23]
	v_mfma_f32_16x16x32_bf16 v[16:19], v[178:181], v[210:213], v[16:19]
	v_mfma_f32_16x16x32_bf16 v[60:63], v[174:177], v[190:193], v[60:63]
	v_mfma_f32_16x16x32_bf16 v[56:59], v[182:185], v[190:193], v[56:59]
	v_mfma_f32_16x16x32_bf16 v[52:55], v[174:177], v[198:201], v[52:55]
	v_mfma_f32_16x16x32_bf16 v[48:51], v[182:185], v[198:201], v[48:51]
	v_mfma_f32_16x16x32_bf16 v[36:39], v[174:177], v[206:209], v[36:39]
	v_mfma_f32_16x16x32_bf16 v[32:35], v[182:185], v[206:209], v[32:35]
	v_mfma_f32_16x16x32_bf16 v[20:23], v[174:177], v[214:217], v[20:23]
	v_mfma_f32_16x16x32_bf16 v[16:19], v[182:185], v[214:217], v[16:19]
	v_mfma_f32_16x16x32_bf16 v[44:47], v[218:221], v[186:189], v[44:47]
	v_mfma_f32_16x16x32_bf16 v[40:43], v[226:229], v[186:189], v[40:43]
	v_mfma_f32_16x16x32_bf16 v[28:31], v[218:221], v[194:197], v[28:31]
	v_mfma_f32_16x16x32_bf16 v[24:27], v[226:229], v[194:197], v[24:27]
	v_mfma_f32_16x16x32_bf16 v[12:15], v[218:221], v[202:205], v[12:15]
	v_mfma_f32_16x16x32_bf16 v[8:11], v[226:229], v[202:205], v[8:11]
	v_mfma_f32_16x16x32_bf16 v[4:7], v[218:221], v[210:213], v[4:7]
	v_mfma_f32_16x16x32_bf16 v[0:3], v[226:229], v[210:213], v[0:3]
	v_mfma_f32_16x16x32_bf16 v[44:47], v[222:225], v[190:193], v[44:47]
	v_mfma_f32_16x16x32_bf16 v[40:43], v[230:233], v[190:193], v[40:43]
	v_mfma_f32_16x16x32_bf16 v[28:31], v[222:225], v[198:201], v[28:31]
	v_mfma_f32_16x16x32_bf16 v[24:27], v[230:233], v[198:201], v[24:27]
	v_mfma_f32_16x16x32_bf16 v[12:15], v[222:225], v[206:209], v[12:15]
	v_mfma_f32_16x16x32_bf16 v[8:11], v[230:233], v[206:209], v[8:11]
	v_mfma_f32_16x16x32_bf16 v[4:7], v[222:225], v[214:217], v[4:7]
	v_mfma_f32_16x16x32_bf16 v[0:3], v[230:233], v[214:217], v[0:3]
	s_setprio 0
	s_barrier
; #define PG8_STAGE(bufoff, gbase, voff) do { _Pragma("unroll") for (int _i = 0; _i < 2; ++_i) \
;         __builtin_amdgcn_global_load_lds((const unsigned*)((const char*)(gbase) + (voff)[_i]), (PG8_LAS unsigned*)(lds + (bufoff) + ldsw + _i * 8192), 16, 0, 0); } while (0)
; #define PG8_LDA(dst, b, h) do { _Pragma("unroll") for (int m = 0; m < 4; ++m) _Pragma("unroll") for (int k = 0; k < 2; ++k) dst[m][k] = *(const PG8_LAS bf16x8*)(lds + PG8_SA(b, h) + aoff + m * 2048 + k * 1024); } while (0)
; template <class Epi, class Sched, bool STAMP = false>
; __device__ __forceinline__ void gemm_phase(PG8_LAS unsigned char* lds, const Gemm g, const Sched& S, const Epi& E, unsigned long long* stamps) {
;     ...
;         for (int t = 0; t < nt; t += 2) {
;             const bool last = (t == nt - 2);
;             const char* a1 = cA + (size_t)(t + 1) * kstep;
;             const char* a2 = last ? nA : cA + (size_t)(t + 2) * kstep; const char* b2 = last ? nB : cB + (size_t)(t + 2) * kstep;
;             const char* a3 = a2 + kstep; const char* b3 = b2 + kstep;
;             if (last && has_next) S.a_ready(nxt);
;             PG8_LDB(B0, 0, 0); PG8_SCHED; PG8_LDA(At, 0, 0); PG8_STAGE(PG8_SA(1, 1), a1 + hstep, voffA);
;             PG8_WAIT_L(8); PG8_BAR; PG8_WAIT_L(0); PG8_MMA(0, 0, At, B0); PG8_BAR; PG8_SCHED;
;             PG8_LDB(B1, 0, 1); PG8_STAGE(PG8_SB(0, 0), b2, voffB);
;             PG8_BAR; PG8_WAIT_L(0); PG8_MMA(0, 1, At, B1); PG8_BAR;
;             PG8_LDA(At, 0, 1); PG8_STAGE(PG8_SA(0, 0), a2, voffA);
;             PG8_BAR; PG8_WAIT_L(0); PG8_MMA(1, 0, At, B0); PG8_BAR; PG8_SCHED;
;             PG8_STAGE(PG8_SB(0, 1), b2 + hstep, voffB);
;             PG8_WAIT_V(6); PG8_BAR; PG8_MMA(1, 1, At, B1); PG8_BAR;
;             PG8_LDB(B0, 1, 0); PG8_SCHED; PG8_LDA(At, 1, 0); PG8_STAGE(PG8_SA(0, 1), a2 + hstep, voffA);
;             PG8_WAIT_L(8); PG8_BAR; PG8_WAIT_L(0); PG8_MMA(0, 0, At, B0); PG8_BAR; PG8_SCHED;
;             PG8_LDB(B1, 1, 1); PG8_STAGE(PG8_SB(1, 0), b3, voffB);
;             PG8_BAR; PG8_WAIT_L(0); PG8_MMA(0, 1, At, B1); PG8_BAR;
;             PG8_LDA(At, 1, 1); PG8_STAGE(PG8_SA(1, 0), a3, voffA);
;             PG8_BAR; PG8_WAIT_L(0); PG8_MMA(1, 0, At, B0); PG8_BAR; PG8_SCHED;
;             PG8_STAGE(PG8_SB(1, 1), b3 + hstep, voffB);
;             PG8_WAIT_V(6); PG8_BAR; PG8_MMA(1, 1, At, B1); PG8_BAR;
;         }
.Lzp8_mid:
	ds_read_b128 v[170:173], v155
	ds_read_b128 v[174:177], v156
	ds_read_b128 v[178:181], v157
	ds_read_b128 v[182:185], v165
	s_add_u32 s44, s52, 0xb4000
	s_addc_u32 s45, s53, 0
	s_mov_b32 m0, s63
	ds_read_b128 v[186:189], v145 offset:32768
	ds_read_b128 v[190:193], v145 offset:33792
	ds_read_b128 v[194:197], v145 offset:34816
	ds_read_b128 v[198:201], v145 offset:35840
	ds_read_b128 v[202:205], v145 offset:36864
	ds_read_b128 v[206:209], v145 offset:37888
	ds_read_b128 v[210:213], v145 offset:38912
	ds_read_b128 v[214:217], v145 offset:39936
	global_load_lds_dwordx4 v128, s[44:45]
	s_mov_b32 m0, s64
	s_nop 0
	global_load_lds_dwordx4 v132, s[44:45]
	s_waitcnt lgkmcnt(8)
	s_barrier
	s_waitcnt lgkmcnt(0)
	s_setprio 1
	s_waitcnt lgkmcnt(0)
	v_mfma_f32_16x16x32_bf16 v[124:127], v[170:173], v[186:189], v[124:127]
	v_mfma_f32_16x16x32_bf16 v[120:123], v[178:181], v[186:189], v[120:123]
	v_mfma_f32_16x16x32_bf16 v[116:119], v[170:173], v[194:197], v[116:119]
	v_mfma_f32_16x16x32_bf16 v[112:115], v[178:181], v[194:197], v[112:115]
	v_mfma_f32_16x16x32_bf16 v[100:103], v[170:173], v[202:205], v[100:103]
	v_mfma_f32_16x16x32_bf16 v[96:99], v[178:181], v[202:205], v[96:99]
	v_mfma_f32_16x16x32_bf16 v[84:87], v[170:173], v[210:213], v[84:87]
	v_mfma_f32_16x16x32_bf16 v[80:83], v[178:181], v[210:213], v[80:83]
	v_mfma_f32_16x16x32_bf16 v[124:127], v[174:177], v[190:193], v[124:127]
	v_mfma_f32_16x16x32_bf16 v[120:123], v[182:185], v[190:193], v[120:123]
	v_mfma_f32_16x16x32_bf16 v[116:119], v[174:177], v[198:201], v[116:119]
	v_mfma_f32_16x16x32_bf16 v[112:115], v[182:185], v[198:201], v[112:115]
	v_mfma_f32_16x16x32_bf16 v[100:103], v[174:177], v[206:209], v[100:103]
	v_mfma_f32_16x16x32_bf16 v[96:99], v[182:185], v[206:209], v[96:99]
	v_mfma_f32_16x16x32_bf16 v[84:87], v[174:177], v[214:217], v[84:87]
	v_mfma_f32_16x16x32_bf16 v[80:83], v[182:185], v[214:217], v[80:83]
	s_setprio 0
	s_barrier
	s_mov_b32 m0, s65
	ds_read_b128 v[218:221], v166
	ds_read_b128 v[222:225], v167
	ds_read_b128 v[226:229], v168
	ds_read_b128 v[230:233], v169
	s_add_u32 s100, s48, 0x80
	s_addc_u32 s101, s49, 0
	global_load_lds_dwordx4 v130, s[100:101]
	s_mov_b32 m0, s66
	s_nop 0
	global_load_lds_dwordx4 v134, s[100:101]
	s_waitcnt lgkmcnt(0)
	s_barrier
	s_waitcnt lgkmcnt(0)
	s_setprio 1
	s_waitcnt lgkmcnt(0)
	v_mfma_f32_16x16x32_bf16 v[108:111], v[218:221], v[186:189], v[108:111]
	v_mfma_f32_16x16x32_bf16 v[104:107], v[226:229], v[186:189], v[104:107]
	v_mfma_f32_16x16x32_bf16 v[92:95], v[218:221], v[194:197], v[92:95]
	v_mfma_f32_16x16x32_bf16 v[88:91], v[226:229], v[194:197], v[88:91]
	v_mfma_f32_16x16x32_bf16 v[76:79], v[218:221], v[202:205], v[76:79]
	v_mfma_f32_16x16x32_bf16 v[72:75], v[226:229], v[202:205], v[72:75]
	v_mfma_f32_16x16x32_bf16 v[68:71], v[218:221], v[210:213], v[68:71]
	v_mfma_f32_16x16x32_bf16 v[64:67], v[226:229], v[210:213], v[64:67]
	v_mfma_f32_16x16x32_bf16 v[108:111], v[222:225], v[190:193], v[108:111]
	v_mfma_f32_16x16x32_bf16 v[104:107], v[230:233], v[190:193], v[104:107]
	v_mfma_f32_16x16x32_bf16 v[92:95], v[222:225], v[198:201], v[92:95]
	v_mfma_f32_16x16x32_bf16 v[88:91], v[230:233], v[198:201], v[88:91]
	v_mfma_f32_16x16x32_bf16 v[76:79], v[222:225], v[206:209], v[76:79]
	v_mfma_f32_16x16x32_bf16 v[72:75], v[230:233], v[206:209], v[72:75]
	v_mfma_f32_16x16x32_bf16 v[68:71], v[222:225], v[214:217], v[68:71]
	v_mfma_f32_16x16x32_bf16 v[64:67], v[230:233], v[214:217], v[64:67]
	s_setprio 0
	s_mov_b32 m0, s67
	s_barrier
	ds_read_b128 v[186:189], v145 offset:49152
	ds_read_b128 v[190:193], v145 offset:50176
	ds_read_b128 v[194:197], v145 offset:51200
	ds_read_b128 v[198:201], v145 offset:52224
	ds_read_b128 v[202:205], v145 offset:53248
	ds_read_b128 v[206:209], v145 offset:54272
	ds_read_b128 v[210:213], v145 offset:55296
	ds_read_b128 v[214:217], v145 offset:56320
	s_add_u32 s100, s52, 0x80
	s_addc_u32 s101, s53, 0
	global_load_lds_dwordx4 v128, s[100:101]
	s_mov_b32 m0, s68
	s_nop 0
	global_load_lds_dwordx4 v132, s[100:101]
	s_add_u32 s44, s48, 0xb4080
	s_addc_u32 s45, s49, 0
	s_mov_b32 m0, s69
	s_nop 0
	global_load_lds_dwordx4 v130, s[44:45]
	s_mov_b32 m0, s70
	s_nop 0
	global_load_lds_dwordx4 v134, s[44:45]
	s_waitcnt vmcnt(6)
	s_barrier
	s_waitcnt lgkmcnt(0)
	s_setprio 1
	s_waitcnt lgkmcnt(0)
	v_mfma_f32_16x16x32_bf16 v[60:63], v[170:173], v[186:189], v[60:63]
	v_mfma_f32_16x16x32_bf16 v[56:59], v[178:181], v[186:189], v[56:59]
	v_mfma_f32_16x16x32_bf16 v[52:55], v[170:173], v[194:197], v[52:55]
	v_mfma_f32_16x16x32_bf16 v[48:51], v[178:181], v[194:197], v[48:51]
	v_mfma_f32_16x16x32_bf16 v[36:39], v[170:173], v[202:205], v[36:39]
	v_mfma_f32_16x16x32_bf16 v[32:35], v[178:181], v[202:205], v[32:35]
	v_mfma_f32_16x16x32_bf16 v[20:23], v[170:173], v[210:213], v[20:23]
	v_mfma_f32_16x16x32_bf16 v[16:19], v[178:181], v[210:213], v[16:19]
	v_mfma_f32_16x16x32_bf16 v[60:63], v[174:177], v[190:193], v[60:63]
	v_mfma_f32_16x16x32_bf16 v[56:59], v[182:185], v[190:193], v[56:59]
	v_mfma_f32_16x16x32_bf16 v[52:55], v[174:177], v[198:201], v[52:55]
	v_mfma_f32_16x16x32_bf16 v[48:51], v[182:185], v[198:201], v[48:51]
	v_mfma_f32_16x16x32_bf16 v[36:39], v[174:177], v[206:209], v[36:39]
	v_mfma_f32_16x16x32_bf16 v[32:35], v[182:185], v[206:209], v[32:35]
	v_mfma_f32_16x16x32_bf16 v[20:23], v[174:177], v[214:217], v[20:23]
	v_mfma_f32_16x16x32_bf16 v[16:19], v[182:185], v[214:217], v[16:19]
	v_mfma_f32_16x16x32_bf16 v[44:47], v[218:221], v[186:189], v[44:47]
	v_mfma_f32_16x16x32_bf16 v[40:43], v[226:229], v[186:189], v[40:43]
	v_mfma_f32_16x16x32_bf16 v[28:31], v[218:221], v[194:197], v[28:31]
	v_mfma_f32_16x16x32_bf16 v[24:27], v[226:229], v[194:197], v[24:27]
	v_mfma_f32_16x16x32_bf16 v[12:15], v[218:221], v[202:205], v[12:15]
	v_mfma_f32_16x16x32_bf16 v[8:11], v[226:229], v[202:205], v[8:11]
	v_mfma_f32_16x16x32_bf16 v[4:7], v[218:221], v[210:213], v[4:7]
	v_mfma_f32_16x16x32_bf16 v[0:3], v[226:229], v[210:213], v[0:3]
	v_mfma_f32_16x16x32_bf16 v[44:47], v[222:225], v[190:193], v[44:47]
	v_mfma_f32_16x16x32_bf16 v[40:43], v[230:233], v[190:193], v[40:43]
	v_mfma_f32_16x16x32_bf16 v[28:31], v[222:225], v[198:201], v[28:31]
	v_mfma_f32_16x16x32_bf16 v[24:27], v[230:233], v[198:201], v[24:27]
	v_mfma_f32_16x16x32_bf16 v[12:15], v[222:225], v[206:209], v[12:15]
	v_mfma_f32_16x16x32_bf16 v[8:11], v[230:233], v[206:209], v[8:11]
	v_mfma_f32_16x16x32_bf16 v[4:7], v[222:225], v[214:217], v[4:7]
	v_mfma_f32_16x16x32_bf16 v[0:3], v[230:233], v[214:217], v[0:3]
	s_setprio 0
	s_add_i32 s10, s10, 2
	s_add_u32 s88, s88, 0x100
	s_addc_u32 s89, s89, 0
	s_cmp_gt_u32 s10, 41
	s_mov_b64 s[44:45], s[46:47]
	s_barrier
; #define PG8_STAMP() do { if (STAMP && wid == 0 && nts < 64) { const unsigned long long _c = 0ull; \
;         ts_lo = (lane == nts) ? (int)(unsigned)_c : ts_lo; ts_hi = (lane == nts) ? (int)(unsigned)(_c >> 32) : ts_hi; ++nts; } } while (0)
; #define PG8_WAIT_V(n) asm volatile("s_waitcnt vmcnt(" #n ")" ::: "memory")
; #define PG8_BAR __builtin_amdgcn_s_barrier()
;     DI void operator()(const f32x4 (&acc)[2][2][4][2], const Unit& u, int wr, int wc, int fr, int fq) const {
;         const int row0 = u.pm * BM + wr * 64 + fr, col0 = u.pn * BM + wc * 32 + 8 * fq;
; #pragma unroll
;         for (int ai = 0; ai < 2; ++ai)
; #pragma unroll
;             for (int m = 0; m < 4; ++m) { u16* rowp = O + (size_t)(row0 + ai * HALF + m * 16) * ldc + col0;
; #pragma unroll
;                 for (int bj = 0; bj < 2; ++bj) { const f32x4 v0 = acc[ai][bj][m][0], v1 = acc[ai][bj][m][1];
;                     uint4 w = {pack2(v0[0], v0[1]), pack2(v0[2], v0[3]), pack2(v1[0], v1[1]), pack2(v1[2], v1[3])}; *(uint4*)(rowp + bj * HALF) = w; } }
; template <class Epi, class Sched, bool STAMP = false>
; __device__ __forceinline__ void gemm_phase(PG8_LAS unsigned char* lds, const Gemm g, const Sched& S, const Epi& E, unsigned long long* stamps) {
;     ...
;         if constexpr (!Epi::AFTER_DRAIN) { E(acc, cur, wr, wc, fr, fq); S.done(cur); }
;         PG8_STAMP();
;         if (!has_next) break;
; #pragma unroll
;         for (int a = 0; a < 2; ++a)
; #pragma unroll
;             for (int b = 0; b < 2; ++b)
; #pragma unroll
;                 for (int m = 0; m < 4; ++m)
; #pragma unroll
;                     for (int n = 0; n < 2; ++n) acc[a][b][m][n] = (f32x4){0.f, 0.f, 0.f, 0.f};
;         cur = nxt; cA = nA; cB = nB; ++ui;
;     }
;     PG8_WAIT_V(0);
;     if (wr == 0) PG8_BAR;
;     PG8_BAR;
	s_cbranch_scc0 .LBB0_473
	v_lshl_add_u32 v170, s84, 8, v144
	v_lshl_or_b32 v172, s87, 8, v146
	v_ashrrev_i32_e32 v171, 31, v170
	v_ashrrev_i32_e32 v173, 31, v172
	v_lshlrev_b64 v[174:175], 11, v[170:171]
	v_lshl_add_u64 v[174:175], s[14:15], 0, v[174:175]
	v_lshlrev_b64 v[172:173], 1, v[172:173]
	v_lshl_add_u64 v[174:175], v[174:175], 0, v[172:173]
	v_cvt_pk_bf16_f32 v60, v60, v61
	v_cvt_pk_bf16_f32 v61, v62, v63
	v_cvt_pk_bf16_f32 v62, v56, v57
	v_add_co_u32_e32 v56, vcc, s78, v174
	v_cvt_pk_bf16_f32 v68, v68, v69
	v_cvt_pk_bf16_f32 v69, v70, v71
	v_cvt_pk_bf16_f32 v70, v64, v65
	v_lshl_add_u64 v[64:65], v[174:175], 0, s[34:35]
	v_addc_co_u32_e32 v57, vcc, 0, v175, vcc
	v_cvt_pk_bf16_f32 v44, v44, v45
	v_cvt_pk_bf16_f32 v45, v46, v47
	v_cvt_pk_bf16_f32 v46, v40, v41
	v_cvt_pk_bf16_f32 v47, v42, v43
	v_cvt_pk_bf16_f32 v108, v108, v109
	v_cvt_pk_bf16_f32 v109, v110, v111
	v_cvt_pk_bf16_f32 v110, v104, v105
	v_or_b32_e32 v104, 16, v170
	global_store_dwordx4 v[64:65], v[44:47], off offset:256
	v_ashrrev_i32_e32 v105, 31, v104
	v_cvt_pk_bf16_f32 v92, v92, v93
	v_add_co_u32_e32 v46, vcc, s79, v174
	v_cvt_pk_bf16_f32 v93, v94, v95
	v_cvt_pk_bf16_f32 v94, v88, v89
	v_or_b32_e32 v88, 32, v170
	v_lshl_add_u64 v[44:45], v[174:175], 0, s[36:37]
	v_addc_co_u32_e32 v47, vcc, 0, v175, vcc
	v_cvt_pk_bf16_f32 v28, v28, v29
	v_cvt_pk_bf16_f32 v29, v30, v31
	v_cvt_pk_bf16_f32 v30, v24, v25
	v_cvt_pk_bf16_f32 v31, v26, v27
	v_lshlrev_b64 v[104:105], 11, v[104:105]
	v_ashrrev_i32_e32 v89, 31, v88
	v_cvt_pk_bf16_f32 v76, v76, v77
	v_cvt_pk_bf16_f32 v77, v78, v79
	v_cvt_pk_bf16_f32 v78, v72, v73
	v_or_b32_e32 v72, 48, v170
	global_store_dwordx4 v[44:45], v[28:31], off offset:256
	v_cvt_pk_bf16_f32 v111, v106, v107
	v_lshl_add_u64 v[104:105], s[14:15], 0, v[104:105]
	v_add_co_u32_e32 v30, vcc, s82, v174
	v_lshlrev_b64 v[88:89], 11, v[88:89]
	v_ashrrev_i32_e32 v73, 31, v72
	v_lshl_add_u64 v[28:29], v[174:175], 0, s[40:41]
	v_addc_co_u32_e32 v31, vcc, 0, v175, vcc
	v_cvt_pk_bf16_f32 v12, v12, v13
	v_cvt_pk_bf16_f32 v13, v14, v15
	v_cvt_pk_bf16_f32 v14, v8, v9
	v_cvt_pk_bf16_f32 v15, v10, v11
	global_store_dwordx4 v[174:175], v[108:111], off offset:256
	v_cvt_pk_bf16_f32 v95, v90, v91
	v_lshl_add_u64 v[88:89], s[14:15], 0, v[88:89]
	v_lshl_add_u64 v[108:109], v[104:105], 0, v[172:173]
	v_lshlrev_b64 v[72:73], 11, v[72:73]
	global_store_dwordx4 v[28:29], v[12:15], off offset:256
	global_store_dwordx4 v[108:109], v[92:95], off offset:256
	v_cvt_pk_bf16_f32 v79, v74, v75
	v_add_co_u32_e32 v14, vcc, s83, v174
	v_lshl_add_u64 v[92:93], v[88:89], 0, v[172:173]
	v_lshl_add_u64 v[72:73], s[14:15], 0, v[72:73]
	v_addc_co_u32_e32 v15, vcc, 0, v175, vcc
	v_cvt_pk_bf16_f32 v124, v124, v125
	v_cvt_pk_bf16_f32 v125, v126, v127
	v_cvt_pk_bf16_f32 v126, v120, v121
	v_cvt_pk_bf16_f32 v127, v122, v123
	v_cvt_pk_bf16_f32 v104, v116, v117
	v_cvt_pk_bf16_f32 v105, v118, v119
	v_cvt_pk_bf16_f32 v106, v112, v113
	v_cvt_pk_bf16_f32 v107, v114, v115
	v_cvt_pk_bf16_f32 v88, v100, v101
	v_cvt_pk_bf16_f32 v89, v102, v103
	v_cvt_pk_bf16_f32 v90, v96, v97
	v_cvt_pk_bf16_f32 v91, v98, v99
	global_store_dwordx4 v[92:93], v[76:79], off offset:256
	v_cvt_pk_bf16_f32 v74, v80, v81
	v_cvt_pk_bf16_f32 v75, v82, v83
	v_lshl_add_u64 v[76:77], v[72:73], 0, v[172:173]
	v_cvt_pk_bf16_f32 v72, v84, v85
	v_cvt_pk_bf16_f32 v73, v86, v87
	v_cvt_pk_bf16_f32 v71, v66, v67
	v_cvt_pk_bf16_f32 v63, v58, v59
	v_cvt_pk_bf16_f32 v40, v52, v53
	v_cvt_pk_bf16_f32 v41, v54, v55
	v_cvt_pk_bf16_f32 v42, v48, v49
	v_cvt_pk_bf16_f32 v43, v50, v51
	v_cvt_pk_bf16_f32 v24, v36, v37
	v_cvt_pk_bf16_f32 v25, v38, v39
	v_cvt_pk_bf16_f32 v26, v32, v33
	v_cvt_pk_bf16_f32 v27, v34, v35
	v_lshl_add_u64 v[12:13], v[174:175], 0, s[42:43]
	v_cvt_pk_bf16_f32 v8, v20, v21
	v_cvt_pk_bf16_f32 v9, v22, v23
	v_cvt_pk_bf16_f32 v10, v16, v17
	v_cvt_pk_bf16_f32 v11, v18, v19
	v_cvt_pk_bf16_f32 v4, v4, v5
	v_cvt_pk_bf16_f32 v5, v6, v7
	v_cvt_pk_bf16_f32 v6, v0, v1
	v_cvt_pk_bf16_f32 v7, v2, v3
	s_and_b64 vcc, exec, s[2:3]
	s_mov_b32 s87, s85
	s_mov_b32 s84, s86
	s_mov_b64 s[46:47], s[0:1]
	s_mov_b64 s[44:45], s[4:5]
	global_store_dwordx4 v[174:175], v[124:127], off
	global_store_dwordx4 v[108:109], v[104:107], off
	global_store_dwordx4 v[92:93], v[88:91], off
	global_store_dwordx4 v[76:77], v[72:75], off
	global_store_dwordx4 v[76:77], v[68:71], off offset:256
	global_store_dwordx4 v[56:57], v[60:63], off
	global_store_dwordx4 v[46:47], v[40:43], off
	global_store_dwordx4 v[30:31], v[24:27], off
	global_store_dwordx4 v[14:15], v[8:11], off
	global_store_dwordx4 v[12:13], v[4:7], off offset:256
	s_cbranch_vccz .LBB0_462
	s_waitcnt vmcnt(0)
	s_cmpk_gt_u32 s55, 0xff
	s_cbranch_scc1 .LBB0_477
	s_barrier

; #define PG8_STAGE(bufoff, gbase, voff) do { _Pragma("unroll") for (int _i = 0; _i < 2; ++_i) \
;         __builtin_amdgcn_global_load_lds((const unsigned*)((const char*)(gbase) + (voff)[_i]), (PG8_LAS unsigned*)(lds + (bufoff) + ldsw + _i * 8192), 16, 0, 0); } while (0)
; template <class Epi, class Sched, bool STAMP = false>
; __device__ __forceinline__ void gemm_phase(PG8_LAS unsigned char* lds, const Gemm g, const Sched& S, const Epi& E, unsigned long long* stamps) {
;     ...
;     for (;;) {
;         const bool has_next = S.next(ui + 1, nxt);
;         const char* nA = has_next ? (const char*)g.A + (size_t)nxt.pm * tstep : cA; const char* nB = has_next ? (const char*)g.Bt + (size_t)nxt.pn * tstep : cB;
;         for (int t = 0; t < nt; t += 2) {
;             const bool last = (t == nt - 2);
;             const char* a1 = cA + (size_t)(t + 1) * kstep;
;             const char* a2 = last ? nA : cA + (size_t)(t + 2) * kstep; const char* b2 = last ? nB : cB + (size_t)(t + 2) * kstep;
;             const char* a3 = a2 + kstep; const char* b3 = b2 + kstep;
;             if (last && has_next) S.a_ready(nxt);
;             PG8_LDB(B0, 0, 0); PG8_SCHED; PG8_LDA(At, 0, 0); PG8_STAGE(PG8_SA(1, 1), a1 + hstep, voffA);
;             PG8_WAIT_L(8); PG8_BAR; PG8_WAIT_L(0); PG8_MMA(0, 0, At, B0); PG8_BAR; PG8_SCHED;
;             PG8_LDB(B1, 0, 1); PG8_STAGE(PG8_SB(0, 0), b2, voffB);
;             PG8_BAR; PG8_WAIT_L(0); PG8_MMA(0, 1, At, B1); PG8_BAR;
;             PG8_LDA(At, 0, 1); PG8_STAGE(PG8_SA(0, 0), a2, voffA);
;             PG8_BAR; PG8_WAIT_L(0); PG8_MMA(1, 0, At, B0); PG8_BAR; PG8_SCHED;
;             PG8_STAGE(PG8_SB(0, 1), b2 + hstep, voffB);
;             PG8_WAIT_V(6); PG8_BAR; PG8_MMA(1, 1, At, B1); PG8_BAR;
;             PG8_LDB(B0, 1, 0); PG8_SCHED; PG8_LDA(At, 1, 0); PG8_STAGE(PG8_SA(0, 1), a2 + hstep, voffA);
;             PG8_WAIT_L(8); PG8_BAR; PG8_WAIT_L(0); PG8_MMA(0, 0, At, B0); PG8_BAR; PG8_SCHED;
;             PG8_LDB(B1, 1, 1); PG8_STAGE(PG8_SB(1, 0), b3, voffB);
;             PG8_BAR; PG8_WAIT_L(0); PG8_MMA(0, 1, At, B1); PG8_BAR;
;             PG8_LDA(At, 1, 1); PG8_STAGE(PG8_SA(1, 0), a3, voffA);
;             PG8_BAR; PG8_WAIT_L(0); PG8_MMA(1, 0, At, B0); PG8_BAR; PG8_SCHED;
;             PG8_STAGE(PG8_SB(1, 1), b3 + hstep, voffB);
;             PG8_WAIT_V(6); PG8_BAR; PG8_MMA(1, 1, At, B1); PG8_BAR;
;         }
.LBB0_513:
	s_add_u32 s81, s42, 0x100
	s_addc_u32 s82, s43, 0
	s_mov_b32 s10, -2
	s_waitcnt lgkmcnt(0)
	ds_read_b128 v[170:173], v147
	ds_read_b128 v[174:177], v148
	ds_read_b128 v[178:181], v149
	ds_read_b128 v[182:185], v150
	s_add_u32 s42, s40, 0x100
	s_addc_u32 s43, s41, 0
	s_cmp_eq_u32 s10, 12
	s_cselect_b32 s47, s7, s43
	s_cselect_b32 s46, s6, s42
	s_cselect_b32 s45, s1, s82
	s_cselect_b32 s44, s0, s81
	s_mov_b32 m0, s71
	ds_read_b128 v[186:189], v145
	ds_read_b128 v[190:193], v145 offset:1024
	ds_read_b128 v[194:197], v145 offset:2048
	ds_read_b128 v[198:201], v145 offset:3072
	ds_read_b128 v[202:205], v145 offset:4096
	ds_read_b128 v[206:209], v145 offset:5120
	ds_read_b128 v[210:213], v145 offset:6144
	ds_read_b128 v[214:217], v145 offset:7168
	global_load_lds_dwordx4 v136, s[40:41]
	s_mov_b32 m0, s75
	s_nop 0
	global_load_lds_dwordx4 v138, s[40:41]
	s_waitcnt lgkmcnt(8)
	s_barrier
	s_waitcnt lgkmcnt(0)
	s_setprio 1
	s_waitcnt lgkmcnt(0)
	v_mfma_f32_16x16x32_bf16 v[124:127], v[170:173], v[186:189], 0
	v_mfma_f32_16x16x32_bf16 v[120:123], v[178:181], v[186:189], 0
	v_mfma_f32_16x16x32_bf16 v[116:119], v[170:173], v[194:197], 0
	v_mfma_f32_16x16x32_bf16 v[112:115], v[178:181], v[194:197], 0
	v_mfma_f32_16x16x32_bf16 v[108:111], v[170:173], v[202:205], 0
	v_mfma_f32_16x16x32_bf16 v[104:107], v[178:181], v[202:205], 0
	v_mfma_f32_16x16x32_bf16 v[100:103], v[170:173], v[210:213], 0
	v_mfma_f32_16x16x32_bf16 v[96:99], v[178:181], v[210:213], 0
	v_mfma_f32_16x16x32_bf16 v[124:127], v[174:177], v[190:193], v[124:127]
	v_mfma_f32_16x16x32_bf16 v[120:123], v[182:185], v[190:193], v[120:123]
	v_mfma_f32_16x16x32_bf16 v[116:119], v[174:177], v[198:201], v[116:119]
	v_mfma_f32_16x16x32_bf16 v[112:115], v[182:185], v[198:201], v[112:115]
	v_mfma_f32_16x16x32_bf16 v[108:111], v[174:177], v[206:209], v[108:111]
	v_mfma_f32_16x16x32_bf16 v[104:107], v[182:185], v[206:209], v[104:107]
	v_mfma_f32_16x16x32_bf16 v[100:103], v[174:177], v[214:217], v[100:103]
	v_mfma_f32_16x16x32_bf16 v[96:99], v[182:185], v[214:217], v[96:99]
	s_setprio 0
	s_barrier
	s_mov_b32 m0, s55
	ds_read_b128 v[218:221], v151
	ds_read_b128 v[222:225], v152
	ds_read_b128 v[226:229], v153
	ds_read_b128 v[230:233], v154
	global_load_lds_dwordx4 v132, s[44:45]
	s_mov_b32 m0, s56
	s_nop 0
	global_load_lds_dwordx4 v128, s[44:45]
	s_waitcnt lgkmcnt(0)
	s_barrier
	s_waitcnt lgkmcnt(0)
	s_setprio 1
	s_waitcnt lgkmcnt(0)
	v_mfma_f32_16x16x32_bf16 v[60:63], v[218:221], v[186:189], 0
	v_mfma_f32_16x16x32_bf16 v[56:59], v[226:229], v[186:189], 0
	v_mfma_f32_16x16x32_bf16 v[52:55], v[218:221], v[194:197], 0
	v_mfma_f32_16x16x32_bf16 v[48:51], v[226:229], v[194:197], 0
	v_mfma_f32_16x16x32_bf16 v[44:47], v[218:221], v[202:205], 0
	v_mfma_f32_16x16x32_bf16 v[40:43], v[226:229], v[202:205], 0
	v_mfma_f32_16x16x32_bf16 v[36:39], v[218:221], v[210:213], 0
	v_mfma_f32_16x16x32_bf16 v[32:35], v[226:229], v[210:213], 0
	v_mfma_f32_16x16x32_bf16 v[60:63], v[222:225], v[190:193], v[60:63]
	v_mfma_f32_16x16x32_bf16 v[56:59], v[230:233], v[190:193], v[56:59]
	v_mfma_f32_16x16x32_bf16 v[52:55], v[222:225], v[198:201], v[52:55]
	v_mfma_f32_16x16x32_bf16 v[48:51], v[230:233], v[198:201], v[48:51]
	v_mfma_f32_16x16x32_bf16 v[44:47], v[222:225], v[206:209], v[44:47]
	v_mfma_f32_16x16x32_bf16 v[40:43], v[230:233], v[206:209], v[40:43]
	v_mfma_f32_16x16x32_bf16 v[36:39], v[222:225], v[214:217], v[36:39]
	v_mfma_f32_16x16x32_bf16 v[32:35], v[230:233], v[214:217], v[32:35]
	s_setprio 0
	s_mov_b32 m0, s52
	s_barrier
	ds_read_b128 v[186:189], v145 offset:16384
	ds_read_b128 v[190:193], v145 offset:17408
	ds_read_b128 v[194:197], v145 offset:18432
	ds_read_b128 v[198:201], v145 offset:19456
	ds_read_b128 v[202:205], v145 offset:20480
	ds_read_b128 v[206:209], v145 offset:21504
	ds_read_b128 v[210:213], v145 offset:22528
	ds_read_b128 v[214:217], v145 offset:23552
	global_load_lds_dwordx4 v134, s[46:47]
	s_mov_b32 m0, s57
	s_nop 0
	global_load_lds_dwordx4 v130, s[46:47]
	s_add_u32 s40, s44, 0x44000
	s_addc_u32 s41, s45, 0
	s_mov_b32 m0, s58
	s_nop 0
	global_load_lds_dwordx4 v132, s[40:41]
	s_mov_b32 m0, s59
	s_nop 0
	global_load_lds_dwordx4 v128, s[40:41]
	s_waitcnt vmcnt(6)
	s_barrier
	s_waitcnt lgkmcnt(0)
	s_setprio 1
	s_waitcnt lgkmcnt(0)
	v_mfma_f32_16x16x32_bf16 v[92:95], v[170:173], v[186:189], 0
	v_mfma_f32_16x16x32_bf16 v[88:91], v[178:181], v[186:189], 0
	v_mfma_f32_16x16x32_bf16 v[84:87], v[170:173], v[194:197], 0
	v_mfma_f32_16x16x32_bf16 v[80:83], v[178:181], v[194:197], 0
	v_mfma_f32_16x16x32_bf16 v[76:79], v[170:173], v[202:205], 0
	v_mfma_f32_16x16x32_bf16 v[72:75], v[178:181], v[202:205], 0
	v_mfma_f32_16x16x32_bf16 v[68:71], v[170:173], v[210:213], 0
	v_mfma_f32_16x16x32_bf16 v[64:67], v[178:181], v[210:213], 0
	v_mfma_f32_16x16x32_bf16 v[92:95], v[174:177], v[190:193], v[92:95]
	v_mfma_f32_16x16x32_bf16 v[88:91], v[182:185], v[190:193], v[88:91]
	v_mfma_f32_16x16x32_bf16 v[84:87], v[174:177], v[198:201], v[84:87]
	v_mfma_f32_16x16x32_bf16 v[80:83], v[182:185], v[198:201], v[80:83]
	v_mfma_f32_16x16x32_bf16 v[76:79], v[174:177], v[206:209], v[76:79]
	v_mfma_f32_16x16x32_bf16 v[72:75], v[182:185], v[206:209], v[72:75]
	v_mfma_f32_16x16x32_bf16 v[68:71], v[174:177], v[214:217], v[68:71]
	v_mfma_f32_16x16x32_bf16 v[64:67], v[182:185], v[214:217], v[64:67]
	v_mfma_f32_16x16x32_bf16 v[28:31], v[218:221], v[186:189], 0
	v_mfma_f32_16x16x32_bf16 v[24:27], v[226:229], v[186:189], 0
	v_mfma_f32_16x16x32_bf16 v[20:23], v[218:221], v[194:197], 0
	v_mfma_f32_16x16x32_bf16 v[16:19], v[226:229], v[194:197], 0
	v_mfma_f32_16x16x32_bf16 v[12:15], v[218:221], v[202:205], 0
	v_mfma_f32_16x16x32_bf16 v[8:11], v[226:229], v[202:205], 0
	v_mfma_f32_16x16x32_bf16 v[4:7], v[218:221], v[210:213], 0
	v_mfma_f32_16x16x32_bf16 v[0:3], v[226:229], v[210:213], 0
	v_mfma_f32_16x16x32_bf16 v[28:31], v[222:225], v[190:193], v[28:31]
	v_mfma_f32_16x16x32_bf16 v[24:27], v[230:233], v[190:193], v[24:27]
	v_mfma_f32_16x16x32_bf16 v[20:23], v[222:225], v[198:201], v[20:23]
	v_mfma_f32_16x16x32_bf16 v[16:19], v[230:233], v[198:201], v[16:19]
	v_mfma_f32_16x16x32_bf16 v[12:15], v[222:225], v[206:209], v[12:15]
	v_mfma_f32_16x16x32_bf16 v[8:11], v[230:233], v[206:209], v[8:11]
	v_mfma_f32_16x16x32_bf16 v[4:7], v[222:225], v[214:217], v[4:7]
	v_mfma_f32_16x16x32_bf16 v[0:3], v[230:233], v[214:217], v[0:3]
	s_setprio 0
	s_barrier
	s_branch .Lzp9_mid
; #define PG8_STAGE(bufoff, gbase, voff) do { _Pragma("unroll") for (int _i = 0; _i < 2; ++_i) \
;         __builtin_amdgcn_global_load_lds((const unsigned*)((const char*)(gbase) + (voff)[_i]), (PG8_LAS unsigned*)(lds + (bufoff) + ldsw + _i * 8192), 16, 0, 0); } while (0)
; #define PG8_LDA(dst, b, h) do { _Pragma("unroll") for (int m = 0; m < 4; ++m) _Pragma("unroll") for (int k = 0; k < 2; ++k) dst[m][k] = *(const PG8_LAS bf16x8*)(lds + PG8_SA(b, h) + aoff + m * 2048 + k * 1024); } while (0)
; template <class Epi, class Sched, bool STAMP = false>
; __device__ __forceinline__ void gemm_phase(PG8_LAS unsigned char* lds, const Gemm g, const Sched& S, const Epi& E, unsigned long long* stamps) {
;     ...
;         for (int t = 0; t < nt; t += 2) {
;             const bool last = (t == nt - 2);
;             const char* a1 = cA + (size_t)(t + 1) * kstep;
;             const char* a2 = last ? nA : cA + (size_t)(t + 2) * kstep; const char* b2 = last ? nB : cB + (size_t)(t + 2) * kstep;
;             const char* a3 = a2 + kstep; const char* b3 = b2 + kstep;
;             if (last && has_next) S.a_ready(nxt);
;             PG8_LDB(B0, 0, 0); PG8_SCHED; PG8_LDA(At, 0, 0); PG8_STAGE(PG8_SA(1, 1), a1 + hstep, voffA);
;             PG8_WAIT_L(8); PG8_BAR; PG8_WAIT_L(0); PG8_MMA(0, 0, At, B0); PG8_BAR; PG8_SCHED;
;             PG8_LDB(B1, 0, 1); PG8_STAGE(PG8_SB(0, 0), b2, voffB);
;             PG8_BAR; PG8_WAIT_L(0); PG8_MMA(0, 1, At, B1); PG8_BAR;
;             PG8_LDA(At, 0, 1); PG8_STAGE(PG8_SA(0, 0), a2, voffA);
;             PG8_BAR; PG8_WAIT_L(0); PG8_MMA(1, 0, At, B0); PG8_BAR; PG8_SCHED;
;             PG8_STAGE(PG8_SB(0, 1), b2 + hstep, voffB);
;             PG8_WAIT_V(6); PG8_BAR; PG8_MMA(1, 1, At, B1); PG8_BAR;
;             PG8_LDB(B0, 1, 0); PG8_SCHED; PG8_LDA(At, 1, 0); PG8_STAGE(PG8_SA(0, 1), a2 + hstep, voffA);
;             PG8_WAIT_L(8); PG8_BAR; PG8_WAIT_L(0); PG8_MMA(0, 0, At, B0); PG8_BAR; PG8_SCHED;
;             PG8_LDB(B1, 1, 1); PG8_STAGE(PG8_SB(1, 0), b3, voffB);
;             PG8_BAR; PG8_WAIT_L(0); PG8_MMA(0, 1, At, B1); PG8_BAR;
;             PG8_LDA(At, 1, 1); PG8_STAGE(PG8_SA(1, 0), a3, voffA);
;             PG8_BAR; PG8_WAIT_L(0); PG8_MMA(1, 0, At, B0); PG8_BAR; PG8_SCHED;
;             PG8_STAGE(PG8_SB(1, 1), b3 + hstep, voffB);
;             PG8_WAIT_V(6); PG8_BAR; PG8_MMA(1, 1, At, B1); PG8_BAR;
;         }
.LBB0_514:
	ds_read_b128 v[170:173], v147
	ds_read_b128 v[174:177], v148
	ds_read_b128 v[178:181], v149
	ds_read_b128 v[182:185], v150
	s_add_u32 s42, s40, 0x100
	s_addc_u32 s43, s41, 0
	s_cmp_eq_u32 s10, 12
	s_cselect_b32 s47, s7, s43
	s_cselect_b32 s46, s6, s42
	s_cselect_b32 s45, s1, s82
	s_cselect_b32 s44, s0, s81
	s_mov_b32 m0, s71
	ds_read_b128 v[186:189], v145
	ds_read_b128 v[190:193], v145 offset:1024
	ds_read_b128 v[194:197], v145 offset:2048
	ds_read_b128 v[198:201], v145 offset:3072
	ds_read_b128 v[202:205], v145 offset:4096
	ds_read_b128 v[206:209], v145 offset:5120
	ds_read_b128 v[210:213], v145 offset:6144
	ds_read_b128 v[214:217], v145 offset:7168
	global_load_lds_dwordx4 v136, s[40:41]
	s_mov_b32 m0, s75
	s_nop 0
	global_load_lds_dwordx4 v138, s[40:41]
	s_waitcnt lgkmcnt(8)
	s_barrier
	s_waitcnt lgkmcnt(0)
	s_setprio 1
	s_waitcnt lgkmcnt(0)
	v_mfma_f32_16x16x32_bf16 v[124:127], v[170:173], v[186:189], v[124:127]
	v_mfma_f32_16x16x32_bf16 v[120:123], v[178:181], v[186:189], v[120:123]
	v_mfma_f32_16x16x32_bf16 v[116:119], v[170:173], v[194:197], v[116:119]
	v_mfma_f32_16x16x32_bf16 v[112:115], v[178:181], v[194:197], v[112:115]
	v_mfma_f32_16x16x32_bf16 v[108:111], v[170:173], v[202:205], v[108:111]
	v_mfma_f32_16x16x32_bf16 v[104:107], v[178:181], v[202:205], v[104:107]
	v_mfma_f32_16x16x32_bf16 v[100:103], v[170:173], v[210:213], v[100:103]
	v_mfma_f32_16x16x32_bf16 v[96:99], v[178:181], v[210:213], v[96:99]
	v_mfma_f32_16x16x32_bf16 v[124:127], v[174:177], v[190:193], v[124:127]
	v_mfma_f32_16x16x32_bf16 v[120:123], v[182:185], v[190:193], v[120:123]
	v_mfma_f32_16x16x32_bf16 v[116:119], v[174:177], v[198:201], v[116:119]
	v_mfma_f32_16x16x32_bf16 v[112:115], v[182:185], v[198:201], v[112:115]
	v_mfma_f32_16x16x32_bf16 v[108:111], v[174:177], v[206:209], v[108:111]
	v_mfma_f32_16x16x32_bf16 v[104:107], v[182:185], v[206:209], v[104:107]
	v_mfma_f32_16x16x32_bf16 v[100:103], v[174:177], v[214:217], v[100:103]
	v_mfma_f32_16x16x32_bf16 v[96:99], v[182:185], v[214:217], v[96:99]
	s_setprio 0
	s_barrier
	s_mov_b32 m0, s55
	ds_read_b128 v[218:221], v151
	ds_read_b128 v[222:225], v152
	ds_read_b128 v[226:229], v153
	ds_read_b128 v[230:233], v154
	global_load_lds_dwordx4 v132, s[44:45]
	s_mov_b32 m0, s56
	s_nop 0
	global_load_lds_dwordx4 v128, s[44:45]
	s_waitcnt lgkmcnt(0)
	s_barrier
	s_waitcnt lgkmcnt(0)
	s_setprio 1
	s_waitcnt lgkmcnt(0)
	v_mfma_f32_16x16x32_bf16 v[60:63], v[218:221], v[186:189], v[60:63]
	v_mfma_f32_16x16x32_bf16 v[56:59], v[226:229], v[186:189], v[56:59]
	v_mfma_f32_16x16x32_bf16 v[52:55], v[218:221], v[194:197], v[52:55]
	v_mfma_f32_16x16x32_bf16 v[48:51], v[226:229], v[194:197], v[48:51]
	v_mfma_f32_16x16x32_bf16 v[44:47], v[218:221], v[202:205], v[44:47]
	v_mfma_f32_16x16x32_bf16 v[40:43], v[226:229], v[202:205], v[40:43]
	v_mfma_f32_16x16x32_bf16 v[36:39], v[218:221], v[210:213], v[36:39]
	v_mfma_f32_16x16x32_bf16 v[32:35], v[226:229], v[210:213], v[32:35]
	v_mfma_f32_16x16x32_bf16 v[60:63], v[222:225], v[190:193], v[60:63]
	v_mfma_f32_16x16x32_bf16 v[56:59], v[230:233], v[190:193], v[56:59]
	v_mfma_f32_16x16x32_bf16 v[52:55], v[222:225], v[198:201], v[52:55]
	v_mfma_f32_16x16x32_bf16 v[48:51], v[230:233], v[198:201], v[48:51]
	v_mfma_f32_16x16x32_bf16 v[44:47], v[222:225], v[206:209], v[44:47]
	v_mfma_f32_16x16x32_bf16 v[40:43], v[230:233], v[206:209], v[40:43]
	v_mfma_f32_16x16x32_bf16 v[36:39], v[222:225], v[214:217], v[36:39]
	v_mfma_f32_16x16x32_bf16 v[32:35], v[230:233], v[214:217], v[32:35]
	s_setprio 0
	s_mov_b32 m0, s52
	s_barrier
	ds_read_b128 v[186:189], v145 offset:16384
	ds_read_b128 v[190:193], v145 offset:17408
	ds_read_b128 v[194:197], v145 offset:18432
	ds_read_b128 v[198:201], v145 offset:19456
	ds_read_b128 v[202:205], v145 offset:20480
	ds_read_b128 v[206:209], v145 offset:21504
	ds_read_b128 v[210:213], v145 offset:22528
	ds_read_b128 v[214:217], v145 offset:23552
	global_load_lds_dwordx4 v134, s[46:47]
	s_mov_b32 m0, s57
	s_nop 0
	global_load_lds_dwordx4 v130, s[46:47]
	s_add_u32 s40, s44, 0x44000
	s_addc_u32 s41, s45, 0
	s_mov_b32 m0, s58
	s_nop 0
	global_load_lds_dwordx4 v132, s[40:41]
	s_mov_b32 m0, s59
	s_nop 0
	global_load_lds_dwordx4 v128, s[40:41]
	s_waitcnt vmcnt(6)
	s_barrier
	s_waitcnt lgkmcnt(0)
	s_setprio 1
	s_waitcnt lgkmcnt(0)
	v_mfma_f32_16x16x32_bf16 v[92:95], v[170:173], v[186:189], v[92:95]
	v_mfma_f32_16x16x32_bf16 v[88:91], v[178:181], v[186:189], v[88:91]
	v_mfma_f32_16x16x32_bf16 v[84:87], v[170:173], v[194:197], v[84:87]
	v_mfma_f32_16x16x32_bf16 v[80:83], v[178:181], v[194:197], v[80:83]
	v_mfma_f32_16x16x32_bf16 v[76:79], v[170:173], v[202:205], v[76:79]
	v_mfma_f32_16x16x32_bf16 v[72:75], v[178:181], v[202:205], v[72:75]
	v_mfma_f32_16x16x32_bf16 v[68:71], v[170:173], v[210:213], v[68:71]
	v_mfma_f32_16x16x32_bf16 v[64:67], v[178:181], v[210:213], v[64:67]
	v_mfma_f32_16x16x32_bf16 v[92:95], v[174:177], v[190:193], v[92:95]
	v_mfma_f32_16x16x32_bf16 v[88:91], v[182:185], v[190:193], v[88:91]
	v_mfma_f32_16x16x32_bf16 v[84:87], v[174:177], v[198:201], v[84:87]
	v_mfma_f32_16x16x32_bf16 v[80:83], v[182:185], v[198:201], v[80:83]
	v_mfma_f32_16x16x32_bf16 v[76:79], v[174:177], v[206:209], v[76:79]
	v_mfma_f32_16x16x32_bf16 v[72:75], v[182:185], v[206:209], v[72:75]
	v_mfma_f32_16x16x32_bf16 v[68:71], v[174:177], v[214:217], v[68:71]
	v_mfma_f32_16x16x32_bf16 v[64:67], v[182:185], v[214:217], v[64:67]
	v_mfma_f32_16x16x32_bf16 v[28:31], v[218:221], v[186:189], v[28:31]
	v_mfma_f32_16x16x32_bf16 v[24:27], v[226:229], v[186:189], v[24:27]
	v_mfma_f32_16x16x32_bf16 v[20:23], v[218:221], v[194:197], v[20:23]
	v_mfma_f32_16x16x32_bf16 v[16:19], v[226:229], v[194:197], v[16:19]
	v_mfma_f32_16x16x32_bf16 v[12:15], v[218:221], v[202:205], v[12:15]
	v_mfma_f32_16x16x32_bf16 v[8:11], v[226:229], v[202:205], v[8:11]
	v_mfma_f32_16x16x32_bf16 v[4:7], v[218:221], v[210:213], v[4:7]
	v_mfma_f32_16x16x32_bf16 v[0:3], v[226:229], v[210:213], v[0:3]
	v_mfma_f32_16x16x32_bf16 v[28:31], v[222:225], v[190:193], v[28:31]
	v_mfma_f32_16x16x32_bf16 v[24:27], v[230:233], v[190:193], v[24:27]
	v_mfma_f32_16x16x32_bf16 v[20:23], v[222:225], v[198:201], v[20:23]
	v_mfma_f32_16x16x32_bf16 v[16:19], v[230:233], v[198:201], v[16:19]
	v_mfma_f32_16x16x32_bf16 v[12:15], v[222:225], v[206:209], v[12:15]
	v_mfma_f32_16x16x32_bf16 v[8:11], v[230:233], v[206:209], v[8:11]
	v_mfma_f32_16x16x32_bf16 v[4:7], v[222:225], v[214:217], v[4:7]
	v_mfma_f32_16x16x32_bf16 v[0:3], v[230:233], v[214:217], v[0:3]
	s_setprio 0
	s_barrier
; #define PG8_STAGE(bufoff, gbase, voff) do { _Pragma("unroll") for (int _i = 0; _i < 2; ++_i) \
;         __builtin_amdgcn_global_load_lds((const unsigned*)((const char*)(gbase) + (voff)[_i]), (PG8_LAS unsigned*)(lds + (bufoff) + ldsw + _i * 8192), 16, 0, 0); } while (0)
; #define PG8_LDA(dst, b, h) do { _Pragma("unroll") for (int m = 0; m < 4; ++m) _Pragma("unroll") for (int k = 0; k < 2; ++k) dst[m][k] = *(const PG8_LAS bf16x8*)(lds + PG8_SA(b, h) + aoff + m * 2048 + k * 1024); } while (0)
; template <class Epi, class Sched, bool STAMP = false>
; __device__ __forceinline__ void gemm_phase(PG8_LAS unsigned char* lds, const Gemm g, const Sched& S, const Epi& E, unsigned long long* stamps) {
;     ...
;         for (int t = 0; t < nt; t += 2) {
;             const bool last = (t == nt - 2);
;             const char* a1 = cA + (size_t)(t + 1) * kstep;
;             const char* a2 = last ? nA : cA + (size_t)(t + 2) * kstep; const char* b2 = last ? nB : cB + (size_t)(t + 2) * kstep;
;             const char* a3 = a2 + kstep; const char* b3 = b2 + kstep;
;             if (last && has_next) S.a_ready(nxt);
;             PG8_LDB(B0, 0, 0); PG8_SCHED; PG8_LDA(At, 0, 0); PG8_STAGE(PG8_SA(1, 1), a1 + hstep, voffA);
;             PG8_WAIT_L(8); PG8_BAR; PG8_WAIT_L(0); PG8_MMA(0, 0, At, B0); PG8_BAR; PG8_SCHED;
;             PG8_LDB(B1, 0, 1); PG8_STAGE(PG8_SB(0, 0), b2, voffB);
;             PG8_BAR; PG8_WAIT_L(0); PG8_MMA(0, 1, At, B1); PG8_BAR;
;             PG8_LDA(At, 0, 1); PG8_STAGE(PG8_SA(0, 0), a2, voffA);
;             PG8_BAR; PG8_WAIT_L(0); PG8_MMA(1, 0, At, B0); PG8_BAR; PG8_SCHED;
;             PG8_STAGE(PG8_SB(0, 1), b2 + hstep, voffB);
;             PG8_WAIT_V(6); PG8_BAR; PG8_MMA(1, 1, At, B1); PG8_BAR;
;             PG8_LDB(B0, 1, 0); PG8_SCHED; PG8_LDA(At, 1, 0); PG8_STAGE(PG8_SA(0, 1), a2 + hstep, voffA);
;             PG8_WAIT_L(8); PG8_BAR; PG8_WAIT_L(0); PG8_MMA(0, 0, At, B0); PG8_BAR; PG8_SCHED;
;             PG8_LDB(B1, 1, 1); PG8_STAGE(PG8_SB(1, 0), b3, voffB);
;             PG8_BAR; PG8_WAIT_L(0); PG8_MMA(0, 1, At, B1); PG8_BAR;
;             PG8_LDA(At, 1, 1); PG8_STAGE(PG8_SA(1, 0), a3, voffA);
;             PG8_BAR; PG8_WAIT_L(0); PG8_MMA(1, 0, At, B0); PG8_BAR; PG8_SCHED;
;             PG8_STAGE(PG8_SB(1, 1), b3 + hstep, voffB);
;             PG8_WAIT_V(6); PG8_BAR; PG8_MMA(1, 1, At, B1); PG8_BAR;
;         }
.Lzp9_mid:
	ds_read_b128 v[170:173], v155
	ds_read_b128 v[174:177], v156
	ds_read_b128 v[178:181], v157
	ds_read_b128 v[182:185], v165
	s_add_u32 s40, s46, 0x44000
	s_addc_u32 s41, s47, 0
	s_mov_b32 m0, s60
	ds_read_b128 v[186:189], v145 offset:32768
	ds_read_b128 v[190:193], v145 offset:33792
	ds_read_b128 v[194:197], v145 offset:34816
	ds_read_b128 v[198:201], v145 offset:35840
	ds_read_b128 v[202:205], v145 offset:36864
	ds_read_b128 v[206:209], v145 offset:37888
	ds_read_b128 v[210:213], v145 offset:38912
	ds_read_b128 v[214:217], v145 offset:39936
	global_load_lds_dwordx4 v134, s[40:41]
	s_mov_b32 m0, s61
	s_nop 0
	global_load_lds_dwordx4 v130, s[40:41]
	s_waitcnt lgkmcnt(8)
	s_barrier
	s_waitcnt lgkmcnt(0)
	s_setprio 1
	s_waitcnt lgkmcnt(0)
	v_mfma_f32_16x16x32_bf16 v[124:127], v[170:173], v[186:189], v[124:127]
	v_mfma_f32_16x16x32_bf16 v[120:123], v[178:181], v[186:189], v[120:123]
	v_mfma_f32_16x16x32_bf16 v[116:119], v[170:173], v[194:197], v[116:119]
	v_mfma_f32_16x16x32_bf16 v[112:115], v[178:181], v[194:197], v[112:115]
	v_mfma_f32_16x16x32_bf16 v[108:111], v[170:173], v[202:205], v[108:111]
	v_mfma_f32_16x16x32_bf16 v[104:107], v[178:181], v[202:205], v[104:107]
	v_mfma_f32_16x16x32_bf16 v[100:103], v[170:173], v[210:213], v[100:103]
	v_mfma_f32_16x16x32_bf16 v[96:99], v[178:181], v[210:213], v[96:99]
	v_mfma_f32_16x16x32_bf16 v[124:127], v[174:177], v[190:193], v[124:127]
	v_mfma_f32_16x16x32_bf16 v[120:123], v[182:185], v[190:193], v[120:123]
	v_mfma_f32_16x16x32_bf16 v[116:119], v[174:177], v[198:201], v[116:119]
	v_mfma_f32_16x16x32_bf16 v[112:115], v[182:185], v[198:201], v[112:115]
	v_mfma_f32_16x16x32_bf16 v[108:111], v[174:177], v[206:209], v[108:111]
	v_mfma_f32_16x16x32_bf16 v[104:107], v[182:185], v[206:209], v[104:107]
	v_mfma_f32_16x16x32_bf16 v[100:103], v[174:177], v[214:217], v[100:103]
	v_mfma_f32_16x16x32_bf16 v[96:99], v[182:185], v[214:217], v[96:99]
	s_setprio 0
	s_barrier
	s_mov_b32 m0, s64
	ds_read_b128 v[218:221], v166
	ds_read_b128 v[222:225], v167
	ds_read_b128 v[226:229], v168
	ds_read_b128 v[230:233], v169
	s_add_u32 s100, s44, 0x80
	s_addc_u32 s101, s45, 0
	global_load_lds_dwordx4 v132, s[100:101]
	s_mov_b32 m0, s65
	s_nop 0
	global_load_lds_dwordx4 v128, s[100:101]
	s_waitcnt lgkmcnt(0)
	s_barrier
	s_waitcnt lgkmcnt(0)
	s_setprio 1
	s_waitcnt lgkmcnt(0)
	v_mfma_f32_16x16x32_bf16 v[60:63], v[218:221], v[186:189], v[60:63]
	v_mfma_f32_16x16x32_bf16 v[56:59], v[226:229], v[186:189], v[56:59]
	v_mfma_f32_16x16x32_bf16 v[52:55], v[218:221], v[194:197], v[52:55]
	v_mfma_f32_16x16x32_bf16 v[48:51], v[226:229], v[194:197], v[48:51]
	v_mfma_f32_16x16x32_bf16 v[44:47], v[218:221], v[202:205], v[44:47]
	v_mfma_f32_16x16x32_bf16 v[40:43], v[226:229], v[202:205], v[40:43]
	v_mfma_f32_16x16x32_bf16 v[36:39], v[218:221], v[210:213], v[36:39]
	v_mfma_f32_16x16x32_bf16 v[32:35], v[226:229], v[210:213], v[32:35]
	v_mfma_f32_16x16x32_bf16 v[60:63], v[222:225], v[190:193], v[60:63]
	v_mfma_f32_16x16x32_bf16 v[56:59], v[230:233], v[190:193], v[56:59]
	v_mfma_f32_16x16x32_bf16 v[52:55], v[222:225], v[198:201], v[52:55]
	v_mfma_f32_16x16x32_bf16 v[48:51], v[230:233], v[198:201], v[48:51]
	v_mfma_f32_16x16x32_bf16 v[44:47], v[222:225], v[206:209], v[44:47]
	v_mfma_f32_16x16x32_bf16 v[40:43], v[230:233], v[206:209], v[40:43]
	v_mfma_f32_16x16x32_bf16 v[36:39], v[222:225], v[214:217], v[36:39]
	v_mfma_f32_16x16x32_bf16 v[32:35], v[230:233], v[214:217], v[32:35]
	s_setprio 0
	s_mov_b32 m0, s66
	s_barrier
	ds_read_b128 v[186:189], v145 offset:49152
	ds_read_b128 v[190:193], v145 offset:50176
	ds_read_b128 v[194:197], v145 offset:51200
	ds_read_b128 v[198:201], v145 offset:52224
	ds_read_b128 v[202:205], v145 offset:53248
	ds_read_b128 v[206:209], v145 offset:54272
	ds_read_b128 v[210:213], v145 offset:55296
	ds_read_b128 v[214:217], v145 offset:56320
	s_add_u32 s100, s46, 0x80
	s_addc_u32 s101, s47, 0
	global_load_lds_dwordx4 v134, s[100:101]
	s_mov_b32 m0, s67
	s_nop 0
	global_load_lds_dwordx4 v130, s[100:101]
	s_add_u32 s40, s44, 0x44080
	s_addc_u32 s41, s45, 0
	s_mov_b32 m0, s68
	s_nop 0
	global_load_lds_dwordx4 v132, s[40:41]
	s_mov_b32 m0, s69
	s_nop 0
	global_load_lds_dwordx4 v128, s[40:41]
	s_waitcnt vmcnt(6)
	s_barrier
	s_waitcnt lgkmcnt(0)
	s_setprio 1
	s_waitcnt lgkmcnt(0)
	v_mfma_f32_16x16x32_bf16 v[92:95], v[170:173], v[186:189], v[92:95]
	v_mfma_f32_16x16x32_bf16 v[88:91], v[178:181], v[186:189], v[88:91]
	v_mfma_f32_16x16x32_bf16 v[84:87], v[170:173], v[194:197], v[84:87]
	v_mfma_f32_16x16x32_bf16 v[80:83], v[178:181], v[194:197], v[80:83]
	v_mfma_f32_16x16x32_bf16 v[76:79], v[170:173], v[202:205], v[76:79]
	v_mfma_f32_16x16x32_bf16 v[72:75], v[178:181], v[202:205], v[72:75]
	v_mfma_f32_16x16x32_bf16 v[68:71], v[170:173], v[210:213], v[68:71]
	v_mfma_f32_16x16x32_bf16 v[64:67], v[178:181], v[210:213], v[64:67]
	v_mfma_f32_16x16x32_bf16 v[92:95], v[174:177], v[190:193], v[92:95]
	v_mfma_f32_16x16x32_bf16 v[88:91], v[182:185], v[190:193], v[88:91]
	v_mfma_f32_16x16x32_bf16 v[84:87], v[174:177], v[198:201], v[84:87]
	v_mfma_f32_16x16x32_bf16 v[80:83], v[182:185], v[198:201], v[80:83]
	v_mfma_f32_16x16x32_bf16 v[76:79], v[174:177], v[206:209], v[76:79]
	v_mfma_f32_16x16x32_bf16 v[72:75], v[182:185], v[206:209], v[72:75]
	v_mfma_f32_16x16x32_bf16 v[68:71], v[174:177], v[214:217], v[68:71]
	v_mfma_f32_16x16x32_bf16 v[64:67], v[182:185], v[214:217], v[64:67]
	v_mfma_f32_16x16x32_bf16 v[28:31], v[218:221], v[186:189], v[28:31]
	v_mfma_f32_16x16x32_bf16 v[24:27], v[226:229], v[186:189], v[24:27]
	v_mfma_f32_16x16x32_bf16 v[20:23], v[218:221], v[194:197], v[20:23]
	v_mfma_f32_16x16x32_bf16 v[16:19], v[226:229], v[194:197], v[16:19]
	v_mfma_f32_16x16x32_bf16 v[12:15], v[218:221], v[202:205], v[12:15]
	v_mfma_f32_16x16x32_bf16 v[8:11], v[226:229], v[202:205], v[8:11]
	v_mfma_f32_16x16x32_bf16 v[4:7], v[218:221], v[210:213], v[4:7]
	v_mfma_f32_16x16x32_bf16 v[0:3], v[226:229], v[210:213], v[0:3]
	v_mfma_f32_16x16x32_bf16 v[28:31], v[222:225], v[190:193], v[28:31]
	v_mfma_f32_16x16x32_bf16 v[24:27], v[230:233], v[190:193], v[24:27]
	v_mfma_f32_16x16x32_bf16 v[20:23], v[222:225], v[198:201], v[20:23]
	v_mfma_f32_16x16x32_bf16 v[16:19], v[230:233], v[198:201], v[16:19]
	v_mfma_f32_16x16x32_bf16 v[12:15], v[222:225], v[206:209], v[12:15]
	v_mfma_f32_16x16x32_bf16 v[8:11], v[230:233], v[206:209], v[8:11]
	v_mfma_f32_16x16x32_bf16 v[4:7], v[222:225], v[214:217], v[4:7]
	v_mfma_f32_16x16x32_bf16 v[0:3], v[230:233], v[214:217], v[0:3]
	s_setprio 0
	s_add_i32 s10, s10, 2
	s_add_u32 s81, s81, 0x100
	s_addc_u32 s82, s82, 0
	s_cmp_gt_u32 s10, 13
	s_mov_b64 s[40:41], s[42:43]
	s_barrier
;     DI void operator()(const f32x4 (&acc)[2][2][4][2], const Unit& u, int wr, int wc, int fr, int fq) const {
;         const int row0 = u.pm * BM + wr * 64 + fr, col0 = u.pn * BM + wc * 32 + 8 * fq;
; #pragma unroll
;         for (int ai = 0; ai < 2; ++ai)
; #pragma unroll
;             for (int m = 0; m < 4; ++m) { u16* rowp = O + (size_t)(row0 + ai * HALF + m * 16) * ldc + col0;
; #pragma unroll
;                 for (int bj = 0; bj < 2; ++bj) { const f32x4 v0 = acc[ai][bj][m][0], v1 = acc[ai][bj][m][1];
;                     uint4 w = {pack2(v0[0], v0[1]), pack2(v0[2], v0[3]), pack2(v1[0], v1[1]), pack2(v1[2], v1[3])}; *(uint4*)(rowp + bj * HALF) = w; } }
;         if (kmaxp) {
; #pragma unroll
;             for (int bj = 0; bj < 2; ++bj) {
;                 const int cb = u.pn * BM + bj * HALF + wc * 32;
;                 const bool isA = (cb >= 384 && cb < 768), isB = (cb >= 1408 && cb < 1664);
;                 if (isA || isB) {
	s_cbranch_scc0 .LBB0_514
	s_lshl_b32 s46, s79, 8
	v_or_b32_e32 v170, s46, v146
	v_lshl_add_u32 v180, s80, 8, v144
	v_ashrrev_i32_e32 v171, 31, v170
	v_mov_b64_e32 v[174:175], s[12:13]
	v_mad_i64_i32 v[172:173], s[40:41], v180, s76, v[174:175]
	v_lshlrev_b64 v[176:177], 1, v[170:171]
	v_lshl_add_u64 v[178:179], v[172:173], 0, v[176:177]
	v_cvt_pk_bf16_f32 v170, v124, v125
	v_cvt_pk_bf16_f32 v171, v126, v127
	v_cvt_pk_bf16_f32 v172, v120, v121
	v_cvt_pk_bf16_f32 v173, v122, v123
	global_store_dwordx4 v[178:179], v[170:173], off
	s_or_b32 s10, s46, s63
	s_nop 0
	v_cvt_pk_bf16_f32 v170, v60, v61
	v_cvt_pk_bf16_f32 v171, v62, v63
	v_cvt_pk_bf16_f32 v172, v56, v57
	v_cvt_pk_bf16_f32 v173, v58, v59
	global_store_dwordx4 v[178:179], v[170:173], off offset:256
	s_nop 1
	v_or_b32_e32 v170, 16, v180
	v_mad_i64_i32 v[170:171], s[40:41], v170, s76, v[174:175]
	v_lshl_add_u64 v[178:179], v[170:171], 0, v[176:177]
	v_cvt_pk_bf16_f32 v170, v116, v117
	v_cvt_pk_bf16_f32 v171, v118, v119
	v_cvt_pk_bf16_f32 v172, v112, v113
	v_cvt_pk_bf16_f32 v173, v114, v115
	global_store_dwordx4 v[178:179], v[170:173], off
	s_nop 1
	v_cvt_pk_bf16_f32 v170, v52, v53
	v_cvt_pk_bf16_f32 v171, v54, v55
	v_cvt_pk_bf16_f32 v172, v48, v49
	v_cvt_pk_bf16_f32 v173, v50, v51
	global_store_dwordx4 v[178:179], v[170:173], off offset:256
	s_nop 1
	v_or_b32_e32 v170, 32, v180
	v_mad_i64_i32 v[170:171], s[40:41], v170, s76, v[174:175]
	v_lshl_add_u64 v[178:179], v[170:171], 0, v[176:177]
	v_cvt_pk_bf16_f32 v170, v108, v109
	v_cvt_pk_bf16_f32 v171, v110, v111
	v_cvt_pk_bf16_f32 v172, v104, v105
	v_cvt_pk_bf16_f32 v173, v106, v107
	global_store_dwordx4 v[178:179], v[170:173], off
	s_nop 1
	v_cvt_pk_bf16_f32 v170, v44, v45
	v_cvt_pk_bf16_f32 v171, v46, v47
	v_cvt_pk_bf16_f32 v172, v40, v41
	v_cvt_pk_bf16_f32 v173, v42, v43
	global_store_dwordx4 v[178:179], v[170:173], off offset:256
	s_nop 1
	v_or_b32_e32 v170, 48, v180
	v_mad_i64_i32 v[170:171], s[40:41], v170, s76, v[174:175]
	v_lshl_add_u64 v[178:179], v[170:171], 0, v[176:177]
	v_cvt_pk_bf16_f32 v170, v100, v101
	v_cvt_pk_bf16_f32 v171, v102, v103
	v_cvt_pk_bf16_f32 v172, v96, v97
	v_cvt_pk_bf16_f32 v173, v98, v99
	global_store_dwordx4 v[178:179], v[170:173], off
	s_nop 1
	v_cvt_pk_bf16_f32 v170, v36, v37
	v_cvt_pk_bf16_f32 v171, v38, v39
	v_cvt_pk_bf16_f32 v172, v32, v33
	v_cvt_pk_bf16_f32 v173, v34, v35
	global_store_dwordx4 v[178:179], v[170:173], off offset:256
	s_nop 1
	v_add_u32_e32 v170, 0x80, v180
	v_mad_i64_i32 v[170:171], s[40:41], v170, s76, v[174:175]
	v_lshl_add_u64 v[178:179], v[170:171], 0, v[176:177]
	v_cvt_pk_bf16_f32 v170, v92, v93
	v_cvt_pk_bf16_f32 v171, v94, v95
	v_cvt_pk_bf16_f32 v172, v88, v89
	v_cvt_pk_bf16_f32 v173, v90, v91
	global_store_dwordx4 v[178:179], v[170:173], off
	s_nop 1
	v_cvt_pk_bf16_f32 v170, v28, v29
	v_cvt_pk_bf16_f32 v171, v30, v31
	v_cvt_pk_bf16_f32 v172, v24, v25
	v_cvt_pk_bf16_f32 v173, v26, v27
	global_store_dwordx4 v[178:179], v[170:173], off offset:256
	s_nop 1
	v_add_u32_e32 v170, 0x90, v180
	v_mad_i64_i32 v[170:171], s[40:41], v170, s76, v[174:175]
	v_lshl_add_u64 v[178:179], v[170:171], 0, v[176:177]
	v_cvt_pk_bf16_f32 v170, v84, v85
	v_cvt_pk_bf16_f32 v171, v86, v87
	v_cvt_pk_bf16_f32 v172, v80, v81
	v_cvt_pk_bf16_f32 v173, v82, v83
	global_store_dwordx4 v[178:179], v[170:173], off
	s_nop 1
	v_cvt_pk_bf16_f32 v170, v20, v21
	v_cvt_pk_bf16_f32 v171, v22, v23
	v_cvt_pk_bf16_f32 v172, v16, v17
	v_cvt_pk_bf16_f32 v173, v18, v19
	global_store_dwordx4 v[178:179], v[170:173], off offset:256
	s_nop 1
	v_add_u32_e32 v170, 0xa0, v180
	v_mad_i64_i32 v[170:171], s[40:41], v170, s76, v[174:175]
	v_lshl_add_u64 v[178:179], v[170:171], 0, v[176:177]
	v_cvt_pk_bf16_f32 v170, v76, v77
	v_cvt_pk_bf16_f32 v171, v78, v79
	v_cvt_pk_bf16_f32 v172, v72, v73
	v_cvt_pk_bf16_f32 v173, v74, v75
	global_store_dwordx4 v[178:179], v[170:173], off
	s_nop 1
	v_cvt_pk_bf16_f32 v170, v12, v13
	v_cvt_pk_bf16_f32 v171, v14, v15
	v_cvt_pk_bf16_f32 v172, v8, v9
	v_cvt_pk_bf16_f32 v173, v10, v11
	global_store_dwordx4 v[178:179], v[170:173], off offset:256
	s_nop 1
	v_add_u32_e32 v170, 0xb0, v180
	v_mad_i64_i32 v[170:171], s[40:41], v170, s76, v[174:175]
	s_add_i32 s40, s46, 0xfffffe80
	s_cmpk_gt_u32 s40, 0x17f
	s_cselect_b64 s[40:41], -1, 0
	s_add_i32 s42, s46, 0xfffffa80
	s_cmpk_gt_u32 s42, 0xff
	s_cselect_b64 s[42:43], -1, 0
	v_lshl_add_u64 v[174:175], v[170:171], 0, v[176:177]
	v_cvt_pk_bf16_f32 v170, v68, v69
	v_cvt_pk_bf16_f32 v171, v70, v71
	v_cvt_pk_bf16_f32 v172, v64, v65
	v_cvt_pk_bf16_f32 v173, v66, v67
	s_and_b64 s[42:43], s[40:41], s[42:43]
	global_store_dwordx4 v[174:175], v[170:173], off
	s_and_b64 vcc, exec, s[42:43]
	s_nop 0
	v_cvt_pk_bf16_f32 v170, v4, v5
	v_cvt_pk_bf16_f32 v171, v6, v7
	v_cvt_pk_bf16_f32 v172, v0, v1
	v_cvt_pk_bf16_f32 v173, v2, v3
	global_store_dwordx4 v[174:175], v[170:173], off offset:256
	s_cbranch_vccnz .LBB0_526
;     DI void operator()(const f32x4 (&acc)[2][2][4][2], const Unit& u, int wr, int wc, int fr, int fq) const {
;     ...
;                 if (isA || isB) {
;                     float mx = 0.f;
; #pragma unroll
;                     for (int ai = 0; ai < 2; ++ai)
; #pragma unroll
;                         for (int m = 0; m < 4; ++m) {
;                             const f32x4 a = acc[ai][bj][m][0], b = acc[ai][bj][m][1];
;                             float s0 = a[0] * a[0] + a[1] * a[1] + a[2] * a[2] + a[3] * a[3] + b[0] * b[0] + b[1] * b[1] + b[2] * b[2] + b[3] * b[3];
;                             s0 += __shfl_xor(s0, 16);
;                             s0 += __shfl_xor(s0, 32);
;                             mx = fmaxf(mx, s0);
;                         }
; #pragma unroll
;                     for (int o = 1; o <= 8; o <<= 1) mx = fmaxf(mx, __shfl_xor(mx, o));
;                     if ((threadIdx.x & 63) == 0) atomicMax((unsigned*)kmaxp + (isA ? ((cb - 384) >> 5) : (12 + ((cb - 1408) >> 5))), __float_as_uint(mx));
;                 }
	v_mul_f32_e32 v125, v125, v125
	v_mul_f32_e32 v117, v117, v117
	v_fmac_f32_e32 v125, v124, v124
	v_fmac_f32_e32 v117, v116, v116
	v_mul_f32_e32 v109, v109, v109
	v_mul_f32_e32 v101, v101, v101
	v_fmac_f32_e32 v125, v126, v126
	v_fmac_f32_e32 v117, v118, v118
	v_fmac_f32_e32 v109, v108, v108
	v_fmac_f32_e32 v101, v100, v100
	v_fmac_f32_e32 v125, v127, v127
	v_fmac_f32_e32 v117, v119, v119
	v_fmac_f32_e32 v109, v110, v110
	v_fmac_f32_e32 v101, v102, v102
	v_fmac_f32_e32 v125, v120, v120
	v_fmac_f32_e32 v117, v112, v112
	v_fmac_f32_e32 v109, v111, v111
	v_fmac_f32_e32 v101, v103, v103
	v_fmac_f32_e32 v125, v121, v121
	v_fmac_f32_e32 v117, v113, v113
	v_fmac_f32_e32 v109, v104, v104
	v_fmac_f32_e32 v101, v96, v96
	v_fmac_f32_e32 v125, v122, v122
	v_fmac_f32_e32 v117, v114, v114
	v_fmac_f32_e32 v109, v105, v105
	v_fmac_f32_e32 v101, v97, v97
	v_fmac_f32_e32 v125, v123, v123
	v_fmac_f32_e32 v117, v115, v115
	v_fmac_f32_e32 v109, v106, v106
	v_fmac_f32_e32 v101, v98, v98
	v_mul_f32_e32 v93, v93, v93
	v_mul_f32_e32 v85, v85, v85
	ds_bpermute_b32 v120, v160, v125
	ds_bpermute_b32 v112, v160, v117
	v_fmac_f32_e32 v109, v107, v107
	v_fmac_f32_e32 v101, v99, v99
	v_fmac_f32_e32 v93, v92, v92
	v_fmac_f32_e32 v85, v84, v84
	v_mul_f32_e32 v77, v77, v77
	v_mul_f32_e32 v69, v69, v69
	ds_bpermute_b32 v104, v160, v109
	ds_bpermute_b32 v96, v160, v101
	v_fmac_f32_e32 v93, v94, v94
	v_fmac_f32_e32 v85, v86, v86
	v_fmac_f32_e32 v77, v76, v76
	v_fmac_f32_e32 v69, v68, v68
	v_fmac_f32_e32 v93, v95, v95
	v_fmac_f32_e32 v85, v87, v87
	v_fmac_f32_e32 v77, v78, v78
	v_fmac_f32_e32 v69, v70, v70
	v_fmac_f32_e32 v93, v88, v88
	v_fmac_f32_e32 v85, v80, v80
	v_fmac_f32_e32 v77, v79, v79
	v_fmac_f32_e32 v69, v71, v71
	v_fmac_f32_e32 v93, v89, v89
	v_fmac_f32_e32 v85, v81, v81
	v_fmac_f32_e32 v77, v72, v72
	v_fmac_f32_e32 v69, v64, v64
	s_waitcnt lgkmcnt(0)
	v_add_f32_e32 v113, v125, v120
	v_add_f32_e32 v112, v117, v112
	v_fmac_f32_e32 v93, v90, v90
	v_fmac_f32_e32 v85, v82, v82
	v_fmac_f32_e32 v77, v73, v73
	v_fmac_f32_e32 v69, v65, v65
	ds_bpermute_b32 v114, v159, v113
	ds_bpermute_b32 v115, v159, v112
	v_add_f32_e32 v99, v109, v104
	v_add_f32_e32 v96, v101, v96
	v_fmac_f32_e32 v93, v91, v91
	v_fmac_f32_e32 v85, v83, v83
	v_fmac_f32_e32 v77, v74, v74
	v_fmac_f32_e32 v69, v66, v66
	ds_bpermute_b32 v100, v159, v99
	ds_bpermute_b32 v101, v159, v96
	ds_bpermute_b32 v88, v160, v93
	ds_bpermute_b32 v80, v160, v85
	v_fmac_f32_e32 v77, v75, v75
	v_fmac_f32_e32 v69, v67, v67
	ds_bpermute_b32 v72, v160, v77
	ds_bpermute_b32 v64, v160, v69
	s_waitcnt lgkmcnt(0)
	v_add_f32_e32 v97, v113, v114
	v_add_f32_e32 v98, v112, v115
	v_max3_f32 v89, v97, 0, v98
	v_add_f32_e32 v90, v99, v100
	v_add_f32_e32 v91, v96, v101
	v_add_f32_e32 v88, v93, v88
	v_add_f32_e32 v65, v85, v80
	v_max3_f32 v89, v89, v90, v91
	ds_bpermute_b32 v90, v159, v88
	ds_bpermute_b32 v66, v159, v65
	v_add_f32_e32 v67, v77, v72
	v_add_f32_e32 v64, v69, v64
	ds_bpermute_b32 v68, v159, v67
	ds_bpermute_b32 v69, v159, v64
	s_waitcnt lgkmcnt(0)
	v_add_f32_e32 v70, v88, v90
	v_add_f32_e32 v65, v65, v66
	v_max3_f32 v65, v89, v70, v65
	v_add_f32_e32 v66, v67, v68
	v_add_f32_e32 v64, v64, v69
	v_max3_f32 v64, v65, v66, v64
	ds_bpermute_b32 v65, v164, v64
	s_waitcnt lgkmcnt(0)
	v_max_f32_e32 v65, v65, v65
	v_max_f32_e32 v64, v64, v65
	ds_bpermute_b32 v65, v163, v64
	s_waitcnt lgkmcnt(0)
	v_max_f32_e32 v65, v65, v65
	v_max_f32_e32 v64, v64, v65
	ds_bpermute_b32 v65, v162, v64
	s_waitcnt lgkmcnt(0)
	v_max_f32_e32 v65, v65, v65
	v_max_f32_e32 v64, v64, v65
	ds_bpermute_b32 v65, v161, v64
	s_and_saveexec_b64 s[42:43], s[2:3]
	s_cbranch_execz .LBB0_525
	s_mov_b64 s[44:45], -1
	s_and_b64 vcc, exec, s[40:41]
	s_cbranch_vccz .LBB0_519
	s_add_i32 s40, s10, 0xfffffa80
	s_ashr_i32 s40, s40, 5
	s_add_i32 s40, s40, 12
	s_mov_b64 s[44:45], 0

; #define PG8_STAGE(bufoff, gbase, voff) do { _Pragma("unroll") for (int _i = 0; _i < 2; ++_i) \
;         __builtin_amdgcn_global_load_lds((const unsigned*)((const char*)(gbase) + (voff)[_i]), (PG8_LAS unsigned*)(lds + (bufoff) + ldsw + _i * 8192), 16, 0, 0); } while (0)
; template <class Epi, class Sched, bool STAMP = false>
; __device__ __forceinline__ void gemm_phase(PG8_LAS unsigned char* lds, const Gemm g, const Sched& S, const Epi& E, unsigned long long* stamps) {
;     ...
;     for (;;) {
;         const bool has_next = S.next(ui + 1, nxt);
;         const char* nA = has_next ? (const char*)g.A + (size_t)nxt.pm * tstep : cA; const char* nB = has_next ? (const char*)g.Bt + (size_t)nxt.pn * tstep : cB;
;         for (int t = 0; t < nt; t += 2) {
;             const bool last = (t == nt - 2);
;             const char* a1 = cA + (size_t)(t + 1) * kstep;
;             const char* a2 = last ? nA : cA + (size_t)(t + 2) * kstep; const char* b2 = last ? nB : cB + (size_t)(t + 2) * kstep;
;             const char* a3 = a2 + kstep; const char* b3 = b2 + kstep;
;             if (last && has_next) S.a_ready(nxt);
;             PG8_LDB(B0, 0, 0); PG8_SCHED; PG8_LDA(At, 0, 0); PG8_STAGE(PG8_SA(1, 1), a1 + hstep, voffA);
;             PG8_WAIT_L(8); PG8_BAR; PG8_WAIT_L(0); PG8_MMA(0, 0, At, B0); PG8_BAR; PG8_SCHED;
;             PG8_LDB(B1, 0, 1); PG8_STAGE(PG8_SB(0, 0), b2, voffB);
;             PG8_BAR; PG8_WAIT_L(0); PG8_MMA(0, 1, At, B1); PG8_BAR;
;             PG8_LDA(At, 0, 1); PG8_STAGE(PG8_SA(0, 0), a2, voffA);
;             PG8_BAR; PG8_WAIT_L(0); PG8_MMA(1, 0, At, B0); PG8_BAR; PG8_SCHED;
;             PG8_STAGE(PG8_SB(0, 1), b2 + hstep, voffB);
;             PG8_WAIT_V(6); PG8_BAR; PG8_MMA(1, 1, At, B1); PG8_BAR;
;             PG8_LDB(B0, 1, 0); PG8_SCHED; PG8_LDA(At, 1, 0); PG8_STAGE(PG8_SA(0, 1), a2 + hstep, voffA);
;             PG8_WAIT_L(8); PG8_BAR; PG8_WAIT_L(0); PG8_MMA(0, 0, At, B0); PG8_BAR; PG8_SCHED;
;             PG8_LDB(B1, 1, 1); PG8_STAGE(PG8_SB(1, 0), b3, voffB);
;             PG8_BAR; PG8_WAIT_L(0); PG8_MMA(0, 1, At, B1); PG8_BAR;
;             PG8_LDA(At, 1, 1); PG8_STAGE(PG8_SA(1, 0), a3, voffA);
;             PG8_BAR; PG8_WAIT_L(0); PG8_MMA(1, 0, At, B0); PG8_BAR; PG8_SCHED;
;             PG8_STAGE(PG8_SB(1, 1), b3 + hstep, voffB);
;             PG8_WAIT_V(6); PG8_BAR; PG8_MMA(1, 1, At, B1); PG8_BAR;
;         }
.LBB0_687:
	s_add_u32 s76, s36, 0x100
	s_addc_u32 s77, s37, 0
	s_mov_b32 s10, -2
	ds_read_b128 v[170:173], v147
	ds_read_b128 v[174:177], v148
	ds_read_b128 v[178:181], v149
	ds_read_b128 v[182:185], v150
	s_add_u32 s36, s34, 0x100
	s_addc_u32 s37, s35, 0
	s_cmp_eq_u32 s10, 12
	s_cselect_b32 s43, s5, s37
	s_cselect_b32 s42, s4, s36
	s_cselect_b32 s41, s1, s77
	s_cselect_b32 s40, s0, s76
	s_mov_b32 m0, s63
	ds_read_b128 v[186:189], v145
	ds_read_b128 v[190:193], v145 offset:1024
	ds_read_b128 v[194:197], v145 offset:2048
	ds_read_b128 v[198:201], v145 offset:3072
	ds_read_b128 v[202:205], v145 offset:4096
	ds_read_b128 v[206:209], v145 offset:5120
	ds_read_b128 v[210:213], v145 offset:6144
	ds_read_b128 v[214:217], v145 offset:7168
	global_load_lds_dwordx4 v136, s[34:35]
	s_mov_b32 m0, s64
	s_nop 0
	global_load_lds_dwordx4 v138, s[34:35]
	s_waitcnt lgkmcnt(8)
	s_barrier
	s_waitcnt lgkmcnt(0)
	s_setprio 1
	s_waitcnt lgkmcnt(0)
	v_mfma_f32_16x16x32_bf16 v[124:127], v[170:173], v[186:189], 0
	v_mfma_f32_16x16x32_bf16 v[120:123], v[178:181], v[186:189], 0
	v_mfma_f32_16x16x32_bf16 v[116:119], v[170:173], v[194:197], 0
	v_mfma_f32_16x16x32_bf16 v[112:115], v[178:181], v[194:197], 0
	v_mfma_f32_16x16x32_bf16 v[100:103], v[170:173], v[202:205], 0
	v_mfma_f32_16x16x32_bf16 v[96:99], v[178:181], v[202:205], 0
	v_mfma_f32_16x16x32_bf16 v[84:87], v[170:173], v[210:213], 0
	v_mfma_f32_16x16x32_bf16 v[80:83], v[178:181], v[210:213], 0
	v_mfma_f32_16x16x32_bf16 v[124:127], v[174:177], v[190:193], v[124:127]
	v_mfma_f32_16x16x32_bf16 v[120:123], v[182:185], v[190:193], v[120:123]
	v_mfma_f32_16x16x32_bf16 v[116:119], v[174:177], v[198:201], v[116:119]
	v_mfma_f32_16x16x32_bf16 v[112:115], v[182:185], v[198:201], v[112:115]
	v_mfma_f32_16x16x32_bf16 v[100:103], v[174:177], v[206:209], v[100:103]
	v_mfma_f32_16x16x32_bf16 v[96:99], v[182:185], v[206:209], v[96:99]
	v_mfma_f32_16x16x32_bf16 v[84:87], v[174:177], v[214:217], v[84:87]
	v_mfma_f32_16x16x32_bf16 v[80:83], v[182:185], v[214:217], v[80:83]
	s_setprio 0
	s_barrier
	s_mov_b32 m0, s48
	ds_read_b128 v[218:221], v151
	ds_read_b128 v[222:225], v152
	ds_read_b128 v[226:229], v153
	ds_read_b128 v[230:233], v154
	global_load_lds_dwordx4 v130, s[40:41]
	s_mov_b32 m0, s49
	s_nop 0
	global_load_lds_dwordx4 v134, s[40:41]
	s_waitcnt lgkmcnt(0)
	s_barrier
	s_waitcnt lgkmcnt(0)
	s_setprio 1
	s_waitcnt lgkmcnt(0)
	v_mfma_f32_16x16x32_bf16 v[108:111], v[218:221], v[186:189], 0
	v_mfma_f32_16x16x32_bf16 v[104:107], v[226:229], v[186:189], 0
	v_mfma_f32_16x16x32_bf16 v[92:95], v[218:221], v[194:197], 0
	v_mfma_f32_16x16x32_bf16 v[88:91], v[226:229], v[194:197], 0
	v_mfma_f32_16x16x32_bf16 v[76:79], v[218:221], v[202:205], 0
	v_mfma_f32_16x16x32_bf16 v[72:75], v[226:229], v[202:205], 0
	v_mfma_f32_16x16x32_bf16 v[68:71], v[218:221], v[210:213], 0
	v_mfma_f32_16x16x32_bf16 v[64:67], v[226:229], v[210:213], 0
	v_mfma_f32_16x16x32_bf16 v[108:111], v[222:225], v[190:193], v[108:111]
	v_mfma_f32_16x16x32_bf16 v[104:107], v[230:233], v[190:193], v[104:107]
	v_mfma_f32_16x16x32_bf16 v[92:95], v[222:225], v[198:201], v[92:95]
	v_mfma_f32_16x16x32_bf16 v[88:91], v[230:233], v[198:201], v[88:91]
	v_mfma_f32_16x16x32_bf16 v[76:79], v[222:225], v[206:209], v[76:79]
	v_mfma_f32_16x16x32_bf16 v[72:75], v[230:233], v[206:209], v[72:75]
	v_mfma_f32_16x16x32_bf16 v[68:71], v[222:225], v[214:217], v[68:71]
	v_mfma_f32_16x16x32_bf16 v[64:67], v[230:233], v[214:217], v[64:67]
	s_setprio 0
	s_mov_b32 m0, s47
	s_barrier
	ds_read_b128 v[186:189], v145 offset:16384
	ds_read_b128 v[190:193], v145 offset:17408
	ds_read_b128 v[194:197], v145 offset:18432
	ds_read_b128 v[198:201], v145 offset:19456
	ds_read_b128 v[202:205], v145 offset:20480
	ds_read_b128 v[206:209], v145 offset:21504
	ds_read_b128 v[210:213], v145 offset:22528
	ds_read_b128 v[214:217], v145 offset:23552
	global_load_lds_dwordx4 v128, s[42:43]
	s_mov_b32 m0, s50
	s_nop 0
	global_load_lds_dwordx4 v132, s[42:43]
	s_add_u32 s34, s40, 0x44000
	s_addc_u32 s35, s41, 0
	s_mov_b32 m0, s51
	s_nop 0
	global_load_lds_dwordx4 v130, s[34:35]
	s_mov_b32 m0, s52
	s_nop 0
	global_load_lds_dwordx4 v134, s[34:35]
	s_waitcnt vmcnt(6)
	s_barrier
	s_waitcnt lgkmcnt(0)
	s_setprio 1
	s_waitcnt lgkmcnt(0)
	v_mfma_f32_16x16x32_bf16 v[60:63], v[170:173], v[186:189], 0
	v_mfma_f32_16x16x32_bf16 v[56:59], v[178:181], v[186:189], 0
	v_mfma_f32_16x16x32_bf16 v[52:55], v[170:173], v[194:197], 0
	v_mfma_f32_16x16x32_bf16 v[48:51], v[178:181], v[194:197], 0
	v_mfma_f32_16x16x32_bf16 v[36:39], v[170:173], v[202:205], 0
	v_mfma_f32_16x16x32_bf16 v[32:35], v[178:181], v[202:205], 0
	v_mfma_f32_16x16x32_bf16 v[20:23], v[170:173], v[210:213], 0
	v_mfma_f32_16x16x32_bf16 v[16:19], v[178:181], v[210:213], 0
	v_mfma_f32_16x16x32_bf16 v[60:63], v[174:177], v[190:193], v[60:63]
	v_mfma_f32_16x16x32_bf16 v[56:59], v[182:185], v[190:193], v[56:59]
	v_mfma_f32_16x16x32_bf16 v[52:55], v[174:177], v[198:201], v[52:55]
	v_mfma_f32_16x16x32_bf16 v[48:51], v[182:185], v[198:201], v[48:51]
	v_mfma_f32_16x16x32_bf16 v[36:39], v[174:177], v[206:209], v[36:39]
	v_mfma_f32_16x16x32_bf16 v[32:35], v[182:185], v[206:209], v[32:35]
	v_mfma_f32_16x16x32_bf16 v[20:23], v[174:177], v[214:217], v[20:23]
	v_mfma_f32_16x16x32_bf16 v[16:19], v[182:185], v[214:217], v[16:19]
	v_mfma_f32_16x16x32_bf16 v[44:47], v[218:221], v[186:189], 0
	v_mfma_f32_16x16x32_bf16 v[40:43], v[226:229], v[186:189], 0
	v_mfma_f32_16x16x32_bf16 v[28:31], v[218:221], v[194:197], 0
	v_mfma_f32_16x16x32_bf16 v[24:27], v[226:229], v[194:197], 0
	v_mfma_f32_16x16x32_bf16 v[12:15], v[218:221], v[202:205], 0
	v_mfma_f32_16x16x32_bf16 v[8:11], v[226:229], v[202:205], 0
	v_mfma_f32_16x16x32_bf16 v[4:7], v[218:221], v[210:213], 0
	v_mfma_f32_16x16x32_bf16 v[0:3], v[226:229], v[210:213], 0
	v_mfma_f32_16x16x32_bf16 v[44:47], v[222:225], v[190:193], v[44:47]
	v_mfma_f32_16x16x32_bf16 v[40:43], v[230:233], v[190:193], v[40:43]
	v_mfma_f32_16x16x32_bf16 v[28:31], v[222:225], v[198:201], v[28:31]
	v_mfma_f32_16x16x32_bf16 v[24:27], v[230:233], v[198:201], v[24:27]
	v_mfma_f32_16x16x32_bf16 v[12:15], v[222:225], v[206:209], v[12:15]
	v_mfma_f32_16x16x32_bf16 v[8:11], v[230:233], v[206:209], v[8:11]
	v_mfma_f32_16x16x32_bf16 v[4:7], v[222:225], v[214:217], v[4:7]
	v_mfma_f32_16x16x32_bf16 v[0:3], v[230:233], v[214:217], v[0:3]
	s_setprio 0
	s_barrier
	s_branch .Lzp10_mid
; #define PG8_STAGE(bufoff, gbase, voff) do { _Pragma("unroll") for (int _i = 0; _i < 2; ++_i) \
;         __builtin_amdgcn_global_load_lds((const unsigned*)((const char*)(gbase) + (voff)[_i]), (PG8_LAS unsigned*)(lds + (bufoff) + ldsw + _i * 8192), 16, 0, 0); } while (0)
; #define PG8_LDA(dst, b, h) do { _Pragma("unroll") for (int m = 0; m < 4; ++m) _Pragma("unroll") for (int k = 0; k < 2; ++k) dst[m][k] = *(const PG8_LAS bf16x8*)(lds + PG8_SA(b, h) + aoff + m * 2048 + k * 1024); } while (0)
; template <class Epi, class Sched, bool STAMP = false>
; __device__ __forceinline__ void gemm_phase(PG8_LAS unsigned char* lds, const Gemm g, const Sched& S, const Epi& E, unsigned long long* stamps) {
;     ...
;         for (int t = 0; t < nt; t += 2) {
;             const bool last = (t == nt - 2);
;             const char* a1 = cA + (size_t)(t + 1) * kstep;
;             const char* a2 = last ? nA : cA + (size_t)(t + 2) * kstep; const char* b2 = last ? nB : cB + (size_t)(t + 2) * kstep;
;             const char* a3 = a2 + kstep; const char* b3 = b2 + kstep;
;             if (last && has_next) S.a_ready(nxt);
;             PG8_LDB(B0, 0, 0); PG8_SCHED; PG8_LDA(At, 0, 0); PG8_STAGE(PG8_SA(1, 1), a1 + hstep, voffA);
;             PG8_WAIT_L(8); PG8_BAR; PG8_WAIT_L(0); PG8_MMA(0, 0, At, B0); PG8_BAR; PG8_SCHED;
;             PG8_LDB(B1, 0, 1); PG8_STAGE(PG8_SB(0, 0), b2, voffB);
;             PG8_BAR; PG8_WAIT_L(0); PG8_MMA(0, 1, At, B1); PG8_BAR;
;             PG8_LDA(At, 0, 1); PG8_STAGE(PG8_SA(0, 0), a2, voffA);
;             PG8_BAR; PG8_WAIT_L(0); PG8_MMA(1, 0, At, B0); PG8_BAR; PG8_SCHED;
;             PG8_STAGE(PG8_SB(0, 1), b2 + hstep, voffB);
;             PG8_WAIT_V(6); PG8_BAR; PG8_MMA(1, 1, At, B1); PG8_BAR;
;             PG8_LDB(B0, 1, 0); PG8_SCHED; PG8_LDA(At, 1, 0); PG8_STAGE(PG8_SA(0, 1), a2 + hstep, voffA);
;             PG8_WAIT_L(8); PG8_BAR; PG8_WAIT_L(0); PG8_MMA(0, 0, At, B0); PG8_BAR; PG8_SCHED;
;             PG8_LDB(B1, 1, 1); PG8_STAGE(PG8_SB(1, 0), b3, voffB);
;             PG8_BAR; PG8_WAIT_L(0); PG8_MMA(0, 1, At, B1); PG8_BAR;
;             PG8_LDA(At, 1, 1); PG8_STAGE(PG8_SA(1, 0), a3, voffA);
;             PG8_BAR; PG8_WAIT_L(0); PG8_MMA(1, 0, At, B0); PG8_BAR; PG8_SCHED;
;             PG8_STAGE(PG8_SB(1, 1), b3 + hstep, voffB);
;             PG8_WAIT_V(6); PG8_BAR; PG8_MMA(1, 1, At, B1); PG8_BAR;
;         }
.LBB0_688:
	ds_read_b128 v[170:173], v147
	ds_read_b128 v[174:177], v148
	ds_read_b128 v[178:181], v149
	ds_read_b128 v[182:185], v150
	s_add_u32 s36, s34, 0x100
	s_addc_u32 s37, s35, 0
	s_cmp_eq_u32 s10, 12
	s_cselect_b32 s43, s5, s37
	s_cselect_b32 s42, s4, s36
	s_cselect_b32 s41, s1, s77
	s_cselect_b32 s40, s0, s76
	s_mov_b32 m0, s63
	ds_read_b128 v[186:189], v145
	ds_read_b128 v[190:193], v145 offset:1024
	ds_read_b128 v[194:197], v145 offset:2048
	ds_read_b128 v[198:201], v145 offset:3072
	ds_read_b128 v[202:205], v145 offset:4096
	ds_read_b128 v[206:209], v145 offset:5120
	ds_read_b128 v[210:213], v145 offset:6144
	ds_read_b128 v[214:217], v145 offset:7168
	global_load_lds_dwordx4 v136, s[34:35]
	s_mov_b32 m0, s64
	s_nop 0
	global_load_lds_dwordx4 v138, s[34:35]
	s_waitcnt lgkmcnt(8)
	s_barrier
	s_waitcnt lgkmcnt(0)
	s_setprio 1
	s_waitcnt lgkmcnt(0)
	v_mfma_f32_16x16x32_bf16 v[124:127], v[170:173], v[186:189], v[124:127]
	v_mfma_f32_16x16x32_bf16 v[120:123], v[178:181], v[186:189], v[120:123]
	v_mfma_f32_16x16x32_bf16 v[116:119], v[170:173], v[194:197], v[116:119]
	v_mfma_f32_16x16x32_bf16 v[112:115], v[178:181], v[194:197], v[112:115]
	v_mfma_f32_16x16x32_bf16 v[100:103], v[170:173], v[202:205], v[100:103]
	v_mfma_f32_16x16x32_bf16 v[96:99], v[178:181], v[202:205], v[96:99]
	v_mfma_f32_16x16x32_bf16 v[84:87], v[170:173], v[210:213], v[84:87]
	v_mfma_f32_16x16x32_bf16 v[80:83], v[178:181], v[210:213], v[80:83]
	v_mfma_f32_16x16x32_bf16 v[124:127], v[174:177], v[190:193], v[124:127]
	v_mfma_f32_16x16x32_bf16 v[120:123], v[182:185], v[190:193], v[120:123]
	v_mfma_f32_16x16x32_bf16 v[116:119], v[174:177], v[198:201], v[116:119]
	v_mfma_f32_16x16x32_bf16 v[112:115], v[182:185], v[198:201], v[112:115]
	v_mfma_f32_16x16x32_bf16 v[100:103], v[174:177], v[206:209], v[100:103]
	v_mfma_f32_16x16x32_bf16 v[96:99], v[182:185], v[206:209], v[96:99]
	v_mfma_f32_16x16x32_bf16 v[84:87], v[174:177], v[214:217], v[84:87]
	v_mfma_f32_16x16x32_bf16 v[80:83], v[182:185], v[214:217], v[80:83]
	s_setprio 0
	s_barrier
	s_mov_b32 m0, s48
	ds_read_b128 v[218:221], v151
	ds_read_b128 v[222:225], v152
	ds_read_b128 v[226:229], v153
	ds_read_b128 v[230:233], v154
	global_load_lds_dwordx4 v130, s[40:41]
	s_mov_b32 m0, s49
	s_nop 0
	global_load_lds_dwordx4 v134, s[40:41]
	s_waitcnt lgkmcnt(0)
	s_barrier
	s_waitcnt lgkmcnt(0)
	s_setprio 1
	s_waitcnt lgkmcnt(0)
	v_mfma_f32_16x16x32_bf16 v[108:111], v[218:221], v[186:189], v[108:111]
	v_mfma_f32_16x16x32_bf16 v[104:107], v[226:229], v[186:189], v[104:107]
	v_mfma_f32_16x16x32_bf16 v[92:95], v[218:221], v[194:197], v[92:95]
	v_mfma_f32_16x16x32_bf16 v[88:91], v[226:229], v[194:197], v[88:91]
	v_mfma_f32_16x16x32_bf16 v[76:79], v[218:221], v[202:205], v[76:79]
	v_mfma_f32_16x16x32_bf16 v[72:75], v[226:229], v[202:205], v[72:75]
	v_mfma_f32_16x16x32_bf16 v[68:71], v[218:221], v[210:213], v[68:71]
	v_mfma_f32_16x16x32_bf16 v[64:67], v[226:229], v[210:213], v[64:67]
	v_mfma_f32_16x16x32_bf16 v[108:111], v[222:225], v[190:193], v[108:111]
	v_mfma_f32_16x16x32_bf16 v[104:107], v[230:233], v[190:193], v[104:107]
	v_mfma_f32_16x16x32_bf16 v[92:95], v[222:225], v[198:201], v[92:95]
	v_mfma_f32_16x16x32_bf16 v[88:91], v[230:233], v[198:201], v[88:91]
	v_mfma_f32_16x16x32_bf16 v[76:79], v[222:225], v[206:209], v[76:79]
	v_mfma_f32_16x16x32_bf16 v[72:75], v[230:233], v[206:209], v[72:75]
	v_mfma_f32_16x16x32_bf16 v[68:71], v[222:225], v[214:217], v[68:71]
	v_mfma_f32_16x16x32_bf16 v[64:67], v[230:233], v[214:217], v[64:67]
	s_setprio 0
	s_mov_b32 m0, s47
	s_barrier
	ds_read_b128 v[186:189], v145 offset:16384
	ds_read_b128 v[190:193], v145 offset:17408
	ds_read_b128 v[194:197], v145 offset:18432
	ds_read_b128 v[198:201], v145 offset:19456
	ds_read_b128 v[202:205], v145 offset:20480
	ds_read_b128 v[206:209], v145 offset:21504
	ds_read_b128 v[210:213], v145 offset:22528
	ds_read_b128 v[214:217], v145 offset:23552
	global_load_lds_dwordx4 v128, s[42:43]
	s_mov_b32 m0, s50
	s_nop 0
	global_load_lds_dwordx4 v132, s[42:43]
	s_add_u32 s34, s40, 0x44000
	s_addc_u32 s35, s41, 0
	s_mov_b32 m0, s51
	s_nop 0
	global_load_lds_dwordx4 v130, s[34:35]
	s_mov_b32 m0, s52
	s_nop 0
	global_load_lds_dwordx4 v134, s[34:35]
	s_waitcnt vmcnt(6)
	s_barrier
	s_waitcnt lgkmcnt(0)
	s_setprio 1
	s_waitcnt lgkmcnt(0)
	v_mfma_f32_16x16x32_bf16 v[60:63], v[170:173], v[186:189], v[60:63]
	v_mfma_f32_16x16x32_bf16 v[56:59], v[178:181], v[186:189], v[56:59]
	v_mfma_f32_16x16x32_bf16 v[52:55], v[170:173], v[194:197], v[52:55]
	v_mfma_f32_16x16x32_bf16 v[48:51], v[178:181], v[194:197], v[48:51]
	v_mfma_f32_16x16x32_bf16 v[36:39], v[170:173], v[202:205], v[36:39]
	v_mfma_f32_16x16x32_bf16 v[32:35], v[178:181], v[202:205], v[32:35]
	v_mfma_f32_16x16x32_bf16 v[20:23], v[170:173], v[210:213], v[20:23]
	v_mfma_f32_16x16x32_bf16 v[16:19], v[178:181], v[210:213], v[16:19]
	v_mfma_f32_16x16x32_bf16 v[60:63], v[174:177], v[190:193], v[60:63]
	v_mfma_f32_16x16x32_bf16 v[56:59], v[182:185], v[190:193], v[56:59]
	v_mfma_f32_16x16x32_bf16 v[52:55], v[174:177], v[198:201], v[52:55]
	v_mfma_f32_16x16x32_bf16 v[48:51], v[182:185], v[198:201], v[48:51]
	v_mfma_f32_16x16x32_bf16 v[36:39], v[174:177], v[206:209], v[36:39]
	v_mfma_f32_16x16x32_bf16 v[32:35], v[182:185], v[206:209], v[32:35]
	v_mfma_f32_16x16x32_bf16 v[20:23], v[174:177], v[214:217], v[20:23]
	v_mfma_f32_16x16x32_bf16 v[16:19], v[182:185], v[214:217], v[16:19]
	v_mfma_f32_16x16x32_bf16 v[44:47], v[218:221], v[186:189], v[44:47]
	v_mfma_f32_16x16x32_bf16 v[40:43], v[226:229], v[186:189], v[40:43]
	v_mfma_f32_16x16x32_bf16 v[28:31], v[218:221], v[194:197], v[28:31]
	v_mfma_f32_16x16x32_bf16 v[24:27], v[226:229], v[194:197], v[24:27]
	v_mfma_f32_16x16x32_bf16 v[12:15], v[218:221], v[202:205], v[12:15]
	v_mfma_f32_16x16x32_bf16 v[8:11], v[226:229], v[202:205], v[8:11]
	v_mfma_f32_16x16x32_bf16 v[4:7], v[218:221], v[210:213], v[4:7]
	v_mfma_f32_16x16x32_bf16 v[0:3], v[226:229], v[210:213], v[0:3]
	v_mfma_f32_16x16x32_bf16 v[44:47], v[222:225], v[190:193], v[44:47]
	v_mfma_f32_16x16x32_bf16 v[40:43], v[230:233], v[190:193], v[40:43]
	v_mfma_f32_16x16x32_bf16 v[28:31], v[222:225], v[198:201], v[28:31]
	v_mfma_f32_16x16x32_bf16 v[24:27], v[230:233], v[198:201], v[24:27]
	v_mfma_f32_16x16x32_bf16 v[12:15], v[222:225], v[206:209], v[12:15]
	v_mfma_f32_16x16x32_bf16 v[8:11], v[230:233], v[206:209], v[8:11]
	v_mfma_f32_16x16x32_bf16 v[4:7], v[222:225], v[214:217], v[4:7]
	v_mfma_f32_16x16x32_bf16 v[0:3], v[230:233], v[214:217], v[0:3]
	s_setprio 0
	s_barrier
; #define PG8_STAGE(bufoff, gbase, voff) do { _Pragma("unroll") for (int _i = 0; _i < 2; ++_i) \
;         __builtin_amdgcn_global_load_lds((const unsigned*)((const char*)(gbase) + (voff)[_i]), (PG8_LAS unsigned*)(lds + (bufoff) + ldsw + _i * 8192), 16, 0, 0); } while (0)
; #define PG8_LDA(dst, b, h) do { _Pragma("unroll") for (int m = 0; m < 4; ++m) _Pragma("unroll") for (int k = 0; k < 2; ++k) dst[m][k] = *(const PG8_LAS bf16x8*)(lds + PG8_SA(b, h) + aoff + m * 2048 + k * 1024); } while (0)
; template <class Epi, class Sched, bool STAMP = false>
; __device__ __forceinline__ void gemm_phase(PG8_LAS unsigned char* lds, const Gemm g, const Sched& S, const Epi& E, unsigned long long* stamps) {
;     ...
;         for (int t = 0; t < nt; t += 2) {
;             const bool last = (t == nt - 2);
;             const char* a1 = cA + (size_t)(t + 1) * kstep;
;             const char* a2 = last ? nA : cA + (size_t)(t + 2) * kstep; const char* b2 = last ? nB : cB + (size_t)(t + 2) * kstep;
;             const char* a3 = a2 + kstep; const char* b3 = b2 + kstep;
;             if (last && has_next) S.a_ready(nxt);
;             PG8_LDB(B0, 0, 0); PG8_SCHED; PG8_LDA(At, 0, 0); PG8_STAGE(PG8_SA(1, 1), a1 + hstep, voffA);
;             PG8_WAIT_L(8); PG8_BAR; PG8_WAIT_L(0); PG8_MMA(0, 0, At, B0); PG8_BAR; PG8_SCHED;
;             PG8_LDB(B1, 0, 1); PG8_STAGE(PG8_SB(0, 0), b2, voffB);
;             PG8_BAR; PG8_WAIT_L(0); PG8_MMA(0, 1, At, B1); PG8_BAR;
;             PG8_LDA(At, 0, 1); PG8_STAGE(PG8_SA(0, 0), a2, voffA);
;             PG8_BAR; PG8_WAIT_L(0); PG8_MMA(1, 0, At, B0); PG8_BAR; PG8_SCHED;
;             PG8_STAGE(PG8_SB(0, 1), b2 + hstep, voffB);
;             PG8_WAIT_V(6); PG8_BAR; PG8_MMA(1, 1, At, B1); PG8_BAR;
;             PG8_LDB(B0, 1, 0); PG8_SCHED; PG8_LDA(At, 1, 0); PG8_STAGE(PG8_SA(0, 1), a2 + hstep, voffA);
;             PG8_WAIT_L(8); PG8_BAR; PG8_WAIT_L(0); PG8_MMA(0, 0, At, B0); PG8_BAR; PG8_SCHED;
;             PG8_LDB(B1, 1, 1); PG8_STAGE(PG8_SB(1, 0), b3, voffB);
;             PG8_BAR; PG8_WAIT_L(0); PG8_MMA(0, 1, At, B1); PG8_BAR;
;             PG8_LDA(At, 1, 1); PG8_STAGE(PG8_SA(1, 0), a3, voffA);
;             PG8_BAR; PG8_WAIT_L(0); PG8_MMA(1, 0, At, B0); PG8_BAR; PG8_SCHED;
;             PG8_STAGE(PG8_SB(1, 1), b3 + hstep, voffB);
;             PG8_WAIT_V(6); PG8_BAR; PG8_MMA(1, 1, At, B1); PG8_BAR;
;         }
.Lzp10_mid:
	ds_read_b128 v[170:173], v155
	ds_read_b128 v[174:177], v156
	ds_read_b128 v[178:181], v157
	ds_read_b128 v[182:185], v165
	s_add_u32 s34, s42, 0x44000
	s_addc_u32 s35, s43, 0
	s_mov_b32 m0, s53
	ds_read_b128 v[186:189], v145 offset:32768
	ds_read_b128 v[190:193], v145 offset:33792
	ds_read_b128 v[194:197], v145 offset:34816
	ds_read_b128 v[198:201], v145 offset:35840
	ds_read_b128 v[202:205], v145 offset:36864
	ds_read_b128 v[206:209], v145 offset:37888
	ds_read_b128 v[210:213], v145 offset:38912
	ds_read_b128 v[214:217], v145 offset:39936
	global_load_lds_dwordx4 v128, s[34:35]
	s_mov_b32 m0, s54
	s_nop 0
	global_load_lds_dwordx4 v132, s[34:35]
	s_waitcnt lgkmcnt(8)
	s_barrier
	s_waitcnt lgkmcnt(0)
	s_setprio 1
	s_waitcnt lgkmcnt(0)
	v_mfma_f32_16x16x32_bf16 v[124:127], v[170:173], v[186:189], v[124:127]
	v_mfma_f32_16x16x32_bf16 v[120:123], v[178:181], v[186:189], v[120:123]
	v_mfma_f32_16x16x32_bf16 v[116:119], v[170:173], v[194:197], v[116:119]
	v_mfma_f32_16x16x32_bf16 v[112:115], v[178:181], v[194:197], v[112:115]
	v_mfma_f32_16x16x32_bf16 v[100:103], v[170:173], v[202:205], v[100:103]
	v_mfma_f32_16x16x32_bf16 v[96:99], v[178:181], v[202:205], v[96:99]
	v_mfma_f32_16x16x32_bf16 v[84:87], v[170:173], v[210:213], v[84:87]
	v_mfma_f32_16x16x32_bf16 v[80:83], v[178:181], v[210:213], v[80:83]
	v_mfma_f32_16x16x32_bf16 v[124:127], v[174:177], v[190:193], v[124:127]
	v_mfma_f32_16x16x32_bf16 v[120:123], v[182:185], v[190:193], v[120:123]
	v_mfma_f32_16x16x32_bf16 v[116:119], v[174:177], v[198:201], v[116:119]
	v_mfma_f32_16x16x32_bf16 v[112:115], v[182:185], v[198:201], v[112:115]
	v_mfma_f32_16x16x32_bf16 v[100:103], v[174:177], v[206:209], v[100:103]
	v_mfma_f32_16x16x32_bf16 v[96:99], v[182:185], v[206:209], v[96:99]
	v_mfma_f32_16x16x32_bf16 v[84:87], v[174:177], v[214:217], v[84:87]
	v_mfma_f32_16x16x32_bf16 v[80:83], v[182:185], v[214:217], v[80:83]
	s_setprio 0
	s_barrier
	s_mov_b32 m0, s55
	ds_read_b128 v[218:221], v166
	ds_read_b128 v[222:225], v167
	ds_read_b128 v[226:229], v168
	ds_read_b128 v[230:233], v169
	s_add_u32 s100, s40, 0x80
	s_addc_u32 s101, s41, 0
	global_load_lds_dwordx4 v130, s[100:101]
	s_mov_b32 m0, s56
	s_nop 0
	global_load_lds_dwordx4 v134, s[100:101]
	s_waitcnt lgkmcnt(0)
	s_barrier
	s_waitcnt lgkmcnt(0)
	s_setprio 1
	s_waitcnt lgkmcnt(0)
	v_mfma_f32_16x16x32_bf16 v[108:111], v[218:221], v[186:189], v[108:111]
	v_mfma_f32_16x16x32_bf16 v[104:107], v[226:229], v[186:189], v[104:107]
	v_mfma_f32_16x16x32_bf16 v[92:95], v[218:221], v[194:197], v[92:95]
	v_mfma_f32_16x16x32_bf16 v[88:91], v[226:229], v[194:197], v[88:91]
	v_mfma_f32_16x16x32_bf16 v[76:79], v[218:221], v[202:205], v[76:79]
	v_mfma_f32_16x16x32_bf16 v[72:75], v[226:229], v[202:205], v[72:75]
	v_mfma_f32_16x16x32_bf16 v[68:71], v[218:221], v[210:213], v[68:71]
	v_mfma_f32_16x16x32_bf16 v[64:67], v[226:229], v[210:213], v[64:67]
	v_mfma_f32_16x16x32_bf16 v[108:111], v[222:225], v[190:193], v[108:111]
	v_mfma_f32_16x16x32_bf16 v[104:107], v[230:233], v[190:193], v[104:107]
	v_mfma_f32_16x16x32_bf16 v[92:95], v[222:225], v[198:201], v[92:95]
	v_mfma_f32_16x16x32_bf16 v[88:91], v[230:233], v[198:201], v[88:91]
	v_mfma_f32_16x16x32_bf16 v[76:79], v[222:225], v[206:209], v[76:79]
	v_mfma_f32_16x16x32_bf16 v[72:75], v[230:233], v[206:209], v[72:75]
	v_mfma_f32_16x16x32_bf16 v[68:71], v[222:225], v[214:217], v[68:71]
	v_mfma_f32_16x16x32_bf16 v[64:67], v[230:233], v[214:217], v[64:67]
	s_setprio 0
	s_mov_b32 m0, s57
	s_barrier
	ds_read_b128 v[186:189], v145 offset:49152
	ds_read_b128 v[190:193], v145 offset:50176
	ds_read_b128 v[194:197], v145 offset:51200
	ds_read_b128 v[198:201], v145 offset:52224
	ds_read_b128 v[202:205], v145 offset:53248
	ds_read_b128 v[206:209], v145 offset:54272
	ds_read_b128 v[210:213], v145 offset:55296
	ds_read_b128 v[214:217], v145 offset:56320
	s_add_u32 s100, s42, 0x80
	s_addc_u32 s101, s43, 0
	global_load_lds_dwordx4 v128, s[100:101]
	s_mov_b32 m0, s58
	s_nop 0
	global_load_lds_dwordx4 v132, s[100:101]
	s_add_u32 s34, s40, 0x44080
	s_addc_u32 s35, s41, 0
	s_mov_b32 m0, s59
	s_nop 0
	global_load_lds_dwordx4 v130, s[34:35]
	s_mov_b32 m0, s60
	s_nop 0
	global_load_lds_dwordx4 v134, s[34:35]
	s_waitcnt vmcnt(6)
	s_barrier
	s_waitcnt lgkmcnt(0)
	s_setprio 1
	s_waitcnt lgkmcnt(0)
	v_mfma_f32_16x16x32_bf16 v[60:63], v[170:173], v[186:189], v[60:63]
	v_mfma_f32_16x16x32_bf16 v[56:59], v[178:181], v[186:189], v[56:59]
	v_mfma_f32_16x16x32_bf16 v[52:55], v[170:173], v[194:197], v[52:55]
	v_mfma_f32_16x16x32_bf16 v[48:51], v[178:181], v[194:197], v[48:51]
	v_mfma_f32_16x16x32_bf16 v[36:39], v[170:173], v[202:205], v[36:39]
	v_mfma_f32_16x16x32_bf16 v[32:35], v[178:181], v[202:205], v[32:35]
	v_mfma_f32_16x16x32_bf16 v[20:23], v[170:173], v[210:213], v[20:23]
	v_mfma_f32_16x16x32_bf16 v[16:19], v[178:181], v[210:213], v[16:19]
	v_mfma_f32_16x16x32_bf16 v[60:63], v[174:177], v[190:193], v[60:63]
	v_mfma_f32_16x16x32_bf16 v[56:59], v[182:185], v[190:193], v[56:59]
	v_mfma_f32_16x16x32_bf16 v[52:55], v[174:177], v[198:201], v[52:55]
	v_mfma_f32_16x16x32_bf16 v[48:51], v[182:185], v[198:201], v[48:51]
	v_mfma_f32_16x16x32_bf16 v[36:39], v[174:177], v[206:209], v[36:39]
	v_mfma_f32_16x16x32_bf16 v[32:35], v[182:185], v[206:209], v[32:35]
	v_mfma_f32_16x16x32_bf16 v[20:23], v[174:177], v[214:217], v[20:23]
	v_mfma_f32_16x16x32_bf16 v[16:19], v[182:185], v[214:217], v[16:19]
	v_mfma_f32_16x16x32_bf16 v[44:47], v[218:221], v[186:189], v[44:47]
	v_mfma_f32_16x16x32_bf16 v[40:43], v[226:229], v[186:189], v[40:43]
	v_mfma_f32_16x16x32_bf16 v[28:31], v[218:221], v[194:197], v[28:31]
	v_mfma_f32_16x16x32_bf16 v[24:27], v[226:229], v[194:197], v[24:27]
	v_mfma_f32_16x16x32_bf16 v[12:15], v[218:221], v[202:205], v[12:15]
	v_mfma_f32_16x16x32_bf16 v[8:11], v[226:229], v[202:205], v[8:11]
	v_mfma_f32_16x16x32_bf16 v[4:7], v[218:221], v[210:213], v[4:7]
	v_mfma_f32_16x16x32_bf16 v[0:3], v[226:229], v[210:213], v[0:3]
	v_mfma_f32_16x16x32_bf16 v[44:47], v[222:225], v[190:193], v[44:47]
	v_mfma_f32_16x16x32_bf16 v[40:43], v[230:233], v[190:193], v[40:43]
	v_mfma_f32_16x16x32_bf16 v[28:31], v[222:225], v[198:201], v[28:31]
	v_mfma_f32_16x16x32_bf16 v[24:27], v[230:233], v[198:201], v[24:27]
	v_mfma_f32_16x16x32_bf16 v[12:15], v[222:225], v[206:209], v[12:15]
	v_mfma_f32_16x16x32_bf16 v[8:11], v[230:233], v[206:209], v[8:11]
	v_mfma_f32_16x16x32_bf16 v[4:7], v[222:225], v[214:217], v[4:7]
	v_mfma_f32_16x16x32_bf16 v[0:3], v[230:233], v[214:217], v[0:3]
	s_setprio 0
	s_add_i32 s10, s10, 2
	s_add_u32 s76, s76, 0x100
	s_addc_u32 s77, s77, 0
	s_cmp_gt_u32 s10, 13
	s_mov_b64 s[34:35], s[36:37]
	s_barrier
; #define PG8_WAIT_V(n) asm volatile("s_waitcnt vmcnt(" #n ")" ::: "memory")
; #define PG8_BAR __builtin_amdgcn_s_barrier()
;     DI void operator()(const f32x4 (&acc)[2][2][4][2], const Unit& u, int wr, int wc, int fr, int fq) const {
;         const int row0 = u.pm * BM + wr * 64 + fr, col0 = u.pn * BM + wc * 32 + 8 * fq;
; #pragma unroll
;         for (int ai = 0; ai < 2; ++ai)
; #pragma unroll
;             for (int m = 0; m < 4; ++m) { u16* rowp = O + (size_t)(row0 + ai * HALF + m * 16) * ldc + col0;
; #pragma unroll
;                 for (int bj = 0; bj < 2; ++bj) { const f32x4 v0 = acc[ai][bj][m][0], v1 = acc[ai][bj][m][1];
;                     uint4 w = {pack2(v0[0], v0[1]), pack2(v0[2], v0[3]), pack2(v1[0], v1[1]), pack2(v1[2], v1[3])}; *(uint4*)(rowp + bj * HALF) = w; } }
; template <class Epi, class Sched, bool STAMP = false>
; __device__ __forceinline__ void gemm_phase(PG8_LAS unsigned char* lds, const Gemm g, const Sched& S, const Epi& E, unsigned long long* stamps) {
;     ...
;         cur = nxt; cA = nA; cB = nB; ++ui;
;     }
;     PG8_WAIT_V(0);
;     if (wr == 0) PG8_BAR;
;     PG8_BAR;
	s_cbranch_scc0 .LBB0_688
	v_lshl_add_u32 v170, s69, 8, v144
	v_lshl_or_b32 v172, s75, 8, v146
	v_ashrrev_i32_e32 v171, 31, v170
	v_ashrrev_i32_e32 v173, 31, v172
	v_lshlrev_b64 v[174:175], 11, v[170:171]
	v_lshl_add_u64 v[174:175], s[14:15], 0, v[174:175]
	v_lshlrev_b64 v[172:173], 1, v[172:173]
	v_lshl_add_u64 v[174:175], v[174:175], 0, v[172:173]
	v_cvt_pk_bf16_f32 v60, v60, v61
	v_cvt_pk_bf16_f32 v61, v62, v63
	v_cvt_pk_bf16_f32 v62, v56, v57
	v_add_co_u32_e32 v56, vcc, s65, v174
	v_cvt_pk_bf16_f32 v68, v68, v69
	v_cvt_pk_bf16_f32 v69, v70, v71
	v_cvt_pk_bf16_f32 v70, v64, v65
	v_lshl_add_u64 v[64:65], v[174:175], 0, s[16:17]
	v_addc_co_u32_e32 v57, vcc, 0, v175, vcc
	v_cvt_pk_bf16_f32 v44, v44, v45
	v_cvt_pk_bf16_f32 v45, v46, v47
	v_cvt_pk_bf16_f32 v46, v40, v41
	v_cvt_pk_bf16_f32 v47, v42, v43
	v_cvt_pk_bf16_f32 v108, v108, v109
	v_cvt_pk_bf16_f32 v109, v110, v111
	v_cvt_pk_bf16_f32 v110, v104, v105
	v_or_b32_e32 v104, 16, v170
	global_store_dwordx4 v[64:65], v[44:47], off offset:256
	v_ashrrev_i32_e32 v105, 31, v104
	v_cvt_pk_bf16_f32 v92, v92, v93
	v_add_co_u32_e32 v46, vcc, s66, v174
	v_cvt_pk_bf16_f32 v93, v94, v95
	v_cvt_pk_bf16_f32 v94, v88, v89
	v_or_b32_e32 v88, 32, v170
	v_lshl_add_u64 v[44:45], v[174:175], 0, s[18:19]
	v_addc_co_u32_e32 v47, vcc, 0, v175, vcc
	v_cvt_pk_bf16_f32 v28, v28, v29
	v_cvt_pk_bf16_f32 v29, v30, v31
	v_cvt_pk_bf16_f32 v30, v24, v25
	v_cvt_pk_bf16_f32 v31, v26, v27
	v_lshlrev_b64 v[104:105], 11, v[104:105]
	v_ashrrev_i32_e32 v89, 31, v88
	v_cvt_pk_bf16_f32 v76, v76, v77
	v_cvt_pk_bf16_f32 v77, v78, v79
	v_cvt_pk_bf16_f32 v78, v72, v73
	v_or_b32_e32 v72, 48, v170
	global_store_dwordx4 v[44:45], v[28:31], off offset:256
	v_cvt_pk_bf16_f32 v111, v106, v107
	v_lshl_add_u64 v[104:105], s[14:15], 0, v[104:105]
	v_add_co_u32_e32 v30, vcc, s67, v174
	v_lshlrev_b64 v[88:89], 11, v[88:89]
	v_ashrrev_i32_e32 v73, 31, v72
	v_lshl_add_u64 v[28:29], v[174:175], 0, s[20:21]
	v_addc_co_u32_e32 v31, vcc, 0, v175, vcc
	v_cvt_pk_bf16_f32 v12, v12, v13
	v_cvt_pk_bf16_f32 v13, v14, v15
	v_cvt_pk_bf16_f32 v14, v8, v9
	v_cvt_pk_bf16_f32 v15, v10, v11
	global_store_dwordx4 v[174:175], v[108:111], off offset:256
	v_cvt_pk_bf16_f32 v95, v90, v91
	v_lshl_add_u64 v[88:89], s[14:15], 0, v[88:89]
	v_lshl_add_u64 v[108:109], v[104:105], 0, v[172:173]
	v_lshlrev_b64 v[72:73], 11, v[72:73]
	global_store_dwordx4 v[28:29], v[12:15], off offset:256
	global_store_dwordx4 v[108:109], v[92:95], off offset:256
	v_cvt_pk_bf16_f32 v79, v74, v75
	v_add_co_u32_e32 v14, vcc, s68, v174
	v_lshl_add_u64 v[92:93], v[88:89], 0, v[172:173]
	v_lshl_add_u64 v[72:73], s[14:15], 0, v[72:73]
	v_addc_co_u32_e32 v15, vcc, 0, v175, vcc
	v_cvt_pk_bf16_f32 v124, v124, v125
	v_cvt_pk_bf16_f32 v125, v126, v127
	v_cvt_pk_bf16_f32 v126, v120, v121
	v_cvt_pk_bf16_f32 v127, v122, v123
	v_cvt_pk_bf16_f32 v104, v116, v117
	v_cvt_pk_bf16_f32 v105, v118, v119
	v_cvt_pk_bf16_f32 v106, v112, v113
	v_cvt_pk_bf16_f32 v107, v114, v115
	v_cvt_pk_bf16_f32 v88, v100, v101
	v_cvt_pk_bf16_f32 v89, v102, v103
	v_cvt_pk_bf16_f32 v90, v96, v97
	v_cvt_pk_bf16_f32 v91, v98, v99
	global_store_dwordx4 v[92:93], v[76:79], off offset:256
	v_cvt_pk_bf16_f32 v74, v80, v81
	v_cvt_pk_bf16_f32 v75, v82, v83
	v_lshl_add_u64 v[76:77], v[72:73], 0, v[172:173]
	v_cvt_pk_bf16_f32 v72, v84, v85
	v_cvt_pk_bf16_f32 v73, v86, v87
	v_cvt_pk_bf16_f32 v71, v66, v67
	v_cvt_pk_bf16_f32 v63, v58, v59
	v_cvt_pk_bf16_f32 v40, v52, v53
	v_cvt_pk_bf16_f32 v41, v54, v55
	v_cvt_pk_bf16_f32 v42, v48, v49
	v_cvt_pk_bf16_f32 v43, v50, v51
	v_cvt_pk_bf16_f32 v24, v36, v37
	v_cvt_pk_bf16_f32 v25, v38, v39
	v_cvt_pk_bf16_f32 v26, v32, v33
	v_cvt_pk_bf16_f32 v27, v34, v35
	v_lshl_add_u64 v[12:13], v[174:175], 0, s[28:29]
	v_cvt_pk_bf16_f32 v8, v20, v21
	v_cvt_pk_bf16_f32 v9, v22, v23
	v_cvt_pk_bf16_f32 v10, v16, v17
	v_cvt_pk_bf16_f32 v11, v18, v19
	v_cvt_pk_bf16_f32 v4, v4, v5
	v_cvt_pk_bf16_f32 v5, v6, v7
	v_cvt_pk_bf16_f32 v6, v0, v1
	v_cvt_pk_bf16_f32 v7, v2, v3
	s_and_b64 vcc, exec, s[2:3]
	s_mov_b32 s75, s70
	s_mov_b32 s69, s71
	s_mov_b64 s[36:37], s[0:1]
	s_mov_b64 s[34:35], s[4:5]
	global_store_dwordx4 v[174:175], v[124:127], off
	global_store_dwordx4 v[108:109], v[104:107], off
	global_store_dwordx4 v[92:93], v[88:91], off
	global_store_dwordx4 v[76:77], v[72:75], off
	global_store_dwordx4 v[76:77], v[68:71], off offset:256
	global_store_dwordx4 v[56:57], v[60:63], off
	global_store_dwordx4 v[46:47], v[40:43], off
	global_store_dwordx4 v[30:31], v[24:27], off
	global_store_dwordx4 v[14:15], v[8:11], off
	global_store_dwordx4 v[12:13], v[4:7], off offset:256
	s_cbranch_vccz .LBB0_677
	s_waitcnt vmcnt(0)
	s_cmpk_gt_u32 s45, 0xff
	s_cbranch_scc1 .LBB0_692
	s_barrier

; #define PG8_STAGE(bufoff, gbase, voff) do { _Pragma("unroll") for (int _i = 0; _i < 2; ++_i) \
;         __builtin_amdgcn_global_load_lds((const unsigned*)((const char*)(gbase) + (voff)[_i]), (PG8_LAS unsigned*)(lds + (bufoff) + ldsw + _i * 8192), 16, 0, 0); } while (0)
; #define PG8_LDA(dst, b, h) do { _Pragma("unroll") for (int m = 0; m < 4; ++m) _Pragma("unroll") for (int k = 0; k < 2; ++k) dst[m][k] = *(const PG8_LAS bf16x8*)(lds + PG8_SA(b, h) + aoff + m * 2048 + k * 1024); } while (0)
; #define PG8_LDB(dst, b, h) do { _Pragma("unroll") for (int n = 0; n < 2; ++n) _Pragma("unroll") for (int k = 0; k < 2; ++k) dst[n][k] = *(const PG8_LAS bf16x8*)(lds + PG8_SB(b, h) + boff + n * 2048 + k * 1024); } while (0)
; #define PG8_MMA(ai, bj, At, Bt) do { __builtin_amdgcn_s_setprio(1); _Pragma("unroll") for (int m = 0; m < 4; ++m) _Pragma("unroll") for (int n = 0; n < 2; ++n) _Pragma("unroll") for (int k = 0; k < 2; ++k) \
;         acc[ai][bj][m][n] = __builtin_amdgcn_mfma_f32_16x16x32_bf16(Bt[n][k], At[m][k], acc[ai][bj][m][n], 0, 0, 0); __builtin_amdgcn_s_setprio(0); } while (0)
; #define PG8_BAR __builtin_amdgcn_s_barrier()
; template <class Epi, class Sched, bool STAMP = false>
; __device__ __forceinline__ void gemm_phase(PG8_LAS unsigned char* lds, const Gemm g, const Sched& S, const Epi& E, unsigned long long* stamps) {
;     ...
;         for (int t = 0; t < nt; t += 2) {
;             const bool last = (t == nt - 2);
;             const char* a1 = cA + (size_t)(t + 1) * kstep;
;             const char* a2 = last ? nA : cA + (size_t)(t + 2) * kstep; const char* b2 = last ? nB : cB + (size_t)(t + 2) * kstep;
;             const char* a3 = a2 + kstep; const char* b3 = b2 + kstep;
;             if (last && has_next) S.a_ready(nxt);
;             PG8_LDB(B0, 0, 0); PG8_SCHED; PG8_LDA(At, 0, 0); PG8_STAGE(PG8_SA(1, 1), a1 + hstep, voffA);
;             PG8_WAIT_L(8); PG8_BAR; PG8_WAIT_L(0); PG8_MMA(0, 0, At, B0); PG8_BAR; PG8_SCHED;
;             PG8_LDB(B1, 0, 1); PG8_STAGE(PG8_SB(0, 0), b2, voffB);
;             PG8_BAR; PG8_WAIT_L(0); PG8_MMA(0, 1, At, B1); PG8_BAR;
;             PG8_LDA(At, 0, 1); PG8_STAGE(PG8_SA(0, 0), a2, voffA);
;             PG8_BAR; PG8_WAIT_L(0); PG8_MMA(1, 0, At, B0); PG8_BAR; PG8_SCHED;
;             PG8_STAGE(PG8_SB(0, 1), b2 + hstep, voffB);
;             PG8_WAIT_V(6); PG8_BAR; PG8_MMA(1, 1, At, B1); PG8_BAR;
.LBB0_726:
	s_add_u32 s62, s18, 0x100
	s_addc_u32 s63, s19, 0
	s_mov_b32 s10, -2
	s_cmp_eq_u32 s46, s99
	s_cbranch_scc1 .Lgu4_half_loop_z
	ds_read_b128 v[140:143], v147
	ds_read_b128 v[170:173], v148
	ds_read_b128 v[174:177], v149
	ds_read_b128 v[178:181], v150
	s_add_u32 s18, s16, 0x100
	s_addc_u32 s19, s17, 0
	s_cmp_eq_u32 s10, 12
	s_cselect_b32 s29, s5, s19
	s_cselect_b32 s28, s4, s18
	s_cselect_b32 s21, s1, s63
	s_cselect_b32 s20, s0, s62
	s_mov_b32 m0, s55
	ds_read_b128 v[182:185], v145
	ds_read_b128 v[186:189], v145 offset:1024
	ds_read_b128 v[190:193], v145 offset:2048
	ds_read_b128 v[194:197], v145 offset:3072
	ds_read_b128 v[198:201], v145 offset:4096
	ds_read_b128 v[202:205], v145 offset:5120
	ds_read_b128 v[206:209], v145 offset:6144
	ds_read_b128 v[210:213], v145 offset:7168
	global_load_lds_dwordx4 v132, s[16:17]
	s_mov_b32 m0, s56
	s_nop 0
	global_load_lds_dwordx4 v134, s[16:17]
	s_waitcnt lgkmcnt(8)
	s_barrier
	s_waitcnt lgkmcnt(0)
	s_setprio 1
	s_waitcnt lgkmcnt(0)
	v_mfma_f32_16x16x32_bf16 v[124:127], v[140:143], v[182:185], 0
	v_mfma_f32_16x16x32_bf16 v[120:123], v[174:177], v[182:185], 0
	v_mfma_f32_16x16x32_bf16 v[108:111], v[140:143], v[190:193], 0
	v_mfma_f32_16x16x32_bf16 v[104:107], v[174:177], v[190:193], 0
	v_mfma_f32_16x16x32_bf16 v[92:95], v[140:143], v[198:201], 0
	v_mfma_f32_16x16x32_bf16 v[88:91], v[174:177], v[198:201], 0
	v_mfma_f32_16x16x32_bf16 v[76:79], v[140:143], v[206:209], 0
	v_mfma_f32_16x16x32_bf16 v[72:75], v[174:177], v[206:209], 0
	v_mfma_f32_16x16x32_bf16 v[124:127], v[170:173], v[186:189], v[124:127]
	v_mfma_f32_16x16x32_bf16 v[120:123], v[178:181], v[186:189], v[120:123]
	v_mfma_f32_16x16x32_bf16 v[108:111], v[170:173], v[194:197], v[108:111]
	v_mfma_f32_16x16x32_bf16 v[104:107], v[178:181], v[194:197], v[104:107]
	v_mfma_f32_16x16x32_bf16 v[92:95], v[170:173], v[202:205], v[92:95]
	v_mfma_f32_16x16x32_bf16 v[88:91], v[178:181], v[202:205], v[88:91]
	v_mfma_f32_16x16x32_bf16 v[76:79], v[170:173], v[210:213], v[76:79]
	v_mfma_f32_16x16x32_bf16 v[72:75], v[178:181], v[210:213], v[72:75]
	s_setprio 0
	s_barrier
	s_mov_b32 m0, s37
	ds_read_b128 v[214:217], v151
	ds_read_b128 v[218:221], v152
	ds_read_b128 v[222:225], v153
	ds_read_b128 v[226:229], v154
	global_load_lds_dwordx4 v130, s[20:21]
	s_mov_b32 m0, s40
	s_nop 0
	global_load_lds_dwordx4 v128, s[20:21]
	s_waitcnt lgkmcnt(0)
	s_barrier
	s_waitcnt lgkmcnt(0)
	s_setprio 1
	s_waitcnt lgkmcnt(0)
	v_mfma_f32_16x16x32_bf16 v[116:119], v[214:217], v[182:185], 0
	v_mfma_f32_16x16x32_bf16 v[112:115], v[222:225], v[182:185], 0
	v_mfma_f32_16x16x32_bf16 v[100:103], v[214:217], v[190:193], 0
	v_mfma_f32_16x16x32_bf16 v[96:99], v[222:225], v[190:193], 0
	v_mfma_f32_16x16x32_bf16 v[84:87], v[214:217], v[198:201], 0
	v_mfma_f32_16x16x32_bf16 v[80:83], v[222:225], v[198:201], 0
	v_mfma_f32_16x16x32_bf16 v[68:71], v[214:217], v[206:209], 0
	v_mfma_f32_16x16x32_bf16 v[64:67], v[222:225], v[206:209], 0
	v_mfma_f32_16x16x32_bf16 v[116:119], v[218:221], v[186:189], v[116:119]
	v_mfma_f32_16x16x32_bf16 v[112:115], v[226:229], v[186:189], v[112:115]
	v_mfma_f32_16x16x32_bf16 v[100:103], v[218:221], v[194:197], v[100:103]
	v_mfma_f32_16x16x32_bf16 v[96:99], v[226:229], v[194:197], v[96:99]
	v_mfma_f32_16x16x32_bf16 v[84:87], v[218:221], v[202:205], v[84:87]
	v_mfma_f32_16x16x32_bf16 v[80:83], v[226:229], v[202:205], v[80:83]
	v_mfma_f32_16x16x32_bf16 v[68:71], v[218:221], v[210:213], v[68:71]
	v_mfma_f32_16x16x32_bf16 v[64:67], v[226:229], v[210:213], v[64:67]
	s_setprio 0
	s_mov_b32 m0, s34
	s_barrier
	ds_read_b128 v[182:185], v145 offset:16384
	ds_read_b128 v[186:189], v145 offset:17408
	ds_read_b128 v[190:193], v145 offset:18432
	ds_read_b128 v[194:197], v145 offset:19456
	ds_read_b128 v[198:201], v145 offset:20480
	ds_read_b128 v[202:205], v145 offset:21504
	ds_read_b128 v[206:209], v145 offset:22528
	ds_read_b128 v[210:213], v145 offset:23552
	global_load_lds_dwordx4 v130, s[28:29]
	s_mov_b32 m0, s41
	s_nop 0
	global_load_lds_dwordx4 v128, s[28:29]
	s_add_u32 s16, s20, 0x44000
	s_addc_u32 s17, s21, 0
	s_mov_b32 m0, s42
	s_nop 0
	global_load_lds_dwordx4 v130, s[16:17]
	s_mov_b32 m0, s43
	s_nop 0
	global_load_lds_dwordx4 v128, s[16:17]
	s_waitcnt vmcnt(6)
	s_barrier
	s_waitcnt lgkmcnt(0)
	s_setprio 1
	s_waitcnt lgkmcnt(0)
	v_mfma_f32_16x16x32_bf16 v[60:63], v[140:143], v[182:185], 0
	v_mfma_f32_16x16x32_bf16 v[56:59], v[174:177], v[182:185], 0
	v_mfma_f32_16x16x32_bf16 v[44:47], v[140:143], v[190:193], 0
	v_mfma_f32_16x16x32_bf16 v[40:43], v[174:177], v[190:193], 0
	v_mfma_f32_16x16x32_bf16 v[28:31], v[140:143], v[198:201], 0
	v_mfma_f32_16x16x32_bf16 v[24:27], v[174:177], v[198:201], 0
	v_mfma_f32_16x16x32_bf16 v[12:15], v[140:143], v[206:209], 0
	v_mfma_f32_16x16x32_bf16 v[8:11], v[174:177], v[206:209], 0
	v_mfma_f32_16x16x32_bf16 v[60:63], v[170:173], v[186:189], v[60:63]
	v_mfma_f32_16x16x32_bf16 v[56:59], v[178:181], v[186:189], v[56:59]
	v_mfma_f32_16x16x32_bf16 v[44:47], v[170:173], v[194:197], v[44:47]
	v_mfma_f32_16x16x32_bf16 v[40:43], v[178:181], v[194:197], v[40:43]
	v_mfma_f32_16x16x32_bf16 v[28:31], v[170:173], v[202:205], v[28:31]
	v_mfma_f32_16x16x32_bf16 v[24:27], v[178:181], v[202:205], v[24:27]
	v_mfma_f32_16x16x32_bf16 v[12:15], v[170:173], v[210:213], v[12:15]
	v_mfma_f32_16x16x32_bf16 v[8:11], v[178:181], v[210:213], v[8:11]
	v_mfma_f32_16x16x32_bf16 v[52:55], v[214:217], v[182:185], 0
	v_mfma_f32_16x16x32_bf16 v[48:51], v[222:225], v[182:185], 0
	v_mfma_f32_16x16x32_bf16 v[36:39], v[214:217], v[190:193], 0
	v_mfma_f32_16x16x32_bf16 v[32:35], v[222:225], v[190:193], 0
	v_mfma_f32_16x16x32_bf16 v[20:23], v[214:217], v[198:201], 0
	v_mfma_f32_16x16x32_bf16 v[16:19], v[222:225], v[198:201], 0
	v_mfma_f32_16x16x32_bf16 v[4:7], v[214:217], v[206:209], 0
	v_mfma_f32_16x16x32_bf16 v[0:3], v[222:225], v[206:209], 0
	v_mfma_f32_16x16x32_bf16 v[52:55], v[218:221], v[186:189], v[52:55]
	v_mfma_f32_16x16x32_bf16 v[48:51], v[226:229], v[186:189], v[48:51]
	v_mfma_f32_16x16x32_bf16 v[36:39], v[218:221], v[194:197], v[36:39]
	v_mfma_f32_16x16x32_bf16 v[32:35], v[226:229], v[194:197], v[32:35]
	v_mfma_f32_16x16x32_bf16 v[20:23], v[218:221], v[202:205], v[20:23]
	v_mfma_f32_16x16x32_bf16 v[16:19], v[226:229], v[202:205], v[16:19]
	v_mfma_f32_16x16x32_bf16 v[4:7], v[218:221], v[210:213], v[4:7]
	v_mfma_f32_16x16x32_bf16 v[0:3], v[226:229], v[210:213], v[0:3]
	s_setprio 0
	s_barrier
	s_branch .Lzp11_mid
; #define PG8_STAGE(bufoff, gbase, voff) do { _Pragma("unroll") for (int _i = 0; _i < 2; ++_i) \
;         __builtin_amdgcn_global_load_lds((const unsigned*)((const char*)(gbase) + (voff)[_i]), (PG8_LAS unsigned*)(lds + (bufoff) + ldsw + _i * 8192), 16, 0, 0); } while (0)
; #define PG8_LDA(dst, b, h) do { _Pragma("unroll") for (int m = 0; m < 4; ++m) _Pragma("unroll") for (int k = 0; k < 2; ++k) dst[m][k] = *(const PG8_LAS bf16x8*)(lds + PG8_SA(b, h) + aoff + m * 2048 + k * 1024); } while (0)
; #define PG8_LDB(dst, b, h) do { _Pragma("unroll") for (int n = 0; n < 2; ++n) _Pragma("unroll") for (int k = 0; k < 2; ++k) dst[n][k] = *(const PG8_LAS bf16x8*)(lds + PG8_SB(b, h) + boff + n * 2048 + k * 1024); } while (0)
; #define PG8_MMA(ai, bj, At, Bt) do { __builtin_amdgcn_s_setprio(1); _Pragma("unroll") for (int m = 0; m < 4; ++m) _Pragma("unroll") for (int n = 0; n < 2; ++n) _Pragma("unroll") for (int k = 0; k < 2; ++k) \
;         acc[ai][bj][m][n] = __builtin_amdgcn_mfma_f32_16x16x32_bf16(Bt[n][k], At[m][k], acc[ai][bj][m][n], 0, 0, 0); __builtin_amdgcn_s_setprio(0); } while (0)
; #define PG8_WAIT_V(n) asm volatile("s_waitcnt vmcnt(" #n ")" ::: "memory")
; template <class Epi, class Sched, bool STAMP = false>
; __device__ __forceinline__ void gemm_phase(PG8_LAS unsigned char* lds, const Gemm g, const Sched& S, const Epi& E, unsigned long long* stamps) {
;     ...
;             const bool last = (t == nt - 2);
;             const char* a1 = cA + (size_t)(t + 1) * kstep;
;             const char* a2 = last ? nA : cA + (size_t)(t + 2) * kstep; const char* b2 = last ? nB : cB + (size_t)(t + 2) * kstep;
;             const char* a3 = a2 + kstep; const char* b3 = b2 + kstep;
;             if (last && has_next) S.a_ready(nxt);
;             PG8_LDB(B0, 0, 0); PG8_SCHED; PG8_LDA(At, 0, 0); PG8_STAGE(PG8_SA(1, 1), a1 + hstep, voffA);
;             PG8_WAIT_L(8); PG8_BAR; PG8_WAIT_L(0); PG8_MMA(0, 0, At, B0); PG8_BAR; PG8_SCHED;
;             PG8_LDB(B1, 0, 1); PG8_STAGE(PG8_SB(0, 0), b2, voffB);
;             PG8_BAR; PG8_WAIT_L(0); PG8_MMA(0, 1, At, B1); PG8_BAR;
;             PG8_LDA(At, 0, 1); PG8_STAGE(PG8_SA(0, 0), a2, voffA);
;             PG8_BAR; PG8_WAIT_L(0); PG8_MMA(1, 0, At, B0); PG8_BAR; PG8_SCHED;
;             PG8_STAGE(PG8_SB(0, 1), b2 + hstep, voffB);
;             PG8_WAIT_V(6); PG8_BAR; PG8_MMA(1, 1, At, B1); PG8_BAR;
.LBB0_727:
	ds_read_b128 v[140:143], v147
	ds_read_b128 v[170:173], v148
	ds_read_b128 v[174:177], v149
	ds_read_b128 v[178:181], v150
	s_add_u32 s18, s16, 0x100
	s_addc_u32 s19, s17, 0
	s_cmp_eq_u32 s10, 12
	s_cselect_b32 s29, s5, s19
	s_cselect_b32 s28, s4, s18
	s_cselect_b32 s21, s1, s63
	s_cselect_b32 s20, s0, s62
	s_mov_b32 m0, s55
	ds_read_b128 v[182:185], v145
	ds_read_b128 v[186:189], v145 offset:1024
	ds_read_b128 v[190:193], v145 offset:2048
	ds_read_b128 v[194:197], v145 offset:3072
	ds_read_b128 v[198:201], v145 offset:4096
	ds_read_b128 v[202:205], v145 offset:5120
	ds_read_b128 v[206:209], v145 offset:6144
	ds_read_b128 v[210:213], v145 offset:7168
	global_load_lds_dwordx4 v132, s[16:17]
	s_mov_b32 m0, s56
	s_nop 0
	global_load_lds_dwordx4 v134, s[16:17]
	s_waitcnt lgkmcnt(8)
	s_barrier
	s_waitcnt lgkmcnt(0)
	s_setprio 1
	s_waitcnt lgkmcnt(0)
	v_mfma_f32_16x16x32_bf16 v[124:127], v[140:143], v[182:185], v[124:127]
	v_mfma_f32_16x16x32_bf16 v[120:123], v[174:177], v[182:185], v[120:123]
	v_mfma_f32_16x16x32_bf16 v[108:111], v[140:143], v[190:193], v[108:111]
	v_mfma_f32_16x16x32_bf16 v[104:107], v[174:177], v[190:193], v[104:107]
	v_mfma_f32_16x16x32_bf16 v[92:95], v[140:143], v[198:201], v[92:95]
	v_mfma_f32_16x16x32_bf16 v[88:91], v[174:177], v[198:201], v[88:91]
	v_mfma_f32_16x16x32_bf16 v[76:79], v[140:143], v[206:209], v[76:79]
	v_mfma_f32_16x16x32_bf16 v[72:75], v[174:177], v[206:209], v[72:75]
	v_mfma_f32_16x16x32_bf16 v[124:127], v[170:173], v[186:189], v[124:127]
	v_mfma_f32_16x16x32_bf16 v[120:123], v[178:181], v[186:189], v[120:123]
	v_mfma_f32_16x16x32_bf16 v[108:111], v[170:173], v[194:197], v[108:111]
	v_mfma_f32_16x16x32_bf16 v[104:107], v[178:181], v[194:197], v[104:107]
	v_mfma_f32_16x16x32_bf16 v[92:95], v[170:173], v[202:205], v[92:95]
	v_mfma_f32_16x16x32_bf16 v[88:91], v[178:181], v[202:205], v[88:91]
	v_mfma_f32_16x16x32_bf16 v[76:79], v[170:173], v[210:213], v[76:79]
	v_mfma_f32_16x16x32_bf16 v[72:75], v[178:181], v[210:213], v[72:75]
	s_setprio 0
	s_barrier
	s_mov_b32 m0, s37
	ds_read_b128 v[214:217], v151
	ds_read_b128 v[218:221], v152
	ds_read_b128 v[222:225], v153
	ds_read_b128 v[226:229], v154
	global_load_lds_dwordx4 v130, s[20:21]
	s_mov_b32 m0, s40
	s_nop 0
	global_load_lds_dwordx4 v128, s[20:21]
	s_waitcnt lgkmcnt(0)
	s_barrier
	s_waitcnt lgkmcnt(0)
	s_setprio 1
	s_waitcnt lgkmcnt(0)
	v_mfma_f32_16x16x32_bf16 v[116:119], v[214:217], v[182:185], v[116:119]
	v_mfma_f32_16x16x32_bf16 v[112:115], v[222:225], v[182:185], v[112:115]
	v_mfma_f32_16x16x32_bf16 v[100:103], v[214:217], v[190:193], v[100:103]
	v_mfma_f32_16x16x32_bf16 v[96:99], v[222:225], v[190:193], v[96:99]
	v_mfma_f32_16x16x32_bf16 v[84:87], v[214:217], v[198:201], v[84:87]
	v_mfma_f32_16x16x32_bf16 v[80:83], v[222:225], v[198:201], v[80:83]
	v_mfma_f32_16x16x32_bf16 v[68:71], v[214:217], v[206:209], v[68:71]
	v_mfma_f32_16x16x32_bf16 v[64:67], v[222:225], v[206:209], v[64:67]
	v_mfma_f32_16x16x32_bf16 v[116:119], v[218:221], v[186:189], v[116:119]
	v_mfma_f32_16x16x32_bf16 v[112:115], v[226:229], v[186:189], v[112:115]
	v_mfma_f32_16x16x32_bf16 v[100:103], v[218:221], v[194:197], v[100:103]
	v_mfma_f32_16x16x32_bf16 v[96:99], v[226:229], v[194:197], v[96:99]
	v_mfma_f32_16x16x32_bf16 v[84:87], v[218:221], v[202:205], v[84:87]
	v_mfma_f32_16x16x32_bf16 v[80:83], v[226:229], v[202:205], v[80:83]
	v_mfma_f32_16x16x32_bf16 v[68:71], v[218:221], v[210:213], v[68:71]
	v_mfma_f32_16x16x32_bf16 v[64:67], v[226:229], v[210:213], v[64:67]
	s_setprio 0
	s_mov_b32 m0, s34
	s_barrier
	ds_read_b128 v[182:185], v145 offset:16384
	ds_read_b128 v[186:189], v145 offset:17408
	ds_read_b128 v[190:193], v145 offset:18432
	ds_read_b128 v[194:197], v145 offset:19456
	ds_read_b128 v[198:201], v145 offset:20480
	ds_read_b128 v[202:205], v145 offset:21504
	ds_read_b128 v[206:209], v145 offset:22528
	ds_read_b128 v[210:213], v145 offset:23552
	global_load_lds_dwordx4 v130, s[28:29]
	s_mov_b32 m0, s41
	s_nop 0
	global_load_lds_dwordx4 v128, s[28:29]
	s_add_u32 s16, s20, 0x44000
	s_addc_u32 s17, s21, 0
	s_mov_b32 m0, s42
	s_nop 0
	global_load_lds_dwordx4 v130, s[16:17]
	s_mov_b32 m0, s43
	s_nop 0
	global_load_lds_dwordx4 v128, s[16:17]
	s_waitcnt vmcnt(6)
	s_barrier
	s_waitcnt lgkmcnt(0)
	s_setprio 1
	s_waitcnt lgkmcnt(0)
	v_mfma_f32_16x16x32_bf16 v[60:63], v[140:143], v[182:185], v[60:63]
	v_mfma_f32_16x16x32_bf16 v[56:59], v[174:177], v[182:185], v[56:59]
	v_mfma_f32_16x16x32_bf16 v[44:47], v[140:143], v[190:193], v[44:47]
	v_mfma_f32_16x16x32_bf16 v[40:43], v[174:177], v[190:193], v[40:43]
	v_mfma_f32_16x16x32_bf16 v[28:31], v[140:143], v[198:201], v[28:31]
	v_mfma_f32_16x16x32_bf16 v[24:27], v[174:177], v[198:201], v[24:27]
	v_mfma_f32_16x16x32_bf16 v[12:15], v[140:143], v[206:209], v[12:15]
	v_mfma_f32_16x16x32_bf16 v[8:11], v[174:177], v[206:209], v[8:11]
	v_mfma_f32_16x16x32_bf16 v[60:63], v[170:173], v[186:189], v[60:63]
	v_mfma_f32_16x16x32_bf16 v[56:59], v[178:181], v[186:189], v[56:59]
	v_mfma_f32_16x16x32_bf16 v[44:47], v[170:173], v[194:197], v[44:47]
	v_mfma_f32_16x16x32_bf16 v[40:43], v[178:181], v[194:197], v[40:43]
	v_mfma_f32_16x16x32_bf16 v[28:31], v[170:173], v[202:205], v[28:31]
	v_mfma_f32_16x16x32_bf16 v[24:27], v[178:181], v[202:205], v[24:27]
	v_mfma_f32_16x16x32_bf16 v[12:15], v[170:173], v[210:213], v[12:15]
	v_mfma_f32_16x16x32_bf16 v[8:11], v[178:181], v[210:213], v[8:11]
	v_mfma_f32_16x16x32_bf16 v[52:55], v[214:217], v[182:185], v[52:55]
	v_mfma_f32_16x16x32_bf16 v[48:51], v[222:225], v[182:185], v[48:51]
	v_mfma_f32_16x16x32_bf16 v[36:39], v[214:217], v[190:193], v[36:39]
	v_mfma_f32_16x16x32_bf16 v[32:35], v[222:225], v[190:193], v[32:35]
	v_mfma_f32_16x16x32_bf16 v[20:23], v[214:217], v[198:201], v[20:23]
	v_mfma_f32_16x16x32_bf16 v[16:19], v[222:225], v[198:201], v[16:19]
	v_mfma_f32_16x16x32_bf16 v[4:7], v[214:217], v[206:209], v[4:7]
	v_mfma_f32_16x16x32_bf16 v[0:3], v[222:225], v[206:209], v[0:3]
	v_mfma_f32_16x16x32_bf16 v[52:55], v[218:221], v[186:189], v[52:55]
	v_mfma_f32_16x16x32_bf16 v[48:51], v[226:229], v[186:189], v[48:51]
	v_mfma_f32_16x16x32_bf16 v[36:39], v[218:221], v[194:197], v[36:39]
	v_mfma_f32_16x16x32_bf16 v[32:35], v[226:229], v[194:197], v[32:35]
	v_mfma_f32_16x16x32_bf16 v[20:23], v[218:221], v[202:205], v[20:23]
	v_mfma_f32_16x16x32_bf16 v[16:19], v[226:229], v[202:205], v[16:19]
	v_mfma_f32_16x16x32_bf16 v[4:7], v[218:221], v[210:213], v[4:7]
	v_mfma_f32_16x16x32_bf16 v[0:3], v[226:229], v[210:213], v[0:3]
	s_setprio 0
	s_barrier
; #define PG8_STAGE(bufoff, gbase, voff) do { _Pragma("unroll") for (int _i = 0; _i < 2; ++_i) \
;         __builtin_amdgcn_global_load_lds((const unsigned*)((const char*)(gbase) + (voff)[_i]), (PG8_LAS unsigned*)(lds + (bufoff) + ldsw + _i * 8192), 16, 0, 0); } while (0)
; #define PG8_LDA(dst, b, h) do { _Pragma("unroll") for (int m = 0; m < 4; ++m) _Pragma("unroll") for (int k = 0; k < 2; ++k) dst[m][k] = *(const PG8_LAS bf16x8*)(lds + PG8_SA(b, h) + aoff + m * 2048 + k * 1024); } while (0)
; #define PG8_LDB(dst, b, h) do { _Pragma("unroll") for (int n = 0; n < 2; ++n) _Pragma("unroll") for (int k = 0; k < 2; ++k) dst[n][k] = *(const PG8_LAS bf16x8*)(lds + PG8_SB(b, h) + boff + n * 2048 + k * 1024); } while (0)
; #define PG8_MMA(ai, bj, At, Bt) do { __builtin_amdgcn_s_setprio(1); _Pragma("unroll") for (int m = 0; m < 4; ++m) _Pragma("unroll") for (int n = 0; n < 2; ++n) _Pragma("unroll") for (int k = 0; k < 2; ++k) \
;         acc[ai][bj][m][n] = __builtin_amdgcn_mfma_f32_16x16x32_bf16(Bt[n][k], At[m][k], acc[ai][bj][m][n], 0, 0, 0); __builtin_amdgcn_s_setprio(0); } while (0)
; #define PG8_WAIT_V(n) asm volatile("s_waitcnt vmcnt(" #n ")" ::: "memory")
; #define PG8_WAIT_L(n) asm volatile("s_waitcnt lgkmcnt(" #n ")" ::: "memory")
; #define PG8_BAR __builtin_amdgcn_s_barrier()
; #define PG8_SCHED __builtin_amdgcn_sched_barrier(0)
; template <class Epi, class Sched, bool STAMP = false>
; __device__ __forceinline__ void gemm_phase(PG8_LAS unsigned char* lds, const Gemm g, const Sched& S, const Epi& E, unsigned long long* stamps) {
;     ...
;             PG8_LDB(B0, 1, 0); PG8_SCHED; PG8_LDA(At, 1, 0); PG8_STAGE(PG8_SA(0, 1), a2 + hstep, voffA);
;             PG8_WAIT_L(8); PG8_BAR; PG8_WAIT_L(0); PG8_MMA(0, 0, At, B0); PG8_BAR; PG8_SCHED;
;             PG8_LDB(B1, 1, 1); PG8_STAGE(PG8_SB(1, 0), b3, voffB);
;             PG8_BAR; PG8_WAIT_L(0); PG8_MMA(0, 1, At, B1); PG8_BAR;
;             PG8_LDA(At, 1, 1); PG8_STAGE(PG8_SA(1, 0), a3, voffA);
;             PG8_BAR; PG8_WAIT_L(0); PG8_MMA(1, 0, At, B0); PG8_BAR; PG8_SCHED;
;             PG8_STAGE(PG8_SB(1, 1), b3 + hstep, voffB);
;             PG8_WAIT_V(6); PG8_BAR; PG8_MMA(1, 1, At, B1); PG8_BAR;
.Lzp11_mid:
	ds_read_b128 v[140:143], v155
	ds_read_b128 v[170:173], v156
	ds_read_b128 v[174:177], v157
	ds_read_b128 v[178:181], v165
	s_add_u32 s16, s28, 0x44000
	s_addc_u32 s17, s29, 0
	s_mov_b32 m0, s44
	ds_read_b128 v[182:185], v145 offset:32768
	ds_read_b128 v[186:189], v145 offset:33792
	ds_read_b128 v[190:193], v145 offset:34816
	ds_read_b128 v[194:197], v145 offset:35840
	ds_read_b128 v[198:201], v145 offset:36864
	ds_read_b128 v[202:205], v145 offset:37888
	ds_read_b128 v[206:209], v145 offset:38912
	ds_read_b128 v[210:213], v145 offset:39936
	global_load_lds_dwordx4 v130, s[16:17]
	s_mov_b32 m0, s45
	s_nop 0
	global_load_lds_dwordx4 v128, s[16:17]
	s_waitcnt lgkmcnt(8)
	s_barrier
	s_waitcnt lgkmcnt(0)
	s_setprio 1
	s_waitcnt lgkmcnt(0)
	v_mfma_f32_16x16x32_bf16 v[124:127], v[140:143], v[182:185], v[124:127]
	v_mfma_f32_16x16x32_bf16 v[120:123], v[174:177], v[182:185], v[120:123]
	v_mfma_f32_16x16x32_bf16 v[108:111], v[140:143], v[190:193], v[108:111]
	v_mfma_f32_16x16x32_bf16 v[104:107], v[174:177], v[190:193], v[104:107]
	v_mfma_f32_16x16x32_bf16 v[92:95], v[140:143], v[198:201], v[92:95]
	v_mfma_f32_16x16x32_bf16 v[88:91], v[174:177], v[198:201], v[88:91]
	v_mfma_f32_16x16x32_bf16 v[76:79], v[140:143], v[206:209], v[76:79]
	v_mfma_f32_16x16x32_bf16 v[72:75], v[174:177], v[206:209], v[72:75]
	v_mfma_f32_16x16x32_bf16 v[124:127], v[170:173], v[186:189], v[124:127]
	v_mfma_f32_16x16x32_bf16 v[120:123], v[178:181], v[186:189], v[120:123]
	v_mfma_f32_16x16x32_bf16 v[108:111], v[170:173], v[194:197], v[108:111]
	v_mfma_f32_16x16x32_bf16 v[104:107], v[178:181], v[194:197], v[104:107]
	v_mfma_f32_16x16x32_bf16 v[92:95], v[170:173], v[202:205], v[92:95]
	v_mfma_f32_16x16x32_bf16 v[88:91], v[178:181], v[202:205], v[88:91]
	v_mfma_f32_16x16x32_bf16 v[76:79], v[170:173], v[210:213], v[76:79]
	v_mfma_f32_16x16x32_bf16 v[72:75], v[178:181], v[210:213], v[72:75]
	s_setprio 0
	s_barrier
	s_mov_b32 m0, s48
	ds_read_b128 v[214:217], v166
	ds_read_b128 v[218:221], v167
	ds_read_b128 v[222:225], v168
	ds_read_b128 v[226:229], v169
	s_add_u32 s100, s20, 0x80
	s_addc_u32 s101, s21, 0
	global_load_lds_dwordx4 v130, s[100:101]
	s_mov_b32 m0, s49
	s_nop 0
	global_load_lds_dwordx4 v128, s[100:101]
	s_waitcnt lgkmcnt(0)
	s_barrier
	s_waitcnt lgkmcnt(0)
	s_setprio 1
	s_waitcnt lgkmcnt(0)
	v_mfma_f32_16x16x32_bf16 v[116:119], v[214:217], v[182:185], v[116:119]
	v_mfma_f32_16x16x32_bf16 v[112:115], v[222:225], v[182:185], v[112:115]
	v_mfma_f32_16x16x32_bf16 v[100:103], v[214:217], v[190:193], v[100:103]
	v_mfma_f32_16x16x32_bf16 v[96:99], v[222:225], v[190:193], v[96:99]
	v_mfma_f32_16x16x32_bf16 v[84:87], v[214:217], v[198:201], v[84:87]
	v_mfma_f32_16x16x32_bf16 v[80:83], v[222:225], v[198:201], v[80:83]
	v_mfma_f32_16x16x32_bf16 v[68:71], v[214:217], v[206:209], v[68:71]
	v_mfma_f32_16x16x32_bf16 v[64:67], v[222:225], v[206:209], v[64:67]
	v_mfma_f32_16x16x32_bf16 v[116:119], v[218:221], v[186:189], v[116:119]
	v_mfma_f32_16x16x32_bf16 v[112:115], v[226:229], v[186:189], v[112:115]
	v_mfma_f32_16x16x32_bf16 v[100:103], v[218:221], v[194:197], v[100:103]
	v_mfma_f32_16x16x32_bf16 v[96:99], v[226:229], v[194:197], v[96:99]
	v_mfma_f32_16x16x32_bf16 v[84:87], v[218:221], v[202:205], v[84:87]
	v_mfma_f32_16x16x32_bf16 v[80:83], v[226:229], v[202:205], v[80:83]
	v_mfma_f32_16x16x32_bf16 v[68:71], v[218:221], v[210:213], v[68:71]
	v_mfma_f32_16x16x32_bf16 v[64:67], v[226:229], v[210:213], v[64:67]
	s_setprio 0
	s_mov_b32 m0, s50
	s_barrier
	ds_read_b128 v[182:185], v145 offset:49152
	ds_read_b128 v[186:189], v145 offset:50176
	ds_read_b128 v[190:193], v145 offset:51200
	ds_read_b128 v[194:197], v145 offset:52224
	ds_read_b128 v[198:201], v145 offset:53248
	ds_read_b128 v[202:205], v145 offset:54272
	ds_read_b128 v[206:209], v145 offset:55296
	ds_read_b128 v[210:213], v145 offset:56320
	s_add_u32 s100, s28, 0x80
	s_addc_u32 s101, s29, 0
	global_load_lds_dwordx4 v130, s[100:101]
	s_mov_b32 m0, s51
	s_nop 0
	global_load_lds_dwordx4 v128, s[100:101]
	s_add_u32 s16, s20, 0x44080
	s_addc_u32 s17, s21, 0
	s_mov_b32 m0, s52
	s_nop 0
	global_load_lds_dwordx4 v130, s[16:17]
	s_mov_b32 m0, s53
	s_nop 0
	global_load_lds_dwordx4 v128, s[16:17]
	s_waitcnt vmcnt(6)
	s_barrier
	s_waitcnt lgkmcnt(0)
	s_setprio 1
	s_waitcnt lgkmcnt(0)
	v_mfma_f32_16x16x32_bf16 v[60:63], v[140:143], v[182:185], v[60:63]
	v_mfma_f32_16x16x32_bf16 v[56:59], v[174:177], v[182:185], v[56:59]
	v_mfma_f32_16x16x32_bf16 v[44:47], v[140:143], v[190:193], v[44:47]
	v_mfma_f32_16x16x32_bf16 v[40:43], v[174:177], v[190:193], v[40:43]
	v_mfma_f32_16x16x32_bf16 v[28:31], v[140:143], v[198:201], v[28:31]
	v_mfma_f32_16x16x32_bf16 v[24:27], v[174:177], v[198:201], v[24:27]
	v_mfma_f32_16x16x32_bf16 v[12:15], v[140:143], v[206:209], v[12:15]
	v_mfma_f32_16x16x32_bf16 v[8:11], v[174:177], v[206:209], v[8:11]
	v_mfma_f32_16x16x32_bf16 v[60:63], v[170:173], v[186:189], v[60:63]
	v_mfma_f32_16x16x32_bf16 v[56:59], v[178:181], v[186:189], v[56:59]
	v_mfma_f32_16x16x32_bf16 v[44:47], v[170:173], v[194:197], v[44:47]
	v_mfma_f32_16x16x32_bf16 v[40:43], v[178:181], v[194:197], v[40:43]
	v_mfma_f32_16x16x32_bf16 v[28:31], v[170:173], v[202:205], v[28:31]
	v_mfma_f32_16x16x32_bf16 v[24:27], v[178:181], v[202:205], v[24:27]
	v_mfma_f32_16x16x32_bf16 v[12:15], v[170:173], v[210:213], v[12:15]
	v_mfma_f32_16x16x32_bf16 v[8:11], v[178:181], v[210:213], v[8:11]
	v_mfma_f32_16x16x32_bf16 v[52:55], v[214:217], v[182:185], v[52:55]
	v_mfma_f32_16x16x32_bf16 v[48:51], v[222:225], v[182:185], v[48:51]
	v_mfma_f32_16x16x32_bf16 v[36:39], v[214:217], v[190:193], v[36:39]
	v_mfma_f32_16x16x32_bf16 v[32:35], v[222:225], v[190:193], v[32:35]
	v_mfma_f32_16x16x32_bf16 v[20:23], v[214:217], v[198:201], v[20:23]
	v_mfma_f32_16x16x32_bf16 v[16:19], v[222:225], v[198:201], v[16:19]
	v_mfma_f32_16x16x32_bf16 v[4:7], v[214:217], v[206:209], v[4:7]
	v_mfma_f32_16x16x32_bf16 v[0:3], v[222:225], v[206:209], v[0:3]
	v_mfma_f32_16x16x32_bf16 v[52:55], v[218:221], v[186:189], v[52:55]
	v_mfma_f32_16x16x32_bf16 v[48:51], v[226:229], v[186:189], v[48:51]
	v_mfma_f32_16x16x32_bf16 v[36:39], v[218:221], v[194:197], v[36:39]
	v_mfma_f32_16x16x32_bf16 v[32:35], v[226:229], v[194:197], v[32:35]
	v_mfma_f32_16x16x32_bf16 v[20:23], v[218:221], v[202:205], v[20:23]
	v_mfma_f32_16x16x32_bf16 v[16:19], v[226:229], v[202:205], v[16:19]
	v_mfma_f32_16x16x32_bf16 v[4:7], v[218:221], v[210:213], v[4:7]
	v_mfma_f32_16x16x32_bf16 v[0:3], v[226:229], v[210:213], v[0:3]
	s_setprio 0
	s_add_i32 s10, s10, 2
	s_add_u32 s62, s62, 0x100
	s_addc_u32 s63, s63, 0
	s_cmp_gt_u32 s10, 13
	s_mov_b64 s[16:17], s[18:19]
	s_barrier
; DI float ex2(float x) { return __builtin_amdgcn_exp2f(x); }
;     DI void operator()(const f32x4 (&acc)[2][2][4][2], const Unit& u, int wr, int wc, int fr, int fq) const {
;         const int row0 = u.pm * BM + wr * 64 + fr, hcol0 = ((u.pn * BM + wc * 32) >> 1) + 4 * fq;
; #pragma unroll
;         for (int ai = 0; ai < 2; ++ai)
; #pragma unroll
;             for (int m = 0; m < 4; ++m) { u16* rowp = O + (size_t)(row0 + ai * HALF + m * 16) * ldc + hcol0;
; #pragma unroll
;                 for (int bj = 0; bj < 2; ++bj) { const f32x4 g = acc[ai][bj][m][0], up = acc[ai][bj][m][1]; float r[4];
; #pragma unroll
;                     for (int j = 0; j < 4; ++j) r[j] = g[j] * up[j] * __builtin_amdgcn_rcpf(1.f + ex2(-LOG2E * g[j]));
;                     uint2 w = {pack2(r[0], r[1]), pack2(r[2], r[3])}; *(uint2*)(rowp + bj * (HALF / 2)) = w; } }
	s_cbranch_scc0 .LBB0_727
	v_exp_f32_e64 v171, -v124
	v_exp_f32_e64 v175, -v125
	s_lshl_b32 s10, s61, 8
	v_add_f32_e32 v171, 1.0, v171
	v_rcp_f32_e32 v174, v171
	v_add_f32_e32 v171, 1.0, v175
	v_exp_f32_e64 v176, -v126
	v_exp_f32_e64 v177, -v127
	v_rcp_f32_e32 v175, v171
	v_add_f32_e32 v171, 1.0, v176
	v_rcp_f32_e32 v176, v171
	v_add_f32_e32 v171, 1.0, v177
	v_rcp_f32_e32 v177, v171
	v_pk_mul_f32 v[122:123], v[126:127], v[122:123]
	v_pk_mul_f32 v[120:121], v[124:125], v[120:121]
	s_or_b32 s10, s10, s47
	v_pk_mul_f32 v[120:121], v[120:121], v[174:175]
	v_pk_mul_f32 v[122:123], v[122:123], v[176:177]
	s_ashr_i32 s10, s10, 1
	v_cvt_pk_bf16_f32 v120, v120, v121
	v_cvt_pk_bf16_f32 v121, v122, v123
	v_or_b32_e32 v140, s10, v146
	v_exp_f32_e64 v122, -v116
	v_exp_f32_e64 v123, -v117
	v_lshl_add_u32 v170, s60, 8, v144
	v_ashrrev_i32_e32 v141, 31, v140
	v_mov_b64_e32 v[142:143], s[12:13]
	v_mad_i64_i32 v[172:173], s[16:17], v170, s57, v[142:143]
	v_lshlrev_b64 v[140:141], 1, v[140:141]
	v_lshl_add_u64 v[172:173], v[172:173], 0, v[140:141]
	global_store_dwordx2 v[172:173], v[120:121], off
	v_add_f32_e32 v120, 1.0, v122
	v_add_f32_e32 v121, 1.0, v123
	v_exp_f32_e64 v122, -v118
	v_exp_f32_e64 v123, -v119
	v_rcp_f32_e32 v120, v120
	v_rcp_f32_e32 v121, v121
	v_add_f32_e32 v122, 1.0, v122
	v_add_f32_e32 v123, 1.0, v123
	v_rcp_f32_e32 v122, v122
	v_rcp_f32_e32 v123, v123
	v_pk_mul_f32 v[114:115], v[118:119], v[114:115]
	v_pk_mul_f32 v[112:113], v[116:117], v[112:113]
	v_pk_mul_f32 v[112:113], v[112:113], v[120:121]
	v_pk_mul_f32 v[114:115], v[114:115], v[122:123]
	v_cvt_pk_bf16_f32 v112, v112, v113
	v_cvt_pk_bf16_f32 v113, v114, v115
	v_exp_f32_e64 v114, -v108
	v_exp_f32_e64 v115, -v109
	v_exp_f32_e64 v116, -v110
	v_exp_f32_e64 v117, -v111
	v_add_f32_e32 v114, 1.0, v114
	v_add_f32_e32 v115, 1.0, v115
	v_add_f32_e32 v116, 1.0, v116
	v_add_f32_e32 v117, 1.0, v117
	v_rcp_f32_e32 v114, v114
	v_rcp_f32_e32 v115, v115
	v_rcp_f32_e32 v116, v116
	v_rcp_f32_e32 v117, v117
	v_pk_mul_f32 v[106:107], v[110:111], v[106:107]
	v_pk_mul_f32 v[104:105], v[108:109], v[104:105]
	global_store_dwordx2 v[172:173], v[112:113], off offset:128
	v_pk_mul_f32 v[104:105], v[104:105], v[114:115]
	v_pk_mul_f32 v[106:107], v[106:107], v[116:117]
	v_cvt_pk_bf16_f32 v104, v104, v105
	v_cvt_pk_bf16_f32 v105, v106, v107
	v_exp_f32_e64 v106, -v100
	v_exp_f32_e64 v107, -v101
	v_or_b32_e32 v112, 16, v170
	v_mad_i64_i32 v[112:113], s[16:17], v112, s57, v[142:143]
	v_lshl_add_u64 v[112:113], v[112:113], 0, v[140:141]
	global_store_dwordx2 v[112:113], v[104:105], off
	v_add_f32_e32 v104, 1.0, v106
	v_add_f32_e32 v105, 1.0, v107
	v_exp_f32_e64 v106, -v102
	v_exp_f32_e64 v107, -v103
	v_rcp_f32_e32 v104, v104
	v_rcp_f32_e32 v105, v105
	v_add_f32_e32 v106, 1.0, v106
	v_add_f32_e32 v107, 1.0, v107
	v_rcp_f32_e32 v106, v106
	v_rcp_f32_e32 v107, v107
	v_pk_mul_f32 v[98:99], v[102:103], v[98:99]
	v_pk_mul_f32 v[96:97], v[100:101], v[96:97]
	v_pk_mul_f32 v[96:97], v[96:97], v[104:105]
	v_pk_mul_f32 v[98:99], v[98:99], v[106:107]
	v_cvt_pk_bf16_f32 v96, v96, v97
	v_cvt_pk_bf16_f32 v97, v98, v99
	v_exp_f32_e64 v98, -v92
	v_exp_f32_e64 v99, -v93
	v_exp_f32_e64 v100, -v94
	v_exp_f32_e64 v101, -v95
	v_add_f32_e32 v98, 1.0, v98
	v_add_f32_e32 v99, 1.0, v99
	v_add_f32_e32 v100, 1.0, v100
	v_add_f32_e32 v101, 1.0, v101
	v_rcp_f32_e32 v98, v98
	v_rcp_f32_e32 v99, v99
	v_rcp_f32_e32 v100, v100
	v_rcp_f32_e32 v101, v101
	v_pk_mul_f32 v[90:91], v[94:95], v[90:91]
	v_pk_mul_f32 v[88:89], v[92:93], v[88:89]
	global_store_dwordx2 v[112:113], v[96:97], off offset:128
	v_pk_mul_f32 v[88:89], v[88:89], v[98:99]
	v_pk_mul_f32 v[90:91], v[90:91], v[100:101]
	v_cvt_pk_bf16_f32 v88, v88, v89
	v_cvt_pk_bf16_f32 v89, v90, v91
	v_exp_f32_e64 v90, -v84
	v_exp_f32_e64 v91, -v85
	v_or_b32_e32 v96, 32, v170
	v_mad_i64_i32 v[96:97], s[16:17], v96, s57, v[142:143]
	v_lshl_add_u64 v[96:97], v[96:97], 0, v[140:141]
	global_store_dwordx2 v[96:97], v[88:89], off
	v_add_f32_e32 v88, 1.0, v90
	v_add_f32_e32 v89, 1.0, v91
	v_exp_f32_e64 v90, -v86
	v_exp_f32_e64 v91, -v87
	v_rcp_f32_e32 v88, v88
	v_rcp_f32_e32 v89, v89
	v_add_f32_e32 v90, 1.0, v90
	v_add_f32_e32 v91, 1.0, v91
	v_rcp_f32_e32 v90, v90
	v_rcp_f32_e32 v91, v91
	v_pk_mul_f32 v[82:83], v[86:87], v[82:83]
	v_pk_mul_f32 v[80:81], v[84:85], v[80:81]
	v_pk_mul_f32 v[80:81], v[80:81], v[88:89]
	v_pk_mul_f32 v[82:83], v[82:83], v[90:91]
	v_cvt_pk_bf16_f32 v80, v80, v81
	v_cvt_pk_bf16_f32 v81, v82, v83
	v_exp_f32_e64 v82, -v76
	v_exp_f32_e64 v83, -v77
	v_exp_f32_e64 v84, -v78
	v_exp_f32_e64 v85, -v79
	v_add_f32_e32 v82, 1.0, v82
	v_add_f32_e32 v83, 1.0, v83
	v_add_f32_e32 v84, 1.0, v84
	v_add_f32_e32 v85, 1.0, v85
	v_rcp_f32_e32 v82, v82
	v_rcp_f32_e32 v83, v83
	v_rcp_f32_e32 v84, v84
	v_rcp_f32_e32 v85, v85
	v_pk_mul_f32 v[74:75], v[78:79], v[74:75]
	v_pk_mul_f32 v[72:73], v[76:77], v[72:73]
	global_store_dwordx2 v[96:97], v[80:81], off offset:128
	v_pk_mul_f32 v[72:73], v[72:73], v[82:83]
	v_pk_mul_f32 v[74:75], v[74:75], v[84:85]
	v_cvt_pk_bf16_f32 v72, v72, v73
	v_cvt_pk_bf16_f32 v73, v74, v75
	v_exp_f32_e64 v74, -v68
	v_exp_f32_e64 v75, -v69
	v_or_b32_e32 v80, 48, v170
	v_mad_i64_i32 v[80:81], s[16:17], v80, s57, v[142:143]
	v_lshl_add_u64 v[80:81], v[80:81], 0, v[140:141]
	global_store_dwordx2 v[80:81], v[72:73], off
	v_add_f32_e32 v72, 1.0, v74
	v_add_f32_e32 v73, 1.0, v75
	v_exp_f32_e64 v74, -v70
	v_exp_f32_e64 v75, -v71
	v_rcp_f32_e32 v72, v72
	v_rcp_f32_e32 v73, v73
	v_add_f32_e32 v74, 1.0, v74
	v_add_f32_e32 v75, 1.0, v75
	v_rcp_f32_e32 v74, v74
	v_rcp_f32_e32 v75, v75
	v_pk_mul_f32 v[66:67], v[70:71], v[66:67]
	v_pk_mul_f32 v[64:65], v[68:69], v[64:65]
; DI float ex2(float x) { return __builtin_amdgcn_exp2f(x); }
;     DI void operator()(const f32x4 (&acc)[2][2][4][2], const Unit& u, int wr, int wc, int fr, int fq) const {
;         const int row0 = u.pm * BM + wr * 64 + fr, hcol0 = ((u.pn * BM + wc * 32) >> 1) + 4 * fq;
; #pragma unroll
;         for (int ai = 0; ai < 2; ++ai)
; #pragma unroll
;             for (int m = 0; m < 4; ++m) { u16* rowp = O + (size_t)(row0 + ai * HALF + m * 16) * ldc + hcol0;
; #pragma unroll
;                 for (int bj = 0; bj < 2; ++bj) { const f32x4 g = acc[ai][bj][m][0], up = acc[ai][bj][m][1]; float r[4];
; #pragma unroll
;                     for (int j = 0; j < 4; ++j) r[j] = g[j] * up[j] * __builtin_amdgcn_rcpf(1.f + ex2(-LOG2E * g[j]));
;                     uint2 w = {pack2(r[0], r[1]), pack2(r[2], r[3])}; *(uint2*)(rowp + bj * (HALF / 2)) = w; } }
; template <class Epi, class Sched, bool STAMP = false>
; __device__ __forceinline__ void gemm_phase(PG8_LAS unsigned char* lds, const Gemm g, const Sched& S, const Epi& E, unsigned long long* stamps) {
;     ...
;         if (!has_next) break;
; #pragma unroll
;         for (int a = 0; a < 2; ++a)
; #pragma unroll
;             for (int b = 0; b < 2; ++b)
; #pragma unroll
;                 for (int m = 0; m < 4; ++m)
; #pragma unroll
;                     for (int n = 0; n < 2; ++n) acc[a][b][m][n] = (f32x4){0.f, 0.f, 0.f, 0.f};
;         cur = nxt; cA = nA; cB = nB; ++ui;
	v_pk_mul_f32 v[64:65], v[64:65], v[72:73]
	v_pk_mul_f32 v[66:67], v[66:67], v[74:75]
	v_cvt_pk_bf16_f32 v64, v64, v65
	v_cvt_pk_bf16_f32 v65, v66, v67
	v_exp_f32_e64 v66, -v60
	v_exp_f32_e64 v67, -v61
	v_exp_f32_e64 v68, -v62
	v_exp_f32_e64 v69, -v63
	v_add_f32_e32 v66, 1.0, v66
	v_add_f32_e32 v67, 1.0, v67
	v_add_f32_e32 v68, 1.0, v68
	v_add_f32_e32 v69, 1.0, v69
	v_rcp_f32_e32 v66, v66
	v_rcp_f32_e32 v67, v67
	v_rcp_f32_e32 v68, v68
	v_rcp_f32_e32 v69, v69
	v_pk_mul_f32 v[58:59], v[62:63], v[58:59]
	v_pk_mul_f32 v[56:57], v[60:61], v[56:57]
	global_store_dwordx2 v[80:81], v[64:65], off offset:128
	v_pk_mul_f32 v[56:57], v[56:57], v[66:67]
	v_pk_mul_f32 v[58:59], v[58:59], v[68:69]
	v_cvt_pk_bf16_f32 v56, v56, v57
	v_cvt_pk_bf16_f32 v57, v58, v59
	v_exp_f32_e64 v58, -v52
	v_exp_f32_e64 v59, -v53
	v_add_u32_e32 v64, 0x80, v170
	v_mad_i64_i32 v[64:65], s[16:17], v64, s57, v[142:143]
	v_lshl_add_u64 v[64:65], v[64:65], 0, v[140:141]
	global_store_dwordx2 v[64:65], v[56:57], off
	v_add_f32_e32 v56, 1.0, v58
	v_add_f32_e32 v57, 1.0, v59
	v_exp_f32_e64 v58, -v54
	v_exp_f32_e64 v59, -v55
	v_rcp_f32_e32 v56, v56
	v_rcp_f32_e32 v57, v57
	v_add_f32_e32 v58, 1.0, v58
	v_add_f32_e32 v59, 1.0, v59
	v_rcp_f32_e32 v58, v58
	v_rcp_f32_e32 v59, v59
	v_pk_mul_f32 v[50:51], v[54:55], v[50:51]
	v_pk_mul_f32 v[48:49], v[52:53], v[48:49]
	v_pk_mul_f32 v[48:49], v[48:49], v[56:57]
	v_pk_mul_f32 v[50:51], v[50:51], v[58:59]
	v_cvt_pk_bf16_f32 v48, v48, v49
	v_cvt_pk_bf16_f32 v49, v50, v51
	v_exp_f32_e64 v50, -v44
	v_exp_f32_e64 v51, -v45
	v_exp_f32_e64 v52, -v46
	v_exp_f32_e64 v53, -v47
	v_add_f32_e32 v50, 1.0, v50
	v_add_f32_e32 v51, 1.0, v51
	v_add_f32_e32 v52, 1.0, v52
	v_add_f32_e32 v53, 1.0, v53
	v_rcp_f32_e32 v50, v50
	v_rcp_f32_e32 v51, v51
	v_rcp_f32_e32 v52, v52
	v_rcp_f32_e32 v53, v53
	v_pk_mul_f32 v[42:43], v[46:47], v[42:43]
	v_pk_mul_f32 v[40:41], v[44:45], v[40:41]
	global_store_dwordx2 v[64:65], v[48:49], off offset:128
	v_pk_mul_f32 v[40:41], v[40:41], v[50:51]
	v_pk_mul_f32 v[42:43], v[42:43], v[52:53]
	v_cvt_pk_bf16_f32 v40, v40, v41
	v_cvt_pk_bf16_f32 v41, v42, v43
	v_exp_f32_e64 v42, -v36
	v_exp_f32_e64 v43, -v37
	v_add_u32_e32 v48, 0x90, v170
	v_mad_i64_i32 v[48:49], s[16:17], v48, s57, v[142:143]
	v_lshl_add_u64 v[48:49], v[48:49], 0, v[140:141]
	global_store_dwordx2 v[48:49], v[40:41], off
	v_add_f32_e32 v40, 1.0, v42
	v_add_f32_e32 v41, 1.0, v43
	v_exp_f32_e64 v42, -v38
	v_exp_f32_e64 v43, -v39
	v_rcp_f32_e32 v40, v40
	v_rcp_f32_e32 v41, v41
	v_add_f32_e32 v42, 1.0, v42
	v_add_f32_e32 v43, 1.0, v43
	v_rcp_f32_e32 v42, v42
	v_rcp_f32_e32 v43, v43
	v_pk_mul_f32 v[34:35], v[38:39], v[34:35]
	v_pk_mul_f32 v[32:33], v[36:37], v[32:33]
	v_pk_mul_f32 v[32:33], v[32:33], v[40:41]
	v_pk_mul_f32 v[34:35], v[34:35], v[42:43]
	v_cvt_pk_bf16_f32 v32, v32, v33
	v_cvt_pk_bf16_f32 v33, v34, v35
	v_exp_f32_e64 v34, -v28
	v_exp_f32_e64 v35, -v29
	v_exp_f32_e64 v36, -v30
	v_exp_f32_e64 v37, -v31
	v_add_f32_e32 v34, 1.0, v34
	v_add_f32_e32 v35, 1.0, v35
	v_add_f32_e32 v36, 1.0, v36
	v_add_f32_e32 v37, 1.0, v37
	v_rcp_f32_e32 v34, v34
	v_rcp_f32_e32 v35, v35
	v_rcp_f32_e32 v36, v36
	v_rcp_f32_e32 v37, v37
	v_pk_mul_f32 v[26:27], v[30:31], v[26:27]
	v_pk_mul_f32 v[24:25], v[28:29], v[24:25]
	global_store_dwordx2 v[48:49], v[32:33], off offset:128
	v_pk_mul_f32 v[24:25], v[24:25], v[34:35]
	v_pk_mul_f32 v[26:27], v[26:27], v[36:37]
	v_cvt_pk_bf16_f32 v24, v24, v25
	v_cvt_pk_bf16_f32 v25, v26, v27
	v_exp_f32_e64 v26, -v20
	v_exp_f32_e64 v27, -v21
	v_add_u32_e32 v32, 0xa0, v170
	v_mad_i64_i32 v[32:33], s[16:17], v32, s57, v[142:143]
	v_lshl_add_u64 v[32:33], v[32:33], 0, v[140:141]
	global_store_dwordx2 v[32:33], v[24:25], off
	v_add_f32_e32 v24, 1.0, v26
	v_add_f32_e32 v25, 1.0, v27
	v_exp_f32_e64 v26, -v22
	v_exp_f32_e64 v27, -v23
	v_rcp_f32_e32 v24, v24
	v_rcp_f32_e32 v25, v25
	v_add_f32_e32 v26, 1.0, v26
	v_add_f32_e32 v27, 1.0, v27
	v_rcp_f32_e32 v26, v26
	v_rcp_f32_e32 v27, v27
	v_pk_mul_f32 v[18:19], v[22:23], v[18:19]
	v_pk_mul_f32 v[16:17], v[20:21], v[16:17]
	v_pk_mul_f32 v[16:17], v[16:17], v[24:25]
	v_pk_mul_f32 v[18:19], v[18:19], v[26:27]
	v_cvt_pk_bf16_f32 v16, v16, v17
	v_cvt_pk_bf16_f32 v17, v18, v19
	v_exp_f32_e64 v18, -v12
	v_exp_f32_e64 v19, -v13
	v_exp_f32_e64 v20, -v14
	v_exp_f32_e64 v21, -v15
	v_add_f32_e32 v18, 1.0, v18
	v_add_f32_e32 v19, 1.0, v19
	v_add_f32_e32 v20, 1.0, v20
	v_add_f32_e32 v21, 1.0, v21
	v_rcp_f32_e32 v18, v18
	v_rcp_f32_e32 v19, v19
	v_rcp_f32_e32 v20, v20
	v_rcp_f32_e32 v21, v21
	v_pk_mul_f32 v[10:11], v[14:15], v[10:11]
	v_pk_mul_f32 v[8:9], v[12:13], v[8:9]
	global_store_dwordx2 v[32:33], v[16:17], off offset:128
	v_pk_mul_f32 v[8:9], v[8:9], v[18:19]
	v_pk_mul_f32 v[10:11], v[10:11], v[20:21]
	v_cvt_pk_bf16_f32 v8, v8, v9
	v_cvt_pk_bf16_f32 v9, v10, v11
	v_exp_f32_e64 v10, -v4
	v_exp_f32_e64 v11, -v5
	v_add_u32_e32 v16, 0xb0, v170
	v_mad_i64_i32 v[16:17], s[16:17], v16, s57, v[142:143]
	v_lshl_add_u64 v[16:17], v[16:17], 0, v[140:141]
	global_store_dwordx2 v[16:17], v[8:9], off
	v_add_f32_e32 v8, 1.0, v10
	v_add_f32_e32 v9, 1.0, v11
	v_exp_f32_e64 v10, -v6
	v_exp_f32_e64 v11, -v7
	v_rcp_f32_e32 v8, v8
	v_rcp_f32_e32 v9, v9
	v_add_f32_e32 v10, 1.0, v10
	v_add_f32_e32 v11, 1.0, v11
	v_rcp_f32_e32 v10, v10
	v_rcp_f32_e32 v11, v11
	v_pk_mul_f32 v[2:3], v[6:7], v[2:3]
	v_pk_mul_f32 v[0:1], v[4:5], v[0:1]
	s_and_b64 vcc, exec, s[2:3]
	v_pk_mul_f32 v[0:1], v[0:1], v[8:9]
	v_pk_mul_f32 v[2:3], v[2:3], v[10:11]
	v_cvt_pk_bf16_f32 v0, v0, v1
	v_cvt_pk_bf16_f32 v1, v2, v3
	s_mov_b32 s61, s58
	s_mov_b32 s60, s59
	s_mov_b64 s[18:19], s[0:1]
	s_mov_b64 s[16:17], s[4:5]
	global_store_dwordx2 v[16:17], v[0:1], off offset:128
	s_cbranch_vccz .LBB0_720
	s_branch .Lgu4_done

; #define PG8_STAGE(bufoff, gbase, voff) do { _Pragma("unroll") for (int _i = 0; _i < 2; ++_i) \
;         __builtin_amdgcn_global_load_lds((const unsigned*)((const char*)(gbase) + (voff)[_i]), (PG8_LAS unsigned*)(lds + (bufoff) + ldsw + _i * 8192), 16, 0, 0); } while (0)
; #define PG8_LDA(dst, b, h) do { _Pragma("unroll") for (int m = 0; m < 4; ++m) _Pragma("unroll") for (int k = 0; k < 2; ++k) dst[m][k] = *(const PG8_LAS bf16x8*)(lds + PG8_SA(b, h) + aoff + m * 2048 + k * 1024); } while (0)
; #define PG8_LDB(dst, b, h) do { _Pragma("unroll") for (int n = 0; n < 2; ++n) _Pragma("unroll") for (int k = 0; k < 2; ++k) dst[n][k] = *(const PG8_LAS bf16x8*)(lds + PG8_SB(b, h) + boff + n * 2048 + k * 1024); } while (0)
; #define PG8_MMA(ai, bj, At, Bt) do { __builtin_amdgcn_s_setprio(1); _Pragma("unroll") for (int m = 0; m < 4; ++m) _Pragma("unroll") for (int n = 0; n < 2; ++n) _Pragma("unroll") for (int k = 0; k < 2; ++k) \
;         acc[ai][bj][m][n] = __builtin_amdgcn_mfma_f32_16x16x32_bf16(Bt[n][k], At[m][k], acc[ai][bj][m][n], 0, 0, 0); __builtin_amdgcn_s_setprio(0); } while (0)
; #define PG8_WAIT_V(n) asm volatile("s_waitcnt vmcnt(" #n ")" ::: "memory")
; #define PG8_WAIT_L(n) asm volatile("s_waitcnt lgkmcnt(" #n ")" ::: "memory")
; #define PG8_BAR __builtin_amdgcn_s_barrier()
; #define PG8_SCHED __builtin_amdgcn_sched_barrier(0)
; template <class Epi, class Sched, bool STAMP = false>
; __device__ __forceinline__ void gemm_phase(PG8_LAS unsigned char* lds, const Gemm g, const Sched& S, const Epi& E, unsigned long long* stamps) {
;     ...
;             PG8_LDB(B0, 0, 0); PG8_SCHED; PG8_LDA(At, 0, 0); PG8_STAGE(PG8_SA(1, 1), a1 + hstep, voffA);
;             PG8_WAIT_L(8); PG8_BAR; PG8_WAIT_L(0); PG8_MMA(0, 0, At, B0); PG8_BAR; PG8_SCHED;
;             PG8_LDB(B1, 0, 1); PG8_STAGE(PG8_SB(0, 0), b2, voffB);
;             PG8_BAR; PG8_WAIT_L(0); PG8_MMA(0, 1, At, B1); PG8_BAR;
;             PG8_LDA(At, 0, 1); PG8_STAGE(PG8_SA(0, 0), a2, voffA);
;             PG8_BAR; PG8_WAIT_L(0); PG8_MMA(1, 0, At, B0); PG8_BAR; PG8_SCHED;
;             PG8_STAGE(PG8_SB(0, 1), b2 + hstep, voffB);
;             PG8_WAIT_V(6); PG8_BAR; PG8_MMA(1, 1, At, B1); PG8_BAR;
;             PG8_LDB(B0, 1, 0); PG8_SCHED; PG8_LDA(At, 1, 0); PG8_STAGE(PG8_SA(0, 1), a2 + hstep, voffA);
;             PG8_WAIT_L(8); PG8_BAR; PG8_WAIT_L(0); PG8_MMA(0, 0, At, B0); PG8_BAR; PG8_SCHED;
.Lgu4_half_loop:
	ds_read_b128 v[140:143], v147
	ds_read_b128 v[170:173], v148
	ds_read_b128 v[174:177], v149
	ds_read_b128 v[178:181], v150
	s_add_u32 s18, s16, 0x100
	s_addc_u32 s19, s17, 0
	s_cmp_eq_u32 s10, 12
	s_cselect_b32 s29, s5, s19
	s_cselect_b32 s28, s4, s18
	s_cselect_b32 s21, s1, s63
	s_cselect_b32 s20, s0, s62
	s_mov_b32 m0, s55
	ds_read_b128 v[182:185], v145
	ds_read_b128 v[186:189], v145 offset:1024
	ds_read_b128 v[190:193], v145 offset:2048
	ds_read_b128 v[194:197], v145 offset:3072
	ds_read_b128 v[198:201], v145 offset:4096
	ds_read_b128 v[202:205], v145 offset:5120
	ds_read_b128 v[206:209], v145 offset:6144
	ds_read_b128 v[210:213], v145 offset:7168
	global_load_lds_dwordx4 v132, s[16:17]
	s_mov_b32 m0, s56
	s_nop 0
	global_load_lds_dwordx4 v134, s[16:17]
	s_waitcnt lgkmcnt(8)
	s_barrier
	s_waitcnt lgkmcnt(0)
	s_setprio 1
	s_waitcnt lgkmcnt(0)
	v_mfma_f32_16x16x32_bf16 v[124:127], v[140:143], v[182:185], v[124:127]
	v_mfma_f32_16x16x32_bf16 v[120:123], v[174:177], v[182:185], v[120:123]
	v_mfma_f32_16x16x32_bf16 v[108:111], v[140:143], v[190:193], v[108:111]
	v_mfma_f32_16x16x32_bf16 v[104:107], v[174:177], v[190:193], v[104:107]
	v_mfma_f32_16x16x32_bf16 v[92:95], v[140:143], v[198:201], v[92:95]
	v_mfma_f32_16x16x32_bf16 v[88:91], v[174:177], v[198:201], v[88:91]
	v_mfma_f32_16x16x32_bf16 v[76:79], v[140:143], v[206:209], v[76:79]
	v_mfma_f32_16x16x32_bf16 v[72:75], v[174:177], v[206:209], v[72:75]
	v_mfma_f32_16x16x32_bf16 v[124:127], v[170:173], v[186:189], v[124:127]
	v_mfma_f32_16x16x32_bf16 v[120:123], v[178:181], v[186:189], v[120:123]
	v_mfma_f32_16x16x32_bf16 v[108:111], v[170:173], v[194:197], v[108:111]
	v_mfma_f32_16x16x32_bf16 v[104:107], v[178:181], v[194:197], v[104:107]
	v_mfma_f32_16x16x32_bf16 v[92:95], v[170:173], v[202:205], v[92:95]
	v_mfma_f32_16x16x32_bf16 v[88:91], v[178:181], v[202:205], v[88:91]
	v_mfma_f32_16x16x32_bf16 v[76:79], v[170:173], v[210:213], v[76:79]
	v_mfma_f32_16x16x32_bf16 v[72:75], v[178:181], v[210:213], v[72:75]
	s_setprio 0
	s_barrier
	s_mov_b32 m0, s37
	s_nop 0
	global_load_lds_dwordx4 v130, s[20:21]
	s_mov_b32 m0, s40
	s_nop 0
	global_load_lds_dwordx4 v128, s[20:21]
	s_waitcnt lgkmcnt(0)
	s_barrier
	s_waitcnt lgkmcnt(0)
	s_setprio 1
	s_waitcnt lgkmcnt(0)
	s_setprio 0
	s_mov_b32 m0, s34
	s_barrier
	ds_read_b128 v[182:185], v145 offset:16384
	ds_read_b128 v[186:189], v145 offset:17408
	ds_read_b128 v[190:193], v145 offset:18432
	ds_read_b128 v[194:197], v145 offset:19456
	ds_read_b128 v[198:201], v145 offset:20480
	ds_read_b128 v[202:205], v145 offset:21504
	ds_read_b128 v[206:209], v145 offset:22528
	ds_read_b128 v[210:213], v145 offset:23552
	global_load_lds_dwordx4 v130, s[28:29]
	s_mov_b32 m0, s41
	s_nop 0
	global_load_lds_dwordx4 v128, s[28:29]
	s_add_u32 s16, s20, 0x44000
	s_addc_u32 s17, s21, 0
	s_mov_b32 m0, s42
	s_nop 0
	s_mov_b32 m0, s43
	s_nop 0
	s_waitcnt vmcnt(4)
	s_barrier
	s_waitcnt lgkmcnt(0)
	s_setprio 1
	s_waitcnt lgkmcnt(0)
	v_mfma_f32_16x16x32_bf16 v[60:63], v[140:143], v[182:185], v[60:63]
	v_mfma_f32_16x16x32_bf16 v[56:59], v[174:177], v[182:185], v[56:59]
	v_mfma_f32_16x16x32_bf16 v[44:47], v[140:143], v[190:193], v[44:47]
	v_mfma_f32_16x16x32_bf16 v[40:43], v[174:177], v[190:193], v[40:43]
	v_mfma_f32_16x16x32_bf16 v[28:31], v[140:143], v[198:201], v[28:31]
	v_mfma_f32_16x16x32_bf16 v[24:27], v[174:177], v[198:201], v[24:27]
	v_mfma_f32_16x16x32_bf16 v[12:15], v[140:143], v[206:209], v[12:15]
	v_mfma_f32_16x16x32_bf16 v[8:11], v[174:177], v[206:209], v[8:11]
	v_mfma_f32_16x16x32_bf16 v[60:63], v[170:173], v[186:189], v[60:63]
	v_mfma_f32_16x16x32_bf16 v[56:59], v[178:181], v[186:189], v[56:59]
	v_mfma_f32_16x16x32_bf16 v[44:47], v[170:173], v[194:197], v[44:47]
	v_mfma_f32_16x16x32_bf16 v[40:43], v[178:181], v[194:197], v[40:43]
	v_mfma_f32_16x16x32_bf16 v[28:31], v[170:173], v[202:205], v[28:31]
	v_mfma_f32_16x16x32_bf16 v[24:27], v[178:181], v[202:205], v[24:27]
	v_mfma_f32_16x16x32_bf16 v[12:15], v[170:173], v[210:213], v[12:15]
	v_mfma_f32_16x16x32_bf16 v[8:11], v[178:181], v[210:213], v[8:11]
	s_setprio 0
	s_barrier
	ds_read_b128 v[140:143], v155
	ds_read_b128 v[170:173], v156
	ds_read_b128 v[174:177], v157
	ds_read_b128 v[178:181], v165
	s_add_u32 s16, s28, 0x44000
	s_addc_u32 s17, s29, 0
	s_mov_b32 m0, s44
	ds_read_b128 v[182:185], v145 offset:32768
	ds_read_b128 v[186:189], v145 offset:33792
	ds_read_b128 v[190:193], v145 offset:34816
	ds_read_b128 v[194:197], v145 offset:35840
	ds_read_b128 v[198:201], v145 offset:36864
	ds_read_b128 v[202:205], v145 offset:37888
	ds_read_b128 v[206:209], v145 offset:38912
	ds_read_b128 v[210:213], v145 offset:39936
	global_load_lds_dwordx4 v130, s[16:17]
	s_mov_b32 m0, s45
	s_nop 0
	global_load_lds_dwordx4 v128, s[16:17]
	s_waitcnt lgkmcnt(8)
	s_barrier
	s_waitcnt lgkmcnt(0)
	s_setprio 1
	s_waitcnt lgkmcnt(0)
	v_mfma_f32_16x16x32_bf16 v[124:127], v[140:143], v[182:185], v[124:127]
	v_mfma_f32_16x16x32_bf16 v[120:123], v[174:177], v[182:185], v[120:123]
	v_mfma_f32_16x16x32_bf16 v[108:111], v[140:143], v[190:193], v[108:111]
	v_mfma_f32_16x16x32_bf16 v[104:107], v[174:177], v[190:193], v[104:107]
	v_mfma_f32_16x16x32_bf16 v[92:95], v[140:143], v[198:201], v[92:95]
	v_mfma_f32_16x16x32_bf16 v[88:91], v[174:177], v[198:201], v[88:91]
	v_mfma_f32_16x16x32_bf16 v[76:79], v[140:143], v[206:209], v[76:79]
	v_mfma_f32_16x16x32_bf16 v[72:75], v[174:177], v[206:209], v[72:75]
	v_mfma_f32_16x16x32_bf16 v[124:127], v[170:173], v[186:189], v[124:127]
	v_mfma_f32_16x16x32_bf16 v[120:123], v[178:181], v[186:189], v[120:123]
	v_mfma_f32_16x16x32_bf16 v[108:111], v[170:173], v[194:197], v[108:111]
	v_mfma_f32_16x16x32_bf16 v[104:107], v[178:181], v[194:197], v[104:107]
	v_mfma_f32_16x16x32_bf16 v[92:95], v[170:173], v[202:205], v[92:95]
	v_mfma_f32_16x16x32_bf16 v[88:91], v[178:181], v[202:205], v[88:91]
	v_mfma_f32_16x16x32_bf16 v[76:79], v[170:173], v[210:213], v[76:79]
	v_mfma_f32_16x16x32_bf16 v[72:75], v[178:181], v[210:213], v[72:75]
	s_setprio 0
	s_barrier
; #define PG8_STAGE(bufoff, gbase, voff) do { _Pragma("unroll") for (int _i = 0; _i < 2; ++_i) \
;         __builtin_amdgcn_global_load_lds((const unsigned*)((const char*)(gbase) + (voff)[_i]), (PG8_LAS unsigned*)(lds + (bufoff) + ldsw + _i * 8192), 16, 0, 0); } while (0)
; #define PG8_LDA(dst, b, h) do { _Pragma("unroll") for (int m = 0; m < 4; ++m) _Pragma("unroll") for (int k = 0; k < 2; ++k) dst[m][k] = *(const PG8_LAS bf16x8*)(lds + PG8_SA(b, h) + aoff + m * 2048 + k * 1024); } while (0)
; #define PG8_LDB(dst, b, h) do { _Pragma("unroll") for (int n = 0; n < 2; ++n) _Pragma("unroll") for (int k = 0; k < 2; ++k) dst[n][k] = *(const PG8_LAS bf16x8*)(lds + PG8_SB(b, h) + boff + n * 2048 + k * 1024); } while (0)
; #define PG8_MMA(ai, bj, At, Bt) do { __builtin_amdgcn_s_setprio(1); _Pragma("unroll") for (int m = 0; m < 4; ++m) _Pragma("unroll") for (int n = 0; n < 2; ++n) _Pragma("unroll") for (int k = 0; k < 2; ++k) \
;         acc[ai][bj][m][n] = __builtin_amdgcn_mfma_f32_16x16x32_bf16(Bt[n][k], At[m][k], acc[ai][bj][m][n], 0, 0, 0); __builtin_amdgcn_s_setprio(0); } while (0)
; #define PG8_WAIT_V(n) asm volatile("s_waitcnt vmcnt(" #n ")" ::: "memory")
; #define PG8_WAIT_L(n) asm volatile("s_waitcnt lgkmcnt(" #n ")" ::: "memory")
; #define PG8_BAR __builtin_amdgcn_s_barrier()
; #define PG8_SCHED __builtin_amdgcn_sched_barrier(0)
; template <class Epi, class Sched, bool STAMP = false>
; __device__ __forceinline__ void gemm_phase(PG8_LAS unsigned char* lds, const Gemm g, const Sched& S, const Epi& E, unsigned long long* stamps) {
;     ...
;             PG8_LDB(B1, 1, 1); PG8_STAGE(PG8_SB(1, 0), b3, voffB);
;             PG8_BAR; PG8_WAIT_L(0); PG8_MMA(0, 1, At, B1); PG8_BAR;
;             PG8_LDA(At, 1, 1); PG8_STAGE(PG8_SA(1, 0), a3, voffA);
;             PG8_BAR; PG8_WAIT_L(0); PG8_MMA(1, 0, At, B0); PG8_BAR; PG8_SCHED;
;             PG8_STAGE(PG8_SB(1, 1), b3 + hstep, voffB);
;             PG8_WAIT_V(6); PG8_BAR; PG8_MMA(1, 1, At, B1); PG8_BAR;
	s_mov_b32 m0, s48
	s_add_u32 s100, s20, 0x80
	s_addc_u32 s101, s21, 0
	global_load_lds_dwordx4 v130, s[100:101]
	s_mov_b32 m0, s49
	s_nop 0
	global_load_lds_dwordx4 v128, s[100:101]
	s_waitcnt lgkmcnt(0)
	s_barrier
	s_waitcnt lgkmcnt(0)
	s_setprio 1
	s_waitcnt lgkmcnt(0)
	s_setprio 0
	s_mov_b32 m0, s50
	s_barrier
	ds_read_b128 v[182:185], v145 offset:49152
	ds_read_b128 v[186:189], v145 offset:50176
	ds_read_b128 v[190:193], v145 offset:51200
	ds_read_b128 v[194:197], v145 offset:52224
	ds_read_b128 v[198:201], v145 offset:53248
	ds_read_b128 v[202:205], v145 offset:54272
	ds_read_b128 v[206:209], v145 offset:55296
	ds_read_b128 v[210:213], v145 offset:56320
	s_add_u32 s100, s28, 0x80
	s_addc_u32 s101, s29, 0
	global_load_lds_dwordx4 v130, s[100:101]
	s_mov_b32 m0, s51
	s_nop 0
	global_load_lds_dwordx4 v128, s[100:101]
	s_add_u32 s16, s20, 0x44080
	s_addc_u32 s17, s21, 0
	s_mov_b32 m0, s52
	s_nop 0
	s_mov_b32 m0, s53
	s_nop 0
	s_waitcnt vmcnt(4)
	s_barrier
	s_waitcnt lgkmcnt(0)
	s_setprio 1
	s_waitcnt lgkmcnt(0)
	v_mfma_f32_16x16x32_bf16 v[60:63], v[140:143], v[182:185], v[60:63]
	v_mfma_f32_16x16x32_bf16 v[56:59], v[174:177], v[182:185], v[56:59]
	v_mfma_f32_16x16x32_bf16 v[44:47], v[140:143], v[190:193], v[44:47]
	v_mfma_f32_16x16x32_bf16 v[40:43], v[174:177], v[190:193], v[40:43]
	v_mfma_f32_16x16x32_bf16 v[28:31], v[140:143], v[198:201], v[28:31]
	v_mfma_f32_16x16x32_bf16 v[24:27], v[174:177], v[198:201], v[24:27]
	v_mfma_f32_16x16x32_bf16 v[12:15], v[140:143], v[206:209], v[12:15]
	v_mfma_f32_16x16x32_bf16 v[8:11], v[174:177], v[206:209], v[8:11]
	v_mfma_f32_16x16x32_bf16 v[60:63], v[170:173], v[186:189], v[60:63]
	v_mfma_f32_16x16x32_bf16 v[56:59], v[178:181], v[186:189], v[56:59]
	v_mfma_f32_16x16x32_bf16 v[44:47], v[170:173], v[194:197], v[44:47]
	v_mfma_f32_16x16x32_bf16 v[40:43], v[178:181], v[194:197], v[40:43]
	v_mfma_f32_16x16x32_bf16 v[28:31], v[170:173], v[202:205], v[28:31]
	v_mfma_f32_16x16x32_bf16 v[24:27], v[178:181], v[202:205], v[24:27]
	v_mfma_f32_16x16x32_bf16 v[12:15], v[170:173], v[210:213], v[12:15]
	v_mfma_f32_16x16x32_bf16 v[8:11], v[178:181], v[210:213], v[8:11]
	s_setprio 0
	s_add_i32 s10, s10, 2
	s_add_u32 s62, s62, 0x100
	s_addc_u32 s63, s63, 0
	s_cmp_gt_u32 s10, 13
	s_mov_b64 s[16:17], s[18:19]
	s_barrier
	s_cbranch_scc0 .Lgu4_half_loop
; DI float ex2(float x) { return __builtin_amdgcn_exp2f(x); }
;     DI void operator()(const f32x4 (&acc)[2][2][4][2], const Unit& u, int wr, int wc, int fr, int fq) const {
;         const int row0 = u.pm * BM + wr * 64 + fr, hcol0 = ((u.pn * BM + wc * 32) >> 1) + 4 * fq;
; #pragma unroll
;         for (int ai = 0; ai < 2; ++ai)
; #pragma unroll
;             for (int m = 0; m < 4; ++m) { u16* rowp = O + (size_t)(row0 + ai * HALF + m * 16) * ldc + hcol0;
; #pragma unroll
;                 for (int bj = 0; bj < 2; ++bj) { const f32x4 g = acc[ai][bj][m][0], up = acc[ai][bj][m][1]; float r[4];
; #pragma unroll
;                     for (int j = 0; j < 4; ++j) r[j] = g[j] * up[j] * __builtin_amdgcn_rcpf(1.f + ex2(-LOG2E * g[j]));
;                     uint2 w = {pack2(r[0], r[1]), pack2(r[2], r[3])}; *(uint2*)(rowp + bj * (HALF / 2)) = w; } }
	v_exp_f32_e64 v171, -v124
	v_exp_f32_e64 v175, -v125
	s_lshl_b32 s10, s61, 8
	v_add_f32_e32 v171, 1.0, v171
	v_rcp_f32_e32 v174, v171
	v_add_f32_e32 v171, 1.0, v175
	v_exp_f32_e64 v176, -v126
	v_exp_f32_e64 v177, -v127
	v_rcp_f32_e32 v175, v171
	v_add_f32_e32 v171, 1.0, v176
	v_rcp_f32_e32 v176, v171
	v_add_f32_e32 v171, 1.0, v177
	v_rcp_f32_e32 v177, v171
	v_pk_mul_f32 v[122:123], v[126:127], v[122:123]
	v_pk_mul_f32 v[120:121], v[124:125], v[120:121]
	s_or_b32 s10, s10, s47
	s_or_b32 s10, s10, s98
	v_pk_mul_f32 v[120:121], v[120:121], v[174:175]
	v_pk_mul_f32 v[122:123], v[122:123], v[176:177]
	s_ashr_i32 s10, s10, 1
	v_cvt_pk_bf16_f32 v120, v120, v121
	v_cvt_pk_bf16_f32 v121, v122, v123
	v_or_b32_e32 v140, s10, v146
	v_lshl_add_u32 v170, s60, 8, v144
	v_ashrrev_i32_e32 v141, 31, v140
	v_mov_b64_e32 v[142:143], s[12:13]
	v_mad_i64_i32 v[172:173], s[16:17], v170, s57, v[142:143]
	v_lshlrev_b64 v[140:141], 1, v[140:141]
	v_lshl_add_u64 v[172:173], v[172:173], 0, v[140:141]
	global_store_dwordx2 v[172:173], v[120:121], off
	v_exp_f32_e64 v114, -v108
	v_exp_f32_e64 v115, -v109
	v_exp_f32_e64 v116, -v110
	v_exp_f32_e64 v117, -v111
	v_add_f32_e32 v114, 1.0, v114
	v_add_f32_e32 v115, 1.0, v115
	v_add_f32_e32 v116, 1.0, v116
	v_add_f32_e32 v117, 1.0, v117
	v_rcp_f32_e32 v114, v114
	v_rcp_f32_e32 v115, v115
	v_rcp_f32_e32 v116, v116
	v_rcp_f32_e32 v117, v117
	v_pk_mul_f32 v[106:107], v[110:111], v[106:107]
	v_pk_mul_f32 v[104:105], v[108:109], v[104:105]
	v_pk_mul_f32 v[104:105], v[104:105], v[114:115]
	v_pk_mul_f32 v[106:107], v[106:107], v[116:117]
	v_cvt_pk_bf16_f32 v104, v104, v105
	v_cvt_pk_bf16_f32 v105, v106, v107
	v_or_b32_e32 v112, 16, v170
	v_mad_i64_i32 v[112:113], s[16:17], v112, s57, v[142:143]
	v_lshl_add_u64 v[112:113], v[112:113], 0, v[140:141]
	global_store_dwordx2 v[112:113], v[104:105], off
	v_exp_f32_e64 v98, -v92
	v_exp_f32_e64 v99, -v93
	v_exp_f32_e64 v100, -v94
	v_exp_f32_e64 v101, -v95
	v_add_f32_e32 v98, 1.0, v98
	v_add_f32_e32 v99, 1.0, v99
	v_add_f32_e32 v100, 1.0, v100
	v_add_f32_e32 v101, 1.0, v101
	v_rcp_f32_e32 v98, v98
	v_rcp_f32_e32 v99, v99
	v_rcp_f32_e32 v100, v100
	v_rcp_f32_e32 v101, v101
	v_pk_mul_f32 v[90:91], v[94:95], v[90:91]
	v_pk_mul_f32 v[88:89], v[92:93], v[88:89]
	v_pk_mul_f32 v[88:89], v[88:89], v[98:99]
	v_pk_mul_f32 v[90:91], v[90:91], v[100:101]
	v_cvt_pk_bf16_f32 v88, v88, v89
	v_cvt_pk_bf16_f32 v89, v90, v91
	v_or_b32_e32 v96, 32, v170
	v_mad_i64_i32 v[96:97], s[16:17], v96, s57, v[142:143]
	v_lshl_add_u64 v[96:97], v[96:97], 0, v[140:141]
	global_store_dwordx2 v[96:97], v[88:89], off
	v_exp_f32_e64 v82, -v76
	v_exp_f32_e64 v83, -v77
	v_exp_f32_e64 v84, -v78
	v_exp_f32_e64 v85, -v79
	v_add_f32_e32 v82, 1.0, v82
	v_add_f32_e32 v83, 1.0, v83
	v_add_f32_e32 v84, 1.0, v84
	v_add_f32_e32 v85, 1.0, v85
	v_rcp_f32_e32 v82, v82
	v_rcp_f32_e32 v83, v83
	v_rcp_f32_e32 v84, v84
	v_rcp_f32_e32 v85, v85
	v_pk_mul_f32 v[74:75], v[78:79], v[74:75]
	v_pk_mul_f32 v[72:73], v[76:77], v[72:73]
	v_pk_mul_f32 v[72:73], v[72:73], v[82:83]
	v_pk_mul_f32 v[74:75], v[74:75], v[84:85]
	v_cvt_pk_bf16_f32 v72, v72, v73
	v_cvt_pk_bf16_f32 v73, v74, v75
	v_or_b32_e32 v80, 48, v170
	v_mad_i64_i32 v[80:81], s[16:17], v80, s57, v[142:143]
	v_lshl_add_u64 v[80:81], v[80:81], 0, v[140:141]
	global_store_dwordx2 v[80:81], v[72:73], off
	v_exp_f32_e64 v66, -v60
	v_exp_f32_e64 v67, -v61
	v_exp_f32_e64 v68, -v62
	v_exp_f32_e64 v69, -v63
	v_add_f32_e32 v66, 1.0, v66
	v_add_f32_e32 v67, 1.0, v67
	v_add_f32_e32 v68, 1.0, v68
	v_add_f32_e32 v69, 1.0, v69
	v_rcp_f32_e32 v66, v66
	v_rcp_f32_e32 v67, v67
	v_rcp_f32_e32 v68, v68
	v_rcp_f32_e32 v69, v69
	v_pk_mul_f32 v[58:59], v[62:63], v[58:59]
	v_pk_mul_f32 v[56:57], v[60:61], v[56:57]
	v_pk_mul_f32 v[56:57], v[56:57], v[66:67]
	v_pk_mul_f32 v[58:59], v[58:59], v[68:69]
	v_cvt_pk_bf16_f32 v56, v56, v57
	v_cvt_pk_bf16_f32 v57, v58, v59
	v_add_u32_e32 v64, 0x80, v170
	v_mad_i64_i32 v[64:65], s[16:17], v64, s57, v[142:143]
	v_lshl_add_u64 v[64:65], v[64:65], 0, v[140:141]
	global_store_dwordx2 v[64:65], v[56:57], off
	v_exp_f32_e64 v50, -v44
	v_exp_f32_e64 v51, -v45
	v_exp_f32_e64 v52, -v46
	v_exp_f32_e64 v53, -v47
	v_add_f32_e32 v50, 1.0, v50
	v_add_f32_e32 v51, 1.0, v51
	v_add_f32_e32 v52, 1.0, v52
	v_add_f32_e32 v53, 1.0, v53
	v_rcp_f32_e32 v50, v50
	v_rcp_f32_e32 v51, v51
	v_rcp_f32_e32 v52, v52
	v_rcp_f32_e32 v53, v53
	v_pk_mul_f32 v[42:43], v[46:47], v[42:43]
	v_pk_mul_f32 v[40:41], v[44:45], v[40:41]
	v_pk_mul_f32 v[40:41], v[40:41], v[50:51]
	v_pk_mul_f32 v[42:43], v[42:43], v[52:53]
	v_cvt_pk_bf16_f32 v40, v40, v41
	v_cvt_pk_bf16_f32 v41, v42, v43
	v_add_u32_e32 v48, 0x90, v170
	v_mad_i64_i32 v[48:49], s[16:17], v48, s57, v[142:143]
	v_lshl_add_u64 v[48:49], v[48:49], 0, v[140:141]
	global_store_dwordx2 v[48:49], v[40:41], off
	v_exp_f32_e64 v34, -v28
	v_exp_f32_e64 v35, -v29
	v_exp_f32_e64 v36, -v30
	v_exp_f32_e64 v37, -v31
	v_add_f32_e32 v34, 1.0, v34
	v_add_f32_e32 v35, 1.0, v35
	v_add_f32_e32 v36, 1.0, v36
	v_add_f32_e32 v37, 1.0, v37
	v_rcp_f32_e32 v34, v34
	v_rcp_f32_e32 v35, v35
	v_rcp_f32_e32 v36, v36
	v_rcp_f32_e32 v37, v37
	v_pk_mul_f32 v[26:27], v[30:31], v[26:27]
	v_pk_mul_f32 v[24:25], v[28:29], v[24:25]
	v_pk_mul_f32 v[24:25], v[24:25], v[34:35]
	v_pk_mul_f32 v[26:27], v[26:27], v[36:37]
	v_cvt_pk_bf16_f32 v24, v24, v25
	v_cvt_pk_bf16_f32 v25, v26, v27
	v_add_u32_e32 v32, 0xa0, v170
	v_mad_i64_i32 v[32:33], s[16:17], v32, s57, v[142:143]
	v_lshl_add_u64 v[32:33], v[32:33], 0, v[140:141]
	global_store_dwordx2 v[32:33], v[24:25], off
	v_exp_f32_e64 v18, -v12
	v_exp_f32_e64 v19, -v13
	v_exp_f32_e64 v20, -v14
	v_exp_f32_e64 v21, -v15
	v_add_f32_e32 v18, 1.0, v18
	v_add_f32_e32 v19, 1.0, v19
	v_add_f32_e32 v20, 1.0, v20
	v_add_f32_e32 v21, 1.0, v21
	v_rcp_f32_e32 v18, v18
	v_rcp_f32_e32 v19, v19
	v_rcp_f32_e32 v20, v20
	v_rcp_f32_e32 v21, v21
	v_pk_mul_f32 v[10:11], v[14:15], v[10:11]
	v_pk_mul_f32 v[8:9], v[12:13], v[8:9]
	v_pk_mul_f32 v[8:9], v[8:9], v[18:19]
	v_pk_mul_f32 v[10:11], v[10:11], v[20:21]
	v_cvt_pk_bf16_f32 v8, v8, v9
	v_cvt_pk_bf16_f32 v9, v10, v11
	v_add_u32_e32 v16, 0xb0, v170
	v_mad_i64_i32 v[16:17], s[16:17], v16, s57, v[142:143]
	v_lshl_add_u64 v[16:17], v[16:17], 0, v[140:141]
	global_store_dwordx2 v[16:17], v[8:9], off
	s_and_b64 vcc, exec, s[2:3]
	s_mov_b32 s61, s58
	s_mov_b32 s60, s59
	s_mov_b64 s[18:19], s[0:1]
	s_mov_b64 s[16:17], s[4:5]

; #define PG8_STAGE(bufoff, gbase, voff) do { _Pragma("unroll") for (int _i = 0; _i < 2; ++_i) \
;         __builtin_amdgcn_global_load_lds((const unsigned*)((const char*)(gbase) + (voff)[_i]), (PG8_LAS unsigned*)(lds + (bufoff) + ldsw + _i * 8192), 16, 0, 0); } while (0)
; #define PG8_LDA(dst, b, h) do { _Pragma("unroll") for (int m = 0; m < 4; ++m) _Pragma("unroll") for (int k = 0; k < 2; ++k) dst[m][k] = *(const PG8_LAS bf16x8*)(lds + PG8_SA(b, h) + aoff + m * 2048 + k * 1024); } while (0)
; #define PG8_LDB(dst, b, h) do { _Pragma("unroll") for (int n = 0; n < 2; ++n) _Pragma("unroll") for (int k = 0; k < 2; ++k) dst[n][k] = *(const PG8_LAS bf16x8*)(lds + PG8_SB(b, h) + boff + n * 2048 + k * 1024); } while (0)
; #define PG8_MMA(ai, bj, At, Bt) do { __builtin_amdgcn_s_setprio(1); _Pragma("unroll") for (int m = 0; m < 4; ++m) _Pragma("unroll") for (int n = 0; n < 2; ++n) _Pragma("unroll") for (int k = 0; k < 2; ++k) \
;         acc[ai][bj][m][n] = __builtin_amdgcn_mfma_f32_16x16x32_bf16(Bt[n][k], At[m][k], acc[ai][bj][m][n], 0, 0, 0); __builtin_amdgcn_s_setprio(0); } while (0)
; #define PG8_BAR __builtin_amdgcn_s_barrier()
; template <class Epi, class Sched, bool STAMP = false>
; __device__ __forceinline__ void gemm_phase(PG8_LAS unsigned char* lds, const Gemm g, const Sched& S, const Epi& E, unsigned long long* stamps) {
;     ...
;         for (int t = 0; t < nt; t += 2) {
;             const bool last = (t == nt - 2);
;             const char* a1 = cA + (size_t)(t + 1) * kstep;
;             const char* a2 = last ? nA : cA + (size_t)(t + 2) * kstep; const char* b2 = last ? nB : cB + (size_t)(t + 2) * kstep;
;             const char* a3 = a2 + kstep; const char* b3 = b2 + kstep;
;             if (last && has_next) S.a_ready(nxt);
;             PG8_LDB(B0, 0, 0); PG8_SCHED; PG8_LDA(At, 0, 0); PG8_STAGE(PG8_SA(1, 1), a1 + hstep, voffA);
;             PG8_WAIT_L(8); PG8_BAR; PG8_WAIT_L(0); PG8_MMA(0, 0, At, B0); PG8_BAR; PG8_SCHED;
;             PG8_LDB(B1, 0, 1); PG8_STAGE(PG8_SB(0, 0), b2, voffB);
;             PG8_BAR; PG8_WAIT_L(0); PG8_MMA(0, 1, At, B1); PG8_BAR;
;             PG8_LDA(At, 0, 1); PG8_STAGE(PG8_SA(0, 0), a2, voffA);
;             PG8_BAR; PG8_WAIT_L(0); PG8_MMA(1, 0, At, B0); PG8_BAR; PG8_SCHED;
;             PG8_STAGE(PG8_SB(0, 1), b2 + hstep, voffB);
;             PG8_WAIT_V(6); PG8_BAR; PG8_MMA(1, 1, At, B1); PG8_BAR;
.LBB0_760:
	s_add_u32 s68, s30, 0x100
	s_addc_u32 s69, s31, 0
	s_mov_b32 s10, -2
	ds_read_b128 v[170:173], v147
	ds_read_b128 v[174:177], v148
	ds_read_b128 v[178:181], v149
	ds_read_b128 v[182:185], v150
	s_add_u32 s30, s28, 0x100
	s_addc_u32 s31, s29, 0
	s_cmp_eq_u32 s10, 40
	s_cselect_b32 s37, s5, s31
	s_cselect_b32 s36, s4, s30
	s_cselect_b32 s35, s1, s69
	s_cselect_b32 s34, s0, s68
	s_mov_b32 m0, s58
	ds_read_b128 v[186:189], v145
	ds_read_b128 v[190:193], v145 offset:1024
	ds_read_b128 v[194:197], v145 offset:2048
	ds_read_b128 v[198:201], v145 offset:3072
	ds_read_b128 v[202:205], v145 offset:4096
	ds_read_b128 v[206:209], v145 offset:5120
	ds_read_b128 v[210:213], v145 offset:6144
	ds_read_b128 v[214:217], v145 offset:7168
	global_load_lds_dwordx4 v136, s[28:29]
	s_mov_b32 m0, s59
	s_nop 0
	global_load_lds_dwordx4 v138, s[28:29]
	s_waitcnt lgkmcnt(8)
	s_barrier
	s_waitcnt lgkmcnt(0)
	s_setprio 1
	s_waitcnt lgkmcnt(0)
	v_mfma_f32_16x16x32_bf16 v[124:127], v[170:173], v[186:189], 0
	v_mfma_f32_16x16x32_bf16 v[120:123], v[178:181], v[186:189], 0
	v_mfma_f32_16x16x32_bf16 v[116:119], v[170:173], v[194:197], 0
	v_mfma_f32_16x16x32_bf16 v[112:115], v[178:181], v[194:197], 0
	v_mfma_f32_16x16x32_bf16 v[100:103], v[170:173], v[202:205], 0
	v_mfma_f32_16x16x32_bf16 v[96:99], v[178:181], v[202:205], 0
	v_mfma_f32_16x16x32_bf16 v[84:87], v[170:173], v[210:213], 0
	v_mfma_f32_16x16x32_bf16 v[80:83], v[178:181], v[210:213], 0
	v_mfma_f32_16x16x32_bf16 v[124:127], v[174:177], v[190:193], v[124:127]
	v_mfma_f32_16x16x32_bf16 v[120:123], v[182:185], v[190:193], v[120:123]
	v_mfma_f32_16x16x32_bf16 v[116:119], v[174:177], v[198:201], v[116:119]
	v_mfma_f32_16x16x32_bf16 v[112:115], v[182:185], v[198:201], v[112:115]
	v_mfma_f32_16x16x32_bf16 v[100:103], v[174:177], v[206:209], v[100:103]
	v_mfma_f32_16x16x32_bf16 v[96:99], v[182:185], v[206:209], v[96:99]
	v_mfma_f32_16x16x32_bf16 v[84:87], v[174:177], v[214:217], v[84:87]
	v_mfma_f32_16x16x32_bf16 v[80:83], v[182:185], v[214:217], v[80:83]
	s_setprio 0
	s_barrier
	s_mov_b32 m0, s43
	ds_read_b128 v[218:221], v151
	ds_read_b128 v[222:225], v152
	ds_read_b128 v[226:229], v153
	ds_read_b128 v[230:233], v154
	global_load_lds_dwordx4 v130, s[34:35]
	s_mov_b32 m0, s44
	s_nop 0
	global_load_lds_dwordx4 v134, s[34:35]
	s_waitcnt lgkmcnt(0)
	s_barrier
	s_waitcnt lgkmcnt(0)
	s_setprio 1
	s_waitcnt lgkmcnt(0)
	v_mfma_f32_16x16x32_bf16 v[108:111], v[218:221], v[186:189], 0
	v_mfma_f32_16x16x32_bf16 v[104:107], v[226:229], v[186:189], 0
	v_mfma_f32_16x16x32_bf16 v[92:95], v[218:221], v[194:197], 0
	v_mfma_f32_16x16x32_bf16 v[88:91], v[226:229], v[194:197], 0
	v_mfma_f32_16x16x32_bf16 v[76:79], v[218:221], v[202:205], 0
	v_mfma_f32_16x16x32_bf16 v[72:75], v[226:229], v[202:205], 0
	v_mfma_f32_16x16x32_bf16 v[68:71], v[218:221], v[210:213], 0
	v_mfma_f32_16x16x32_bf16 v[64:67], v[226:229], v[210:213], 0
	v_mfma_f32_16x16x32_bf16 v[108:111], v[222:225], v[190:193], v[108:111]
	v_mfma_f32_16x16x32_bf16 v[104:107], v[230:233], v[190:193], v[104:107]
	v_mfma_f32_16x16x32_bf16 v[92:95], v[222:225], v[198:201], v[92:95]
	v_mfma_f32_16x16x32_bf16 v[88:91], v[230:233], v[198:201], v[88:91]
	v_mfma_f32_16x16x32_bf16 v[76:79], v[222:225], v[206:209], v[76:79]
	v_mfma_f32_16x16x32_bf16 v[72:75], v[230:233], v[206:209], v[72:75]
	v_mfma_f32_16x16x32_bf16 v[68:71], v[222:225], v[214:217], v[68:71]
	v_mfma_f32_16x16x32_bf16 v[64:67], v[230:233], v[214:217], v[64:67]
	s_setprio 0
	s_mov_b32 m0, s42
	s_barrier
	ds_read_b128 v[186:189], v145 offset:16384
	ds_read_b128 v[190:193], v145 offset:17408
	ds_read_b128 v[194:197], v145 offset:18432
	ds_read_b128 v[198:201], v145 offset:19456
	ds_read_b128 v[202:205], v145 offset:20480
	ds_read_b128 v[206:209], v145 offset:21504
	ds_read_b128 v[210:213], v145 offset:22528
	ds_read_b128 v[214:217], v145 offset:23552
	global_load_lds_dwordx4 v128, s[36:37]
	s_mov_b32 m0, s45
	s_nop 0
	global_load_lds_dwordx4 v132, s[36:37]
	s_add_u32 s28, s34, 0xb4000
	s_addc_u32 s29, s35, 0
	s_mov_b32 m0, s46
	s_nop 0
	global_load_lds_dwordx4 v130, s[28:29]
	s_mov_b32 m0, s47
	s_nop 0
	global_load_lds_dwordx4 v134, s[28:29]
	s_waitcnt vmcnt(6)
	s_barrier
	s_waitcnt lgkmcnt(0)
	s_setprio 1
	s_waitcnt lgkmcnt(0)
	v_mfma_f32_16x16x32_bf16 v[60:63], v[170:173], v[186:189], 0
	v_mfma_f32_16x16x32_bf16 v[56:59], v[178:181], v[186:189], 0
	v_mfma_f32_16x16x32_bf16 v[52:55], v[170:173], v[194:197], 0
	v_mfma_f32_16x16x32_bf16 v[48:51], v[178:181], v[194:197], 0
	v_mfma_f32_16x16x32_bf16 v[36:39], v[170:173], v[202:205], 0
	v_mfma_f32_16x16x32_bf16 v[32:35], v[178:181], v[202:205], 0
	v_mfma_f32_16x16x32_bf16 v[20:23], v[170:173], v[210:213], 0
	v_mfma_f32_16x16x32_bf16 v[16:19], v[178:181], v[210:213], 0
	v_mfma_f32_16x16x32_bf16 v[60:63], v[174:177], v[190:193], v[60:63]
	v_mfma_f32_16x16x32_bf16 v[56:59], v[182:185], v[190:193], v[56:59]
	v_mfma_f32_16x16x32_bf16 v[52:55], v[174:177], v[198:201], v[52:55]
	v_mfma_f32_16x16x32_bf16 v[48:51], v[182:185], v[198:201], v[48:51]
	v_mfma_f32_16x16x32_bf16 v[36:39], v[174:177], v[206:209], v[36:39]
	v_mfma_f32_16x16x32_bf16 v[32:35], v[182:185], v[206:209], v[32:35]
	v_mfma_f32_16x16x32_bf16 v[20:23], v[174:177], v[214:217], v[20:23]
	v_mfma_f32_16x16x32_bf16 v[16:19], v[182:185], v[214:217], v[16:19]
	v_mfma_f32_16x16x32_bf16 v[44:47], v[218:221], v[186:189], 0
	v_mfma_f32_16x16x32_bf16 v[40:43], v[226:229], v[186:189], 0
	v_mfma_f32_16x16x32_bf16 v[28:31], v[218:221], v[194:197], 0
	v_mfma_f32_16x16x32_bf16 v[24:27], v[226:229], v[194:197], 0
	v_mfma_f32_16x16x32_bf16 v[12:15], v[218:221], v[202:205], 0
	v_mfma_f32_16x16x32_bf16 v[8:11], v[226:229], v[202:205], 0
	v_mfma_f32_16x16x32_bf16 v[4:7], v[218:221], v[210:213], 0
	v_mfma_f32_16x16x32_bf16 v[0:3], v[226:229], v[210:213], 0
	v_mfma_f32_16x16x32_bf16 v[44:47], v[222:225], v[190:193], v[44:47]
	v_mfma_f32_16x16x32_bf16 v[40:43], v[230:233], v[190:193], v[40:43]
	v_mfma_f32_16x16x32_bf16 v[28:31], v[222:225], v[198:201], v[28:31]
	v_mfma_f32_16x16x32_bf16 v[24:27], v[230:233], v[198:201], v[24:27]
	v_mfma_f32_16x16x32_bf16 v[12:15], v[222:225], v[206:209], v[12:15]
	v_mfma_f32_16x16x32_bf16 v[8:11], v[230:233], v[206:209], v[8:11]
	v_mfma_f32_16x16x32_bf16 v[4:7], v[222:225], v[214:217], v[4:7]
	v_mfma_f32_16x16x32_bf16 v[0:3], v[230:233], v[214:217], v[0:3]
	s_setprio 0
	s_barrier
	s_branch .Lzp12_mid
; #define PG8_STAGE(bufoff, gbase, voff) do { _Pragma("unroll") for (int _i = 0; _i < 2; ++_i) \
;         __builtin_amdgcn_global_load_lds((const unsigned*)((const char*)(gbase) + (voff)[_i]), (PG8_LAS unsigned*)(lds + (bufoff) + ldsw + _i * 8192), 16, 0, 0); } while (0)
; #define PG8_LDA(dst, b, h) do { _Pragma("unroll") for (int m = 0; m < 4; ++m) _Pragma("unroll") for (int k = 0; k < 2; ++k) dst[m][k] = *(const PG8_LAS bf16x8*)(lds + PG8_SA(b, h) + aoff + m * 2048 + k * 1024); } while (0)
; #define PG8_LDB(dst, b, h) do { _Pragma("unroll") for (int n = 0; n < 2; ++n) _Pragma("unroll") for (int k = 0; k < 2; ++k) dst[n][k] = *(const PG8_LAS bf16x8*)(lds + PG8_SB(b, h) + boff + n * 2048 + k * 1024); } while (0)
; #define PG8_MMA(ai, bj, At, Bt) do { __builtin_amdgcn_s_setprio(1); _Pragma("unroll") for (int m = 0; m < 4; ++m) _Pragma("unroll") for (int n = 0; n < 2; ++n) _Pragma("unroll") for (int k = 0; k < 2; ++k) \
;         acc[ai][bj][m][n] = __builtin_amdgcn_mfma_f32_16x16x32_bf16(Bt[n][k], At[m][k], acc[ai][bj][m][n], 0, 0, 0); __builtin_amdgcn_s_setprio(0); } while (0)
; #define PG8_WAIT_V(n) asm volatile("s_waitcnt vmcnt(" #n ")" ::: "memory")
; template <class Epi, class Sched, bool STAMP = false>
; __device__ __forceinline__ void gemm_phase(PG8_LAS unsigned char* lds, const Gemm g, const Sched& S, const Epi& E, unsigned long long* stamps) {
;     ...
;             const bool last = (t == nt - 2);
;             const char* a1 = cA + (size_t)(t + 1) * kstep;
;             const char* a2 = last ? nA : cA + (size_t)(t + 2) * kstep; const char* b2 = last ? nB : cB + (size_t)(t + 2) * kstep;
;             const char* a3 = a2 + kstep; const char* b3 = b2 + kstep;
;             if (last && has_next) S.a_ready(nxt);
;             PG8_LDB(B0, 0, 0); PG8_SCHED; PG8_LDA(At, 0, 0); PG8_STAGE(PG8_SA(1, 1), a1 + hstep, voffA);
;             PG8_WAIT_L(8); PG8_BAR; PG8_WAIT_L(0); PG8_MMA(0, 0, At, B0); PG8_BAR; PG8_SCHED;
;             PG8_LDB(B1, 0, 1); PG8_STAGE(PG8_SB(0, 0), b2, voffB);
;             PG8_BAR; PG8_WAIT_L(0); PG8_MMA(0, 1, At, B1); PG8_BAR;
;             PG8_LDA(At, 0, 1); PG8_STAGE(PG8_SA(0, 0), a2, voffA);
;             PG8_BAR; PG8_WAIT_L(0); PG8_MMA(1, 0, At, B0); PG8_BAR; PG8_SCHED;
;             PG8_STAGE(PG8_SB(0, 1), b2 + hstep, voffB);
;             PG8_WAIT_V(6); PG8_BAR; PG8_MMA(1, 1, At, B1); PG8_BAR;
.LBB0_761:
	ds_read_b128 v[170:173], v147
	ds_read_b128 v[174:177], v148
	ds_read_b128 v[178:181], v149
	ds_read_b128 v[182:185], v150
	s_add_u32 s30, s28, 0x100
	s_addc_u32 s31, s29, 0
	s_cmp_eq_u32 s10, 40
	s_cselect_b32 s37, s5, s31
	s_cselect_b32 s36, s4, s30
	s_cselect_b32 s35, s1, s69
	s_cselect_b32 s34, s0, s68
	s_mov_b32 m0, s58
	ds_read_b128 v[186:189], v145
	ds_read_b128 v[190:193], v145 offset:1024
	ds_read_b128 v[194:197], v145 offset:2048
	ds_read_b128 v[198:201], v145 offset:3072
	ds_read_b128 v[202:205], v145 offset:4096
	ds_read_b128 v[206:209], v145 offset:5120
	ds_read_b128 v[210:213], v145 offset:6144
	ds_read_b128 v[214:217], v145 offset:7168
	global_load_lds_dwordx4 v136, s[28:29]
	s_mov_b32 m0, s59
	s_nop 0
	global_load_lds_dwordx4 v138, s[28:29]
	s_waitcnt lgkmcnt(8)
	s_barrier
	s_waitcnt lgkmcnt(0)
	s_setprio 1
	s_waitcnt lgkmcnt(0)
	v_mfma_f32_16x16x32_bf16 v[124:127], v[170:173], v[186:189], v[124:127]
	v_mfma_f32_16x16x32_bf16 v[120:123], v[178:181], v[186:189], v[120:123]
	v_mfma_f32_16x16x32_bf16 v[116:119], v[170:173], v[194:197], v[116:119]
	v_mfma_f32_16x16x32_bf16 v[112:115], v[178:181], v[194:197], v[112:115]
	v_mfma_f32_16x16x32_bf16 v[100:103], v[170:173], v[202:205], v[100:103]
	v_mfma_f32_16x16x32_bf16 v[96:99], v[178:181], v[202:205], v[96:99]
	v_mfma_f32_16x16x32_bf16 v[84:87], v[170:173], v[210:213], v[84:87]
	v_mfma_f32_16x16x32_bf16 v[80:83], v[178:181], v[210:213], v[80:83]
	v_mfma_f32_16x16x32_bf16 v[124:127], v[174:177], v[190:193], v[124:127]
	v_mfma_f32_16x16x32_bf16 v[120:123], v[182:185], v[190:193], v[120:123]
	v_mfma_f32_16x16x32_bf16 v[116:119], v[174:177], v[198:201], v[116:119]
	v_mfma_f32_16x16x32_bf16 v[112:115], v[182:185], v[198:201], v[112:115]
	v_mfma_f32_16x16x32_bf16 v[100:103], v[174:177], v[206:209], v[100:103]
	v_mfma_f32_16x16x32_bf16 v[96:99], v[182:185], v[206:209], v[96:99]
	v_mfma_f32_16x16x32_bf16 v[84:87], v[174:177], v[214:217], v[84:87]
	v_mfma_f32_16x16x32_bf16 v[80:83], v[182:185], v[214:217], v[80:83]
	s_setprio 0
	s_barrier
	s_mov_b32 m0, s43
	ds_read_b128 v[218:221], v151
	ds_read_b128 v[222:225], v152
	ds_read_b128 v[226:229], v153
	ds_read_b128 v[230:233], v154
	global_load_lds_dwordx4 v130, s[34:35]
	s_mov_b32 m0, s44
	s_nop 0
	global_load_lds_dwordx4 v134, s[34:35]
	s_waitcnt lgkmcnt(0)
	s_barrier
	s_waitcnt lgkmcnt(0)
	s_setprio 1
	s_waitcnt lgkmcnt(0)
	v_mfma_f32_16x16x32_bf16 v[108:111], v[218:221], v[186:189], v[108:111]
	v_mfma_f32_16x16x32_bf16 v[104:107], v[226:229], v[186:189], v[104:107]
	v_mfma_f32_16x16x32_bf16 v[92:95], v[218:221], v[194:197], v[92:95]
	v_mfma_f32_16x16x32_bf16 v[88:91], v[226:229], v[194:197], v[88:91]
	v_mfma_f32_16x16x32_bf16 v[76:79], v[218:221], v[202:205], v[76:79]
	v_mfma_f32_16x16x32_bf16 v[72:75], v[226:229], v[202:205], v[72:75]
	v_mfma_f32_16x16x32_bf16 v[68:71], v[218:221], v[210:213], v[68:71]
	v_mfma_f32_16x16x32_bf16 v[64:67], v[226:229], v[210:213], v[64:67]
	v_mfma_f32_16x16x32_bf16 v[108:111], v[222:225], v[190:193], v[108:111]
	v_mfma_f32_16x16x32_bf16 v[104:107], v[230:233], v[190:193], v[104:107]
	v_mfma_f32_16x16x32_bf16 v[92:95], v[222:225], v[198:201], v[92:95]
	v_mfma_f32_16x16x32_bf16 v[88:91], v[230:233], v[198:201], v[88:91]
	v_mfma_f32_16x16x32_bf16 v[76:79], v[222:225], v[206:209], v[76:79]
	v_mfma_f32_16x16x32_bf16 v[72:75], v[230:233], v[206:209], v[72:75]
	v_mfma_f32_16x16x32_bf16 v[68:71], v[222:225], v[214:217], v[68:71]
	v_mfma_f32_16x16x32_bf16 v[64:67], v[230:233], v[214:217], v[64:67]
	s_setprio 0
	s_mov_b32 m0, s42
	s_barrier
	ds_read_b128 v[186:189], v145 offset:16384
	ds_read_b128 v[190:193], v145 offset:17408
	ds_read_b128 v[194:197], v145 offset:18432
	ds_read_b128 v[198:201], v145 offset:19456
	ds_read_b128 v[202:205], v145 offset:20480
	ds_read_b128 v[206:209], v145 offset:21504
	ds_read_b128 v[210:213], v145 offset:22528
	ds_read_b128 v[214:217], v145 offset:23552
	global_load_lds_dwordx4 v128, s[36:37]
	s_mov_b32 m0, s45
	s_nop 0
	global_load_lds_dwordx4 v132, s[36:37]
	s_add_u32 s28, s34, 0xb4000
	s_addc_u32 s29, s35, 0
	s_mov_b32 m0, s46
	s_nop 0
	global_load_lds_dwordx4 v130, s[28:29]
	s_mov_b32 m0, s47
	s_nop 0
	global_load_lds_dwordx4 v134, s[28:29]
	s_waitcnt vmcnt(6)
	s_barrier
	s_waitcnt lgkmcnt(0)
	s_setprio 1
	s_waitcnt lgkmcnt(0)
	v_mfma_f32_16x16x32_bf16 v[60:63], v[170:173], v[186:189], v[60:63]
	v_mfma_f32_16x16x32_bf16 v[56:59], v[178:181], v[186:189], v[56:59]
	v_mfma_f32_16x16x32_bf16 v[52:55], v[170:173], v[194:197], v[52:55]
	v_mfma_f32_16x16x32_bf16 v[48:51], v[178:181], v[194:197], v[48:51]
	v_mfma_f32_16x16x32_bf16 v[36:39], v[170:173], v[202:205], v[36:39]
	v_mfma_f32_16x16x32_bf16 v[32:35], v[178:181], v[202:205], v[32:35]
	v_mfma_f32_16x16x32_bf16 v[20:23], v[170:173], v[210:213], v[20:23]
	v_mfma_f32_16x16x32_bf16 v[16:19], v[178:181], v[210:213], v[16:19]
	v_mfma_f32_16x16x32_bf16 v[60:63], v[174:177], v[190:193], v[60:63]
	v_mfma_f32_16x16x32_bf16 v[56:59], v[182:185], v[190:193], v[56:59]
	v_mfma_f32_16x16x32_bf16 v[52:55], v[174:177], v[198:201], v[52:55]
	v_mfma_f32_16x16x32_bf16 v[48:51], v[182:185], v[198:201], v[48:51]
	v_mfma_f32_16x16x32_bf16 v[36:39], v[174:177], v[206:209], v[36:39]
	v_mfma_f32_16x16x32_bf16 v[32:35], v[182:185], v[206:209], v[32:35]
	v_mfma_f32_16x16x32_bf16 v[20:23], v[174:177], v[214:217], v[20:23]
	v_mfma_f32_16x16x32_bf16 v[16:19], v[182:185], v[214:217], v[16:19]
	v_mfma_f32_16x16x32_bf16 v[44:47], v[218:221], v[186:189], v[44:47]
	v_mfma_f32_16x16x32_bf16 v[40:43], v[226:229], v[186:189], v[40:43]
	v_mfma_f32_16x16x32_bf16 v[28:31], v[218:221], v[194:197], v[28:31]
	v_mfma_f32_16x16x32_bf16 v[24:27], v[226:229], v[194:197], v[24:27]
	v_mfma_f32_16x16x32_bf16 v[12:15], v[218:221], v[202:205], v[12:15]
	v_mfma_f32_16x16x32_bf16 v[8:11], v[226:229], v[202:205], v[8:11]
	v_mfma_f32_16x16x32_bf16 v[4:7], v[218:221], v[210:213], v[4:7]
	v_mfma_f32_16x16x32_bf16 v[0:3], v[226:229], v[210:213], v[0:3]
	v_mfma_f32_16x16x32_bf16 v[44:47], v[222:225], v[190:193], v[44:47]
	v_mfma_f32_16x16x32_bf16 v[40:43], v[230:233], v[190:193], v[40:43]
	v_mfma_f32_16x16x32_bf16 v[28:31], v[222:225], v[198:201], v[28:31]
	v_mfma_f32_16x16x32_bf16 v[24:27], v[230:233], v[198:201], v[24:27]
	v_mfma_f32_16x16x32_bf16 v[12:15], v[222:225], v[206:209], v[12:15]
	v_mfma_f32_16x16x32_bf16 v[8:11], v[230:233], v[206:209], v[8:11]
	v_mfma_f32_16x16x32_bf16 v[4:7], v[222:225], v[214:217], v[4:7]
	v_mfma_f32_16x16x32_bf16 v[0:3], v[230:233], v[214:217], v[0:3]
	s_setprio 0
	s_barrier
; #define PG8_STAGE(bufoff, gbase, voff) do { _Pragma("unroll") for (int _i = 0; _i < 2; ++_i) \
;         __builtin_amdgcn_global_load_lds((const unsigned*)((const char*)(gbase) + (voff)[_i]), (PG8_LAS unsigned*)(lds + (bufoff) + ldsw + _i * 8192), 16, 0, 0); } while (0)
; #define PG8_LDA(dst, b, h) do { _Pragma("unroll") for (int m = 0; m < 4; ++m) _Pragma("unroll") for (int k = 0; k < 2; ++k) dst[m][k] = *(const PG8_LAS bf16x8*)(lds + PG8_SA(b, h) + aoff + m * 2048 + k * 1024); } while (0)
; #define PG8_LDB(dst, b, h) do { _Pragma("unroll") for (int n = 0; n < 2; ++n) _Pragma("unroll") for (int k = 0; k < 2; ++k) dst[n][k] = *(const PG8_LAS bf16x8*)(lds + PG8_SB(b, h) + boff + n * 2048 + k * 1024); } while (0)
; #define PG8_MMA(ai, bj, At, Bt) do { __builtin_amdgcn_s_setprio(1); _Pragma("unroll") for (int m = 0; m < 4; ++m) _Pragma("unroll") for (int n = 0; n < 2; ++n) _Pragma("unroll") for (int k = 0; k < 2; ++k) \
;         acc[ai][bj][m][n] = __builtin_amdgcn_mfma_f32_16x16x32_bf16(Bt[n][k], At[m][k], acc[ai][bj][m][n], 0, 0, 0); __builtin_amdgcn_s_setprio(0); } while (0)
; #define PG8_WAIT_V(n) asm volatile("s_waitcnt vmcnt(" #n ")" ::: "memory")
; #define PG8_WAIT_L(n) asm volatile("s_waitcnt lgkmcnt(" #n ")" ::: "memory")
; #define PG8_BAR __builtin_amdgcn_s_barrier()
; #define PG8_SCHED __builtin_amdgcn_sched_barrier(0)
; template <class Epi, class Sched, bool STAMP = false>
; __device__ __forceinline__ void gemm_phase(PG8_LAS unsigned char* lds, const Gemm g, const Sched& S, const Epi& E, unsigned long long* stamps) {
;     ...
;             PG8_LDB(B0, 1, 0); PG8_SCHED; PG8_LDA(At, 1, 0); PG8_STAGE(PG8_SA(0, 1), a2 + hstep, voffA);
;             PG8_WAIT_L(8); PG8_BAR; PG8_WAIT_L(0); PG8_MMA(0, 0, At, B0); PG8_BAR; PG8_SCHED;
;             PG8_LDB(B1, 1, 1); PG8_STAGE(PG8_SB(1, 0), b3, voffB);
;             PG8_BAR; PG8_WAIT_L(0); PG8_MMA(0, 1, At, B1); PG8_BAR;
;             PG8_LDA(At, 1, 1); PG8_STAGE(PG8_SA(1, 0), a3, voffA);
;             PG8_BAR; PG8_WAIT_L(0); PG8_MMA(1, 0, At, B0); PG8_BAR; PG8_SCHED;
;             PG8_STAGE(PG8_SB(1, 1), b3 + hstep, voffB);
;             PG8_WAIT_V(6); PG8_BAR; PG8_MMA(1, 1, At, B1); PG8_BAR;
.Lzp12_mid:
	ds_read_b128 v[170:173], v155
	ds_read_b128 v[174:177], v156
	ds_read_b128 v[178:181], v157
	ds_read_b128 v[182:185], v165
	s_add_u32 s28, s36, 0xb4000
	s_addc_u32 s29, s37, 0
	s_mov_b32 m0, s48
	ds_read_b128 v[186:189], v145 offset:32768
	ds_read_b128 v[190:193], v145 offset:33792
	ds_read_b128 v[194:197], v145 offset:34816
	ds_read_b128 v[198:201], v145 offset:35840
	ds_read_b128 v[202:205], v145 offset:36864
	ds_read_b128 v[206:209], v145 offset:37888
	ds_read_b128 v[210:213], v145 offset:38912
	ds_read_b128 v[214:217], v145 offset:39936
	global_load_lds_dwordx4 v128, s[28:29]
	s_mov_b32 m0, s49
	s_nop 0
	global_load_lds_dwordx4 v132, s[28:29]
	s_waitcnt lgkmcnt(8)
	s_barrier
	s_waitcnt lgkmcnt(0)
	s_setprio 1
	s_waitcnt lgkmcnt(0)
	v_mfma_f32_16x16x32_bf16 v[124:127], v[170:173], v[186:189], v[124:127]
	v_mfma_f32_16x16x32_bf16 v[120:123], v[178:181], v[186:189], v[120:123]
	v_mfma_f32_16x16x32_bf16 v[116:119], v[170:173], v[194:197], v[116:119]
	v_mfma_f32_16x16x32_bf16 v[112:115], v[178:181], v[194:197], v[112:115]
	v_mfma_f32_16x16x32_bf16 v[100:103], v[170:173], v[202:205], v[100:103]
	v_mfma_f32_16x16x32_bf16 v[96:99], v[178:181], v[202:205], v[96:99]
	v_mfma_f32_16x16x32_bf16 v[84:87], v[170:173], v[210:213], v[84:87]
	v_mfma_f32_16x16x32_bf16 v[80:83], v[178:181], v[210:213], v[80:83]
	v_mfma_f32_16x16x32_bf16 v[124:127], v[174:177], v[190:193], v[124:127]
	v_mfma_f32_16x16x32_bf16 v[120:123], v[182:185], v[190:193], v[120:123]
	v_mfma_f32_16x16x32_bf16 v[116:119], v[174:177], v[198:201], v[116:119]
	v_mfma_f32_16x16x32_bf16 v[112:115], v[182:185], v[198:201], v[112:115]
	v_mfma_f32_16x16x32_bf16 v[100:103], v[174:177], v[206:209], v[100:103]
	v_mfma_f32_16x16x32_bf16 v[96:99], v[182:185], v[206:209], v[96:99]
	v_mfma_f32_16x16x32_bf16 v[84:87], v[174:177], v[214:217], v[84:87]
	v_mfma_f32_16x16x32_bf16 v[80:83], v[182:185], v[214:217], v[80:83]
	s_setprio 0
	s_barrier
	s_mov_b32 m0, s50
	ds_read_b128 v[218:221], v166
	ds_read_b128 v[222:225], v167
	ds_read_b128 v[226:229], v168
	ds_read_b128 v[230:233], v169
	s_add_u32 s100, s34, 0x80
	s_addc_u32 s101, s35, 0
	global_load_lds_dwordx4 v130, s[100:101]
	s_mov_b32 m0, s51
	s_nop 0
	global_load_lds_dwordx4 v134, s[100:101]
	s_waitcnt lgkmcnt(0)
	s_barrier
	s_waitcnt lgkmcnt(0)
	s_setprio 1
	s_waitcnt lgkmcnt(0)
	v_mfma_f32_16x16x32_bf16 v[108:111], v[218:221], v[186:189], v[108:111]
	v_mfma_f32_16x16x32_bf16 v[104:107], v[226:229], v[186:189], v[104:107]
	v_mfma_f32_16x16x32_bf16 v[92:95], v[218:221], v[194:197], v[92:95]
	v_mfma_f32_16x16x32_bf16 v[88:91], v[226:229], v[194:197], v[88:91]
	v_mfma_f32_16x16x32_bf16 v[76:79], v[218:221], v[202:205], v[76:79]
	v_mfma_f32_16x16x32_bf16 v[72:75], v[226:229], v[202:205], v[72:75]
	v_mfma_f32_16x16x32_bf16 v[68:71], v[218:221], v[210:213], v[68:71]
	v_mfma_f32_16x16x32_bf16 v[64:67], v[226:229], v[210:213], v[64:67]
	v_mfma_f32_16x16x32_bf16 v[108:111], v[222:225], v[190:193], v[108:111]
	v_mfma_f32_16x16x32_bf16 v[104:107], v[230:233], v[190:193], v[104:107]
	v_mfma_f32_16x16x32_bf16 v[92:95], v[222:225], v[198:201], v[92:95]
	v_mfma_f32_16x16x32_bf16 v[88:91], v[230:233], v[198:201], v[88:91]
	v_mfma_f32_16x16x32_bf16 v[76:79], v[222:225], v[206:209], v[76:79]
	v_mfma_f32_16x16x32_bf16 v[72:75], v[230:233], v[206:209], v[72:75]
	v_mfma_f32_16x16x32_bf16 v[68:71], v[222:225], v[214:217], v[68:71]
	v_mfma_f32_16x16x32_bf16 v[64:67], v[230:233], v[214:217], v[64:67]
	s_setprio 0
	s_mov_b32 m0, s52
	s_barrier
	ds_read_b128 v[186:189], v145 offset:49152
	ds_read_b128 v[190:193], v145 offset:50176
	ds_read_b128 v[194:197], v145 offset:51200
	ds_read_b128 v[198:201], v145 offset:52224
	ds_read_b128 v[202:205], v145 offset:53248
	ds_read_b128 v[206:209], v145 offset:54272
	ds_read_b128 v[210:213], v145 offset:55296
	ds_read_b128 v[214:217], v145 offset:56320
	s_add_u32 s100, s36, 0x80
	s_addc_u32 s101, s37, 0
	global_load_lds_dwordx4 v128, s[100:101]
	s_mov_b32 m0, s53
	s_nop 0
	global_load_lds_dwordx4 v132, s[100:101]
	s_add_u32 s28, s34, 0xb4080
	s_addc_u32 s29, s35, 0
	s_mov_b32 m0, s54
	s_nop 0
	global_load_lds_dwordx4 v130, s[28:29]
	s_mov_b32 m0, s55
	s_nop 0
	global_load_lds_dwordx4 v134, s[28:29]
	s_waitcnt vmcnt(6)
	s_barrier
	s_waitcnt lgkmcnt(0)
	s_setprio 1
	s_waitcnt lgkmcnt(0)
	v_mfma_f32_16x16x32_bf16 v[60:63], v[170:173], v[186:189], v[60:63]
	v_mfma_f32_16x16x32_bf16 v[56:59], v[178:181], v[186:189], v[56:59]
	v_mfma_f32_16x16x32_bf16 v[52:55], v[170:173], v[194:197], v[52:55]
	v_mfma_f32_16x16x32_bf16 v[48:51], v[178:181], v[194:197], v[48:51]
	v_mfma_f32_16x16x32_bf16 v[36:39], v[170:173], v[202:205], v[36:39]
	v_mfma_f32_16x16x32_bf16 v[32:35], v[178:181], v[202:205], v[32:35]
	v_mfma_f32_16x16x32_bf16 v[20:23], v[170:173], v[210:213], v[20:23]
	v_mfma_f32_16x16x32_bf16 v[16:19], v[178:181], v[210:213], v[16:19]
	v_mfma_f32_16x16x32_bf16 v[60:63], v[174:177], v[190:193], v[60:63]
	v_mfma_f32_16x16x32_bf16 v[56:59], v[182:185], v[190:193], v[56:59]
	v_mfma_f32_16x16x32_bf16 v[52:55], v[174:177], v[198:201], v[52:55]
	v_mfma_f32_16x16x32_bf16 v[48:51], v[182:185], v[198:201], v[48:51]
	v_mfma_f32_16x16x32_bf16 v[36:39], v[174:177], v[206:209], v[36:39]
	v_mfma_f32_16x16x32_bf16 v[32:35], v[182:185], v[206:209], v[32:35]
	v_mfma_f32_16x16x32_bf16 v[20:23], v[174:177], v[214:217], v[20:23]
	v_mfma_f32_16x16x32_bf16 v[16:19], v[182:185], v[214:217], v[16:19]
	v_mfma_f32_16x16x32_bf16 v[44:47], v[218:221], v[186:189], v[44:47]
	v_mfma_f32_16x16x32_bf16 v[40:43], v[226:229], v[186:189], v[40:43]
	v_mfma_f32_16x16x32_bf16 v[28:31], v[218:221], v[194:197], v[28:31]
	v_mfma_f32_16x16x32_bf16 v[24:27], v[226:229], v[194:197], v[24:27]
	v_mfma_f32_16x16x32_bf16 v[12:15], v[218:221], v[202:205], v[12:15]
	v_mfma_f32_16x16x32_bf16 v[8:11], v[226:229], v[202:205], v[8:11]
	v_mfma_f32_16x16x32_bf16 v[4:7], v[218:221], v[210:213], v[4:7]
	v_mfma_f32_16x16x32_bf16 v[0:3], v[226:229], v[210:213], v[0:3]
	v_mfma_f32_16x16x32_bf16 v[44:47], v[222:225], v[190:193], v[44:47]
	v_mfma_f32_16x16x32_bf16 v[40:43], v[230:233], v[190:193], v[40:43]
	v_mfma_f32_16x16x32_bf16 v[28:31], v[222:225], v[198:201], v[28:31]
	v_mfma_f32_16x16x32_bf16 v[24:27], v[230:233], v[198:201], v[24:27]
	v_mfma_f32_16x16x32_bf16 v[12:15], v[222:225], v[206:209], v[12:15]
	v_mfma_f32_16x16x32_bf16 v[8:11], v[230:233], v[206:209], v[8:11]
	v_mfma_f32_16x16x32_bf16 v[4:7], v[222:225], v[214:217], v[4:7]
	v_mfma_f32_16x16x32_bf16 v[0:3], v[230:233], v[214:217], v[0:3]
	s_setprio 0
	s_add_i32 s10, s10, 2
	s_add_u32 s68, s68, 0x100
	s_addc_u32 s69, s69, 0
	s_cmp_gt_u32 s10, 41
	s_mov_b64 s[28:29], s[30:31]
	s_barrier
; #define PG8_WAIT_V(n) asm volatile("s_waitcnt vmcnt(" #n ")" ::: "memory")
; #define PG8_BAR __builtin_amdgcn_s_barrier()
;     DI void operator()(const f32x4 (&acc)[2][2][4][2], const Unit& u, int wr, int wc, int fr, int fq) const {
;         const int row0 = u.pm * BM + wr * 64 + fr, col0 = u.pn * BM + wc * 32 + 8 * fq;
; #pragma unroll
;         for (int ai = 0; ai < 2; ++ai)
; #pragma unroll
;             for (int m = 0; m < 4; ++m) { u16* rowp = O + (size_t)(row0 + ai * HALF + m * 16) * ldc + col0;
; #pragma unroll
;                 for (int bj = 0; bj < 2; ++bj) { const f32x4 v0 = acc[ai][bj][m][0], v1 = acc[ai][bj][m][1];
;                     uint4 w = {pack2(v0[0], v0[1]), pack2(v0[2], v0[3]), pack2(v1[0], v1[1]), pack2(v1[2], v1[3])}; *(uint4*)(rowp + bj * HALF) = w; } }
; template <class Epi, class Sched, bool STAMP = false>
; __device__ __forceinline__ void gemm_phase(PG8_LAS unsigned char* lds, const Gemm g, const Sched& S, const Epi& E, unsigned long long* stamps) {
;     ...
;         cur = nxt; cA = nA; cB = nB; ++ui;
;     }
;     PG8_WAIT_V(0);
;     if (wr == 0) PG8_BAR;
;     PG8_BAR;
	s_cbranch_scc0 .LBB0_761
	v_lshl_add_u32 v170, s64, 8, v144
	v_lshl_or_b32 v172, s67, 8, v146
	v_ashrrev_i32_e32 v171, 31, v170
	v_ashrrev_i32_e32 v173, 31, v172
	v_lshlrev_b64 v[174:175], 11, v[170:171]
	v_lshl_add_u64 v[174:175], s[14:15], 0, v[174:175]
	v_lshlrev_b64 v[172:173], 1, v[172:173]
	v_lshl_add_u64 v[174:175], v[174:175], 0, v[172:173]
	v_cvt_pk_bf16_f32 v60, v60, v61
	v_cvt_pk_bf16_f32 v61, v62, v63
	v_cvt_pk_bf16_f32 v62, v56, v57
	v_add_co_u32_e32 v56, vcc, s60, v174
	v_cvt_pk_bf16_f32 v68, v68, v69
	v_cvt_pk_bf16_f32 v69, v70, v71
	v_cvt_pk_bf16_f32 v70, v64, v65
	v_lshl_add_u64 v[64:65], v[174:175], 0, s[16:17]
	v_addc_co_u32_e32 v57, vcc, 0, v175, vcc
	v_cvt_pk_bf16_f32 v44, v44, v45
	v_cvt_pk_bf16_f32 v45, v46, v47
	v_cvt_pk_bf16_f32 v46, v40, v41
	v_cvt_pk_bf16_f32 v47, v42, v43
	v_cvt_pk_bf16_f32 v108, v108, v109
	v_cvt_pk_bf16_f32 v109, v110, v111
	v_cvt_pk_bf16_f32 v110, v104, v105
	v_or_b32_e32 v104, 16, v170
	global_store_dwordx4 v[64:65], v[44:47], off offset:256
	v_ashrrev_i32_e32 v105, 31, v104
	v_cvt_pk_bf16_f32 v92, v92, v93
	v_add_co_u32_e32 v46, vcc, s61, v174
	v_cvt_pk_bf16_f32 v93, v94, v95
	v_cvt_pk_bf16_f32 v94, v88, v89
	v_or_b32_e32 v88, 32, v170
	v_lshl_add_u64 v[44:45], v[174:175], 0, s[18:19]
	v_addc_co_u32_e32 v47, vcc, 0, v175, vcc
	v_cvt_pk_bf16_f32 v28, v28, v29
	v_cvt_pk_bf16_f32 v29, v30, v31
	v_cvt_pk_bf16_f32 v30, v24, v25
	v_cvt_pk_bf16_f32 v31, v26, v27
	v_lshlrev_b64 v[104:105], 11, v[104:105]
	v_ashrrev_i32_e32 v89, 31, v88
	v_cvt_pk_bf16_f32 v76, v76, v77
	v_cvt_pk_bf16_f32 v77, v78, v79
	v_cvt_pk_bf16_f32 v78, v72, v73
	v_or_b32_e32 v72, 48, v170
	global_store_dwordx4 v[44:45], v[28:31], off offset:256
	v_cvt_pk_bf16_f32 v111, v106, v107
	v_lshl_add_u64 v[104:105], s[14:15], 0, v[104:105]
	v_add_co_u32_e32 v30, vcc, s62, v174
	v_lshlrev_b64 v[88:89], 11, v[88:89]
	v_ashrrev_i32_e32 v73, 31, v72
	v_lshl_add_u64 v[28:29], v[174:175], 0, s[20:21]
	v_addc_co_u32_e32 v31, vcc, 0, v175, vcc
	v_cvt_pk_bf16_f32 v12, v12, v13
	v_cvt_pk_bf16_f32 v13, v14, v15
	v_cvt_pk_bf16_f32 v14, v8, v9
	v_cvt_pk_bf16_f32 v15, v10, v11
	global_store_dwordx4 v[174:175], v[108:111], off offset:256
	v_cvt_pk_bf16_f32 v95, v90, v91
	v_lshl_add_u64 v[88:89], s[14:15], 0, v[88:89]
	v_lshl_add_u64 v[108:109], v[104:105], 0, v[172:173]
	v_lshlrev_b64 v[72:73], 11, v[72:73]
	global_store_dwordx4 v[28:29], v[12:15], off offset:256
	global_store_dwordx4 v[108:109], v[92:95], off offset:256
	v_cvt_pk_bf16_f32 v79, v74, v75
	v_add_co_u32_e32 v14, vcc, s63, v174
	v_lshl_add_u64 v[92:93], v[88:89], 0, v[172:173]
	v_lshl_add_u64 v[72:73], s[14:15], 0, v[72:73]
	v_addc_co_u32_e32 v15, vcc, 0, v175, vcc
	v_cvt_pk_bf16_f32 v124, v124, v125
	v_cvt_pk_bf16_f32 v125, v126, v127
	v_cvt_pk_bf16_f32 v126, v120, v121
	v_cvt_pk_bf16_f32 v127, v122, v123
	v_cvt_pk_bf16_f32 v104, v116, v117
	v_cvt_pk_bf16_f32 v105, v118, v119
	v_cvt_pk_bf16_f32 v106, v112, v113
	v_cvt_pk_bf16_f32 v107, v114, v115
	v_cvt_pk_bf16_f32 v88, v100, v101
	v_cvt_pk_bf16_f32 v89, v102, v103
	v_cvt_pk_bf16_f32 v90, v96, v97
	v_cvt_pk_bf16_f32 v91, v98, v99
	global_store_dwordx4 v[92:93], v[76:79], off offset:256
	v_cvt_pk_bf16_f32 v74, v80, v81
	v_cvt_pk_bf16_f32 v75, v82, v83
	v_lshl_add_u64 v[76:77], v[72:73], 0, v[172:173]
	v_cvt_pk_bf16_f32 v72, v84, v85
	v_cvt_pk_bf16_f32 v73, v86, v87
	v_cvt_pk_bf16_f32 v71, v66, v67
	v_cvt_pk_bf16_f32 v63, v58, v59
	v_cvt_pk_bf16_f32 v40, v52, v53
	v_cvt_pk_bf16_f32 v41, v54, v55
	v_cvt_pk_bf16_f32 v42, v48, v49
	v_cvt_pk_bf16_f32 v43, v50, v51
	v_cvt_pk_bf16_f32 v24, v36, v37
	v_cvt_pk_bf16_f32 v25, v38, v39
	v_cvt_pk_bf16_f32 v26, v32, v33
	v_cvt_pk_bf16_f32 v27, v34, v35
	v_lshl_add_u64 v[12:13], v[174:175], 0, s[26:27]
	v_cvt_pk_bf16_f32 v8, v20, v21
	v_cvt_pk_bf16_f32 v9, v22, v23
	v_cvt_pk_bf16_f32 v10, v16, v17
	v_cvt_pk_bf16_f32 v11, v18, v19
	v_cvt_pk_bf16_f32 v4, v4, v5
	v_cvt_pk_bf16_f32 v5, v6, v7
	v_cvt_pk_bf16_f32 v6, v0, v1
	v_cvt_pk_bf16_f32 v7, v2, v3
	s_and_b64 vcc, exec, s[2:3]
	s_mov_b32 s67, s65
	s_mov_b32 s64, s66
	s_mov_b64 s[30:31], s[0:1]
	s_mov_b64 s[28:29], s[4:5]
	global_store_dwordx4 v[174:175], v[124:127], off
	global_store_dwordx4 v[108:109], v[104:107], off
	global_store_dwordx4 v[92:93], v[88:91], off
	global_store_dwordx4 v[76:77], v[72:75], off
	global_store_dwordx4 v[76:77], v[68:71], off offset:256
	global_store_dwordx4 v[56:57], v[60:63], off
	global_store_dwordx4 v[46:47], v[40:43], off
	global_store_dwordx4 v[30:31], v[24:27], off
	global_store_dwordx4 v[14:15], v[8:11], off
	global_store_dwordx4 v[12:13], v[4:7], off offset:256
	s_cbranch_vccz .LBB0_750
	s_waitcnt vmcnt(0)
	s_cmpk_gt_u32 s40, 0xff
	s_cbranch_scc1 .LBB0_765
	s_barrier
